# MLA attention: s_setprio 1 during softmax+PV segment, 0 during QK scores segment (balances the two waves of a SIMD; even waves waited 36% at barriers)
# speedup vs baseline: 1.0238x; 1.0238x over previous
.LBB0_711:
	s_nop 2
	v_mov_b32_e32 v0, v34
	s_nop 1
	v_permlane32_swap_b32_e32 v34, v0
	v_add_f32_e32 v0, v34, v0
	v_div_scale_f32 v34, s[0:1], v0, v0, 1.0
	v_rcp_f32_e32 v35, v34
	v_readlane_b32 s0, v248, 9
	s_mulk_i32 s0, 0x1200
	s_add_i32 s2, s0, 0
	v_fma_f32 v36, -v34, v35, 1.0
	v_fmac_f32_e32 v35, v36, v35
	v_div_scale_f32 v36, vcc, 1.0, v0, 1.0
	v_mul_f32_e32 v37, v36, v35
	v_fma_f32 v38, -v34, v37, v36
	v_fmac_f32_e32 v37, v38, v35
	v_fma_f32 v34, -v34, v37, v36
	v_div_fmas_f32 v34, v34, v35, v37
	v_div_fixup_f32 v0, v34, v0, 1.0
	v_pk_mul_f32 v[2:3], v[2:3], v[0:1] op_sel_hi:[1,0]
	v_pk_mul_f32 v[4:5], v[4:5], v[0:1] op_sel_hi:[1,0]
	v_add3_u32 v34, s2, v131, v106
	v_cvt_pk_bf16_f32 v2, v2, v3
	v_cvt_pk_bf16_f32 v3, v4, v5
	v_pk_mul_f32 v[4:5], v[6:7], v[0:1] op_sel_hi:[1,0]
	v_pk_mul_f32 v[6:7], v[8:9], v[0:1] op_sel_hi:[1,0]
	v_cvt_pk_bf16_f32 v4, v4, v5
	v_cvt_pk_bf16_f32 v5, v6, v7
	v_add_u32_e32 v8, 0x9000, v34
	s_waitcnt vmcnt(0) lgkmcnt(0)
	s_barrier
	ds_write2_b64 v8, v[2:3], v[4:5] offset1:2
	v_pk_mul_f32 v[2:3], v[10:11], v[0:1] op_sel_hi:[1,0]
	v_pk_mul_f32 v[4:5], v[12:13], v[0:1] op_sel_hi:[1,0]
	v_cvt_pk_bf16_f32 v2, v2, v3
	v_cvt_pk_bf16_f32 v3, v4, v5
	v_pk_mul_f32 v[4:5], v[14:15], v[0:1] op_sel_hi:[1,0]
	v_pk_mul_f32 v[6:7], v[16:17], v[0:1] op_sel_hi:[1,0]
	v_cvt_pk_bf16_f32 v4, v4, v5
	v_cvt_pk_bf16_f32 v5, v6, v7
	ds_write2_b64 v8, v[2:3], v[4:5] offset0:4 offset1:6
	v_pk_mul_f32 v[2:3], v[18:19], v[0:1] op_sel_hi:[1,0]
	v_pk_mul_f32 v[4:5], v[20:21], v[0:1] op_sel_hi:[1,0]
	v_cvt_pk_bf16_f32 v2, v2, v3
	v_cvt_pk_bf16_f32 v3, v4, v5
	v_pk_mul_f32 v[4:5], v[22:23], v[0:1] op_sel_hi:[1,0]
	v_pk_mul_f32 v[6:7], v[24:25], v[0:1] op_sel_hi:[1,0]
	v_cvt_pk_bf16_f32 v4, v4, v5
	v_cvt_pk_bf16_f32 v5, v6, v7
	ds_write2_b64 v8, v[2:3], v[4:5] offset0:8 offset1:10
	v_pk_mul_f32 v[2:3], v[26:27], v[0:1] op_sel_hi:[1,0]
	v_pk_mul_f32 v[4:5], v[28:29], v[0:1] op_sel_hi:[1,0]
	v_cvt_pk_bf16_f32 v2, v2, v3
	v_cvt_pk_bf16_f32 v3, v4, v5
	v_pk_mul_f32 v[4:5], v[30:31], v[0:1] op_sel_hi:[1,0]
	v_pk_mul_f32 v[6:7], v[32:33], v[0:1] op_sel_hi:[1,0]
	v_readlane_b32 s0, v248, 7
	v_cvt_pk_bf16_f32 v4, v4, v5
	v_cvt_pk_bf16_f32 v5, v6, v7
	v_readlane_b32 s1, v248, 8
	ds_write2_b64 v8, v[2:3], v[4:5] offset0:12 offset1:14
	s_lshl_b64 s[0:1], s[0:1], 11
	v_readlane_b32 s10, v249, 53
	s_waitcnt lgkmcnt(0)
	v_readlane_b32 s11, v249, 54
	s_add_u32 s0, s10, s0
	v_readlane_b32 s3, v248, 6
	v_add3_u32 v0, s2, v132, v133
	s_addc_u32 s1, s11, s1
	s_lshl_b32 s3, s3, 1
	ds_read_b128 v[2:5], v0 offset:36864
	s_add_u32 s0, s0, s3
	ds_read_b128 v[6:9], v0 offset:38016
	s_addc_u32 s1, s1, 0
	v_mov_b32_e32 v113, v1
	v_lshl_add_u64 v[10:11], s[0:1], 0, v[112:113]
	v_mov_b32_e32 v115, v1
	v_lshl_add_u64 v[12:13], v[10:11], 0, v[114:115]
	v_mov_b32_e32 v117, v1
	s_waitcnt lgkmcnt(0)
	global_store_dwordx4 v[12:13], v[2:5], off
	v_lshl_add_u64 v[12:13], v[10:11], 0, v[116:117]
	ds_read_b128 v[2:5], v0 offset:39168
	global_store_dwordx4 v[12:13], v[6:9], off
	ds_read_b128 v[6:9], v0 offset:40320
	v_mov_b32_e32 v119, v1
	v_readlane_b32 s96, v249, 30
	v_lshl_add_u64 v[12:13], v[10:11], 0, v[118:119]
	v_mov_b32_e32 v121, v1
	s_add_i32 s9, s9, s96
	s_sub_i32 s6, s6, s96
	v_readlane_b32 s74, v249, 28
	s_waitcnt lgkmcnt(0)
	global_store_dwordx4 v[12:13], v[2:5], off
	v_readlane_b32 s97, v249, 31
	s_cmpk_lt_i32 s9, 0x800
	v_lshl_add_u64 v[2:3], v[10:11], 0, v[120:121]
	v_readlane_b32 s68, v249, 27
	v_readlane_b32 s75, v249, 29
	global_store_dwordx4 v[2:3], v[6:9], off
	s_cbranch_scc0 .LBB0_740

.LBB0_720:
	s_add_i32 s11, s0, 0
	s_lshl_b32 s0, s1, 1
	s_and_b32 s0, s0, -4
	s_add_i32 s96, s0, 0
	s_add_i32 s96, s96, 0x1b000
	s_cmp_le_u32 s5, s33
	v_lshl_add_u32 v141, v130, 2, s11
	s_cselect_b64 s[0:1], -1, 0
	s_cmp_gt_u32 s5, s33
	v_add_u32_e32 v140, s11, v107
	v_add_u32_e32 v139, s11, v124
	v_add_u32_e32 v138, s11, v125
	v_add_u32_e32 v0, s11, v126
	s_cbranch_scc1 .LBB0_723
	v_mov_b32_e32 v50, s96
	ds_read_b32 v58, v50
	v_sub_f32_e32 v59, v113, v137
	ds_read_b128 v[74:77], v141 offset:32832
	ds_read_b128 v[50:53], v141 offset:32768
	ds_read_b128 v[54:57], v141 offset:32800
	s_waitcnt lgkmcnt(0)
	v_sub_f32_e32 v158, v59, v58
	ds_read_b128 v[58:61], v141 offset:32864
	ds_read_b128 v[146:149], v139
	v_sub_f32_e32 v53, v158, v53
	v_sub_f32_e32 v57, v158, v57
	v_sub_f32_e32 v56, v158, v56
	s_waitcnt lgkmcnt(0)
	v_sub_f32_e32 v65, v158, v61
	v_sub_f32_e32 v64, v158, v60
	v_sub_f32_e32 v63, v158, v59
	v_sub_f32_e32 v62, v158, v58
	v_sub_f32_e32 v61, v158, v77
	v_sub_f32_e32 v60, v158, v76
	v_sub_f32_e32 v59, v158, v75
	v_sub_f32_e32 v58, v158, v74
	ds_read_b128 v[74:77], v140
	v_sub_f32_e32 v55, v158, v55
	v_sub_f32_e32 v54, v158, v54
	v_sub_f32_e32 v52, v158, v52
	v_sub_f32_e32 v51, v158, v51
	v_sub_f32_e32 v50, v158, v50
	ds_read_b128 v[66:69], v141 offset:32896
	ds_read_b128 v[70:73], v141 offset:32928
	ds_read_b128 v[142:145], v141 offset:32960
	ds_read_b128 v[78:81], v141 offset:32992
	ds_read_b128 v[150:153], v138
	s_waitcnt lgkmcnt(0)
	v_mfma_f32_32x32x16_bf16 v[50:65], v[74:77], v[86:89], v[50:65]
	ds_read_b128 v[154:157], v0
	v_sub_f32_e32 v77, v158, v145
	v_sub_f32_e32 v76, v158, v144
	v_sub_f32_e32 v75, v158, v143
	v_sub_f32_e32 v74, v158, v142
	v_sub_f32_e32 v81, v158, v81
	v_sub_f32_e32 v80, v158, v80
	v_mfma_f32_32x32x16_bf16 v[50:65], v[146:149], v[90:93], v[50:65]
	ds_read_b128 v[142:145], v140 offset:4096
	v_sub_f32_e32 v79, v158, v79
	v_sub_f32_e32 v78, v158, v78
	v_sub_f32_e32 v73, v158, v73
	v_sub_f32_e32 v72, v158, v72
	v_sub_f32_e32 v71, v158, v71
	v_sub_f32_e32 v70, v158, v70
	v_mfma_f32_32x32x16_bf16 v[50:65], v[150:153], v[94:97], v[50:65]
	v_sub_f32_e32 v69, v158, v69
	v_sub_f32_e32 v68, v158, v68
	v_sub_f32_e32 v67, v158, v67
	v_sub_f32_e32 v66, v158, v66
	ds_read_b128 v[146:149], v139 offset:4096
	s_cmp_lg_u32 s92, s5
	s_waitcnt lgkmcnt(0)
	v_mfma_f32_32x32x16_bf16 v[66:81], v[142:145], v[86:89], v[66:81]
	ds_read_b128 v[142:145], v138 offset:4096
	v_mfma_f32_32x32x16_bf16 v[66:81], v[146:149], v[90:93], v[66:81]
	s_waitcnt lgkmcnt(0)
	v_mfma_f32_32x32x16_bf16 v[66:81], v[142:145], v[94:97], v[66:81]
	ds_read_b128 v[142:145], v0 offset:4096
	s_waitcnt lgkmcnt(0)
	v_mfma_f32_32x32x16_bf16 v[66:81], v[142:145], v[98:101], v[66:81]
	v_mfma_f32_32x32x16_bf16 v[50:65], v[154:157], v[98:101], v[50:65]
	s_cbranch_scc1 .LBB0_723
	s_nop 10
	v_cndmask_b32_e64 v142, v50, v136, s[14:15]
	v_cndmask_b32_e64 v66, v66, v136, s[16:17]
	v_cndmask_b32_e64 v50, v142, v50, s[18:19]
	v_cndmask_b32_e64 v51, v136, v51, s[18:19]
	v_cndmask_b32_e64 v67, v67, v136, s[20:21]
	v_cndmask_b32_e64 v52, v52, v136, s[22:23]
	v_cndmask_b32_e64 v68, v68, v136, s[24:25]
	v_cndmask_b32_e64 v53, v53, v136, s[26:27]
	v_cndmask_b32_e64 v69, v69, v136, s[28:29]
	v_cndmask_b32_e64 v54, v54, v136, s[30:31]
	v_cndmask_b32_e64 v70, v70, v136, s[34:35]
	v_cndmask_b32_e64 v55, v55, v136, s[36:37]
	v_cndmask_b32_e64 v71, v71, v136, s[38:39]
	v_cndmask_b32_e64 v56, v56, v136, s[40:41]
	v_cndmask_b32_e64 v72, v72, v136, s[42:43]
	v_cndmask_b32_e64 v57, v57, v136, s[44:45]
	v_cndmask_b32_e64 v73, v73, v136, s[46:47]
	v_cndmask_b32_e64 v58, v58, v136, s[48:49]
	v_cndmask_b32_e64 v74, v74, v136, s[50:51]
	v_cndmask_b32_e64 v59, v59, v136, s[52:53]
	v_cndmask_b32_e64 v75, v75, v136, s[54:55]
	v_cndmask_b32_e64 v60, v60, v136, s[56:57]
	v_cndmask_b32_e64 v76, v76, v136, s[58:59]
	v_cndmask_b32_e64 v61, v61, v136, s[60:61]
	v_cndmask_b32_e64 v77, v77, v136, s[62:63]
	v_cndmask_b32_e64 v62, v62, v136, s[64:65]
	v_cndmask_b32_e64 v78, v78, v136, s[66:67]
	v_cndmask_b32_e64 v63, v63, v136, s[68:69]
	v_cndmask_b32_e64 v79, v79, v136, s[70:71]
	v_cndmask_b32_e64 v64, v64, v136, s[72:73]
	v_cndmask_b32_e64 v80, v80, v136, s[74:75]
	v_cndmask_b32_e64 v65, v65, v136, s[76:77]
	v_cndmask_b32_e64 v81, v81, v136, s[78:79]

.LBB0_726:
	v_add_u32_e32 v142, s11, v127
	v_add_u32_e32 v143, v142, v128
	v_exp_f32_e32 v50, v50
	v_exp_f32_e32 v51, v51
	v_exp_f32_e32 v52, v52
	v_exp_f32_e32 v53, v53
	ds_read_b64_tr_b16 v[144:145], v143 offset:16384
	ds_read_b64_tr_b16 v[146:147], v143 offset:17408
	v_exp_f32_e32 v54, v54
	v_exp_f32_e32 v55, v55
	v_exp_f32_e32 v56, v56
	v_exp_f32_e32 v57, v57
	v_cvt_pk_bf16_f32 v148, v50, v51
	v_cvt_pk_bf16_f32 v149, v52, v53
	v_cvt_pk_bf16_f32 v150, v54, v55
	v_cvt_pk_bf16_f32 v151, v56, v57
	v_add_u32_e32 v142, v142, v129
	v_exp_f32_e32 v58, v58
	s_waitcnt lgkmcnt(0)
	v_mfma_f32_32x32x16_bf16 v[2:17], v[144:147], v[148:151], v[2:17]
	ds_read_b64_tr_b16 v[144:145], v142 offset:16384
	ds_read_b64_tr_b16 v[146:147], v142 offset:17408
	v_exp_f32_e32 v59, v59
	v_exp_f32_e32 v60, v60
	v_exp_f32_e32 v61, v61
	v_exp_f32_e32 v62, v62
	v_exp_f32_e32 v63, v63
	v_exp_f32_e32 v64, v64
	s_waitcnt lgkmcnt(0)
	v_mfma_f32_32x32x16_bf16 v[18:33], v[144:147], v[148:151], v[18:33]
	ds_read_b64_tr_b16 v[144:145], v143 offset:18432
	ds_read_b64_tr_b16 v[146:147], v143 offset:19456
	v_exp_f32_e32 v65, v65
	v_mfma_f32_32x32x16_bf16 v[34:49], v[82:85], v[148:151], v[34:49]
	v_cvt_pk_bf16_f32 v148, v58, v59
	v_cvt_pk_bf16_f32 v149, v60, v61
	v_cvt_pk_bf16_f32 v150, v62, v63
	v_cvt_pk_bf16_f32 v151, v64, v65
	s_waitcnt lgkmcnt(0)
	s_nop 0
	v_mfma_f32_32x32x16_bf16 v[2:17], v[144:147], v[148:151], v[2:17]
	ds_read_b64_tr_b16 v[144:145], v142 offset:18432
	ds_read_b64_tr_b16 v[146:147], v142 offset:19456
	s_waitcnt lgkmcnt(0)
	v_mfma_f32_32x32x16_bf16 v[18:33], v[144:147], v[148:151], v[18:33]
	v_max_f32_e32 v144, v67, v67
	v_max_f32_e32 v145, v66, v66
	v_max_f32_e32 v144, v145, v144
	v_max3_f32 v144, v144, v68, v69
	v_max3_f32 v144, v144, v70, v71
	v_max3_f32 v144, v144, v72, v73
	v_max3_f32 v144, v144, v74, v75
	v_max3_f32 v144, v144, v76, v77
	v_mfma_f32_32x32x16_bf16 v[34:49], v[82:85], v[148:151], v[34:49]
	v_max3_f32 v144, v144, v78, v79
	v_max3_f32 v144, v144, v80, v81
	v_mov_b32_e32 v145, v144
	s_nop 1
	v_permlane32_swap_b32_e32 v144, v145
	v_max_f32_e32 v145, v145, v145
	v_max_f32_e32 v144, v144, v144
	v_max_f32_e32 v144, v144, v145
	v_cmp_lt_f32_e32 vcc, s8, v144
	s_cbranch_vccz .LBB0_728
	v_max_f32_e32 v144, v144, v144
	v_max_f32_e32 v144, 0, v144
	v_exp_f32_e64 v146, -v144
	v_add_f32_e32 v137, v137, v144
	v_pk_add_f32 v[66:67], v[66:67], v[144:145] op_sel_hi:[1,0] neg_lo:[0,1] neg_hi:[0,1]
	v_pk_add_f32 v[68:69], v[68:69], v[144:145] op_sel_hi:[1,0] neg_lo:[0,1] neg_hi:[0,1]
	v_mul_f32_e32 v34, v34, v146
	v_pk_add_f32 v[70:71], v[70:71], v[144:145] op_sel_hi:[1,0] neg_lo:[0,1] neg_hi:[0,1]
	v_pk_add_f32 v[72:73], v[72:73], v[144:145] op_sel_hi:[1,0] neg_lo:[0,1] neg_hi:[0,1]
	v_pk_add_f32 v[74:75], v[74:75], v[144:145] op_sel_hi:[1,0] neg_lo:[0,1] neg_hi:[0,1]
	v_pk_add_f32 v[76:77], v[76:77], v[144:145] op_sel_hi:[1,0] neg_lo:[0,1] neg_hi:[0,1]
	v_pk_add_f32 v[78:79], v[78:79], v[144:145] op_sel_hi:[1,0] neg_lo:[0,1] neg_hi:[0,1]
	v_pk_add_f32 v[80:81], v[80:81], v[144:145] op_sel_hi:[1,0] neg_lo:[0,1] neg_hi:[0,1]
	v_pk_mul_f32 v[32:33], v[32:33], v[146:147] op_sel_hi:[1,0]
	v_pk_mul_f32 v[30:31], v[30:31], v[146:147] op_sel_hi:[1,0]
	v_pk_mul_f32 v[28:29], v[28:29], v[146:147] op_sel_hi:[1,0]
	v_pk_mul_f32 v[26:27], v[26:27], v[146:147] op_sel_hi:[1,0]
	v_pk_mul_f32 v[24:25], v[24:25], v[146:147] op_sel_hi:[1,0]
	v_pk_mul_f32 v[22:23], v[22:23], v[146:147] op_sel_hi:[1,0]
	v_pk_mul_f32 v[20:21], v[20:21], v[146:147] op_sel_hi:[1,0]
	v_pk_mul_f32 v[18:19], v[18:19], v[146:147] op_sel_hi:[1,0]
	v_pk_mul_f32 v[16:17], v[16:17], v[146:147] op_sel_hi:[1,0]
	v_pk_mul_f32 v[14:15], v[14:15], v[146:147] op_sel_hi:[1,0]
	v_pk_mul_f32 v[12:13], v[12:13], v[146:147] op_sel_hi:[1,0]
	v_pk_mul_f32 v[10:11], v[10:11], v[146:147] op_sel_hi:[1,0]
	v_pk_mul_f32 v[8:9], v[8:9], v[146:147] op_sel_hi:[1,0]
	v_pk_mul_f32 v[6:7], v[6:7], v[146:147] op_sel_hi:[1,0]
	v_pk_mul_f32 v[4:5], v[4:5], v[146:147] op_sel_hi:[1,0]
	v_pk_mul_f32 v[2:3], v[2:3], v[146:147] op_sel_hi:[1,0]
.LBB0_728:
	v_exp_f32_e32 v66, v66
	v_exp_f32_e32 v67, v67
	v_exp_f32_e32 v68, v68
	v_exp_f32_e32 v69, v69
	ds_read_b64_tr_b16 v[144:145], v143 offset:20480
	ds_read_b64_tr_b16 v[146:147], v143 offset:21504
	v_exp_f32_e32 v70, v70
	v_exp_f32_e32 v71, v71
	v_exp_f32_e32 v72, v72
	v_exp_f32_e32 v73, v73
	v_cvt_pk_bf16_f32 v148, v66, v67
	v_cvt_pk_bf16_f32 v149, v68, v69
	v_cvt_pk_bf16_f32 v150, v70, v71
	v_cvt_pk_bf16_f32 v151, v72, v73
	v_exp_f32_e32 v74, v74
	v_exp_f32_e32 v75, v75
	s_waitcnt lgkmcnt(0)
	v_mfma_f32_32x32x16_bf16 v[2:17], v[144:147], v[148:151], v[2:17]
	ds_read_b64_tr_b16 v[144:145], v142 offset:20480
	ds_read_b64_tr_b16 v[146:147], v142 offset:21504
	v_exp_f32_e32 v76, v76
	v_exp_f32_e32 v77, v77
	v_exp_f32_e32 v78, v78
	v_exp_f32_e32 v79, v79
	v_exp_f32_e32 v80, v80
	v_exp_f32_e32 v81, v81
	s_waitcnt lgkmcnt(0)
	v_mfma_f32_32x32x16_bf16 v[18:33], v[144:147], v[148:151], v[18:33]
	ds_read_b64_tr_b16 v[144:145], v143 offset:22528
	ds_read_b64_tr_b16 v[146:147], v143 offset:23552
	v_mfma_f32_32x32x16_bf16 v[34:49], v[82:85], v[148:151], v[34:49]
	v_cvt_pk_bf16_f32 v148, v74, v75
	v_cvt_pk_bf16_f32 v149, v76, v77
	v_cvt_pk_bf16_f32 v150, v78, v79
	v_cvt_pk_bf16_f32 v151, v80, v81
	s_waitcnt lgkmcnt(0)
	s_nop 0
	v_mfma_f32_32x32x16_bf16 v[2:17], v[144:147], v[148:151], v[2:17]
	ds_read_b64_tr_b16 v[144:145], v142 offset:22528
	ds_read_b64_tr_b16 v[146:147], v142 offset:23552
	s_waitcnt lgkmcnt(0)
	v_mfma_f32_32x32x16_bf16 v[18:33], v[144:147], v[148:151], v[18:33]
	v_mfma_f32_32x32x16_bf16 v[34:49], v[82:85], v[148:151], v[34:49]
.LBB0_729:
	s_cmp_lt_u32 s5, s33
	s_cselect_b64 s[0:1], -1, 0
	s_cmp_ge_u32 s5, s33
	s_cbranch_scc1 .LBB0_732
	s_nop 4
	v_mov_b32_e32 v50, s96
	ds_read_b32 v58, v50
	v_sub_f32_e32 v59, v113, v137
	ds_read_b128 v[74:77], v141 offset:33088
	ds_read_b128 v[50:53], v141 offset:33024
	ds_read_b128 v[54:57], v141 offset:33056
	s_waitcnt lgkmcnt(0)
	v_sub_f32_e32 v158, v59, v58
	ds_read_b128 v[58:61], v141 offset:33120
	ds_read_b128 v[146:149], v139 offset:8192
	v_sub_f32_e32 v53, v158, v53
	v_sub_f32_e32 v57, v158, v57
	v_sub_f32_e32 v56, v158, v56
	s_waitcnt lgkmcnt(0)
	v_sub_f32_e32 v65, v158, v61
	v_sub_f32_e32 v64, v158, v60
	v_sub_f32_e32 v63, v158, v59
	v_sub_f32_e32 v62, v158, v58
	v_sub_f32_e32 v61, v158, v77
	v_sub_f32_e32 v60, v158, v76
	v_sub_f32_e32 v59, v158, v75
	v_sub_f32_e32 v58, v158, v74
	ds_read_b128 v[74:77], v140 offset:8192
	v_sub_f32_e32 v55, v158, v55
	v_sub_f32_e32 v54, v158, v54
	v_sub_f32_e32 v52, v158, v52
	v_sub_f32_e32 v51, v158, v51
	v_sub_f32_e32 v50, v158, v50
	ds_read_b128 v[66:69], v141 offset:33152
	ds_read_b128 v[70:73], v141 offset:33184
	ds_read_b128 v[142:145], v141 offset:33216
	ds_read_b128 v[78:81], v141 offset:33248
	ds_read_b128 v[150:153], v138 offset:8192
	s_waitcnt lgkmcnt(0)
	v_mfma_f32_32x32x16_bf16 v[50:65], v[74:77], v[86:89], v[50:65]
	ds_read_b128 v[154:157], v0 offset:8192
	v_sub_f32_e32 v75, v158, v143
	v_sub_f32_e32 v74, v158, v142
	v_sub_f32_e32 v81, v158, v81
	v_sub_f32_e32 v80, v158, v80
	v_sub_f32_e32 v79, v158, v79
	v_sub_f32_e32 v78, v158, v78
	v_mfma_f32_32x32x16_bf16 v[50:65], v[146:149], v[90:93], v[50:65]
	ds_read_b128 v[140:143], v140 offset:12288
	v_sub_f32_e32 v77, v158, v145
	v_sub_f32_e32 v76, v158, v144
	v_sub_f32_e32 v73, v158, v73
	v_sub_f32_e32 v72, v158, v72
	v_sub_f32_e32 v71, v158, v71
	v_sub_f32_e32 v70, v158, v70
	v_mfma_f32_32x32x16_bf16 v[50:65], v[150:153], v[94:97], v[50:65]
	v_sub_f32_e32 v69, v158, v69
	v_sub_f32_e32 v68, v158, v68
	v_sub_f32_e32 v67, v158, v67
	v_sub_f32_e32 v66, v158, v66
	ds_read_b128 v[144:147], v139 offset:12288
	s_cmp_lg_u32 s4, s5
	s_waitcnt lgkmcnt(0)
	v_mfma_f32_32x32x16_bf16 v[66:81], v[140:143], v[86:89], v[66:81]
	ds_read_b128 v[138:141], v138 offset:12288
	v_mfma_f32_32x32x16_bf16 v[66:81], v[144:147], v[90:93], v[66:81]
	s_waitcnt lgkmcnt(0)
	v_mfma_f32_32x32x16_bf16 v[66:81], v[138:141], v[94:97], v[66:81]
	ds_read_b128 v[138:141], v0 offset:12288
	s_waitcnt lgkmcnt(0)
	v_mfma_f32_32x32x16_bf16 v[66:81], v[138:141], v[98:101], v[66:81]
	v_mfma_f32_32x32x16_bf16 v[50:65], v[154:157], v[98:101], v[50:65]
	s_cbranch_scc1 .LBB0_732
	s_nop 10
	v_cndmask_b32_e64 v0, v50, v136, s[14:15]
	v_cndmask_b32_e64 v66, v66, v136, s[16:17]
	v_cndmask_b32_e64 v50, v0, v50, s[18:19]
	v_cndmask_b32_e64 v51, v136, v51, s[18:19]
	v_cndmask_b32_e64 v67, v67, v136, s[20:21]
	v_cndmask_b32_e64 v52, v52, v136, s[22:23]
	v_cndmask_b32_e64 v68, v68, v136, s[24:25]
	v_cndmask_b32_e64 v53, v53, v136, s[26:27]
	v_cndmask_b32_e64 v69, v69, v136, s[28:29]
	v_cndmask_b32_e64 v54, v54, v136, s[30:31]
	v_cndmask_b32_e64 v70, v70, v136, s[34:35]
	v_cndmask_b32_e64 v55, v55, v136, s[36:37]
	v_cndmask_b32_e64 v71, v71, v136, s[38:39]
	v_cndmask_b32_e64 v56, v56, v136, s[40:41]
	v_cndmask_b32_e64 v72, v72, v136, s[42:43]
	v_cndmask_b32_e64 v57, v57, v136, s[44:45]
	v_cndmask_b32_e64 v73, v73, v136, s[46:47]
	v_cndmask_b32_e64 v58, v58, v136, s[48:49]
	v_cndmask_b32_e64 v74, v74, v136, s[50:51]
	v_cndmask_b32_e64 v59, v59, v136, s[52:53]
	v_cndmask_b32_e64 v75, v75, v136, s[54:55]
	v_cndmask_b32_e64 v60, v60, v136, s[56:57]
	v_cndmask_b32_e64 v76, v76, v136, s[58:59]
	v_cndmask_b32_e64 v61, v61, v136, s[60:61]
	v_cndmask_b32_e64 v77, v77, v136, s[62:63]
	v_cndmask_b32_e64 v62, v62, v136, s[64:65]
	v_cndmask_b32_e64 v78, v78, v136, s[66:67]
	v_cndmask_b32_e64 v63, v63, v136, s[68:69]
	v_cndmask_b32_e64 v79, v79, v136, s[70:71]
	v_cndmask_b32_e64 v64, v64, v136, s[72:73]
	v_cndmask_b32_e64 v80, v80, v136, s[74:75]
	v_cndmask_b32_e64 v65, v65, v136, s[76:77]
	v_cndmask_b32_e64 v81, v81, v136, s[78:79]

.LBB0_735:
	v_add_u32_e32 v0, s11, v127
	v_add_u32_e32 v138, v0, v128
	v_exp_f32_e32 v50, v50
	v_exp_f32_e32 v51, v51
	v_exp_f32_e32 v52, v52
	v_exp_f32_e32 v53, v53
	ds_read_b64_tr_b16 v[140:141], v138 offset:24576
	ds_read_b64_tr_b16 v[142:143], v138 offset:25600
	v_exp_f32_e32 v54, v54
	v_exp_f32_e32 v55, v55
	v_exp_f32_e32 v56, v56
	v_exp_f32_e32 v57, v57
	v_cvt_pk_bf16_f32 v144, v50, v51
	v_cvt_pk_bf16_f32 v145, v52, v53
	v_cvt_pk_bf16_f32 v146, v54, v55
	v_cvt_pk_bf16_f32 v147, v56, v57
	v_add_u32_e32 v0, v0, v129
	v_exp_f32_e32 v58, v58
	s_waitcnt lgkmcnt(0)
	v_mfma_f32_32x32x16_bf16 v[2:17], v[140:143], v[144:147], v[2:17]
	ds_read_b64_tr_b16 v[140:141], v0 offset:24576
	ds_read_b64_tr_b16 v[142:143], v0 offset:25600
	v_exp_f32_e32 v59, v59
	v_exp_f32_e32 v60, v60
	v_exp_f32_e32 v61, v61
	v_exp_f32_e32 v62, v62
	v_exp_f32_e32 v63, v63
	v_exp_f32_e32 v64, v64
	s_waitcnt lgkmcnt(0)
	v_mfma_f32_32x32x16_bf16 v[18:33], v[140:143], v[144:147], v[18:33]
	ds_read_b64_tr_b16 v[140:141], v138 offset:26624
	ds_read_b64_tr_b16 v[142:143], v138 offset:27648
	v_exp_f32_e32 v65, v65
	v_max_f32_e32 v139, v67, v67
	v_mfma_f32_32x32x16_bf16 v[34:49], v[82:85], v[144:147], v[34:49]
	v_cvt_pk_bf16_f32 v144, v58, v59
	v_cvt_pk_bf16_f32 v145, v60, v61
	v_cvt_pk_bf16_f32 v146, v62, v63
	v_cvt_pk_bf16_f32 v147, v64, v65
	s_waitcnt lgkmcnt(0)
	s_nop 0
	v_mfma_f32_32x32x16_bf16 v[2:17], v[140:143], v[144:147], v[2:17]
	ds_read_b64_tr_b16 v[140:141], v0 offset:26624
	ds_read_b64_tr_b16 v[142:143], v0 offset:27648
	s_waitcnt lgkmcnt(0)
	v_mfma_f32_32x32x16_bf16 v[18:33], v[140:143], v[144:147], v[18:33]
	v_max_f32_e32 v140, v66, v66
	v_max_f32_e32 v139, v140, v139
	v_max3_f32 v139, v139, v68, v69
	v_max3_f32 v139, v139, v70, v71
	v_max3_f32 v139, v139, v72, v73
	v_max3_f32 v139, v139, v74, v75
	v_max3_f32 v139, v139, v76, v77
	v_mfma_f32_32x32x16_bf16 v[34:49], v[82:85], v[144:147], v[34:49]
	v_max3_f32 v139, v139, v78, v79
	v_max3_f32 v139, v139, v80, v81
	v_mov_b32_e32 v140, v139
	s_nop 1
	v_permlane32_swap_b32_e32 v139, v140
	v_max_f32_e32 v140, v140, v140
	v_max_f32_e32 v139, v139, v139
	v_max_f32_e32 v139, v139, v140
	v_cmp_lt_f32_e32 vcc, s8, v139
	s_cbranch_vccz .LBB0_737
	v_max_f32_e32 v139, v139, v139
	v_max_f32_e32 v140, 0, v139
	v_exp_f32_e64 v142, -v140
	v_add_f32_e32 v137, v137, v140
	v_pk_add_f32 v[66:67], v[66:67], v[140:141] op_sel_hi:[1,0] neg_lo:[0,1] neg_hi:[0,1]
	v_pk_add_f32 v[68:69], v[68:69], v[140:141] op_sel_hi:[1,0] neg_lo:[0,1] neg_hi:[0,1]
	v_mul_f32_e32 v34, v34, v142
	v_pk_add_f32 v[70:71], v[70:71], v[140:141] op_sel_hi:[1,0] neg_lo:[0,1] neg_hi:[0,1]
	v_pk_add_f32 v[72:73], v[72:73], v[140:141] op_sel_hi:[1,0] neg_lo:[0,1] neg_hi:[0,1]
	v_pk_add_f32 v[74:75], v[74:75], v[140:141] op_sel_hi:[1,0] neg_lo:[0,1] neg_hi:[0,1]
	v_pk_add_f32 v[76:77], v[76:77], v[140:141] op_sel_hi:[1,0] neg_lo:[0,1] neg_hi:[0,1]
	v_pk_add_f32 v[78:79], v[78:79], v[140:141] op_sel_hi:[1,0] neg_lo:[0,1] neg_hi:[0,1]
	v_pk_add_f32 v[80:81], v[80:81], v[140:141] op_sel_hi:[1,0] neg_lo:[0,1] neg_hi:[0,1]
	v_pk_mul_f32 v[32:33], v[32:33], v[142:143] op_sel_hi:[1,0]
	v_pk_mul_f32 v[30:31], v[30:31], v[142:143] op_sel_hi:[1,0]
	v_pk_mul_f32 v[28:29], v[28:29], v[142:143] op_sel_hi:[1,0]
	v_pk_mul_f32 v[26:27], v[26:27], v[142:143] op_sel_hi:[1,0]
	v_pk_mul_f32 v[24:25], v[24:25], v[142:143] op_sel_hi:[1,0]
	v_pk_mul_f32 v[22:23], v[22:23], v[142:143] op_sel_hi:[1,0]
	v_pk_mul_f32 v[20:21], v[20:21], v[142:143] op_sel_hi:[1,0]
	v_pk_mul_f32 v[18:19], v[18:19], v[142:143] op_sel_hi:[1,0]
	v_pk_mul_f32 v[16:17], v[16:17], v[142:143] op_sel_hi:[1,0]
	v_pk_mul_f32 v[14:15], v[14:15], v[142:143] op_sel_hi:[1,0]
	v_pk_mul_f32 v[12:13], v[12:13], v[142:143] op_sel_hi:[1,0]
	v_pk_mul_f32 v[10:11], v[10:11], v[142:143] op_sel_hi:[1,0]
	v_pk_mul_f32 v[8:9], v[8:9], v[142:143] op_sel_hi:[1,0]
	v_pk_mul_f32 v[6:7], v[6:7], v[142:143] op_sel_hi:[1,0]
	v_pk_mul_f32 v[4:5], v[4:5], v[142:143] op_sel_hi:[1,0]
	v_pk_mul_f32 v[2:3], v[2:3], v[142:143] op_sel_hi:[1,0]
.LBB0_737:
	v_exp_f32_e32 v66, v66
	v_exp_f32_e32 v67, v67
	v_exp_f32_e32 v68, v68
	v_exp_f32_e32 v69, v69
	ds_read_b64_tr_b16 v[140:141], v138 offset:28672
	ds_read_b64_tr_b16 v[142:143], v138 offset:29696
	v_exp_f32_e32 v70, v70
	v_exp_f32_e32 v71, v71
	v_exp_f32_e32 v72, v72
	v_exp_f32_e32 v73, v73
	v_cvt_pk_bf16_f32 v144, v66, v67
	v_cvt_pk_bf16_f32 v145, v68, v69
	v_cvt_pk_bf16_f32 v146, v70, v71
	v_cvt_pk_bf16_f32 v147, v72, v73
	v_exp_f32_e32 v74, v74
	v_exp_f32_e32 v75, v75
	s_waitcnt lgkmcnt(0)
	v_mfma_f32_32x32x16_bf16 v[2:17], v[140:143], v[144:147], v[2:17]
	ds_read_b64_tr_b16 v[140:141], v0 offset:28672
	ds_read_b64_tr_b16 v[142:143], v0 offset:29696
	v_exp_f32_e32 v76, v76
	v_exp_f32_e32 v77, v77
	v_exp_f32_e32 v78, v78
	v_exp_f32_e32 v79, v79
	v_exp_f32_e32 v80, v80
	v_exp_f32_e32 v81, v81
	s_waitcnt lgkmcnt(0)
	v_mfma_f32_32x32x16_bf16 v[18:33], v[140:143], v[144:147], v[18:33]
	ds_read_b64_tr_b16 v[140:141], v138 offset:30720
	ds_read_b64_tr_b16 v[142:143], v138 offset:31744
	v_mfma_f32_32x32x16_bf16 v[34:49], v[82:85], v[144:147], v[34:49]
	v_cvt_pk_bf16_f32 v144, v74, v75
	v_cvt_pk_bf16_f32 v145, v76, v77
	v_cvt_pk_bf16_f32 v146, v78, v79
	v_cvt_pk_bf16_f32 v147, v80, v81
	s_waitcnt lgkmcnt(0)
	s_nop 0
	v_mfma_f32_32x32x16_bf16 v[2:17], v[140:143], v[144:147], v[2:17]
	ds_read_b64_tr_b16 v[138:139], v0 offset:30720
	ds_read_b64_tr_b16 v[140:141], v0 offset:31744
	s_waitcnt lgkmcnt(0)
	v_mfma_f32_32x32x16_bf16 v[18:33], v[138:141], v[144:147], v[18:33]
	v_mfma_f32_32x32x16_bf16 v[34:49], v[82:85], v[144:147], v[34:49]

.LBB0_750:
	s_add_i32 s91, s0, 0
	s_lshl_b32 s0, s1, 1
	s_and_b32 s0, s0, -4
	s_add_i32 s68, s0, 0
	s_add_i32 s68, s68, 0x1b000
	s_cmp_le_u32 s77, s73
	v_lshl_add_u32 v120, v132, 2, s91
	s_cselect_b64 s[0:1], -1, 0
	s_cmp_gt_u32 s77, s73
	v_add_u32_e32 v119, s91, v125
	v_add_u32_e32 v118, s91, v126
	v_add_u32_e32 v117, s91, v127
	v_add_u32_e32 v0, s91, v128
	s_cbranch_scc1 .LBB0_753
	v_mov_b32_e32 v50, s68
	ds_read_b32 v58, v50
	v_sub_f32_e32 v59, v110, v116
	ds_read_b128 v[74:77], v120 offset:32832
	ds_read_b128 v[50:53], v120 offset:32768
	ds_read_b128 v[54:57], v120 offset:32800
	s_waitcnt lgkmcnt(0)
	v_sub_f32_e32 v121, v59, v58
	ds_read_b128 v[58:61], v120 offset:32864
	ds_read_b128 v[140:143], v118
	v_sub_f32_e32 v53, v121, v53
	v_sub_f32_e32 v57, v121, v57
	v_sub_f32_e32 v56, v121, v56
	s_waitcnt lgkmcnt(0)
	v_sub_f32_e32 v65, v121, v61
	v_sub_f32_e32 v64, v121, v60
	v_sub_f32_e32 v63, v121, v59
	v_sub_f32_e32 v62, v121, v58
	v_sub_f32_e32 v61, v121, v77
	v_sub_f32_e32 v60, v121, v76
	v_sub_f32_e32 v59, v121, v75
	v_sub_f32_e32 v58, v121, v74
	ds_read_b128 v[74:77], v119
	v_sub_f32_e32 v55, v121, v55
	v_sub_f32_e32 v54, v121, v54
	v_sub_f32_e32 v52, v121, v52
	v_sub_f32_e32 v51, v121, v51
	v_sub_f32_e32 v50, v121, v50
	ds_read_b128 v[66:69], v120 offset:32896
	ds_read_b128 v[70:73], v120 offset:32928
	ds_read_b128 v[136:139], v120 offset:32960
	ds_read_b128 v[78:81], v120 offset:32992
	ds_read_b128 v[144:147], v117
	s_waitcnt lgkmcnt(0)
	v_mfma_f32_32x32x16_bf16 v[50:65], v[74:77], v[88:91], v[50:65]
	ds_read_b128 v[148:151], v0
	v_sub_f32_e32 v77, v121, v139
	v_sub_f32_e32 v76, v121, v138
	v_sub_f32_e32 v75, v121, v137
	v_sub_f32_e32 v74, v121, v136
	v_sub_f32_e32 v81, v121, v81
	v_sub_f32_e32 v80, v121, v80
	v_mfma_f32_32x32x16_bf16 v[50:65], v[140:143], v[92:95], v[50:65]
	ds_read_b128 v[136:139], v119 offset:4096
	v_sub_f32_e32 v79, v121, v79
	v_sub_f32_e32 v78, v121, v78
	v_sub_f32_e32 v73, v121, v73
	v_sub_f32_e32 v72, v121, v72
	v_sub_f32_e32 v71, v121, v71
	v_sub_f32_e32 v70, v121, v70
	v_mfma_f32_32x32x16_bf16 v[50:65], v[144:147], v[96:99], v[50:65]
	v_sub_f32_e32 v69, v121, v69
	v_sub_f32_e32 v68, v121, v68
	v_sub_f32_e32 v67, v121, v67
	v_sub_f32_e32 v66, v121, v66
	ds_read_b128 v[140:143], v118 offset:4096
	s_cmp_lg_u32 s73, s77
	s_waitcnt lgkmcnt(0)
	v_mfma_f32_32x32x16_bf16 v[66:81], v[136:139], v[88:91], v[66:81]
	ds_read_b128 v[136:139], v117 offset:4096
	v_mfma_f32_32x32x16_bf16 v[66:81], v[140:143], v[92:95], v[66:81]
	s_waitcnt lgkmcnt(0)
	v_mfma_f32_32x32x16_bf16 v[66:81], v[136:139], v[96:99], v[66:81]
	ds_read_b128 v[136:139], v0 offset:4096
	s_waitcnt lgkmcnt(0)
	v_mfma_f32_32x32x16_bf16 v[66:81], v[136:139], v[100:103], v[66:81]
	v_mfma_f32_32x32x16_bf16 v[50:65], v[148:151], v[100:103], v[50:65]
	s_cbranch_scc1 .LBB0_753
	s_nop 10
	v_cndmask_b32_e64 v121, v50, v115, s[2:3]
	v_cndmask_b32_e64 v66, v66, v115, s[4:5]
	v_cndmask_b32_e64 v50, v121, v50, s[6:7]
	v_cndmask_b32_e64 v51, v115, v51, s[6:7]
	v_cndmask_b32_e64 v67, v67, v115, s[8:9]
	v_cndmask_b32_e64 v52, v52, v115, s[10:11]
	v_cndmask_b32_e64 v68, v68, v115, s[12:13]
	v_cndmask_b32_e64 v53, v53, v115, s[14:15]
	v_cndmask_b32_e64 v69, v69, v115, s[16:17]
	v_cndmask_b32_e64 v54, v54, v115, s[18:19]
	v_cndmask_b32_e64 v70, v70, v115, s[20:21]
	v_cndmask_b32_e64 v55, v55, v115, s[22:23]
	v_cndmask_b32_e64 v71, v71, v115, s[24:25]
	v_cndmask_b32_e64 v56, v56, v115, s[26:27]
	v_cndmask_b32_e64 v72, v72, v115, s[28:29]
	v_cndmask_b32_e64 v57, v57, v115, s[30:31]
	v_cndmask_b32_e64 v73, v73, v115, s[34:35]
	v_cndmask_b32_e64 v58, v58, v115, s[36:37]
	v_cndmask_b32_e64 v74, v74, v115, s[38:39]
	v_cndmask_b32_e64 v59, v59, v115, s[40:41]
	v_cndmask_b32_e64 v75, v75, v115, s[42:43]
	v_cndmask_b32_e64 v60, v60, v115, s[44:45]
	v_cndmask_b32_e64 v76, v76, v115, s[46:47]
	v_cndmask_b32_e64 v61, v61, v115, s[48:49]
	v_cndmask_b32_e64 v77, v77, v115, s[50:51]
	v_cndmask_b32_e64 v62, v62, v115, s[52:53]
	v_cndmask_b32_e64 v78, v78, v115, s[54:55]
	v_cndmask_b32_e64 v63, v63, v115, s[56:57]
	v_cndmask_b32_e64 v79, v79, v115, s[58:59]
	v_cndmask_b32_e64 v64, v64, v115, s[60:61]
	v_cndmask_b32_e64 v80, v80, v115, s[62:63]
	v_cndmask_b32_e64 v65, v65, v115, s[64:65]
	v_cndmask_b32_e64 v81, v81, v115, s[66:67]

.LBB0_756:
	v_add_u32_e32 v121, s91, v129
	v_add_u32_e32 v122, v121, v130
	v_exp_f32_e32 v50, v50
	v_exp_f32_e32 v51, v51
	v_exp_f32_e32 v52, v52
	v_exp_f32_e32 v53, v53
	ds_read_b64_tr_b16 v[136:137], v122 offset:16384
	ds_read_b64_tr_b16 v[138:139], v122 offset:17408
	v_exp_f32_e32 v54, v54
	v_exp_f32_e32 v55, v55
	v_exp_f32_e32 v56, v56
	v_exp_f32_e32 v57, v57
	v_cvt_pk_bf16_f32 v140, v50, v51
	v_cvt_pk_bf16_f32 v141, v52, v53
	v_cvt_pk_bf16_f32 v142, v54, v55
	v_cvt_pk_bf16_f32 v143, v56, v57
	v_add_u32_e32 v121, v121, v131
	v_exp_f32_e32 v58, v58
	s_waitcnt lgkmcnt(0)
	v_mfma_f32_32x32x16_bf16 v[2:17], v[136:139], v[140:143], v[2:17]
	ds_read_b64_tr_b16 v[136:137], v121 offset:16384
	ds_read_b64_tr_b16 v[138:139], v121 offset:17408
	v_exp_f32_e32 v59, v59
	v_exp_f32_e32 v60, v60
	v_exp_f32_e32 v61, v61
	v_exp_f32_e32 v62, v62
	v_exp_f32_e32 v63, v63
	v_exp_f32_e32 v64, v64
	s_waitcnt lgkmcnt(0)
	v_mfma_f32_32x32x16_bf16 v[18:33], v[136:139], v[140:143], v[18:33]
	ds_read_b64_tr_b16 v[136:137], v122 offset:18432
	ds_read_b64_tr_b16 v[138:139], v122 offset:19456
	v_exp_f32_e32 v65, v65
	v_max_f32_e32 v123, v67, v67
	v_mfma_f32_32x32x16_bf16 v[34:49], v[84:87], v[140:143], v[34:49]
	v_cvt_pk_bf16_f32 v140, v58, v59
	v_cvt_pk_bf16_f32 v141, v60, v61
	v_cvt_pk_bf16_f32 v142, v62, v63
	v_cvt_pk_bf16_f32 v143, v64, v65
	s_waitcnt lgkmcnt(0)
	s_nop 0
	v_mfma_f32_32x32x16_bf16 v[2:17], v[136:139], v[140:143], v[2:17]
	ds_read_b64_tr_b16 v[136:137], v121 offset:18432
	ds_read_b64_tr_b16 v[138:139], v121 offset:19456
	s_waitcnt lgkmcnt(0)
	v_mfma_f32_32x32x16_bf16 v[18:33], v[136:139], v[140:143], v[18:33]
	v_max_f32_e32 v136, v66, v66
	v_max_f32_e32 v123, v136, v123
	v_max3_f32 v123, v123, v68, v69
	v_max3_f32 v123, v123, v70, v71
	v_max3_f32 v123, v123, v72, v73
	v_max3_f32 v123, v123, v74, v75
	v_max3_f32 v123, v123, v76, v77
	v_mfma_f32_32x32x16_bf16 v[34:49], v[84:87], v[140:143], v[34:49]
	v_max3_f32 v123, v123, v78, v79
	v_max3_f32 v123, v123, v80, v81
	v_mov_b32_e32 v136, v123
	s_nop 1
	v_permlane32_swap_b32_e32 v123, v136
	v_max_f32_e32 v136, v136, v136
	v_max_f32_e32 v123, v123, v123
	v_max_f32_e32 v123, v123, v136
	v_cmp_lt_f32_e32 vcc, s95, v123
	s_cbranch_vccz .LBB0_758
	v_max_f32_e32 v123, v123, v123
	v_max_f32_e32 v136, 0, v123
	v_exp_f32_e64 v138, -v136
	v_add_f32_e32 v116, v116, v136
	v_pk_add_f32 v[66:67], v[66:67], v[136:137] op_sel_hi:[1,0] neg_lo:[0,1] neg_hi:[0,1]
	v_pk_add_f32 v[68:69], v[68:69], v[136:137] op_sel_hi:[1,0] neg_lo:[0,1] neg_hi:[0,1]
	v_mul_f32_e32 v34, v34, v138
	v_pk_add_f32 v[70:71], v[70:71], v[136:137] op_sel_hi:[1,0] neg_lo:[0,1] neg_hi:[0,1]
	v_pk_add_f32 v[72:73], v[72:73], v[136:137] op_sel_hi:[1,0] neg_lo:[0,1] neg_hi:[0,1]
	v_pk_add_f32 v[74:75], v[74:75], v[136:137] op_sel_hi:[1,0] neg_lo:[0,1] neg_hi:[0,1]
	v_pk_add_f32 v[76:77], v[76:77], v[136:137] op_sel_hi:[1,0] neg_lo:[0,1] neg_hi:[0,1]
	v_pk_add_f32 v[78:79], v[78:79], v[136:137] op_sel_hi:[1,0] neg_lo:[0,1] neg_hi:[0,1]
	v_pk_add_f32 v[80:81], v[80:81], v[136:137] op_sel_hi:[1,0] neg_lo:[0,1] neg_hi:[0,1]
	v_pk_mul_f32 v[32:33], v[32:33], v[138:139] op_sel_hi:[1,0]
	v_pk_mul_f32 v[30:31], v[30:31], v[138:139] op_sel_hi:[1,0]
	v_pk_mul_f32 v[28:29], v[28:29], v[138:139] op_sel_hi:[1,0]
	v_pk_mul_f32 v[26:27], v[26:27], v[138:139] op_sel_hi:[1,0]
	v_pk_mul_f32 v[24:25], v[24:25], v[138:139] op_sel_hi:[1,0]
	v_pk_mul_f32 v[22:23], v[22:23], v[138:139] op_sel_hi:[1,0]
	v_pk_mul_f32 v[20:21], v[20:21], v[138:139] op_sel_hi:[1,0]
	v_pk_mul_f32 v[18:19], v[18:19], v[138:139] op_sel_hi:[1,0]
	v_pk_mul_f32 v[16:17], v[16:17], v[138:139] op_sel_hi:[1,0]
	v_pk_mul_f32 v[14:15], v[14:15], v[138:139] op_sel_hi:[1,0]
	v_pk_mul_f32 v[12:13], v[12:13], v[138:139] op_sel_hi:[1,0]
	v_pk_mul_f32 v[10:11], v[10:11], v[138:139] op_sel_hi:[1,0]
	v_pk_mul_f32 v[8:9], v[8:9], v[138:139] op_sel_hi:[1,0]
	v_pk_mul_f32 v[6:7], v[6:7], v[138:139] op_sel_hi:[1,0]
	v_pk_mul_f32 v[4:5], v[4:5], v[138:139] op_sel_hi:[1,0]
	v_pk_mul_f32 v[2:3], v[2:3], v[138:139] op_sel_hi:[1,0]
.LBB0_758:
	v_exp_f32_e32 v66, v66
	v_exp_f32_e32 v67, v67
	v_exp_f32_e32 v68, v68
	v_exp_f32_e32 v69, v69
	ds_read_b64_tr_b16 v[136:137], v122 offset:20480
	ds_read_b64_tr_b16 v[138:139], v122 offset:21504
	v_exp_f32_e32 v70, v70
	v_exp_f32_e32 v71, v71
	v_exp_f32_e32 v72, v72
	v_exp_f32_e32 v73, v73
	v_cvt_pk_bf16_f32 v140, v66, v67
	v_cvt_pk_bf16_f32 v141, v68, v69
	v_cvt_pk_bf16_f32 v142, v70, v71
	v_cvt_pk_bf16_f32 v143, v72, v73
	v_exp_f32_e32 v74, v74
	v_exp_f32_e32 v75, v75
	s_waitcnt lgkmcnt(0)
	v_mfma_f32_32x32x16_bf16 v[2:17], v[136:139], v[140:143], v[2:17]
	ds_read_b64_tr_b16 v[136:137], v121 offset:20480
	ds_read_b64_tr_b16 v[138:139], v121 offset:21504
	v_exp_f32_e32 v76, v76
	v_exp_f32_e32 v77, v77
	v_exp_f32_e32 v78, v78
	v_exp_f32_e32 v79, v79
	v_exp_f32_e32 v80, v80
	v_exp_f32_e32 v81, v81
	s_waitcnt lgkmcnt(0)
	v_mfma_f32_32x32x16_bf16 v[18:33], v[136:139], v[140:143], v[18:33]
	ds_read_b64_tr_b16 v[136:137], v122 offset:22528
	ds_read_b64_tr_b16 v[138:139], v122 offset:23552
	v_mfma_f32_32x32x16_bf16 v[34:49], v[84:87], v[140:143], v[34:49]
	v_cvt_pk_bf16_f32 v140, v74, v75
	v_cvt_pk_bf16_f32 v141, v76, v77
	v_cvt_pk_bf16_f32 v142, v78, v79
	v_cvt_pk_bf16_f32 v143, v80, v81
	s_waitcnt lgkmcnt(0)
	s_nop 0
	v_mfma_f32_32x32x16_bf16 v[2:17], v[136:139], v[140:143], v[2:17]
	ds_read_b64_tr_b16 v[136:137], v121 offset:22528
	ds_read_b64_tr_b16 v[138:139], v121 offset:23552
	s_waitcnt lgkmcnt(0)
	v_mfma_f32_32x32x16_bf16 v[18:33], v[136:139], v[140:143], v[18:33]
	v_mfma_f32_32x32x16_bf16 v[34:49], v[84:87], v[140:143], v[34:49]
.LBB0_759:
	s_cmp_lt_u32 s77, s73
	s_cselect_b64 s[0:1], -1, 0
	s_cmp_ge_u32 s77, s73
	s_cbranch_scc1 .LBB0_762
	s_nop 4
	v_mov_b32_e32 v50, s68
	ds_read_b32 v58, v50
	v_sub_f32_e32 v59, v110, v116
	ds_read_b128 v[74:77], v120 offset:33088
	ds_read_b128 v[50:53], v120 offset:33024
	ds_read_b128 v[54:57], v120 offset:33056
	s_waitcnt lgkmcnt(0)
	v_sub_f32_e32 v148, v59, v58
	ds_read_b128 v[58:61], v120 offset:33120
	ds_read_b128 v[66:69], v120 offset:33152
	ds_read_b128 v[70:73], v120 offset:33184
	ds_read_b128 v[136:139], v120 offset:33216
	ds_read_b128 v[78:81], v120 offset:33248
	s_waitcnt lgkmcnt(0)
	v_sub_f32_e32 v65, v148, v61
	v_sub_f32_e32 v64, v148, v60
	v_sub_f32_e32 v63, v148, v59
	v_sub_f32_e32 v62, v148, v58
	v_sub_f32_e32 v61, v148, v77
	v_sub_f32_e32 v60, v148, v76
	v_sub_f32_e32 v59, v148, v75
	v_sub_f32_e32 v58, v148, v74
	ds_read_b128 v[74:77], v119 offset:8192
	v_sub_f32_e32 v57, v148, v57
	v_sub_f32_e32 v56, v148, v56
	v_sub_f32_e32 v55, v148, v55
	v_sub_f32_e32 v54, v148, v54
	v_sub_f32_e32 v53, v148, v53
	v_sub_f32_e32 v52, v148, v52
	v_sub_f32_e32 v51, v148, v51
	v_sub_f32_e32 v50, v148, v50
	ds_read_b128 v[120:123], v118 offset:8192
	ds_read_b128 v[140:143], v117 offset:8192
	s_waitcnt lgkmcnt(0)
	v_mfma_f32_32x32x16_bf16 v[50:65], v[74:77], v[88:91], v[50:65]
	ds_read_b128 v[144:147], v0 offset:8192
	v_sub_f32_e32 v81, v148, v81
	v_sub_f32_e32 v80, v148, v80
	v_sub_f32_e32 v79, v148, v79
	v_sub_f32_e32 v78, v148, v78
	v_sub_f32_e32 v77, v148, v139
	v_sub_f32_e32 v76, v148, v138
	v_mfma_f32_32x32x16_bf16 v[50:65], v[120:123], v[92:95], v[50:65]
	ds_read_b128 v[120:123], v119 offset:12288
	v_sub_f32_e32 v75, v148, v137
	v_sub_f32_e32 v74, v148, v136
	v_sub_f32_e32 v73, v148, v73
	v_sub_f32_e32 v72, v148, v72
	v_sub_f32_e32 v71, v148, v71
	v_sub_f32_e32 v70, v148, v70
	v_mfma_f32_32x32x16_bf16 v[50:65], v[140:143], v[96:99], v[50:65]
	v_sub_f32_e32 v69, v148, v69
	v_sub_f32_e32 v68, v148, v68
	v_sub_f32_e32 v67, v148, v67
	v_sub_f32_e32 v66, v148, v66
	ds_read_b128 v[136:139], v118 offset:12288
	s_cmp_lg_u32 s93, s77
	s_waitcnt lgkmcnt(0)
	v_mfma_f32_32x32x16_bf16 v[66:81], v[120:123], v[88:91], v[66:81]
	ds_read_b128 v[118:121], v117 offset:12288
	v_mfma_f32_32x32x16_bf16 v[66:81], v[136:139], v[92:95], v[66:81]
	s_waitcnt lgkmcnt(0)
	v_mfma_f32_32x32x16_bf16 v[66:81], v[118:121], v[96:99], v[66:81]
	ds_read_b128 v[118:121], v0 offset:12288
	s_waitcnt lgkmcnt(0)
	v_mfma_f32_32x32x16_bf16 v[66:81], v[118:121], v[100:103], v[66:81]
	v_mfma_f32_32x32x16_bf16 v[50:65], v[144:147], v[100:103], v[50:65]
	s_cbranch_scc1 .LBB0_762
	s_nop 10
	v_cndmask_b32_e64 v0, v50, v115, s[2:3]
	v_cndmask_b32_e64 v66, v66, v115, s[4:5]
	v_cndmask_b32_e64 v50, v0, v50, s[6:7]
	v_cndmask_b32_e64 v51, v115, v51, s[6:7]
	v_cndmask_b32_e64 v67, v67, v115, s[8:9]
	v_cndmask_b32_e64 v52, v52, v115, s[10:11]
	v_cndmask_b32_e64 v68, v68, v115, s[12:13]
	v_cndmask_b32_e64 v53, v53, v115, s[14:15]
	v_cndmask_b32_e64 v69, v69, v115, s[16:17]
	v_cndmask_b32_e64 v54, v54, v115, s[18:19]
	v_cndmask_b32_e64 v70, v70, v115, s[20:21]
	v_cndmask_b32_e64 v55, v55, v115, s[22:23]
	v_cndmask_b32_e64 v71, v71, v115, s[24:25]
	v_cndmask_b32_e64 v56, v56, v115, s[26:27]
	v_cndmask_b32_e64 v72, v72, v115, s[28:29]
	v_cndmask_b32_e64 v57, v57, v115, s[30:31]
	v_cndmask_b32_e64 v73, v73, v115, s[34:35]
	v_cndmask_b32_e64 v58, v58, v115, s[36:37]
	v_cndmask_b32_e64 v74, v74, v115, s[38:39]
	v_cndmask_b32_e64 v59, v59, v115, s[40:41]
	v_cndmask_b32_e64 v75, v75, v115, s[42:43]
	v_cndmask_b32_e64 v60, v60, v115, s[44:45]
	v_cndmask_b32_e64 v76, v76, v115, s[46:47]
	v_cndmask_b32_e64 v61, v61, v115, s[48:49]
	v_cndmask_b32_e64 v77, v77, v115, s[50:51]
	v_cndmask_b32_e64 v62, v62, v115, s[52:53]
	v_cndmask_b32_e64 v78, v78, v115, s[54:55]
	v_cndmask_b32_e64 v63, v63, v115, s[56:57]
	v_cndmask_b32_e64 v79, v79, v115, s[58:59]
	v_cndmask_b32_e64 v64, v64, v115, s[60:61]
	v_cndmask_b32_e64 v80, v80, v115, s[62:63]
	v_cndmask_b32_e64 v65, v65, v115, s[64:65]
	v_cndmask_b32_e64 v81, v81, v115, s[66:67]

.LBB0_765:
	v_add_u32_e32 v0, s91, v129
	v_add_u32_e32 v117, v0, v130
	v_exp_f32_e32 v50, v50
	v_exp_f32_e32 v51, v51
	v_exp_f32_e32 v52, v52
	v_exp_f32_e32 v53, v53
	ds_read_b64_tr_b16 v[118:119], v117 offset:24576
	ds_read_b64_tr_b16 v[120:121], v117 offset:25600
	v_exp_f32_e32 v54, v54
	v_exp_f32_e32 v55, v55
	v_exp_f32_e32 v56, v56
	v_exp_f32_e32 v57, v57
	v_cvt_pk_bf16_f32 v136, v50, v51
	v_cvt_pk_bf16_f32 v137, v52, v53
	v_cvt_pk_bf16_f32 v138, v54, v55
	v_cvt_pk_bf16_f32 v139, v56, v57
	v_add_u32_e32 v0, v0, v131
	v_exp_f32_e32 v58, v58
	s_waitcnt lgkmcnt(0)
	v_mfma_f32_32x32x16_bf16 v[2:17], v[118:121], v[136:139], v[2:17]
	ds_read_b64_tr_b16 v[118:119], v0 offset:24576
	ds_read_b64_tr_b16 v[120:121], v0 offset:25600
	v_exp_f32_e32 v59, v59
	v_exp_f32_e32 v60, v60
	v_exp_f32_e32 v61, v61
	v_exp_f32_e32 v62, v62
	v_exp_f32_e32 v63, v63
	v_exp_f32_e32 v64, v64
	s_waitcnt lgkmcnt(0)
	v_mfma_f32_32x32x16_bf16 v[18:33], v[118:121], v[136:139], v[18:33]
	ds_read_b64_tr_b16 v[118:119], v117 offset:26624
	ds_read_b64_tr_b16 v[120:121], v117 offset:27648
	v_exp_f32_e32 v65, v65
	v_mfma_f32_32x32x16_bf16 v[34:49], v[84:87], v[136:139], v[34:49]
	v_cvt_pk_bf16_f32 v136, v58, v59
	v_cvt_pk_bf16_f32 v137, v60, v61
	v_cvt_pk_bf16_f32 v138, v62, v63
	v_cvt_pk_bf16_f32 v139, v64, v65
	s_waitcnt lgkmcnt(0)
	s_nop 0
	v_mfma_f32_32x32x16_bf16 v[2:17], v[118:121], v[136:139], v[2:17]
	ds_read_b64_tr_b16 v[118:119], v0 offset:26624
	ds_read_b64_tr_b16 v[120:121], v0 offset:27648
	s_waitcnt lgkmcnt(0)
	v_mfma_f32_32x32x16_bf16 v[18:33], v[118:121], v[136:139], v[18:33]
	v_max_f32_e32 v118, v67, v67
	v_max_f32_e32 v119, v66, v66
	v_max_f32_e32 v118, v119, v118
	v_max3_f32 v118, v118, v68, v69
	v_max3_f32 v118, v118, v70, v71
	v_max3_f32 v118, v118, v72, v73
	v_max3_f32 v118, v118, v74, v75
	v_max3_f32 v118, v118, v76, v77
	v_mfma_f32_32x32x16_bf16 v[34:49], v[84:87], v[136:139], v[34:49]
	v_max3_f32 v118, v118, v78, v79
	v_max3_f32 v118, v118, v80, v81
	v_mov_b32_e32 v119, v118
	s_nop 1
	v_permlane32_swap_b32_e32 v118, v119
	v_max_f32_e32 v119, v119, v119
	v_max_f32_e32 v118, v118, v118
	v_max_f32_e32 v118, v118, v119
	v_cmp_lt_f32_e32 vcc, s95, v118
	s_cbranch_vccz .LBB0_767
	v_max_f32_e32 v118, v118, v118
	v_max_f32_e32 v118, 0, v118
	v_exp_f32_e64 v120, -v118
	v_add_f32_e32 v116, v116, v118
	v_pk_add_f32 v[66:67], v[66:67], v[118:119] op_sel_hi:[1,0] neg_lo:[0,1] neg_hi:[0,1]
	v_pk_add_f32 v[68:69], v[68:69], v[118:119] op_sel_hi:[1,0] neg_lo:[0,1] neg_hi:[0,1]
	v_mul_f32_e32 v34, v34, v120
	v_pk_add_f32 v[70:71], v[70:71], v[118:119] op_sel_hi:[1,0] neg_lo:[0,1] neg_hi:[0,1]
	v_pk_add_f32 v[72:73], v[72:73], v[118:119] op_sel_hi:[1,0] neg_lo:[0,1] neg_hi:[0,1]
	v_pk_add_f32 v[74:75], v[74:75], v[118:119] op_sel_hi:[1,0] neg_lo:[0,1] neg_hi:[0,1]
	v_pk_add_f32 v[76:77], v[76:77], v[118:119] op_sel_hi:[1,0] neg_lo:[0,1] neg_hi:[0,1]
	v_pk_add_f32 v[78:79], v[78:79], v[118:119] op_sel_hi:[1,0] neg_lo:[0,1] neg_hi:[0,1]
	v_pk_add_f32 v[80:81], v[80:81], v[118:119] op_sel_hi:[1,0] neg_lo:[0,1] neg_hi:[0,1]
	v_pk_mul_f32 v[32:33], v[32:33], v[120:121] op_sel_hi:[1,0]
	v_pk_mul_f32 v[30:31], v[30:31], v[120:121] op_sel_hi:[1,0]
	v_pk_mul_f32 v[28:29], v[28:29], v[120:121] op_sel_hi:[1,0]
	v_pk_mul_f32 v[26:27], v[26:27], v[120:121] op_sel_hi:[1,0]
	v_pk_mul_f32 v[24:25], v[24:25], v[120:121] op_sel_hi:[1,0]
	v_pk_mul_f32 v[22:23], v[22:23], v[120:121] op_sel_hi:[1,0]
	v_pk_mul_f32 v[20:21], v[20:21], v[120:121] op_sel_hi:[1,0]
	v_pk_mul_f32 v[18:19], v[18:19], v[120:121] op_sel_hi:[1,0]
	v_pk_mul_f32 v[16:17], v[16:17], v[120:121] op_sel_hi:[1,0]
	v_pk_mul_f32 v[14:15], v[14:15], v[120:121] op_sel_hi:[1,0]
	v_pk_mul_f32 v[12:13], v[12:13], v[120:121] op_sel_hi:[1,0]
	v_pk_mul_f32 v[10:11], v[10:11], v[120:121] op_sel_hi:[1,0]
	v_pk_mul_f32 v[8:9], v[8:9], v[120:121] op_sel_hi:[1,0]
	v_pk_mul_f32 v[6:7], v[6:7], v[120:121] op_sel_hi:[1,0]
	v_pk_mul_f32 v[4:5], v[4:5], v[120:121] op_sel_hi:[1,0]
	v_pk_mul_f32 v[2:3], v[2:3], v[120:121] op_sel_hi:[1,0]
.LBB0_767:
	v_exp_f32_e32 v66, v66
	v_exp_f32_e32 v67, v67
	v_exp_f32_e32 v68, v68
	v_exp_f32_e32 v69, v69
	ds_read_b64_tr_b16 v[118:119], v117 offset:28672
	ds_read_b64_tr_b16 v[120:121], v117 offset:29696
	v_exp_f32_e32 v70, v70
	v_exp_f32_e32 v71, v71
	v_exp_f32_e32 v72, v72
	v_exp_f32_e32 v73, v73
	v_cvt_pk_bf16_f32 v136, v66, v67
	v_cvt_pk_bf16_f32 v137, v68, v69
	v_cvt_pk_bf16_f32 v138, v70, v71
	v_cvt_pk_bf16_f32 v139, v72, v73
	v_exp_f32_e32 v74, v74
	v_exp_f32_e32 v75, v75
	s_waitcnt lgkmcnt(0)
	v_mfma_f32_32x32x16_bf16 v[2:17], v[118:121], v[136:139], v[2:17]
	ds_read_b64_tr_b16 v[118:119], v0 offset:28672
	ds_read_b64_tr_b16 v[120:121], v0 offset:29696
	v_exp_f32_e32 v76, v76
	v_exp_f32_e32 v77, v77
	v_exp_f32_e32 v78, v78
	v_exp_f32_e32 v79, v79
	v_exp_f32_e32 v80, v80
	v_exp_f32_e32 v81, v81
	s_waitcnt lgkmcnt(0)
	v_mfma_f32_32x32x16_bf16 v[18:33], v[118:121], v[136:139], v[18:33]
	ds_read_b64_tr_b16 v[118:119], v117 offset:30720
	ds_read_b64_tr_b16 v[120:121], v117 offset:31744
	v_mfma_f32_32x32x16_bf16 v[34:49], v[84:87], v[136:139], v[34:49]
	v_cvt_pk_bf16_f32 v136, v74, v75
	v_cvt_pk_bf16_f32 v137, v76, v77
	v_cvt_pk_bf16_f32 v138, v78, v79
	v_cvt_pk_bf16_f32 v139, v80, v81
	s_waitcnt lgkmcnt(0)
	s_nop 0
	v_mfma_f32_32x32x16_bf16 v[2:17], v[118:121], v[136:139], v[2:17]
	ds_read_b64_tr_b16 v[118:119], v0 offset:30720
	ds_read_b64_tr_b16 v[120:121], v0 offset:31744
	s_waitcnt lgkmcnt(0)
	v_mfma_f32_32x32x16_bf16 v[18:33], v[118:121], v[136:139], v[18:33]
	v_mfma_f32_32x32x16_bf16 v[34:49], v[84:87], v[136:139], v[34:49]

.LBB0_770:
	s_nop 2
	v_mov_b32_e32 v0, v34
	s_nop 1
	v_permlane32_swap_b32_e32 v34, v0
	v_add_f32_e32 v0, v34, v0
	v_div_scale_f32 v1, s[0:1], v0, v0, 1.0
	v_rcp_f32_e32 v34, v1
	s_mulk_i32 s71, 0x1200
	s_add_i32 s2, s71, 0
	v_mul_u32_u24_e32 v136, 0x90, v133
	v_fma_f32 v35, -v1, v34, 1.0
	v_fmac_f32_e32 v34, v35, v34
	v_div_scale_f32 v35, vcc, 1.0, v0, 1.0
	v_mul_f32_e32 v36, v35, v34
	v_fma_f32 v37, -v1, v36, v35
	v_fmac_f32_e32 v36, v37, v34
	v_fma_f32 v1, -v1, v36, v35
	v_div_fmas_f32 v1, v1, v34, v36
	v_div_fixup_f32 v0, v1, v0, 1.0
	v_add3_u32 v1, s2, v136, v124
	v_pk_mul_f32 v[2:3], v[2:3], v[0:1] op_sel_hi:[1,0]
	v_pk_mul_f32 v[4:5], v[4:5], v[0:1] op_sel_hi:[1,0]
	v_cvt_pk_bf16_f32 v2, v2, v3
	v_cvt_pk_bf16_f32 v3, v4, v5
	v_pk_mul_f32 v[4:5], v[6:7], v[0:1] op_sel_hi:[1,0]
	v_pk_mul_f32 v[6:7], v[8:9], v[0:1] op_sel_hi:[1,0]
	v_cvt_pk_bf16_f32 v4, v4, v5
	v_cvt_pk_bf16_f32 v5, v6, v7
	v_add_u32_e32 v8, 0x9000, v1
	s_waitcnt vmcnt(0) lgkmcnt(0)
	s_barrier
	ds_write2_b64 v8, v[2:3], v[4:5] offset1:2
	v_pk_mul_f32 v[2:3], v[10:11], v[0:1] op_sel_hi:[1,0]
	v_pk_mul_f32 v[4:5], v[12:13], v[0:1] op_sel_hi:[1,0]
	v_cvt_pk_bf16_f32 v2, v2, v3
	v_cvt_pk_bf16_f32 v3, v4, v5
	v_pk_mul_f32 v[4:5], v[14:15], v[0:1] op_sel_hi:[1,0]
	v_pk_mul_f32 v[6:7], v[16:17], v[0:1] op_sel_hi:[1,0]
	v_cvt_pk_bf16_f32 v4, v4, v5
	v_cvt_pk_bf16_f32 v5, v6, v7
	ds_write2_b64 v8, v[2:3], v[4:5] offset0:4 offset1:6
	v_pk_mul_f32 v[2:3], v[18:19], v[0:1] op_sel_hi:[1,0]
	v_pk_mul_f32 v[4:5], v[20:21], v[0:1] op_sel_hi:[1,0]
	v_cvt_pk_bf16_f32 v2, v2, v3
	v_cvt_pk_bf16_f32 v3, v4, v5
	v_pk_mul_f32 v[4:5], v[22:23], v[0:1] op_sel_hi:[1,0]
	v_pk_mul_f32 v[6:7], v[24:25], v[0:1] op_sel_hi:[1,0]
	v_cvt_pk_bf16_f32 v4, v4, v5
	v_cvt_pk_bf16_f32 v5, v6, v7
	ds_write2_b64 v8, v[2:3], v[4:5] offset0:8 offset1:10
	v_pk_mul_f32 v[2:3], v[26:27], v[0:1] op_sel_hi:[1,0]
	v_pk_mul_f32 v[4:5], v[28:29], v[0:1] op_sel_hi:[1,0]
	s_lshl_b64 s[0:1], s[74:75], 11
	v_readlane_b32 s6, v249, 53
	v_cvt_pk_bf16_f32 v2, v2, v3
	v_cvt_pk_bf16_f32 v3, v4, v5
	v_pk_mul_f32 v[4:5], v[30:31], v[0:1] op_sel_hi:[1,0]
	v_pk_mul_f32 v[0:1], v[32:33], v[0:1] op_sel_hi:[1,0]
	v_readlane_b32 s7, v249, 54
	s_add_u32 s0, s6, s0
	v_cvt_pk_bf16_f32 v4, v4, v5
	v_cvt_pk_bf16_f32 v5, v0, v1
	s_addc_u32 s1, s7, s1
	s_lshl_b32 s74, s97, 1
	ds_write2_b64 v8, v[2:3], v[4:5] offset0:12 offset1:14
	s_add_u32 s0, s0, s74
	v_and_b32_e32 v14, 7, v222
	v_mov_b32_e32 v3, 0
	s_addc_u32 s1, s1, 0
	v_lshrrev_b32_e32 v2, 3, v134
	v_lshlrev_b32_e32 v110, 4, v14
	v_mov_b32_e32 v111, v3
	v_lshl_add_u64 v[0:1], s[0:1], 0, v[110:111]
	v_mul_u32_u24_e32 v111, 0x90, v2
	s_waitcnt lgkmcnt(0)
	v_add3_u32 v15, s2, v110, v111
	ds_read_b128 v[4:7], v15 offset:36864
	ds_read_b128 v[8:11], v15 offset:38016
	v_lshlrev_b32_e32 v120, 10, v2
	v_lshlrev_b32_e32 v2, 11, v2
	v_lshl_add_u64 v[12:13], v[0:1], 0, v[2:3]
	v_or_b32_e32 v2, 0x2000, v120
	v_lshlrev_b32_e32 v114, 1, v2
	v_mov_b32_e32 v115, v3
	s_waitcnt lgkmcnt(0)
	global_store_dwordx4 v[12:13], v[4:7], off
	v_readlane_b32 s0, v248, 6
	s_or_b32 s2, s0, 24
	v_lshl_add_u64 v[4:5], v[0:1], 0, v[114:115]
	global_store_dwordx4 v[4:5], v[8:11], off
	ds_read_b128 v[8:11], v15 offset:40320
	v_readfirstlane_b32 s4, v222
	v_or_b32_e32 v2, 0x4000, v120
	s_lshr_b32 s96, s4, 6
	s_lshl_b32 s3, s2, 8
	v_readlane_b32 s8, v248, 7
	v_lshlrev_b32_e32 v112, 1, v2
	v_or_b32_e32 v2, 0x6000, v120
	s_lshl_b32 s76, s96, 5
	s_or_b32 s0, s8, s3
	ds_read_b128 v[4:7], v15 offset:39168
	v_mov_b32_e32 v113, v3
	v_lshlrev_b32_e32 v116, 1, v2
	v_mov_b32_e32 v117, v3
	v_readlane_b32 s9, v248, 8
	s_add_u32 s78, s0, s76
	v_lshl_add_u64 v[12:13], v[0:1], 0, v[112:113]
	v_lshl_add_u64 v[0:1], v[0:1], 0, v[116:117]
	s_addc_u32 s79, s9, 0
	s_waitcnt lgkmcnt(0)
	global_store_dwordx4 v[0:1], v[8:11], off
	v_mov_b32_e32 v1, s79
	v_or_b32_e32 v0, s78, v133
	s_mov_b32 s77, 0
	v_lshlrev_b64 v[0:1], 11, v[0:1]
	s_mov_b32 s75, s77
	v_lshl_add_u64 v[0:1], s[6:7], 0, v[0:1]
	global_store_dwordx4 v[12:13], v[4:7], off
	s_cmp_gt_u32 s4, 63
	s_nop 0
	v_lshl_add_u64 v[4:5], v[0:1], 0, s[74:75]
	v_lshlrev_b32_e32 v0, 1, v124
	v_mov_b32_e32 v1, v3
	v_lshl_add_u64 v[4:5], v[4:5], 0, v[0:1]
	global_load_dwordx4 v[88:91], v[4:5], off
	global_load_dwordx4 v[92:95], v[4:5], off offset:32
	global_load_dwordx4 v[96:99], v[4:5], off offset:64
	global_load_dwordx4 v[100:103], v[4:5], off offset:96
	s_mov_b32 s75, 0x9000
	v_lshlrev_b32_e32 v1, 3, v14
	s_cbranch_scc1 .LBB0_776
	v_cmp_gt_u32_e32 vcc, 32, v134
	v_mov_b32_e32 v2, 0
	s_and_saveexec_b64 s[0:1], vcc
	s_cbranch_execz .LBB0_773
	v_lshlrev_b32_e32 v2, 4, v133
	v_readlane_b32 s6, v249, 62
	v_readlane_b32 s7, v249, 63
	v_readlane_b32 s5, v249, 60
	v_lshl_or_b32 v2, s6, 9, v2
	v_readlane_b32 s6, v249, 51
	v_or_b32_e32 v4, s5, v2
	v_ashrrev_i32_e32 v5, 31, v4
	v_readlane_b32 s7, v249, 52
	s_nop 1
	v_lshl_add_u64 v[4:5], v[4:5], 2, s[6:7]
	global_load_dword v2, v[4:5], off

.LBB0_778:
	s_add_i32 s91, s0, 0
	s_lshl_b32 s0, s1, 1
	s_and_b32 s0, s0, -4
	s_add_i32 s68, s0, 0
	s_add_i32 s68, s68, 0x1b000
	s_cmp_le_u32 s77, s71
	v_lshl_add_u32 v141, v132, 2, s91
	s_cselect_b64 s[0:1], -1, 0
	s_cmp_gt_u32 s77, s71
	v_add_u32_e32 v140, s91, v125
	v_add_u32_e32 v139, s91, v126
	v_add_u32_e32 v138, s91, v127
	v_add_u32_e32 v2, s91, v128
	s_cbranch_scc1 .LBB0_781
	v_mov_b32_e32 v52, s68
	ds_read_b32 v60, v52
	v_sub_f32_e32 v61, v113, v137
	ds_read_b128 v[76:79], v141 offset:32832
	ds_read_b128 v[52:55], v141 offset:32768
	ds_read_b128 v[56:59], v141 offset:32800
	s_waitcnt lgkmcnt(0)
	v_sub_f32_e32 v158, v61, v60
	ds_read_b128 v[60:63], v141 offset:32864
	ds_read_b128 v[146:149], v139
	v_sub_f32_e32 v55, v158, v55
	v_sub_f32_e32 v59, v158, v59
	v_sub_f32_e32 v58, v158, v58
	s_waitcnt lgkmcnt(0)
	v_sub_f32_e32 v67, v158, v63
	v_sub_f32_e32 v66, v158, v62
	v_sub_f32_e32 v65, v158, v61
	v_sub_f32_e32 v64, v158, v60
	v_sub_f32_e32 v63, v158, v79
	v_sub_f32_e32 v62, v158, v78
	v_sub_f32_e32 v61, v158, v77
	v_sub_f32_e32 v60, v158, v76
	ds_read_b128 v[76:79], v140
	v_sub_f32_e32 v57, v158, v57
	v_sub_f32_e32 v56, v158, v56
	v_sub_f32_e32 v54, v158, v54
	v_sub_f32_e32 v53, v158, v53
	v_sub_f32_e32 v52, v158, v52
	ds_read_b128 v[68:71], v141 offset:32896
	ds_read_b128 v[72:75], v141 offset:32928
	ds_read_b128 v[142:145], v141 offset:32960
	ds_read_b128 v[80:83], v141 offset:32992
	ds_read_b128 v[150:153], v138
	s_waitcnt lgkmcnt(0)
	v_mfma_f32_32x32x16_bf16 v[52:67], v[76:79], v[88:91], v[52:67]
	ds_read_b128 v[154:157], v2
	v_sub_f32_e32 v79, v158, v145
	v_sub_f32_e32 v78, v158, v144
	v_sub_f32_e32 v77, v158, v143
	v_sub_f32_e32 v76, v158, v142
	v_sub_f32_e32 v83, v158, v83
	v_sub_f32_e32 v82, v158, v82
	v_mfma_f32_32x32x16_bf16 v[52:67], v[146:149], v[92:95], v[52:67]
	ds_read_b128 v[142:145], v140 offset:4096
	v_sub_f32_e32 v81, v158, v81
	v_sub_f32_e32 v80, v158, v80
	v_sub_f32_e32 v75, v158, v75
	v_sub_f32_e32 v74, v158, v74
	v_sub_f32_e32 v73, v158, v73
	v_sub_f32_e32 v72, v158, v72
	v_mfma_f32_32x32x16_bf16 v[52:67], v[150:153], v[96:99], v[52:67]
	v_sub_f32_e32 v71, v158, v71
	v_sub_f32_e32 v70, v158, v70
	v_sub_f32_e32 v69, v158, v69
	v_sub_f32_e32 v68, v158, v68
	ds_read_b128 v[146:149], v139 offset:4096
	s_cmp_lg_u32 s33, s77
	s_waitcnt lgkmcnt(0)
	v_mfma_f32_32x32x16_bf16 v[68:83], v[142:145], v[88:91], v[68:83]
	ds_read_b128 v[142:145], v138 offset:4096
	v_mfma_f32_32x32x16_bf16 v[68:83], v[146:149], v[92:95], v[68:83]
	s_waitcnt lgkmcnt(0)
	v_mfma_f32_32x32x16_bf16 v[68:83], v[142:145], v[96:99], v[68:83]
	ds_read_b128 v[142:145], v2 offset:4096
	s_waitcnt lgkmcnt(0)
	v_mfma_f32_32x32x16_bf16 v[68:83], v[142:145], v[100:103], v[68:83]
	v_mfma_f32_32x32x16_bf16 v[52:67], v[154:157], v[100:103], v[52:67]
	s_cbranch_scc1 .LBB0_781
	s_nop 10
	v_cndmask_b32_e64 v142, v52, v123, s[2:3]
	v_cndmask_b32_e64 v68, v68, v123, s[4:5]
	v_cndmask_b32_e64 v52, v142, v52, s[6:7]
	v_cndmask_b32_e64 v53, v123, v53, s[6:7]
	v_cndmask_b32_e64 v69, v69, v123, s[8:9]
	v_cndmask_b32_e64 v54, v54, v123, s[10:11]
	v_cndmask_b32_e64 v70, v70, v123, s[12:13]
	v_cndmask_b32_e64 v55, v55, v123, s[14:15]
	v_cndmask_b32_e64 v71, v71, v123, s[16:17]
	v_cndmask_b32_e64 v56, v56, v123, s[18:19]
	v_cndmask_b32_e64 v72, v72, v123, s[20:21]
	v_cndmask_b32_e64 v57, v57, v123, s[22:23]
	v_cndmask_b32_e64 v73, v73, v123, s[24:25]
	v_cndmask_b32_e64 v58, v58, v123, s[26:27]
	v_cndmask_b32_e64 v74, v74, v123, s[28:29]
	v_cndmask_b32_e64 v59, v59, v123, s[30:31]
	v_cndmask_b32_e64 v75, v75, v123, s[34:35]
	v_cndmask_b32_e64 v60, v60, v123, s[36:37]
	v_cndmask_b32_e64 v76, v76, v123, s[38:39]
	v_cndmask_b32_e64 v61, v61, v123, s[40:41]
	v_cndmask_b32_e64 v77, v77, v123, s[42:43]
	v_cndmask_b32_e64 v62, v62, v123, s[44:45]
	v_cndmask_b32_e64 v78, v78, v123, s[46:47]
	v_cndmask_b32_e64 v63, v63, v123, s[48:49]
	v_cndmask_b32_e64 v79, v79, v123, s[50:51]
	v_cndmask_b32_e64 v64, v64, v123, s[52:53]
	v_cndmask_b32_e64 v80, v80, v123, s[54:55]
	v_cndmask_b32_e64 v65, v65, v123, s[56:57]
	v_cndmask_b32_e64 v81, v81, v123, s[58:59]
	v_cndmask_b32_e64 v66, v66, v123, s[60:61]
	v_cndmask_b32_e64 v82, v82, v123, s[62:63]
	v_cndmask_b32_e64 v67, v67, v123, s[64:65]
	v_cndmask_b32_e64 v83, v83, v123, s[66:67]

.LBB0_784:
	v_add_u32_e32 v142, s91, v129
	v_add_u32_e32 v143, v142, v130
	v_exp_f32_e32 v52, v52
	v_exp_f32_e32 v53, v53
	v_exp_f32_e32 v54, v54
	v_exp_f32_e32 v55, v55
	ds_read_b64_tr_b16 v[144:145], v143 offset:16384
	ds_read_b64_tr_b16 v[146:147], v143 offset:17408
	v_exp_f32_e32 v56, v56
	v_exp_f32_e32 v57, v57
	v_exp_f32_e32 v58, v58
	v_exp_f32_e32 v59, v59
	v_cvt_pk_bf16_f32 v148, v52, v53
	v_cvt_pk_bf16_f32 v149, v54, v55
	v_cvt_pk_bf16_f32 v150, v56, v57
	v_cvt_pk_bf16_f32 v151, v58, v59
	v_add_u32_e32 v142, v142, v131
	v_exp_f32_e32 v60, v60
	s_waitcnt lgkmcnt(0)
	v_mfma_f32_32x32x16_bf16 v[4:19], v[144:147], v[148:151], v[4:19]
	ds_read_b64_tr_b16 v[144:145], v142 offset:16384
	ds_read_b64_tr_b16 v[146:147], v142 offset:17408
	v_exp_f32_e32 v61, v61
	v_exp_f32_e32 v62, v62
	v_exp_f32_e32 v63, v63
	v_exp_f32_e32 v64, v64
	v_exp_f32_e32 v65, v65
	v_exp_f32_e32 v66, v66
	s_waitcnt lgkmcnt(0)
	v_mfma_f32_32x32x16_bf16 v[20:35], v[144:147], v[148:151], v[20:35]
	ds_read_b64_tr_b16 v[144:145], v143 offset:18432
	ds_read_b64_tr_b16 v[146:147], v143 offset:19456
	v_exp_f32_e32 v67, v67
	v_mfma_f32_32x32x16_bf16 v[36:51], v[84:87], v[148:151], v[36:51]
	v_cvt_pk_bf16_f32 v148, v60, v61
	v_cvt_pk_bf16_f32 v149, v62, v63
	v_cvt_pk_bf16_f32 v150, v64, v65
	v_cvt_pk_bf16_f32 v151, v66, v67
	s_waitcnt lgkmcnt(0)
	s_nop 0
	v_mfma_f32_32x32x16_bf16 v[4:19], v[144:147], v[148:151], v[4:19]
	ds_read_b64_tr_b16 v[144:145], v142 offset:18432
	ds_read_b64_tr_b16 v[146:147], v142 offset:19456
	s_waitcnt lgkmcnt(0)
	v_mfma_f32_32x32x16_bf16 v[20:35], v[144:147], v[148:151], v[20:35]
	v_max_f32_e32 v144, v69, v69
	v_max_f32_e32 v145, v68, v68
	v_max_f32_e32 v144, v145, v144
	v_max3_f32 v144, v144, v70, v71
	v_max3_f32 v144, v144, v72, v73
	v_max3_f32 v144, v144, v74, v75
	v_max3_f32 v144, v144, v76, v77
	v_max3_f32 v144, v144, v78, v79
	v_mfma_f32_32x32x16_bf16 v[36:51], v[84:87], v[148:151], v[36:51]
	v_max3_f32 v144, v144, v80, v81
	v_max3_f32 v144, v144, v82, v83
	v_mov_b32_e32 v145, v144
	s_nop 1
	v_permlane32_swap_b32_e32 v144, v145
	v_max_f32_e32 v145, v145, v145
	v_max_f32_e32 v144, v144, v144
	v_max_f32_e32 v144, v144, v145
	v_cmp_lt_f32_e32 vcc, s94, v144
	s_cbranch_vccz .LBB0_786
	v_max_f32_e32 v144, v144, v144
	v_max_f32_e32 v144, 0, v144
	v_exp_f32_e64 v146, -v144
	v_add_f32_e32 v137, v137, v144
	v_pk_add_f32 v[68:69], v[68:69], v[144:145] op_sel_hi:[1,0] neg_lo:[0,1] neg_hi:[0,1]
	v_pk_add_f32 v[70:71], v[70:71], v[144:145] op_sel_hi:[1,0] neg_lo:[0,1] neg_hi:[0,1]
	v_mul_f32_e32 v36, v36, v146
	v_pk_add_f32 v[72:73], v[72:73], v[144:145] op_sel_hi:[1,0] neg_lo:[0,1] neg_hi:[0,1]
	v_pk_add_f32 v[74:75], v[74:75], v[144:145] op_sel_hi:[1,0] neg_lo:[0,1] neg_hi:[0,1]
	v_pk_add_f32 v[76:77], v[76:77], v[144:145] op_sel_hi:[1,0] neg_lo:[0,1] neg_hi:[0,1]
	v_pk_add_f32 v[78:79], v[78:79], v[144:145] op_sel_hi:[1,0] neg_lo:[0,1] neg_hi:[0,1]
	v_pk_add_f32 v[80:81], v[80:81], v[144:145] op_sel_hi:[1,0] neg_lo:[0,1] neg_hi:[0,1]
	v_pk_add_f32 v[82:83], v[82:83], v[144:145] op_sel_hi:[1,0] neg_lo:[0,1] neg_hi:[0,1]
	v_pk_mul_f32 v[34:35], v[34:35], v[146:147] op_sel_hi:[1,0]
	v_pk_mul_f32 v[32:33], v[32:33], v[146:147] op_sel_hi:[1,0]
	v_pk_mul_f32 v[30:31], v[30:31], v[146:147] op_sel_hi:[1,0]
	v_pk_mul_f32 v[28:29], v[28:29], v[146:147] op_sel_hi:[1,0]
	v_pk_mul_f32 v[26:27], v[26:27], v[146:147] op_sel_hi:[1,0]
	v_pk_mul_f32 v[24:25], v[24:25], v[146:147] op_sel_hi:[1,0]
	v_pk_mul_f32 v[22:23], v[22:23], v[146:147] op_sel_hi:[1,0]
	v_pk_mul_f32 v[20:21], v[20:21], v[146:147] op_sel_hi:[1,0]
	v_pk_mul_f32 v[18:19], v[18:19], v[146:147] op_sel_hi:[1,0]
	v_pk_mul_f32 v[16:17], v[16:17], v[146:147] op_sel_hi:[1,0]
	v_pk_mul_f32 v[14:15], v[14:15], v[146:147] op_sel_hi:[1,0]
	v_pk_mul_f32 v[12:13], v[12:13], v[146:147] op_sel_hi:[1,0]
	v_pk_mul_f32 v[10:11], v[10:11], v[146:147] op_sel_hi:[1,0]
	v_pk_mul_f32 v[8:9], v[8:9], v[146:147] op_sel_hi:[1,0]
	v_pk_mul_f32 v[6:7], v[6:7], v[146:147] op_sel_hi:[1,0]
	v_pk_mul_f32 v[4:5], v[4:5], v[146:147] op_sel_hi:[1,0]
.LBB0_786:
	v_exp_f32_e32 v68, v68
	v_exp_f32_e32 v69, v69
	v_exp_f32_e32 v70, v70
	v_exp_f32_e32 v71, v71
	ds_read_b64_tr_b16 v[144:145], v143 offset:20480
	ds_read_b64_tr_b16 v[146:147], v143 offset:21504
	v_exp_f32_e32 v72, v72
	v_exp_f32_e32 v73, v73
	v_exp_f32_e32 v74, v74
	v_exp_f32_e32 v75, v75
	v_cvt_pk_bf16_f32 v148, v68, v69
	v_cvt_pk_bf16_f32 v149, v70, v71
	v_cvt_pk_bf16_f32 v150, v72, v73
	v_cvt_pk_bf16_f32 v151, v74, v75
	v_exp_f32_e32 v76, v76
	v_exp_f32_e32 v77, v77
	s_waitcnt lgkmcnt(0)
	v_mfma_f32_32x32x16_bf16 v[4:19], v[144:147], v[148:151], v[4:19]
	ds_read_b64_tr_b16 v[144:145], v142 offset:20480
	ds_read_b64_tr_b16 v[146:147], v142 offset:21504
	v_exp_f32_e32 v78, v78
	v_exp_f32_e32 v79, v79
	v_exp_f32_e32 v80, v80
	v_exp_f32_e32 v81, v81
	v_exp_f32_e32 v82, v82
	v_exp_f32_e32 v83, v83
	s_waitcnt lgkmcnt(0)
	v_mfma_f32_32x32x16_bf16 v[20:35], v[144:147], v[148:151], v[20:35]
	ds_read_b64_tr_b16 v[144:145], v143 offset:22528
	ds_read_b64_tr_b16 v[146:147], v143 offset:23552
	v_mfma_f32_32x32x16_bf16 v[36:51], v[84:87], v[148:151], v[36:51]
	v_cvt_pk_bf16_f32 v148, v76, v77
	v_cvt_pk_bf16_f32 v149, v78, v79
	v_cvt_pk_bf16_f32 v150, v80, v81
	v_cvt_pk_bf16_f32 v151, v82, v83
	s_waitcnt lgkmcnt(0)
	s_nop 0
	v_mfma_f32_32x32x16_bf16 v[4:19], v[144:147], v[148:151], v[4:19]
	ds_read_b64_tr_b16 v[144:145], v142 offset:22528
	ds_read_b64_tr_b16 v[146:147], v142 offset:23552
	s_waitcnt lgkmcnt(0)
	v_mfma_f32_32x32x16_bf16 v[20:35], v[144:147], v[148:151], v[20:35]
	v_mfma_f32_32x32x16_bf16 v[36:51], v[84:87], v[148:151], v[36:51]
.LBB0_787:
	s_cmp_lt_u32 s77, s71
	s_cselect_b64 s[0:1], -1, 0
	s_cmp_ge_u32 s77, s71
	s_cbranch_scc1 .LBB0_790
	s_nop 4
	v_mov_b32_e32 v52, s68
	ds_read_b32 v60, v52
	v_sub_f32_e32 v61, v113, v137
	ds_read_b128 v[76:79], v141 offset:33088
	ds_read_b128 v[52:55], v141 offset:33024
	ds_read_b128 v[56:59], v141 offset:33056
	s_waitcnt lgkmcnt(0)
	v_sub_f32_e32 v158, v61, v60
	ds_read_b128 v[60:63], v141 offset:33120
	ds_read_b128 v[146:149], v139 offset:8192
	v_sub_f32_e32 v55, v158, v55
	v_sub_f32_e32 v59, v158, v59
	v_sub_f32_e32 v58, v158, v58
	s_waitcnt lgkmcnt(0)
	v_sub_f32_e32 v67, v158, v63
	v_sub_f32_e32 v66, v158, v62
	v_sub_f32_e32 v65, v158, v61
	v_sub_f32_e32 v64, v158, v60
	v_sub_f32_e32 v63, v158, v79
	v_sub_f32_e32 v62, v158, v78
	v_sub_f32_e32 v61, v158, v77
	v_sub_f32_e32 v60, v158, v76
	ds_read_b128 v[76:79], v140 offset:8192
	v_sub_f32_e32 v57, v158, v57
	v_sub_f32_e32 v56, v158, v56
	v_sub_f32_e32 v54, v158, v54
	v_sub_f32_e32 v53, v158, v53
	v_sub_f32_e32 v52, v158, v52
	ds_read_b128 v[68:71], v141 offset:33152
	ds_read_b128 v[72:75], v141 offset:33184
	ds_read_b128 v[142:145], v141 offset:33216
	ds_read_b128 v[80:83], v141 offset:33248
	ds_read_b128 v[150:153], v138 offset:8192
	s_waitcnt lgkmcnt(0)
	v_mfma_f32_32x32x16_bf16 v[52:67], v[76:79], v[88:91], v[52:67]
	ds_read_b128 v[154:157], v2 offset:8192
	v_sub_f32_e32 v77, v158, v143
	v_sub_f32_e32 v76, v158, v142
	v_sub_f32_e32 v83, v158, v83
	v_sub_f32_e32 v82, v158, v82
	v_sub_f32_e32 v81, v158, v81
	v_sub_f32_e32 v80, v158, v80
	v_mfma_f32_32x32x16_bf16 v[52:67], v[146:149], v[92:95], v[52:67]
	ds_read_b128 v[140:143], v140 offset:12288
	v_sub_f32_e32 v79, v158, v145
	v_sub_f32_e32 v78, v158, v144
	v_sub_f32_e32 v75, v158, v75
	v_sub_f32_e32 v74, v158, v74
	v_sub_f32_e32 v73, v158, v73
	v_sub_f32_e32 v72, v158, v72
	v_mfma_f32_32x32x16_bf16 v[52:67], v[150:153], v[96:99], v[52:67]
	v_sub_f32_e32 v71, v158, v71
	v_sub_f32_e32 v70, v158, v70
	v_sub_f32_e32 v69, v158, v69
	v_sub_f32_e32 v68, v158, v68
	ds_read_b128 v[144:147], v139 offset:12288
	s_cmp_lg_u32 s76, s77
	s_waitcnt lgkmcnt(0)
	v_mfma_f32_32x32x16_bf16 v[68:83], v[140:143], v[88:91], v[68:83]
	ds_read_b128 v[138:141], v138 offset:12288
	v_mfma_f32_32x32x16_bf16 v[68:83], v[144:147], v[92:95], v[68:83]
	s_waitcnt lgkmcnt(0)
	v_mfma_f32_32x32x16_bf16 v[68:83], v[138:141], v[96:99], v[68:83]
	ds_read_b128 v[138:141], v2 offset:12288
	s_waitcnt lgkmcnt(0)
	v_mfma_f32_32x32x16_bf16 v[68:83], v[138:141], v[100:103], v[68:83]
	v_mfma_f32_32x32x16_bf16 v[52:67], v[154:157], v[100:103], v[52:67]
	s_cbranch_scc1 .LBB0_790
	s_nop 10
	v_cndmask_b32_e64 v2, v52, v123, s[2:3]
	v_cndmask_b32_e64 v68, v68, v123, s[4:5]
	v_cndmask_b32_e64 v52, v2, v52, s[6:7]
	v_cndmask_b32_e64 v53, v123, v53, s[6:7]
	v_cndmask_b32_e64 v69, v69, v123, s[8:9]
	v_cndmask_b32_e64 v54, v54, v123, s[10:11]
	v_cndmask_b32_e64 v70, v70, v123, s[12:13]
	v_cndmask_b32_e64 v55, v55, v123, s[14:15]
	v_cndmask_b32_e64 v71, v71, v123, s[16:17]
	v_cndmask_b32_e64 v56, v56, v123, s[18:19]
	v_cndmask_b32_e64 v72, v72, v123, s[20:21]
	v_cndmask_b32_e64 v57, v57, v123, s[22:23]
	v_cndmask_b32_e64 v73, v73, v123, s[24:25]
	v_cndmask_b32_e64 v58, v58, v123, s[26:27]
	v_cndmask_b32_e64 v74, v74, v123, s[28:29]
	v_cndmask_b32_e64 v59, v59, v123, s[30:31]
	v_cndmask_b32_e64 v75, v75, v123, s[34:35]
	v_cndmask_b32_e64 v60, v60, v123, s[36:37]
	v_cndmask_b32_e64 v76, v76, v123, s[38:39]
	v_cndmask_b32_e64 v61, v61, v123, s[40:41]
	v_cndmask_b32_e64 v77, v77, v123, s[42:43]
	v_cndmask_b32_e64 v62, v62, v123, s[44:45]
	v_cndmask_b32_e64 v78, v78, v123, s[46:47]
	v_cndmask_b32_e64 v63, v63, v123, s[48:49]
	v_cndmask_b32_e64 v79, v79, v123, s[50:51]
	v_cndmask_b32_e64 v64, v64, v123, s[52:53]
	v_cndmask_b32_e64 v80, v80, v123, s[54:55]
	v_cndmask_b32_e64 v65, v65, v123, s[56:57]
	v_cndmask_b32_e64 v81, v81, v123, s[58:59]
	v_cndmask_b32_e64 v66, v66, v123, s[60:61]
	v_cndmask_b32_e64 v82, v82, v123, s[62:63]
	v_cndmask_b32_e64 v67, v67, v123, s[64:65]
	v_cndmask_b32_e64 v83, v83, v123, s[66:67]

.LBB0_793:
	v_add_u32_e32 v2, s91, v129
	v_add_u32_e32 v138, v2, v130
	v_exp_f32_e32 v52, v52
	v_exp_f32_e32 v53, v53
	v_exp_f32_e32 v54, v54
	v_exp_f32_e32 v55, v55
	ds_read_b64_tr_b16 v[140:141], v138 offset:24576
	ds_read_b64_tr_b16 v[142:143], v138 offset:25600
	v_exp_f32_e32 v56, v56
	v_exp_f32_e32 v57, v57
	v_exp_f32_e32 v58, v58
	v_exp_f32_e32 v59, v59
	v_cvt_pk_bf16_f32 v144, v52, v53
	v_cvt_pk_bf16_f32 v145, v54, v55
	v_cvt_pk_bf16_f32 v146, v56, v57
	v_cvt_pk_bf16_f32 v147, v58, v59
	v_add_u32_e32 v2, v2, v131
	v_exp_f32_e32 v60, v60
	s_waitcnt lgkmcnt(0)
	v_mfma_f32_32x32x16_bf16 v[4:19], v[140:143], v[144:147], v[4:19]
	ds_read_b64_tr_b16 v[140:141], v2 offset:24576
	ds_read_b64_tr_b16 v[142:143], v2 offset:25600
	v_exp_f32_e32 v61, v61
	v_exp_f32_e32 v62, v62
	v_exp_f32_e32 v63, v63
	v_exp_f32_e32 v64, v64
	v_exp_f32_e32 v65, v65
	v_exp_f32_e32 v66, v66
	s_waitcnt lgkmcnt(0)
	v_mfma_f32_32x32x16_bf16 v[20:35], v[140:143], v[144:147], v[20:35]
	ds_read_b64_tr_b16 v[140:141], v138 offset:26624
	ds_read_b64_tr_b16 v[142:143], v138 offset:27648
	v_exp_f32_e32 v67, v67
	v_max_f32_e32 v139, v69, v69
	v_mfma_f32_32x32x16_bf16 v[36:51], v[84:87], v[144:147], v[36:51]
	v_cvt_pk_bf16_f32 v144, v60, v61
	v_cvt_pk_bf16_f32 v145, v62, v63
	v_cvt_pk_bf16_f32 v146, v64, v65
	v_cvt_pk_bf16_f32 v147, v66, v67
	s_waitcnt lgkmcnt(0)
	s_nop 0
	v_mfma_f32_32x32x16_bf16 v[4:19], v[140:143], v[144:147], v[4:19]
	ds_read_b64_tr_b16 v[140:141], v2 offset:26624
	ds_read_b64_tr_b16 v[142:143], v2 offset:27648
	s_waitcnt lgkmcnt(0)
	v_mfma_f32_32x32x16_bf16 v[20:35], v[140:143], v[144:147], v[20:35]
	v_max_f32_e32 v140, v68, v68
	v_max_f32_e32 v139, v140, v139
	v_max3_f32 v139, v139, v70, v71
	v_max3_f32 v139, v139, v72, v73
	v_max3_f32 v139, v139, v74, v75
	v_max3_f32 v139, v139, v76, v77
	v_max3_f32 v139, v139, v78, v79
	v_mfma_f32_32x32x16_bf16 v[36:51], v[84:87], v[144:147], v[36:51]
	v_max3_f32 v139, v139, v80, v81
	v_max3_f32 v139, v139, v82, v83
	v_mov_b32_e32 v140, v139
	s_nop 1
	v_permlane32_swap_b32_e32 v139, v140
	v_max_f32_e32 v140, v140, v140
	v_max_f32_e32 v139, v139, v139
	v_max_f32_e32 v139, v139, v140
	v_cmp_lt_f32_e32 vcc, s94, v139
	s_cbranch_vccz .LBB0_795
	v_max_f32_e32 v139, v139, v139
	v_max_f32_e32 v140, 0, v139
	v_exp_f32_e64 v142, -v140
	v_add_f32_e32 v137, v137, v140
	v_pk_add_f32 v[68:69], v[68:69], v[140:141] op_sel_hi:[1,0] neg_lo:[0,1] neg_hi:[0,1]
	v_pk_add_f32 v[70:71], v[70:71], v[140:141] op_sel_hi:[1,0] neg_lo:[0,1] neg_hi:[0,1]
	v_mul_f32_e32 v36, v36, v142
	v_pk_add_f32 v[72:73], v[72:73], v[140:141] op_sel_hi:[1,0] neg_lo:[0,1] neg_hi:[0,1]
	v_pk_add_f32 v[74:75], v[74:75], v[140:141] op_sel_hi:[1,0] neg_lo:[0,1] neg_hi:[0,1]
	v_pk_add_f32 v[76:77], v[76:77], v[140:141] op_sel_hi:[1,0] neg_lo:[0,1] neg_hi:[0,1]
	v_pk_add_f32 v[78:79], v[78:79], v[140:141] op_sel_hi:[1,0] neg_lo:[0,1] neg_hi:[0,1]
	v_pk_add_f32 v[80:81], v[80:81], v[140:141] op_sel_hi:[1,0] neg_lo:[0,1] neg_hi:[0,1]
	v_pk_add_f32 v[82:83], v[82:83], v[140:141] op_sel_hi:[1,0] neg_lo:[0,1] neg_hi:[0,1]
	v_pk_mul_f32 v[34:35], v[34:35], v[142:143] op_sel_hi:[1,0]
	v_pk_mul_f32 v[32:33], v[32:33], v[142:143] op_sel_hi:[1,0]
	v_pk_mul_f32 v[30:31], v[30:31], v[142:143] op_sel_hi:[1,0]
	v_pk_mul_f32 v[28:29], v[28:29], v[142:143] op_sel_hi:[1,0]
	v_pk_mul_f32 v[26:27], v[26:27], v[142:143] op_sel_hi:[1,0]
	v_pk_mul_f32 v[24:25], v[24:25], v[142:143] op_sel_hi:[1,0]
	v_pk_mul_f32 v[22:23], v[22:23], v[142:143] op_sel_hi:[1,0]
	v_pk_mul_f32 v[20:21], v[20:21], v[142:143] op_sel_hi:[1,0]
	v_pk_mul_f32 v[18:19], v[18:19], v[142:143] op_sel_hi:[1,0]
	v_pk_mul_f32 v[16:17], v[16:17], v[142:143] op_sel_hi:[1,0]
	v_pk_mul_f32 v[14:15], v[14:15], v[142:143] op_sel_hi:[1,0]
	v_pk_mul_f32 v[12:13], v[12:13], v[142:143] op_sel_hi:[1,0]
	v_pk_mul_f32 v[10:11], v[10:11], v[142:143] op_sel_hi:[1,0]
	v_pk_mul_f32 v[8:9], v[8:9], v[142:143] op_sel_hi:[1,0]
	v_pk_mul_f32 v[6:7], v[6:7], v[142:143] op_sel_hi:[1,0]
	v_pk_mul_f32 v[4:5], v[4:5], v[142:143] op_sel_hi:[1,0]
.LBB0_795:
	v_exp_f32_e32 v68, v68
	v_exp_f32_e32 v69, v69
	v_exp_f32_e32 v70, v70
	v_exp_f32_e32 v71, v71
	ds_read_b64_tr_b16 v[140:141], v138 offset:28672
	ds_read_b64_tr_b16 v[142:143], v138 offset:29696
	v_exp_f32_e32 v72, v72
	v_exp_f32_e32 v73, v73
	v_exp_f32_e32 v74, v74
	v_exp_f32_e32 v75, v75
	v_cvt_pk_bf16_f32 v144, v68, v69
	v_cvt_pk_bf16_f32 v145, v70, v71
	v_cvt_pk_bf16_f32 v146, v72, v73
	v_cvt_pk_bf16_f32 v147, v74, v75
	v_exp_f32_e32 v76, v76
	v_exp_f32_e32 v77, v77
	s_waitcnt lgkmcnt(0)
	v_mfma_f32_32x32x16_bf16 v[4:19], v[140:143], v[144:147], v[4:19]
	ds_read_b64_tr_b16 v[140:141], v2 offset:28672
	ds_read_b64_tr_b16 v[142:143], v2 offset:29696
	v_exp_f32_e32 v78, v78
	v_exp_f32_e32 v79, v79
	v_exp_f32_e32 v80, v80
	v_exp_f32_e32 v81, v81
	v_exp_f32_e32 v82, v82
	v_exp_f32_e32 v83, v83
	s_waitcnt lgkmcnt(0)
	v_mfma_f32_32x32x16_bf16 v[20:35], v[140:143], v[144:147], v[20:35]
	ds_read_b64_tr_b16 v[140:141], v138 offset:30720
	ds_read_b64_tr_b16 v[142:143], v138 offset:31744
	v_mfma_f32_32x32x16_bf16 v[36:51], v[84:87], v[144:147], v[36:51]
	v_cvt_pk_bf16_f32 v144, v76, v77
	v_cvt_pk_bf16_f32 v145, v78, v79
	v_cvt_pk_bf16_f32 v146, v80, v81
	v_cvt_pk_bf16_f32 v147, v82, v83
	s_waitcnt lgkmcnt(0)
	s_nop 0
	v_mfma_f32_32x32x16_bf16 v[4:19], v[140:143], v[144:147], v[4:19]
	ds_read_b64_tr_b16 v[138:139], v2 offset:30720
	ds_read_b64_tr_b16 v[140:141], v2 offset:31744
	s_waitcnt lgkmcnt(0)
	v_mfma_f32_32x32x16_bf16 v[20:35], v[138:141], v[144:147], v[20:35]
	v_mfma_f32_32x32x16_bf16 v[36:51], v[84:87], v[144:147], v[36:51]

.LBB0_798:
	s_nop 2
	v_mov_b32_e32 v2, v36
	s_nop 1
	v_permlane32_swap_b32_e32 v36, v2
	v_add_f32_e32 v2, v36, v2
	v_div_scale_f32 v3, s[0:1], v2, v2, 1.0
	v_rcp_f32_e32 v36, v3
	s_mulk_i32 s96, 0x1200
	s_add_i32 s2, s96, 0
	s_waitcnt vmcnt(0) lgkmcnt(0)
	s_barrier
	v_fma_f32 v37, -v3, v36, 1.0
	v_fmac_f32_e32 v36, v37, v36
	v_div_scale_f32 v37, vcc, 1.0, v2, 1.0
	v_mul_f32_e32 v38, v37, v36
	v_fma_f32 v39, -v3, v38, v37
	v_fmac_f32_e32 v38, v39, v36
	v_fma_f32 v3, -v3, v38, v37
	v_div_fmas_f32 v3, v3, v36, v38
	v_div_fixup_f32 v2, v3, v2, 1.0
	v_add3_u32 v3, s2, v136, v124
	v_pk_mul_f32 v[4:5], v[4:5], v[2:3] op_sel_hi:[1,0]
	v_pk_mul_f32 v[6:7], v[6:7], v[2:3] op_sel_hi:[1,0]
	v_cvt_pk_bf16_f32 v4, v4, v5
	v_cvt_pk_bf16_f32 v5, v6, v7
	v_pk_mul_f32 v[6:7], v[8:9], v[2:3] op_sel_hi:[1,0]
	v_pk_mul_f32 v[8:9], v[10:11], v[2:3] op_sel_hi:[1,0]
	v_cvt_pk_bf16_f32 v6, v6, v7
	v_cvt_pk_bf16_f32 v7, v8, v9
	v_add_u32_e32 v10, 0x9000, v3
	ds_write2_b64 v10, v[4:5], v[6:7] offset1:2
	v_pk_mul_f32 v[4:5], v[12:13], v[2:3] op_sel_hi:[1,0]
	v_pk_mul_f32 v[6:7], v[14:15], v[2:3] op_sel_hi:[1,0]
	v_cvt_pk_bf16_f32 v4, v4, v5
	v_cvt_pk_bf16_f32 v5, v6, v7
	v_pk_mul_f32 v[6:7], v[16:17], v[2:3] op_sel_hi:[1,0]
	v_pk_mul_f32 v[8:9], v[18:19], v[2:3] op_sel_hi:[1,0]
	v_cvt_pk_bf16_f32 v6, v6, v7
	v_cvt_pk_bf16_f32 v7, v8, v9
	ds_write2_b64 v10, v[4:5], v[6:7] offset0:4 offset1:6
	v_pk_mul_f32 v[4:5], v[20:21], v[2:3] op_sel_hi:[1,0]
	v_pk_mul_f32 v[6:7], v[22:23], v[2:3] op_sel_hi:[1,0]
	v_cvt_pk_bf16_f32 v4, v4, v5
	v_cvt_pk_bf16_f32 v5, v6, v7
	v_pk_mul_f32 v[6:7], v[24:25], v[2:3] op_sel_hi:[1,0]
	v_pk_mul_f32 v[8:9], v[26:27], v[2:3] op_sel_hi:[1,0]
	v_cvt_pk_bf16_f32 v6, v6, v7
	v_cvt_pk_bf16_f32 v7, v8, v9
	ds_write2_b64 v10, v[4:5], v[6:7] offset0:8 offset1:10
	v_pk_mul_f32 v[4:5], v[28:29], v[2:3] op_sel_hi:[1,0]
	v_pk_mul_f32 v[6:7], v[30:31], v[2:3] op_sel_hi:[1,0]
	v_cvt_pk_bf16_f32 v4, v4, v5
	v_cvt_pk_bf16_f32 v5, v6, v7
	v_pk_mul_f32 v[6:7], v[32:33], v[2:3] op_sel_hi:[1,0]
	v_pk_mul_f32 v[2:3], v[34:35], v[2:3] op_sel_hi:[1,0]
	v_cvt_pk_bf16_f32 v6, v6, v7
	v_cvt_pk_bf16_f32 v7, v2, v3
	ds_write2_b64 v10, v[4:5], v[6:7] offset0:12 offset1:14
	s_lshl_b64 s[0:1], s[78:79], 11
	v_readlane_b32 s4, v249, 53
	s_waitcnt lgkmcnt(0)
	v_readlane_b32 s5, v249, 54
	s_add_u32 s0, s4, s0
	v_lshlrev_b32_e32 v118, 1, v1
	v_add3_u32 v1, s2, v110, v111
	s_addc_u32 s1, s5, s1
	ds_read_b128 v[4:7], v1 offset:36864
	s_add_u32 s0, s0, s74
	v_mov_b32_e32 v3, 0
	ds_read_b128 v[8:11], v1 offset:38016
	s_addc_u32 s1, s1, 0
	v_mov_b32_e32 v119, v3
	v_lshl_add_u64 v[12:13], s[0:1], 0, v[118:119]
	v_lshlrev_b32_e32 v120, 1, v120
	v_mov_b32_e32 v121, v3
	v_lshl_add_u64 v[14:15], v[12:13], 0, v[120:121]
	v_mov_b32_e32 v115, v3
	s_waitcnt lgkmcnt(0)
	global_store_dwordx4 v[14:15], v[4:7], off
	v_lshl_add_u64 v[14:15], v[12:13], 0, v[114:115]
	ds_read_b128 v[4:7], v1 offset:39168
	v_readlane_b32 s0, v248, 6
	global_store_dwordx4 v[14:15], v[8:11], off
	ds_read_b128 v[8:11], v1 offset:40320
	s_xor_b32 s68, s0, 23
	v_readfirstlane_b32 s3, v222
	s_lshr_b32 s70, s3, 6
	s_lshl_b32 s2, s68, 8
	v_readlane_b32 s8, v248, 7
	v_mov_b32_e32 v113, v3
	s_lshl_b32 s76, s70, 5
	s_or_b32 s0, s8, s2
	v_lshl_add_u64 v[14:15], v[12:13], 0, v[112:113]
	v_mov_b32_e32 v117, v3
	v_readlane_b32 s9, v248, 8
	s_add_u32 s78, s0, s76
	s_waitcnt lgkmcnt(0)
	global_store_dwordx4 v[14:15], v[4:7], off
	s_addc_u32 s79, s9, 0
	s_mov_b32 s77, 0
	v_lshl_add_u64 v[4:5], v[12:13], 0, v[116:117]
	global_store_dwordx4 v[4:5], v[8:11], off
	v_mov_b32_e32 v5, s79
	v_or_b32_e32 v4, s78, v133
	v_lshlrev_b64 v[4:5], 11, v[4:5]
	s_mov_b32 s75, s77
	v_lshl_add_u64 v[4:5], s[4:5], 0, v[4:5]
	v_lshl_add_u64 v[4:5], v[4:5], 0, s[74:75]
	v_mov_b32_e32 v1, v3
	v_lshl_add_u64 v[4:5], v[4:5], 0, v[0:1]
	global_load_dwordx4 v[88:91], v[4:5], off
	global_load_dwordx4 v[92:95], v[4:5], off offset:32
	global_load_dwordx4 v[96:99], v[4:5], off offset:64
	global_load_dwordx4 v[100:103], v[4:5], off offset:96
	s_cmp_gt_u32 s3, 63
	s_mov_b32 s71, 0x9000
	s_cbranch_scc1 .LBB0_804
	v_cmp_gt_u32_e32 vcc, 32, v134
	v_mov_b32_e32 v1, 0
	s_and_saveexec_b64 s[0:1], vcc
	s_cbranch_execz .LBB0_801
	v_lshlrev_b32_e32 v1, 4, v133
	v_readlane_b32 s4, v249, 62
	v_readlane_b32 s5, v249, 63
	s_nop 0
	v_lshl_or_b32 v1, s4, 9, v1
	v_readlane_b32 s4, v249, 60
	s_nop 1
	v_or_b32_e32 v4, s4, v1
	v_readlane_b32 s4, v249, 51
	v_ashrrev_i32_e32 v5, 31, v4
	v_readlane_b32 s5, v249, 52
	s_nop 1
	v_lshl_add_u64 v[4:5], v[4:5], 2, s[4:5]
	global_load_dword v1, v[4:5], off

.LBB0_806:
	s_add_i32 s95, s0, 0
	s_lshl_b32 s0, s1, 1
	s_and_b32 s0, s0, -4
	s_add_i32 s68, s0, 0
	s_add_i32 s68, s68, 0x1b000
	s_cmp_le_u32 s77, s73
	v_lshl_add_u32 v141, v132, 2, s95
	s_cselect_b64 s[0:1], -1, 0
	s_cmp_gt_u32 s77, s73
	v_add_u32_e32 v140, s95, v125
	v_add_u32_e32 v139, s95, v126
	v_add_u32_e32 v138, s95, v127
	v_add_u32_e32 v2, s95, v128
	s_cbranch_scc1 .LBB0_809
	v_mov_b32_e32 v52, s68
	ds_read_b32 v60, v52
	v_sub_f32_e32 v61, v1, v137
	ds_read_b128 v[76:79], v141 offset:32832
	ds_read_b128 v[52:55], v141 offset:32768
	ds_read_b128 v[56:59], v141 offset:32800
	s_waitcnt lgkmcnt(0)
	v_sub_f32_e32 v158, v61, v60
	ds_read_b128 v[60:63], v141 offset:32864
	ds_read_b128 v[146:149], v139
	v_sub_f32_e32 v55, v158, v55
	v_sub_f32_e32 v59, v158, v59
	v_sub_f32_e32 v58, v158, v58
	s_waitcnt lgkmcnt(0)
	v_sub_f32_e32 v67, v158, v63
	v_sub_f32_e32 v66, v158, v62
	v_sub_f32_e32 v65, v158, v61
	v_sub_f32_e32 v64, v158, v60
	v_sub_f32_e32 v63, v158, v79
	v_sub_f32_e32 v62, v158, v78
	v_sub_f32_e32 v61, v158, v77
	v_sub_f32_e32 v60, v158, v76
	ds_read_b128 v[76:79], v140
	v_sub_f32_e32 v57, v158, v57
	v_sub_f32_e32 v56, v158, v56
	v_sub_f32_e32 v54, v158, v54
	v_sub_f32_e32 v53, v158, v53
	v_sub_f32_e32 v52, v158, v52
	ds_read_b128 v[68:71], v141 offset:32896
	ds_read_b128 v[72:75], v141 offset:32928
	ds_read_b128 v[142:145], v141 offset:32960
	ds_read_b128 v[80:83], v141 offset:32992
	ds_read_b128 v[150:153], v138
	s_waitcnt lgkmcnt(0)
	v_mfma_f32_32x32x16_bf16 v[52:67], v[76:79], v[88:91], v[52:67]
	ds_read_b128 v[154:157], v2
	v_sub_f32_e32 v79, v158, v145
	v_sub_f32_e32 v78, v158, v144
	v_sub_f32_e32 v77, v158, v143
	v_sub_f32_e32 v76, v158, v142
	v_sub_f32_e32 v83, v158, v83
	v_sub_f32_e32 v82, v158, v82
	v_mfma_f32_32x32x16_bf16 v[52:67], v[146:149], v[92:95], v[52:67]
	ds_read_b128 v[142:145], v140 offset:4096
	v_sub_f32_e32 v81, v158, v81
	v_sub_f32_e32 v80, v158, v80
	v_sub_f32_e32 v75, v158, v75
	v_sub_f32_e32 v74, v158, v74
	v_sub_f32_e32 v73, v158, v73
	v_sub_f32_e32 v72, v158, v72
	v_mfma_f32_32x32x16_bf16 v[52:67], v[150:153], v[96:99], v[52:67]
	v_sub_f32_e32 v71, v158, v71
	v_sub_f32_e32 v70, v158, v70
	v_sub_f32_e32 v69, v158, v69
	v_sub_f32_e32 v68, v158, v68
	ds_read_b128 v[146:149], v139 offset:4096
	s_cmp_lg_u32 s73, s77
	s_waitcnt lgkmcnt(0)
	v_mfma_f32_32x32x16_bf16 v[68:83], v[142:145], v[88:91], v[68:83]
	ds_read_b128 v[142:145], v138 offset:4096
	v_mfma_f32_32x32x16_bf16 v[68:83], v[146:149], v[92:95], v[68:83]
	s_waitcnt lgkmcnt(0)
	v_mfma_f32_32x32x16_bf16 v[68:83], v[142:145], v[96:99], v[68:83]
	ds_read_b128 v[142:145], v2 offset:4096
	s_waitcnt lgkmcnt(0)
	v_mfma_f32_32x32x16_bf16 v[68:83], v[142:145], v[100:103], v[68:83]
	v_mfma_f32_32x32x16_bf16 v[52:67], v[154:157], v[100:103], v[52:67]
	s_cbranch_scc1 .LBB0_809
	s_nop 10
	v_cndmask_b32_e64 v142, v52, v121, s[2:3]
	v_cndmask_b32_e64 v68, v68, v121, s[4:5]
	v_cndmask_b32_e64 v52, v142, v52, s[6:7]
	v_cndmask_b32_e64 v53, v121, v53, s[6:7]
	v_cndmask_b32_e64 v69, v69, v121, s[8:9]
	v_cndmask_b32_e64 v54, v54, v121, s[10:11]
	v_cndmask_b32_e64 v70, v70, v121, s[12:13]
	v_cndmask_b32_e64 v55, v55, v121, s[14:15]
	v_cndmask_b32_e64 v71, v71, v121, s[16:17]
	v_cndmask_b32_e64 v56, v56, v121, s[18:19]
	v_cndmask_b32_e64 v72, v72, v121, s[20:21]
	v_cndmask_b32_e64 v57, v57, v121, s[22:23]
	v_cndmask_b32_e64 v73, v73, v121, s[24:25]
	v_cndmask_b32_e64 v58, v58, v121, s[26:27]
	v_cndmask_b32_e64 v74, v74, v121, s[28:29]
	v_cndmask_b32_e64 v59, v59, v121, s[30:31]
	v_cndmask_b32_e64 v75, v75, v121, s[34:35]
	v_cndmask_b32_e64 v60, v60, v121, s[36:37]
	v_cndmask_b32_e64 v76, v76, v121, s[38:39]
	v_cndmask_b32_e64 v61, v61, v121, s[40:41]
	v_cndmask_b32_e64 v77, v77, v121, s[42:43]
	v_cndmask_b32_e64 v62, v62, v121, s[44:45]
	v_cndmask_b32_e64 v78, v78, v121, s[46:47]
	v_cndmask_b32_e64 v63, v63, v121, s[48:49]
	v_cndmask_b32_e64 v79, v79, v121, s[50:51]
	v_cndmask_b32_e64 v64, v64, v121, s[52:53]
	v_cndmask_b32_e64 v80, v80, v121, s[54:55]
	v_cndmask_b32_e64 v65, v65, v121, s[56:57]
	v_cndmask_b32_e64 v81, v81, v121, s[58:59]
	v_cndmask_b32_e64 v66, v66, v121, s[60:61]
	v_cndmask_b32_e64 v82, v82, v121, s[62:63]
	v_cndmask_b32_e64 v67, v67, v121, s[64:65]
	v_cndmask_b32_e64 v83, v83, v121, s[66:67]

.LBB0_812:
	v_add_u32_e32 v142, s95, v129
	v_add_u32_e32 v143, v142, v130
	v_exp_f32_e32 v52, v52
	v_exp_f32_e32 v53, v53
	v_exp_f32_e32 v54, v54
	v_exp_f32_e32 v55, v55
	ds_read_b64_tr_b16 v[144:145], v143 offset:16384
	ds_read_b64_tr_b16 v[146:147], v143 offset:17408
	v_exp_f32_e32 v56, v56
	v_exp_f32_e32 v57, v57
	v_exp_f32_e32 v58, v58
	v_exp_f32_e32 v59, v59
	v_cvt_pk_bf16_f32 v148, v52, v53
	v_cvt_pk_bf16_f32 v149, v54, v55
	v_cvt_pk_bf16_f32 v150, v56, v57
	v_cvt_pk_bf16_f32 v151, v58, v59
	v_add_u32_e32 v142, v142, v131
	v_exp_f32_e32 v60, v60
	s_waitcnt lgkmcnt(0)
	v_mfma_f32_32x32x16_bf16 v[4:19], v[144:147], v[148:151], v[4:19]
	ds_read_b64_tr_b16 v[144:145], v142 offset:16384
	ds_read_b64_tr_b16 v[146:147], v142 offset:17408
	v_exp_f32_e32 v61, v61
	v_exp_f32_e32 v62, v62
	v_exp_f32_e32 v63, v63
	v_exp_f32_e32 v64, v64
	v_exp_f32_e32 v65, v65
	v_exp_f32_e32 v66, v66
	s_waitcnt lgkmcnt(0)
	v_mfma_f32_32x32x16_bf16 v[20:35], v[144:147], v[148:151], v[20:35]
	ds_read_b64_tr_b16 v[144:145], v143 offset:18432
	ds_read_b64_tr_b16 v[146:147], v143 offset:19456
	v_exp_f32_e32 v67, v67
	v_mfma_f32_32x32x16_bf16 v[36:51], v[84:87], v[148:151], v[36:51]
	v_cvt_pk_bf16_f32 v148, v60, v61
	v_cvt_pk_bf16_f32 v149, v62, v63
	v_cvt_pk_bf16_f32 v150, v64, v65
	v_cvt_pk_bf16_f32 v151, v66, v67
	s_waitcnt lgkmcnt(0)
	s_nop 0
	v_mfma_f32_32x32x16_bf16 v[4:19], v[144:147], v[148:151], v[4:19]
	ds_read_b64_tr_b16 v[144:145], v142 offset:18432
	ds_read_b64_tr_b16 v[146:147], v142 offset:19456
	s_waitcnt lgkmcnt(0)
	v_mfma_f32_32x32x16_bf16 v[20:35], v[144:147], v[148:151], v[20:35]
	v_max_f32_e32 v144, v69, v69
	v_max_f32_e32 v145, v68, v68
	v_max_f32_e32 v144, v145, v144
	v_max3_f32 v144, v144, v70, v71
	v_max3_f32 v144, v144, v72, v73
	v_max3_f32 v144, v144, v74, v75
	v_max3_f32 v144, v144, v76, v77
	v_max3_f32 v144, v144, v78, v79
	v_mfma_f32_32x32x16_bf16 v[36:51], v[84:87], v[148:151], v[36:51]
	v_max3_f32 v144, v144, v80, v81
	v_max3_f32 v144, v144, v82, v83
	v_mov_b32_e32 v145, v144
	s_nop 1
	v_permlane32_swap_b32_e32 v144, v145
	v_max_f32_e32 v145, v145, v145
	v_max_f32_e32 v144, v144, v144
	v_max_f32_e32 v144, v144, v145
	v_cmp_lt_f32_e32 vcc, s94, v144
	s_cbranch_vccz .LBB0_814
	v_max_f32_e32 v144, v144, v144
	v_max_f32_e32 v144, 0, v144
	v_exp_f32_e64 v146, -v144
	v_add_f32_e32 v137, v137, v144
	v_pk_add_f32 v[68:69], v[68:69], v[144:145] op_sel_hi:[1,0] neg_lo:[0,1] neg_hi:[0,1]
	v_pk_add_f32 v[70:71], v[70:71], v[144:145] op_sel_hi:[1,0] neg_lo:[0,1] neg_hi:[0,1]
	v_mul_f32_e32 v36, v36, v146
	v_pk_add_f32 v[72:73], v[72:73], v[144:145] op_sel_hi:[1,0] neg_lo:[0,1] neg_hi:[0,1]
	v_pk_add_f32 v[74:75], v[74:75], v[144:145] op_sel_hi:[1,0] neg_lo:[0,1] neg_hi:[0,1]
	v_pk_add_f32 v[76:77], v[76:77], v[144:145] op_sel_hi:[1,0] neg_lo:[0,1] neg_hi:[0,1]
	v_pk_add_f32 v[78:79], v[78:79], v[144:145] op_sel_hi:[1,0] neg_lo:[0,1] neg_hi:[0,1]
	v_pk_add_f32 v[80:81], v[80:81], v[144:145] op_sel_hi:[1,0] neg_lo:[0,1] neg_hi:[0,1]
	v_pk_add_f32 v[82:83], v[82:83], v[144:145] op_sel_hi:[1,0] neg_lo:[0,1] neg_hi:[0,1]
	v_pk_mul_f32 v[34:35], v[34:35], v[146:147] op_sel_hi:[1,0]
	v_pk_mul_f32 v[32:33], v[32:33], v[146:147] op_sel_hi:[1,0]
	v_pk_mul_f32 v[30:31], v[30:31], v[146:147] op_sel_hi:[1,0]
	v_pk_mul_f32 v[28:29], v[28:29], v[146:147] op_sel_hi:[1,0]
	v_pk_mul_f32 v[26:27], v[26:27], v[146:147] op_sel_hi:[1,0]
	v_pk_mul_f32 v[24:25], v[24:25], v[146:147] op_sel_hi:[1,0]
	v_pk_mul_f32 v[22:23], v[22:23], v[146:147] op_sel_hi:[1,0]
	v_pk_mul_f32 v[20:21], v[20:21], v[146:147] op_sel_hi:[1,0]
	v_pk_mul_f32 v[18:19], v[18:19], v[146:147] op_sel_hi:[1,0]
	v_pk_mul_f32 v[16:17], v[16:17], v[146:147] op_sel_hi:[1,0]
	v_pk_mul_f32 v[14:15], v[14:15], v[146:147] op_sel_hi:[1,0]
	v_pk_mul_f32 v[12:13], v[12:13], v[146:147] op_sel_hi:[1,0]
	v_pk_mul_f32 v[10:11], v[10:11], v[146:147] op_sel_hi:[1,0]
	v_pk_mul_f32 v[8:9], v[8:9], v[146:147] op_sel_hi:[1,0]
	v_pk_mul_f32 v[6:7], v[6:7], v[146:147] op_sel_hi:[1,0]
	v_pk_mul_f32 v[4:5], v[4:5], v[146:147] op_sel_hi:[1,0]

.LBB0_815:
	s_cmp_lt_u32 s77, s73
	s_cselect_b64 s[0:1], -1, 0
	s_cmp_ge_u32 s77, s73
	s_cbranch_scc1 .LBB0_818
	s_nop 4
	v_mov_b32_e32 v52, s68
	ds_read_b32 v60, v52
	v_sub_f32_e32 v61, v1, v137
	ds_read_b128 v[76:79], v141 offset:33088
	ds_read_b128 v[52:55], v141 offset:33024
	ds_read_b128 v[56:59], v141 offset:33056
	s_waitcnt lgkmcnt(0)
	v_sub_f32_e32 v158, v61, v60
	ds_read_b128 v[60:63], v141 offset:33120
	ds_read_b128 v[146:149], v139 offset:8192
	v_sub_f32_e32 v55, v158, v55
	v_sub_f32_e32 v59, v158, v59
	v_sub_f32_e32 v58, v158, v58
	s_waitcnt lgkmcnt(0)
	v_sub_f32_e32 v67, v158, v63
	v_sub_f32_e32 v66, v158, v62
	v_sub_f32_e32 v65, v158, v61
	v_sub_f32_e32 v64, v158, v60
	v_sub_f32_e32 v63, v158, v79
	v_sub_f32_e32 v62, v158, v78
	v_sub_f32_e32 v61, v158, v77
	v_sub_f32_e32 v60, v158, v76
	ds_read_b128 v[76:79], v140 offset:8192
	v_sub_f32_e32 v57, v158, v57
	v_sub_f32_e32 v56, v158, v56
	v_sub_f32_e32 v54, v158, v54
	v_sub_f32_e32 v53, v158, v53
	v_sub_f32_e32 v52, v158, v52
	ds_read_b128 v[68:71], v141 offset:33152
	ds_read_b128 v[72:75], v141 offset:33184
	ds_read_b128 v[142:145], v141 offset:33216
	ds_read_b128 v[80:83], v141 offset:33248
	ds_read_b128 v[150:153], v138 offset:8192
	s_waitcnt lgkmcnt(0)
	v_mfma_f32_32x32x16_bf16 v[52:67], v[76:79], v[88:91], v[52:67]
	ds_read_b128 v[154:157], v2 offset:8192
	v_sub_f32_e32 v77, v158, v143
	v_sub_f32_e32 v76, v158, v142
	v_sub_f32_e32 v83, v158, v83
	v_sub_f32_e32 v82, v158, v82
	v_sub_f32_e32 v81, v158, v81
	v_sub_f32_e32 v80, v158, v80
	v_mfma_f32_32x32x16_bf16 v[52:67], v[146:149], v[92:95], v[52:67]
	ds_read_b128 v[140:143], v140 offset:12288
	v_sub_f32_e32 v79, v158, v145
	v_sub_f32_e32 v78, v158, v144
	v_sub_f32_e32 v75, v158, v75
	v_sub_f32_e32 v74, v158, v74
	v_sub_f32_e32 v73, v158, v73
	v_sub_f32_e32 v72, v158, v72
	v_mfma_f32_32x32x16_bf16 v[52:67], v[150:153], v[96:99], v[52:67]
	v_sub_f32_e32 v71, v158, v71
	v_sub_f32_e32 v70, v158, v70
	v_sub_f32_e32 v69, v158, v69
	v_sub_f32_e32 v68, v158, v68
	ds_read_b128 v[144:147], v139 offset:12288
	s_cmp_lg_u32 s92, s77
	s_waitcnt lgkmcnt(0)
	v_mfma_f32_32x32x16_bf16 v[68:83], v[140:143], v[88:91], v[68:83]
	ds_read_b128 v[138:141], v138 offset:12288
	v_mfma_f32_32x32x16_bf16 v[68:83], v[144:147], v[92:95], v[68:83]
	s_waitcnt lgkmcnt(0)
	v_mfma_f32_32x32x16_bf16 v[68:83], v[138:141], v[96:99], v[68:83]
	ds_read_b128 v[138:141], v2 offset:12288
	s_waitcnt lgkmcnt(0)
	v_mfma_f32_32x32x16_bf16 v[68:83], v[138:141], v[100:103], v[68:83]
	v_mfma_f32_32x32x16_bf16 v[52:67], v[154:157], v[100:103], v[52:67]
	s_cbranch_scc1 .LBB0_818
	s_nop 10
	v_cndmask_b32_e64 v2, v52, v121, s[2:3]
	v_cndmask_b32_e64 v68, v68, v121, s[4:5]
	v_cndmask_b32_e64 v52, v2, v52, s[6:7]
	v_cndmask_b32_e64 v53, v121, v53, s[6:7]
	v_cndmask_b32_e64 v69, v69, v121, s[8:9]
	v_cndmask_b32_e64 v54, v54, v121, s[10:11]
	v_cndmask_b32_e64 v70, v70, v121, s[12:13]
	v_cndmask_b32_e64 v55, v55, v121, s[14:15]
	v_cndmask_b32_e64 v71, v71, v121, s[16:17]
	v_cndmask_b32_e64 v56, v56, v121, s[18:19]
	v_cndmask_b32_e64 v72, v72, v121, s[20:21]
	v_cndmask_b32_e64 v57, v57, v121, s[22:23]
	v_cndmask_b32_e64 v73, v73, v121, s[24:25]
	v_cndmask_b32_e64 v58, v58, v121, s[26:27]
	v_cndmask_b32_e64 v74, v74, v121, s[28:29]
	v_cndmask_b32_e64 v59, v59, v121, s[30:31]
	v_cndmask_b32_e64 v75, v75, v121, s[34:35]
	v_cndmask_b32_e64 v60, v60, v121, s[36:37]
	v_cndmask_b32_e64 v76, v76, v121, s[38:39]
	v_cndmask_b32_e64 v61, v61, v121, s[40:41]
	v_cndmask_b32_e64 v77, v77, v121, s[42:43]
	v_cndmask_b32_e64 v62, v62, v121, s[44:45]
	v_cndmask_b32_e64 v78, v78, v121, s[46:47]
	v_cndmask_b32_e64 v63, v63, v121, s[48:49]
	v_cndmask_b32_e64 v79, v79, v121, s[50:51]
	v_cndmask_b32_e64 v64, v64, v121, s[52:53]
	v_cndmask_b32_e64 v80, v80, v121, s[54:55]
	v_cndmask_b32_e64 v65, v65, v121, s[56:57]
	v_cndmask_b32_e64 v81, v81, v121, s[58:59]
	v_cndmask_b32_e64 v66, v66, v121, s[60:61]
	v_cndmask_b32_e64 v82, v82, v121, s[62:63]
	v_cndmask_b32_e64 v67, v67, v121, s[64:65]
	v_cndmask_b32_e64 v83, v83, v121, s[66:67]

.LBB0_821:
	v_add_u32_e32 v2, s95, v129
	v_add_u32_e32 v138, v2, v130
	v_exp_f32_e32 v52, v52
	v_exp_f32_e32 v53, v53
	v_exp_f32_e32 v54, v54
	v_exp_f32_e32 v55, v55
	ds_read_b64_tr_b16 v[140:141], v138 offset:24576
	ds_read_b64_tr_b16 v[142:143], v138 offset:25600
	v_exp_f32_e32 v56, v56
	v_exp_f32_e32 v57, v57
	v_exp_f32_e32 v58, v58
	v_exp_f32_e32 v59, v59
	v_cvt_pk_bf16_f32 v144, v52, v53
	v_cvt_pk_bf16_f32 v145, v54, v55
	v_cvt_pk_bf16_f32 v146, v56, v57
	v_cvt_pk_bf16_f32 v147, v58, v59
	v_add_u32_e32 v2, v2, v131
	v_exp_f32_e32 v60, v60
	s_waitcnt lgkmcnt(0)
	v_mfma_f32_32x32x16_bf16 v[4:19], v[140:143], v[144:147], v[4:19]
	ds_read_b64_tr_b16 v[140:141], v2 offset:24576
	ds_read_b64_tr_b16 v[142:143], v2 offset:25600
	v_exp_f32_e32 v61, v61
	v_exp_f32_e32 v62, v62
	v_exp_f32_e32 v63, v63
	v_exp_f32_e32 v64, v64
	v_exp_f32_e32 v65, v65
	v_exp_f32_e32 v66, v66
	s_waitcnt lgkmcnt(0)
	v_mfma_f32_32x32x16_bf16 v[20:35], v[140:143], v[144:147], v[20:35]
	ds_read_b64_tr_b16 v[140:141], v138 offset:26624
	ds_read_b64_tr_b16 v[142:143], v138 offset:27648
	v_exp_f32_e32 v67, v67
	v_max_f32_e32 v139, v69, v69
	v_mfma_f32_32x32x16_bf16 v[36:51], v[84:87], v[144:147], v[36:51]
	v_cvt_pk_bf16_f32 v144, v60, v61
	v_cvt_pk_bf16_f32 v145, v62, v63
	v_cvt_pk_bf16_f32 v146, v64, v65
	v_cvt_pk_bf16_f32 v147, v66, v67
	s_waitcnt lgkmcnt(0)
	s_nop 0
	v_mfma_f32_32x32x16_bf16 v[4:19], v[140:143], v[144:147], v[4:19]
	ds_read_b64_tr_b16 v[140:141], v2 offset:26624
	ds_read_b64_tr_b16 v[142:143], v2 offset:27648
	s_waitcnt lgkmcnt(0)
	v_mfma_f32_32x32x16_bf16 v[20:35], v[140:143], v[144:147], v[20:35]
	v_max_f32_e32 v140, v68, v68
	v_max_f32_e32 v139, v140, v139
	v_max3_f32 v139, v139, v70, v71
	v_max3_f32 v139, v139, v72, v73
	v_max3_f32 v139, v139, v74, v75
	v_max3_f32 v139, v139, v76, v77
	v_max3_f32 v139, v139, v78, v79
	v_mfma_f32_32x32x16_bf16 v[36:51], v[84:87], v[144:147], v[36:51]
	v_max3_f32 v139, v139, v80, v81
	v_max3_f32 v139, v139, v82, v83
	v_mov_b32_e32 v140, v139
	s_nop 1
	v_permlane32_swap_b32_e32 v139, v140
	v_max_f32_e32 v140, v140, v140
	v_max_f32_e32 v139, v139, v139
	v_max_f32_e32 v139, v139, v140
	v_cmp_lt_f32_e32 vcc, s94, v139
	s_cbranch_vccz .LBB0_823
	v_max_f32_e32 v139, v139, v139
	v_max_f32_e32 v140, 0, v139
	v_exp_f32_e64 v142, -v140
	v_add_f32_e32 v137, v137, v140
	v_pk_add_f32 v[68:69], v[68:69], v[140:141] op_sel_hi:[1,0] neg_lo:[0,1] neg_hi:[0,1]
	v_pk_add_f32 v[70:71], v[70:71], v[140:141] op_sel_hi:[1,0] neg_lo:[0,1] neg_hi:[0,1]
	v_mul_f32_e32 v36, v36, v142
	v_pk_add_f32 v[72:73], v[72:73], v[140:141] op_sel_hi:[1,0] neg_lo:[0,1] neg_hi:[0,1]
	v_pk_add_f32 v[74:75], v[74:75], v[140:141] op_sel_hi:[1,0] neg_lo:[0,1] neg_hi:[0,1]
	v_pk_add_f32 v[76:77], v[76:77], v[140:141] op_sel_hi:[1,0] neg_lo:[0,1] neg_hi:[0,1]
	v_pk_add_f32 v[78:79], v[78:79], v[140:141] op_sel_hi:[1,0] neg_lo:[0,1] neg_hi:[0,1]
	v_pk_add_f32 v[80:81], v[80:81], v[140:141] op_sel_hi:[1,0] neg_lo:[0,1] neg_hi:[0,1]
	v_pk_add_f32 v[82:83], v[82:83], v[140:141] op_sel_hi:[1,0] neg_lo:[0,1] neg_hi:[0,1]
	v_pk_mul_f32 v[34:35], v[34:35], v[142:143] op_sel_hi:[1,0]
	v_pk_mul_f32 v[32:33], v[32:33], v[142:143] op_sel_hi:[1,0]
	v_pk_mul_f32 v[30:31], v[30:31], v[142:143] op_sel_hi:[1,0]
	v_pk_mul_f32 v[28:29], v[28:29], v[142:143] op_sel_hi:[1,0]
	v_pk_mul_f32 v[26:27], v[26:27], v[142:143] op_sel_hi:[1,0]
	v_pk_mul_f32 v[24:25], v[24:25], v[142:143] op_sel_hi:[1,0]
	v_pk_mul_f32 v[22:23], v[22:23], v[142:143] op_sel_hi:[1,0]
	v_pk_mul_f32 v[20:21], v[20:21], v[142:143] op_sel_hi:[1,0]
	v_pk_mul_f32 v[18:19], v[18:19], v[142:143] op_sel_hi:[1,0]
	v_pk_mul_f32 v[16:17], v[16:17], v[142:143] op_sel_hi:[1,0]
	v_pk_mul_f32 v[14:15], v[14:15], v[142:143] op_sel_hi:[1,0]
	v_pk_mul_f32 v[12:13], v[12:13], v[142:143] op_sel_hi:[1,0]
	v_pk_mul_f32 v[10:11], v[10:11], v[142:143] op_sel_hi:[1,0]
	v_pk_mul_f32 v[8:9], v[8:9], v[142:143] op_sel_hi:[1,0]
	v_pk_mul_f32 v[6:7], v[6:7], v[142:143] op_sel_hi:[1,0]
	v_pk_mul_f32 v[4:5], v[4:5], v[142:143] op_sel_hi:[1,0]

.LBB0_826:
	s_nop 2
	v_mov_b32_e32 v1, v36
	s_nop 1
	v_permlane32_swap_b32_e32 v36, v1
	v_add_f32_e32 v1, v36, v1
	v_div_scale_f32 v2, s[0:1], v1, v1, 1.0
	v_rcp_f32_e32 v3, v2
	s_mulk_i32 s70, 0x1200
	s_add_i32 s2, s70, 0
	s_waitcnt vmcnt(0) lgkmcnt(0)
	s_barrier
	v_fma_f32 v36, -v2, v3, 1.0
	v_fmac_f32_e32 v3, v36, v3
	v_div_scale_f32 v36, vcc, 1.0, v1, 1.0
	v_mul_f32_e32 v37, v36, v3
	v_fma_f32 v38, -v2, v37, v36
	v_fmac_f32_e32 v37, v38, v3
	v_fma_f32 v2, -v2, v37, v36
	v_div_fmas_f32 v2, v2, v3, v37
	v_div_fixup_f32 v2, v2, v1, 1.0
	v_pk_mul_f32 v[4:5], v[4:5], v[2:3] op_sel_hi:[1,0]
	v_pk_mul_f32 v[6:7], v[6:7], v[2:3] op_sel_hi:[1,0]
	v_add3_u32 v1, s2, v136, v124
	v_cvt_pk_bf16_f32 v4, v4, v5
	v_cvt_pk_bf16_f32 v5, v6, v7
	v_pk_mul_f32 v[6:7], v[8:9], v[2:3] op_sel_hi:[1,0]
	v_pk_mul_f32 v[8:9], v[10:11], v[2:3] op_sel_hi:[1,0]
	v_cvt_pk_bf16_f32 v6, v6, v7
	v_cvt_pk_bf16_f32 v7, v8, v9
	v_add_u32_e32 v1, 0x9000, v1
	ds_write2_b64 v1, v[4:5], v[6:7] offset1:2
	v_pk_mul_f32 v[4:5], v[12:13], v[2:3] op_sel_hi:[1,0]
	v_pk_mul_f32 v[6:7], v[14:15], v[2:3] op_sel_hi:[1,0]
	v_cvt_pk_bf16_f32 v4, v4, v5
	v_cvt_pk_bf16_f32 v5, v6, v7
	v_pk_mul_f32 v[6:7], v[16:17], v[2:3] op_sel_hi:[1,0]
	v_pk_mul_f32 v[8:9], v[18:19], v[2:3] op_sel_hi:[1,0]
	v_cvt_pk_bf16_f32 v6, v6, v7
	v_cvt_pk_bf16_f32 v7, v8, v9
	ds_write2_b64 v1, v[4:5], v[6:7] offset0:4 offset1:6
	v_pk_mul_f32 v[4:5], v[20:21], v[2:3] op_sel_hi:[1,0]
	v_pk_mul_f32 v[6:7], v[22:23], v[2:3] op_sel_hi:[1,0]
	v_cvt_pk_bf16_f32 v4, v4, v5
	v_cvt_pk_bf16_f32 v5, v6, v7
	v_pk_mul_f32 v[6:7], v[24:25], v[2:3] op_sel_hi:[1,0]
	v_pk_mul_f32 v[8:9], v[26:27], v[2:3] op_sel_hi:[1,0]
	v_cvt_pk_bf16_f32 v6, v6, v7
	v_cvt_pk_bf16_f32 v7, v8, v9
	ds_write2_b64 v1, v[4:5], v[6:7] offset0:8 offset1:10
	v_pk_mul_f32 v[4:5], v[28:29], v[2:3] op_sel_hi:[1,0]
	v_pk_mul_f32 v[6:7], v[30:31], v[2:3] op_sel_hi:[1,0]
	v_cvt_pk_bf16_f32 v4, v4, v5
	v_cvt_pk_bf16_f32 v5, v6, v7
	v_pk_mul_f32 v[6:7], v[32:33], v[2:3] op_sel_hi:[1,0]
	v_pk_mul_f32 v[2:3], v[34:35], v[2:3] op_sel_hi:[1,0]
	v_cvt_pk_bf16_f32 v6, v6, v7
	v_cvt_pk_bf16_f32 v7, v2, v3
	ds_write2_b64 v1, v[4:5], v[6:7] offset0:12 offset1:14
	s_lshl_b64 s[0:1], s[78:79], 11
	v_readlane_b32 s6, v249, 53
	s_waitcnt lgkmcnt(0)
	v_readlane_b32 s7, v249, 54
	s_add_u32 s0, s6, s0
	v_add3_u32 v1, s2, v110, v111
	s_addc_u32 s1, s7, s1
	ds_read_b128 v[4:7], v1 offset:36864
	s_add_u32 s0, s0, s74
	v_mov_b32_e32 v3, 0
	ds_read_b128 v[8:11], v1 offset:38016
	s_addc_u32 s1, s1, 0
	v_mov_b32_e32 v119, v3
	v_lshl_add_u64 v[12:13], s[0:1], 0, v[118:119]
	v_mov_b32_e32 v121, v3
	v_lshl_add_u64 v[14:15], v[12:13], 0, v[120:121]
	v_mov_b32_e32 v115, v3
	s_waitcnt lgkmcnt(0)
	global_store_dwordx4 v[14:15], v[4:7], off
	v_lshl_add_u64 v[14:15], v[12:13], 0, v[114:115]
	ds_read_b128 v[4:7], v1 offset:39168
	v_readlane_b32 s0, v248, 6
	global_store_dwordx4 v[14:15], v[8:11], off
	ds_read_b128 v[8:11], v1 offset:40320
	s_or_b32 s2, s0, 16
	v_readfirstlane_b32 s4, v222
	s_lshr_b32 s70, s4, 6
	s_lshl_b32 s3, s2, 8
	v_readlane_b32 s8, v248, 7
	v_mov_b32_e32 v113, v3
	s_lshl_b32 s76, s70, 5
	s_or_b32 s0, s8, s3
	v_lshl_add_u64 v[14:15], v[12:13], 0, v[112:113]
	v_mov_b32_e32 v117, v3
	v_readlane_b32 s9, v248, 8
	s_add_u32 s78, s0, s76
	s_waitcnt lgkmcnt(0)
	global_store_dwordx4 v[14:15], v[4:7], off
	s_addc_u32 s79, s9, 0
	s_mov_b32 s77, 0
	v_lshl_add_u64 v[4:5], v[12:13], 0, v[116:117]
	global_store_dwordx4 v[4:5], v[8:11], off
	v_mov_b32_e32 v5, s79
	v_or_b32_e32 v4, s78, v133
	v_lshlrev_b64 v[4:5], 11, v[4:5]
	s_mov_b32 s75, s77
	v_lshl_add_u64 v[4:5], s[6:7], 0, v[4:5]
	v_lshl_add_u64 v[4:5], v[4:5], 0, s[74:75]
	v_mov_b32_e32 v1, v3
	v_lshl_add_u64 v[4:5], v[4:5], 0, v[0:1]
	global_load_dwordx4 v[88:91], v[4:5], off
	global_load_dwordx4 v[92:95], v[4:5], off offset:32
	global_load_dwordx4 v[96:99], v[4:5], off offset:64
	global_load_dwordx4 v[100:103], v[4:5], off offset:96
	s_cmp_gt_u32 s4, 63
	s_mov_b32 s71, 0x9000
	s_cbranch_scc1 .LBB0_832
	v_cmp_gt_u32_e32 vcc, 32, v134
	v_mov_b32_e32 v1, 0
	s_and_saveexec_b64 s[0:1], vcc
	s_cbranch_execz .LBB0_829
	v_lshlrev_b32_e32 v1, 4, v133
	v_readlane_b32 s6, v249, 62
	v_readlane_b32 s7, v249, 63
	v_readlane_b32 s5, v249, 60
	v_lshl_or_b32 v1, s6, 9, v1
	v_readlane_b32 s6, v249, 51
	v_or_b32_e32 v4, s5, v1
	v_ashrrev_i32_e32 v5, 31, v4
	v_readlane_b32 s7, v249, 52
	s_nop 1
	v_lshl_add_u64 v[4:5], v[4:5], 2, s[6:7]
	global_load_dword v1, v[4:5], off

.LBB0_834:
	s_add_i32 s91, s0, 0
	s_lshl_b32 s0, s1, 1
	s_and_b32 s0, s0, -4
	s_add_i32 s68, s0, 0
	s_add_i32 s68, s68, 0x1b000
	s_cmp_le_u32 s77, s73
	v_lshl_add_u32 v141, v132, 2, s91
	s_cselect_b64 s[0:1], -1, 0
	s_cmp_gt_u32 s77, s73
	v_add_u32_e32 v140, s91, v125
	v_add_u32_e32 v139, s91, v126
	v_add_u32_e32 v138, s91, v127
	v_add_u32_e32 v2, s91, v128
	s_cbranch_scc1 .LBB0_837
	v_mov_b32_e32 v52, s68
	ds_read_b32 v60, v52
	v_sub_f32_e32 v61, v1, v137
	ds_read_b128 v[76:79], v141 offset:32832
	ds_read_b128 v[52:55], v141 offset:32768
	ds_read_b128 v[56:59], v141 offset:32800
	s_waitcnt lgkmcnt(0)
	v_sub_f32_e32 v158, v61, v60
	ds_read_b128 v[60:63], v141 offset:32864
	ds_read_b128 v[146:149], v139
	v_sub_f32_e32 v55, v158, v55
	v_sub_f32_e32 v59, v158, v59
	v_sub_f32_e32 v58, v158, v58
	s_waitcnt lgkmcnt(0)
	v_sub_f32_e32 v67, v158, v63
	v_sub_f32_e32 v66, v158, v62
	v_sub_f32_e32 v65, v158, v61
	v_sub_f32_e32 v64, v158, v60
	v_sub_f32_e32 v63, v158, v79
	v_sub_f32_e32 v62, v158, v78
	v_sub_f32_e32 v61, v158, v77
	v_sub_f32_e32 v60, v158, v76
	ds_read_b128 v[76:79], v140
	v_sub_f32_e32 v57, v158, v57
	v_sub_f32_e32 v56, v158, v56
	v_sub_f32_e32 v54, v158, v54
	v_sub_f32_e32 v53, v158, v53
	v_sub_f32_e32 v52, v158, v52
	ds_read_b128 v[68:71], v141 offset:32896
	ds_read_b128 v[72:75], v141 offset:32928
	ds_read_b128 v[142:145], v141 offset:32960
	ds_read_b128 v[80:83], v141 offset:32992
	ds_read_b128 v[150:153], v138
	s_waitcnt lgkmcnt(0)
	v_mfma_f32_32x32x16_bf16 v[52:67], v[76:79], v[88:91], v[52:67]
	ds_read_b128 v[154:157], v2
	v_sub_f32_e32 v79, v158, v145
	v_sub_f32_e32 v78, v158, v144
	v_sub_f32_e32 v77, v158, v143
	v_sub_f32_e32 v76, v158, v142
	v_sub_f32_e32 v83, v158, v83
	v_sub_f32_e32 v82, v158, v82
	v_mfma_f32_32x32x16_bf16 v[52:67], v[146:149], v[92:95], v[52:67]
	ds_read_b128 v[142:145], v140 offset:4096
	v_sub_f32_e32 v81, v158, v81
	v_sub_f32_e32 v80, v158, v80
	v_sub_f32_e32 v75, v158, v75
	v_sub_f32_e32 v74, v158, v74
	v_sub_f32_e32 v73, v158, v73
	v_sub_f32_e32 v72, v158, v72
	v_mfma_f32_32x32x16_bf16 v[52:67], v[150:153], v[96:99], v[52:67]
	v_sub_f32_e32 v71, v158, v71
	v_sub_f32_e32 v70, v158, v70
	v_sub_f32_e32 v69, v158, v69
	v_sub_f32_e32 v68, v158, v68
	ds_read_b128 v[146:149], v139 offset:4096
	s_cmp_lg_u32 s76, s77
	s_waitcnt lgkmcnt(0)
	v_mfma_f32_32x32x16_bf16 v[68:83], v[142:145], v[88:91], v[68:83]
	ds_read_b128 v[142:145], v138 offset:4096
	v_mfma_f32_32x32x16_bf16 v[68:83], v[146:149], v[92:95], v[68:83]
	s_waitcnt lgkmcnt(0)
	v_mfma_f32_32x32x16_bf16 v[68:83], v[142:145], v[96:99], v[68:83]
	ds_read_b128 v[142:145], v2 offset:4096
	s_waitcnt lgkmcnt(0)
	v_mfma_f32_32x32x16_bf16 v[68:83], v[142:145], v[100:103], v[68:83]
	v_mfma_f32_32x32x16_bf16 v[52:67], v[154:157], v[100:103], v[52:67]
	s_cbranch_scc1 .LBB0_837
	s_nop 10
	v_cndmask_b32_e64 v142, v52, v121, s[2:3]
	v_cndmask_b32_e64 v68, v68, v121, s[4:5]
	v_cndmask_b32_e64 v52, v142, v52, s[6:7]
	v_cndmask_b32_e64 v53, v121, v53, s[6:7]
	v_cndmask_b32_e64 v69, v69, v121, s[8:9]
	v_cndmask_b32_e64 v54, v54, v121, s[10:11]
	v_cndmask_b32_e64 v70, v70, v121, s[12:13]
	v_cndmask_b32_e64 v55, v55, v121, s[14:15]
	v_cndmask_b32_e64 v71, v71, v121, s[16:17]
	v_cndmask_b32_e64 v56, v56, v121, s[18:19]
	v_cndmask_b32_e64 v72, v72, v121, s[20:21]
	v_cndmask_b32_e64 v57, v57, v121, s[22:23]
	v_cndmask_b32_e64 v73, v73, v121, s[24:25]
	v_cndmask_b32_e64 v58, v58, v121, s[26:27]
	v_cndmask_b32_e64 v74, v74, v121, s[28:29]
	v_cndmask_b32_e64 v59, v59, v121, s[30:31]
	v_cndmask_b32_e64 v75, v75, v121, s[34:35]
	v_cndmask_b32_e64 v60, v60, v121, s[36:37]
	v_cndmask_b32_e64 v76, v76, v121, s[38:39]
	v_cndmask_b32_e64 v61, v61, v121, s[40:41]
	v_cndmask_b32_e64 v77, v77, v121, s[42:43]
	v_cndmask_b32_e64 v62, v62, v121, s[44:45]
	v_cndmask_b32_e64 v78, v78, v121, s[46:47]
	v_cndmask_b32_e64 v63, v63, v121, s[48:49]
	v_cndmask_b32_e64 v79, v79, v121, s[50:51]
	v_cndmask_b32_e64 v64, v64, v121, s[52:53]
	v_cndmask_b32_e64 v80, v80, v121, s[54:55]
	v_cndmask_b32_e64 v65, v65, v121, s[56:57]
	v_cndmask_b32_e64 v81, v81, v121, s[58:59]
	v_cndmask_b32_e64 v66, v66, v121, s[60:61]
	v_cndmask_b32_e64 v82, v82, v121, s[62:63]
	v_cndmask_b32_e64 v67, v67, v121, s[64:65]
	v_cndmask_b32_e64 v83, v83, v121, s[66:67]

.LBB0_840:
	v_add_u32_e32 v142, s91, v129
	v_add_u32_e32 v143, v142, v130
	v_exp_f32_e32 v52, v52
	v_exp_f32_e32 v53, v53
	v_exp_f32_e32 v54, v54
	v_exp_f32_e32 v55, v55
	ds_read_b64_tr_b16 v[144:145], v143 offset:16384
	ds_read_b64_tr_b16 v[146:147], v143 offset:17408
	v_exp_f32_e32 v56, v56
	v_exp_f32_e32 v57, v57
	v_exp_f32_e32 v58, v58
	v_exp_f32_e32 v59, v59
	v_cvt_pk_bf16_f32 v148, v52, v53
	v_cvt_pk_bf16_f32 v149, v54, v55
	v_cvt_pk_bf16_f32 v150, v56, v57
	v_cvt_pk_bf16_f32 v151, v58, v59
	v_add_u32_e32 v142, v142, v131
	v_exp_f32_e32 v60, v60
	s_waitcnt lgkmcnt(0)
	v_mfma_f32_32x32x16_bf16 v[4:19], v[144:147], v[148:151], v[4:19]
	ds_read_b64_tr_b16 v[144:145], v142 offset:16384
	ds_read_b64_tr_b16 v[146:147], v142 offset:17408
	v_exp_f32_e32 v61, v61
	v_exp_f32_e32 v62, v62
	v_exp_f32_e32 v63, v63
	v_exp_f32_e32 v64, v64
	v_exp_f32_e32 v65, v65
	v_exp_f32_e32 v66, v66
	s_waitcnt lgkmcnt(0)
	v_mfma_f32_32x32x16_bf16 v[20:35], v[144:147], v[148:151], v[20:35]
	ds_read_b64_tr_b16 v[144:145], v143 offset:18432
	ds_read_b64_tr_b16 v[146:147], v143 offset:19456
	v_exp_f32_e32 v67, v67
	v_mfma_f32_32x32x16_bf16 v[36:51], v[84:87], v[148:151], v[36:51]
	v_cvt_pk_bf16_f32 v148, v60, v61
	v_cvt_pk_bf16_f32 v149, v62, v63
	v_cvt_pk_bf16_f32 v150, v64, v65
	v_cvt_pk_bf16_f32 v151, v66, v67
	s_waitcnt lgkmcnt(0)
	s_nop 0
	v_mfma_f32_32x32x16_bf16 v[4:19], v[144:147], v[148:151], v[4:19]
	ds_read_b64_tr_b16 v[144:145], v142 offset:18432
	ds_read_b64_tr_b16 v[146:147], v142 offset:19456
	s_waitcnt lgkmcnt(0)
	v_mfma_f32_32x32x16_bf16 v[20:35], v[144:147], v[148:151], v[20:35]
	v_max_f32_e32 v144, v69, v69
	v_max_f32_e32 v145, v68, v68
	v_max_f32_e32 v144, v145, v144
	v_max3_f32 v144, v144, v70, v71
	v_max3_f32 v144, v144, v72, v73
	v_max3_f32 v144, v144, v74, v75
	v_max3_f32 v144, v144, v76, v77
	v_max3_f32 v144, v144, v78, v79
	v_mfma_f32_32x32x16_bf16 v[36:51], v[84:87], v[148:151], v[36:51]
	v_max3_f32 v144, v144, v80, v81
	v_max3_f32 v144, v144, v82, v83
	v_mov_b32_e32 v145, v144
	s_nop 1
	v_permlane32_swap_b32_e32 v144, v145
	v_max_f32_e32 v145, v145, v145
	v_max_f32_e32 v144, v144, v144
	v_max_f32_e32 v144, v144, v145
	v_cmp_lt_f32_e32 vcc, s95, v144
	s_cbranch_vccz .LBB0_842
	v_max_f32_e32 v144, v144, v144
	v_max_f32_e32 v144, 0, v144
	v_exp_f32_e64 v146, -v144
	v_add_f32_e32 v137, v137, v144
	v_pk_add_f32 v[68:69], v[68:69], v[144:145] op_sel_hi:[1,0] neg_lo:[0,1] neg_hi:[0,1]
	v_pk_add_f32 v[70:71], v[70:71], v[144:145] op_sel_hi:[1,0] neg_lo:[0,1] neg_hi:[0,1]
	v_mul_f32_e32 v36, v36, v146
	v_pk_add_f32 v[72:73], v[72:73], v[144:145] op_sel_hi:[1,0] neg_lo:[0,1] neg_hi:[0,1]
	v_pk_add_f32 v[74:75], v[74:75], v[144:145] op_sel_hi:[1,0] neg_lo:[0,1] neg_hi:[0,1]
	v_pk_add_f32 v[76:77], v[76:77], v[144:145] op_sel_hi:[1,0] neg_lo:[0,1] neg_hi:[0,1]
	v_pk_add_f32 v[78:79], v[78:79], v[144:145] op_sel_hi:[1,0] neg_lo:[0,1] neg_hi:[0,1]
	v_pk_add_f32 v[80:81], v[80:81], v[144:145] op_sel_hi:[1,0] neg_lo:[0,1] neg_hi:[0,1]
	v_pk_add_f32 v[82:83], v[82:83], v[144:145] op_sel_hi:[1,0] neg_lo:[0,1] neg_hi:[0,1]
	v_pk_mul_f32 v[34:35], v[34:35], v[146:147] op_sel_hi:[1,0]
	v_pk_mul_f32 v[32:33], v[32:33], v[146:147] op_sel_hi:[1,0]
	v_pk_mul_f32 v[30:31], v[30:31], v[146:147] op_sel_hi:[1,0]
	v_pk_mul_f32 v[28:29], v[28:29], v[146:147] op_sel_hi:[1,0]
	v_pk_mul_f32 v[26:27], v[26:27], v[146:147] op_sel_hi:[1,0]
	v_pk_mul_f32 v[24:25], v[24:25], v[146:147] op_sel_hi:[1,0]
	v_pk_mul_f32 v[22:23], v[22:23], v[146:147] op_sel_hi:[1,0]
	v_pk_mul_f32 v[20:21], v[20:21], v[146:147] op_sel_hi:[1,0]
	v_pk_mul_f32 v[18:19], v[18:19], v[146:147] op_sel_hi:[1,0]
	v_pk_mul_f32 v[16:17], v[16:17], v[146:147] op_sel_hi:[1,0]
	v_pk_mul_f32 v[14:15], v[14:15], v[146:147] op_sel_hi:[1,0]
	v_pk_mul_f32 v[12:13], v[12:13], v[146:147] op_sel_hi:[1,0]
	v_pk_mul_f32 v[10:11], v[10:11], v[146:147] op_sel_hi:[1,0]
	v_pk_mul_f32 v[8:9], v[8:9], v[146:147] op_sel_hi:[1,0]
	v_pk_mul_f32 v[6:7], v[6:7], v[146:147] op_sel_hi:[1,0]
	v_pk_mul_f32 v[4:5], v[4:5], v[146:147] op_sel_hi:[1,0]

.LBB0_843:
	s_cmp_lt_u32 s77, s73
	s_cselect_b64 s[0:1], -1, 0
	s_cmp_ge_u32 s77, s73
	s_cbranch_scc1 .LBB0_846
	s_nop 4
	v_mov_b32_e32 v52, s68
	ds_read_b32 v60, v52
	v_sub_f32_e32 v61, v1, v137
	ds_read_b128 v[76:79], v141 offset:33088
	ds_read_b128 v[52:55], v141 offset:33024
	ds_read_b128 v[56:59], v141 offset:33056
	s_waitcnt lgkmcnt(0)
	v_sub_f32_e32 v158, v61, v60
	ds_read_b128 v[60:63], v141 offset:33120
	ds_read_b128 v[146:149], v139 offset:8192
	v_sub_f32_e32 v55, v158, v55
	v_sub_f32_e32 v59, v158, v59
	v_sub_f32_e32 v58, v158, v58
	s_waitcnt lgkmcnt(0)
	v_sub_f32_e32 v67, v158, v63
	v_sub_f32_e32 v66, v158, v62
	v_sub_f32_e32 v65, v158, v61
	v_sub_f32_e32 v64, v158, v60
	v_sub_f32_e32 v63, v158, v79
	v_sub_f32_e32 v62, v158, v78
	v_sub_f32_e32 v61, v158, v77
	v_sub_f32_e32 v60, v158, v76
	ds_read_b128 v[76:79], v140 offset:8192
	v_sub_f32_e32 v57, v158, v57
	v_sub_f32_e32 v56, v158, v56
	v_sub_f32_e32 v54, v158, v54
	v_sub_f32_e32 v53, v158, v53
	v_sub_f32_e32 v52, v158, v52
	ds_read_b128 v[68:71], v141 offset:33152
	ds_read_b128 v[72:75], v141 offset:33184
	ds_read_b128 v[142:145], v141 offset:33216
	ds_read_b128 v[80:83], v141 offset:33248
	ds_read_b128 v[150:153], v138 offset:8192
	s_waitcnt lgkmcnt(0)
	v_mfma_f32_32x32x16_bf16 v[52:67], v[76:79], v[88:91], v[52:67]
	ds_read_b128 v[154:157], v2 offset:8192
	v_sub_f32_e32 v77, v158, v143
	v_sub_f32_e32 v76, v158, v142
	v_sub_f32_e32 v83, v158, v83
	v_sub_f32_e32 v82, v158, v82
	v_sub_f32_e32 v81, v158, v81
	v_sub_f32_e32 v80, v158, v80
	v_mfma_f32_32x32x16_bf16 v[52:67], v[146:149], v[92:95], v[52:67]
	ds_read_b128 v[140:143], v140 offset:12288
	v_sub_f32_e32 v79, v158, v145
	v_sub_f32_e32 v78, v158, v144
	v_sub_f32_e32 v75, v158, v75
	v_sub_f32_e32 v74, v158, v74
	v_sub_f32_e32 v73, v158, v73
	v_sub_f32_e32 v72, v158, v72
	v_mfma_f32_32x32x16_bf16 v[52:67], v[150:153], v[96:99], v[52:67]
	v_sub_f32_e32 v71, v158, v71
	v_sub_f32_e32 v70, v158, v70
	v_sub_f32_e32 v69, v158, v69
	v_sub_f32_e32 v68, v158, v68
	ds_read_b128 v[144:147], v139 offset:12288
	s_cmp_lg_u32 s93, s77
	s_waitcnt lgkmcnt(0)
	v_mfma_f32_32x32x16_bf16 v[68:83], v[140:143], v[88:91], v[68:83]
	ds_read_b128 v[138:141], v138 offset:12288
	v_mfma_f32_32x32x16_bf16 v[68:83], v[144:147], v[92:95], v[68:83]
	s_waitcnt lgkmcnt(0)
	v_mfma_f32_32x32x16_bf16 v[68:83], v[138:141], v[96:99], v[68:83]
	ds_read_b128 v[138:141], v2 offset:12288
	s_waitcnt lgkmcnt(0)
	v_mfma_f32_32x32x16_bf16 v[68:83], v[138:141], v[100:103], v[68:83]
	v_mfma_f32_32x32x16_bf16 v[52:67], v[154:157], v[100:103], v[52:67]
	s_cbranch_scc1 .LBB0_846
	s_nop 10
	v_cndmask_b32_e64 v2, v52, v121, s[2:3]
	v_cndmask_b32_e64 v68, v68, v121, s[4:5]
	v_cndmask_b32_e64 v52, v2, v52, s[6:7]
	v_cndmask_b32_e64 v53, v121, v53, s[6:7]
	v_cndmask_b32_e64 v69, v69, v121, s[8:9]
	v_cndmask_b32_e64 v54, v54, v121, s[10:11]
	v_cndmask_b32_e64 v70, v70, v121, s[12:13]
	v_cndmask_b32_e64 v55, v55, v121, s[14:15]
	v_cndmask_b32_e64 v71, v71, v121, s[16:17]
	v_cndmask_b32_e64 v56, v56, v121, s[18:19]
	v_cndmask_b32_e64 v72, v72, v121, s[20:21]
	v_cndmask_b32_e64 v57, v57, v121, s[22:23]
	v_cndmask_b32_e64 v73, v73, v121, s[24:25]
	v_cndmask_b32_e64 v58, v58, v121, s[26:27]
	v_cndmask_b32_e64 v74, v74, v121, s[28:29]
	v_cndmask_b32_e64 v59, v59, v121, s[30:31]
	v_cndmask_b32_e64 v75, v75, v121, s[34:35]
	v_cndmask_b32_e64 v60, v60, v121, s[36:37]
	v_cndmask_b32_e64 v76, v76, v121, s[38:39]
	v_cndmask_b32_e64 v61, v61, v121, s[40:41]
	v_cndmask_b32_e64 v77, v77, v121, s[42:43]
	v_cndmask_b32_e64 v62, v62, v121, s[44:45]
	v_cndmask_b32_e64 v78, v78, v121, s[46:47]
	v_cndmask_b32_e64 v63, v63, v121, s[48:49]
	v_cndmask_b32_e64 v79, v79, v121, s[50:51]
	v_cndmask_b32_e64 v64, v64, v121, s[52:53]
	v_cndmask_b32_e64 v80, v80, v121, s[54:55]
	v_cndmask_b32_e64 v65, v65, v121, s[56:57]
	v_cndmask_b32_e64 v81, v81, v121, s[58:59]
	v_cndmask_b32_e64 v66, v66, v121, s[60:61]
	v_cndmask_b32_e64 v82, v82, v121, s[62:63]
	v_cndmask_b32_e64 v67, v67, v121, s[64:65]
	v_cndmask_b32_e64 v83, v83, v121, s[66:67]

.LBB0_849:
	v_add_u32_e32 v2, s91, v129
	v_add_u32_e32 v138, v2, v130
	v_exp_f32_e32 v52, v52
	v_exp_f32_e32 v53, v53
	v_exp_f32_e32 v54, v54
	v_exp_f32_e32 v55, v55
	ds_read_b64_tr_b16 v[140:141], v138 offset:24576
	ds_read_b64_tr_b16 v[142:143], v138 offset:25600
	v_exp_f32_e32 v56, v56
	v_exp_f32_e32 v57, v57
	v_exp_f32_e32 v58, v58
	v_exp_f32_e32 v59, v59
	v_cvt_pk_bf16_f32 v144, v52, v53
	v_cvt_pk_bf16_f32 v145, v54, v55
	v_cvt_pk_bf16_f32 v146, v56, v57
	v_cvt_pk_bf16_f32 v147, v58, v59
	v_add_u32_e32 v2, v2, v131
	v_exp_f32_e32 v60, v60
	s_waitcnt lgkmcnt(0)
	v_mfma_f32_32x32x16_bf16 v[4:19], v[140:143], v[144:147], v[4:19]
	ds_read_b64_tr_b16 v[140:141], v2 offset:24576
	ds_read_b64_tr_b16 v[142:143], v2 offset:25600
	v_exp_f32_e32 v61, v61
	v_exp_f32_e32 v62, v62
	v_exp_f32_e32 v63, v63
	v_exp_f32_e32 v64, v64
	v_exp_f32_e32 v65, v65
	v_exp_f32_e32 v66, v66
	s_waitcnt lgkmcnt(0)
	v_mfma_f32_32x32x16_bf16 v[20:35], v[140:143], v[144:147], v[20:35]
	ds_read_b64_tr_b16 v[140:141], v138 offset:26624
	ds_read_b64_tr_b16 v[142:143], v138 offset:27648
	v_exp_f32_e32 v67, v67
	v_max_f32_e32 v139, v69, v69
	v_mfma_f32_32x32x16_bf16 v[36:51], v[84:87], v[144:147], v[36:51]
	v_cvt_pk_bf16_f32 v144, v60, v61
	v_cvt_pk_bf16_f32 v145, v62, v63
	v_cvt_pk_bf16_f32 v146, v64, v65
	v_cvt_pk_bf16_f32 v147, v66, v67
	s_waitcnt lgkmcnt(0)
	s_nop 0
	v_mfma_f32_32x32x16_bf16 v[4:19], v[140:143], v[144:147], v[4:19]
	ds_read_b64_tr_b16 v[140:141], v2 offset:26624
	ds_read_b64_tr_b16 v[142:143], v2 offset:27648
	s_waitcnt lgkmcnt(0)
	v_mfma_f32_32x32x16_bf16 v[20:35], v[140:143], v[144:147], v[20:35]
	v_max_f32_e32 v140, v68, v68
	v_max_f32_e32 v139, v140, v139
	v_max3_f32 v139, v139, v70, v71
	v_max3_f32 v139, v139, v72, v73
	v_max3_f32 v139, v139, v74, v75
	v_max3_f32 v139, v139, v76, v77
	v_max3_f32 v139, v139, v78, v79
	v_mfma_f32_32x32x16_bf16 v[36:51], v[84:87], v[144:147], v[36:51]
	v_max3_f32 v139, v139, v80, v81
	v_max3_f32 v139, v139, v82, v83
	v_mov_b32_e32 v140, v139
	s_nop 1
	v_permlane32_swap_b32_e32 v139, v140
	v_max_f32_e32 v140, v140, v140
	v_max_f32_e32 v139, v139, v139
	v_max_f32_e32 v139, v139, v140
	v_cmp_lt_f32_e32 vcc, s95, v139
	s_cbranch_vccz .LBB0_851
	v_max_f32_e32 v139, v139, v139
	v_max_f32_e32 v140, 0, v139
	v_exp_f32_e64 v142, -v140
	v_add_f32_e32 v137, v137, v140
	v_pk_add_f32 v[68:69], v[68:69], v[140:141] op_sel_hi:[1,0] neg_lo:[0,1] neg_hi:[0,1]
	v_pk_add_f32 v[70:71], v[70:71], v[140:141] op_sel_hi:[1,0] neg_lo:[0,1] neg_hi:[0,1]
	v_mul_f32_e32 v36, v36, v142
	v_pk_add_f32 v[72:73], v[72:73], v[140:141] op_sel_hi:[1,0] neg_lo:[0,1] neg_hi:[0,1]
	v_pk_add_f32 v[74:75], v[74:75], v[140:141] op_sel_hi:[1,0] neg_lo:[0,1] neg_hi:[0,1]
	v_pk_add_f32 v[76:77], v[76:77], v[140:141] op_sel_hi:[1,0] neg_lo:[0,1] neg_hi:[0,1]
	v_pk_add_f32 v[78:79], v[78:79], v[140:141] op_sel_hi:[1,0] neg_lo:[0,1] neg_hi:[0,1]
	v_pk_add_f32 v[80:81], v[80:81], v[140:141] op_sel_hi:[1,0] neg_lo:[0,1] neg_hi:[0,1]
	v_pk_add_f32 v[82:83], v[82:83], v[140:141] op_sel_hi:[1,0] neg_lo:[0,1] neg_hi:[0,1]
	v_pk_mul_f32 v[34:35], v[34:35], v[142:143] op_sel_hi:[1,0]
	v_pk_mul_f32 v[32:33], v[32:33], v[142:143] op_sel_hi:[1,0]
	v_pk_mul_f32 v[30:31], v[30:31], v[142:143] op_sel_hi:[1,0]
	v_pk_mul_f32 v[28:29], v[28:29], v[142:143] op_sel_hi:[1,0]
	v_pk_mul_f32 v[26:27], v[26:27], v[142:143] op_sel_hi:[1,0]
	v_pk_mul_f32 v[24:25], v[24:25], v[142:143] op_sel_hi:[1,0]
	v_pk_mul_f32 v[22:23], v[22:23], v[142:143] op_sel_hi:[1,0]
	v_pk_mul_f32 v[20:21], v[20:21], v[142:143] op_sel_hi:[1,0]
	v_pk_mul_f32 v[18:19], v[18:19], v[142:143] op_sel_hi:[1,0]
	v_pk_mul_f32 v[16:17], v[16:17], v[142:143] op_sel_hi:[1,0]
	v_pk_mul_f32 v[14:15], v[14:15], v[142:143] op_sel_hi:[1,0]
	v_pk_mul_f32 v[12:13], v[12:13], v[142:143] op_sel_hi:[1,0]
	v_pk_mul_f32 v[10:11], v[10:11], v[142:143] op_sel_hi:[1,0]
	v_pk_mul_f32 v[8:9], v[8:9], v[142:143] op_sel_hi:[1,0]
	v_pk_mul_f32 v[6:7], v[6:7], v[142:143] op_sel_hi:[1,0]
	v_pk_mul_f32 v[4:5], v[4:5], v[142:143] op_sel_hi:[1,0]

.LBB0_854:
	s_nop 2
	v_mov_b32_e32 v1, v36
	s_nop 1
	v_permlane32_swap_b32_e32 v36, v1
	v_add_f32_e32 v1, v36, v1
	v_div_scale_f32 v2, s[0:1], v1, v1, 1.0
	v_rcp_f32_e32 v3, v2
	s_mulk_i32 s70, 0x1200
	s_add_i32 s2, s70, 0
	s_waitcnt vmcnt(0) lgkmcnt(0)
	s_barrier
	v_fma_f32 v36, -v2, v3, 1.0
	v_fmac_f32_e32 v3, v36, v3
	v_div_scale_f32 v36, vcc, 1.0, v1, 1.0
	v_mul_f32_e32 v37, v36, v3
	v_fma_f32 v38, -v2, v37, v36
	v_fmac_f32_e32 v37, v38, v3
	v_fma_f32 v2, -v2, v37, v36
	v_div_fmas_f32 v2, v2, v3, v37
	v_div_fixup_f32 v2, v2, v1, 1.0
	v_pk_mul_f32 v[4:5], v[4:5], v[2:3] op_sel_hi:[1,0]
	v_pk_mul_f32 v[6:7], v[6:7], v[2:3] op_sel_hi:[1,0]
	v_add3_u32 v1, s2, v136, v124
	v_cvt_pk_bf16_f32 v4, v4, v5
	v_cvt_pk_bf16_f32 v5, v6, v7
	v_pk_mul_f32 v[6:7], v[8:9], v[2:3] op_sel_hi:[1,0]
	v_pk_mul_f32 v[8:9], v[10:11], v[2:3] op_sel_hi:[1,0]
	v_cvt_pk_bf16_f32 v6, v6, v7
	v_cvt_pk_bf16_f32 v7, v8, v9
	v_add_u32_e32 v1, 0x9000, v1
	ds_write2_b64 v1, v[4:5], v[6:7] offset1:2
	v_pk_mul_f32 v[4:5], v[12:13], v[2:3] op_sel_hi:[1,0]
	v_pk_mul_f32 v[6:7], v[14:15], v[2:3] op_sel_hi:[1,0]
	v_cvt_pk_bf16_f32 v4, v4, v5
	v_cvt_pk_bf16_f32 v5, v6, v7
	v_pk_mul_f32 v[6:7], v[16:17], v[2:3] op_sel_hi:[1,0]
	v_pk_mul_f32 v[8:9], v[18:19], v[2:3] op_sel_hi:[1,0]
	v_cvt_pk_bf16_f32 v6, v6, v7
	v_cvt_pk_bf16_f32 v7, v8, v9
	ds_write2_b64 v1, v[4:5], v[6:7] offset0:4 offset1:6
	v_pk_mul_f32 v[4:5], v[20:21], v[2:3] op_sel_hi:[1,0]
	v_pk_mul_f32 v[6:7], v[22:23], v[2:3] op_sel_hi:[1,0]
	v_cvt_pk_bf16_f32 v4, v4, v5
	v_cvt_pk_bf16_f32 v5, v6, v7
	v_pk_mul_f32 v[6:7], v[24:25], v[2:3] op_sel_hi:[1,0]
	v_pk_mul_f32 v[8:9], v[26:27], v[2:3] op_sel_hi:[1,0]
	v_cvt_pk_bf16_f32 v6, v6, v7
	v_cvt_pk_bf16_f32 v7, v8, v9
	ds_write2_b64 v1, v[4:5], v[6:7] offset0:8 offset1:10
	v_pk_mul_f32 v[4:5], v[28:29], v[2:3] op_sel_hi:[1,0]
	v_pk_mul_f32 v[6:7], v[30:31], v[2:3] op_sel_hi:[1,0]
	v_cvt_pk_bf16_f32 v4, v4, v5
	v_cvt_pk_bf16_f32 v5, v6, v7
	v_pk_mul_f32 v[6:7], v[32:33], v[2:3] op_sel_hi:[1,0]
	v_pk_mul_f32 v[2:3], v[34:35], v[2:3] op_sel_hi:[1,0]
	v_cvt_pk_bf16_f32 v6, v6, v7
	v_cvt_pk_bf16_f32 v7, v2, v3
	ds_write2_b64 v1, v[4:5], v[6:7] offset0:12 offset1:14
	s_lshl_b64 s[0:1], s[78:79], 11
	v_readlane_b32 s4, v249, 53
	s_waitcnt lgkmcnt(0)
	v_readlane_b32 s5, v249, 54
	s_add_u32 s0, s4, s0
	v_add3_u32 v1, s2, v110, v111
	s_addc_u32 s1, s5, s1
	ds_read_b128 v[4:7], v1 offset:36864
	s_add_u32 s0, s0, s74
	v_mov_b32_e32 v3, 0
	ds_read_b128 v[8:11], v1 offset:38016
	s_addc_u32 s1, s1, 0
	v_mov_b32_e32 v119, v3
	v_lshl_add_u64 v[12:13], s[0:1], 0, v[118:119]
	v_mov_b32_e32 v121, v3
	v_lshl_add_u64 v[14:15], v[12:13], 0, v[120:121]
	v_mov_b32_e32 v115, v3
	s_waitcnt lgkmcnt(0)
	global_store_dwordx4 v[14:15], v[4:7], off
	v_lshl_add_u64 v[14:15], v[12:13], 0, v[114:115]
	ds_read_b128 v[4:7], v1 offset:39168
	v_readlane_b32 s0, v248, 6
	global_store_dwordx4 v[14:15], v[8:11], off
	ds_read_b128 v[8:11], v1 offset:40320
	s_xor_b32 s68, s0, 15
	v_readfirstlane_b32 s3, v222
	s_lshr_b32 s70, s3, 6
	s_lshl_b32 s2, s68, 8
	v_readlane_b32 s8, v248, 7
	v_mov_b32_e32 v113, v3
	s_lshl_b32 s76, s70, 5
	s_or_b32 s0, s8, s2
	v_lshl_add_u64 v[14:15], v[12:13], 0, v[112:113]
	v_mov_b32_e32 v117, v3
	v_readlane_b32 s9, v248, 8
	s_add_u32 s78, s0, s76
	s_waitcnt lgkmcnt(0)
	global_store_dwordx4 v[14:15], v[4:7], off
	s_addc_u32 s79, s9, 0
	s_mov_b32 s77, 0
	v_lshl_add_u64 v[4:5], v[12:13], 0, v[116:117]
	global_store_dwordx4 v[4:5], v[8:11], off
	v_mov_b32_e32 v5, s79
	v_or_b32_e32 v4, s78, v133
	v_lshlrev_b64 v[4:5], 11, v[4:5]
	s_mov_b32 s75, s77
	v_lshl_add_u64 v[4:5], s[4:5], 0, v[4:5]
	v_lshl_add_u64 v[4:5], v[4:5], 0, s[74:75]
	v_mov_b32_e32 v1, v3
	v_lshl_add_u64 v[4:5], v[4:5], 0, v[0:1]
	global_load_dwordx4 v[88:91], v[4:5], off
	global_load_dwordx4 v[92:95], v[4:5], off offset:32
	global_load_dwordx4 v[96:99], v[4:5], off offset:64
	global_load_dwordx4 v[100:103], v[4:5], off offset:96
	s_cmp_gt_u32 s3, 63
	s_mov_b32 s71, 0x9000
	s_cbranch_scc1 .LBB0_860
	v_cmp_gt_u32_e32 vcc, 32, v134
	v_mov_b32_e32 v1, 0
	s_and_saveexec_b64 s[0:1], vcc
	s_cbranch_execz .LBB0_857
	v_lshlrev_b32_e32 v1, 4, v133
	v_readlane_b32 s4, v249, 62
	v_readlane_b32 s5, v249, 63
	s_nop 0
	v_lshl_or_b32 v1, s4, 9, v1
	v_readlane_b32 s4, v249, 60
	s_nop 1
	v_or_b32_e32 v4, s4, v1
	v_readlane_b32 s4, v249, 51
	v_ashrrev_i32_e32 v5, 31, v4
	v_readlane_b32 s5, v249, 52
	s_nop 1
	v_lshl_add_u64 v[4:5], v[4:5], 2, s[4:5]
	global_load_dword v1, v[4:5], off

.LBB0_882:
	s_nop 2
	v_mov_b32_e32 v1, v36
	s_nop 1
	v_permlane32_swap_b32_e32 v36, v1
	v_add_f32_e32 v1, v36, v1
	v_div_scale_f32 v2, s[0:1], v1, v1, 1.0
	v_rcp_f32_e32 v3, v2
	s_mulk_i32 s70, 0x1200
	s_add_i32 s2, s70, 0
	s_waitcnt vmcnt(0) lgkmcnt(0)
	s_barrier
	v_fma_f32 v36, -v2, v3, 1.0
	v_fmac_f32_e32 v3, v36, v3
	v_div_scale_f32 v36, vcc, 1.0, v1, 1.0
	v_mul_f32_e32 v37, v36, v3
	v_fma_f32 v38, -v2, v37, v36
	v_fmac_f32_e32 v37, v38, v3
	v_fma_f32 v2, -v2, v37, v36
	v_div_fmas_f32 v2, v2, v3, v37
	v_div_fixup_f32 v2, v2, v1, 1.0
	v_pk_mul_f32 v[4:5], v[4:5], v[2:3] op_sel_hi:[1,0]
	v_pk_mul_f32 v[6:7], v[6:7], v[2:3] op_sel_hi:[1,0]
	v_add3_u32 v1, s2, v136, v124
	v_cvt_pk_bf16_f32 v4, v4, v5
	v_cvt_pk_bf16_f32 v5, v6, v7
	v_pk_mul_f32 v[6:7], v[8:9], v[2:3] op_sel_hi:[1,0]
	v_pk_mul_f32 v[8:9], v[10:11], v[2:3] op_sel_hi:[1,0]
	v_cvt_pk_bf16_f32 v6, v6, v7
	v_cvt_pk_bf16_f32 v7, v8, v9
	v_add_u32_e32 v1, 0x9000, v1
	ds_write2_b64 v1, v[4:5], v[6:7] offset1:2
	v_pk_mul_f32 v[4:5], v[12:13], v[2:3] op_sel_hi:[1,0]
	v_pk_mul_f32 v[6:7], v[14:15], v[2:3] op_sel_hi:[1,0]
	v_cvt_pk_bf16_f32 v4, v4, v5
	v_cvt_pk_bf16_f32 v5, v6, v7
	v_pk_mul_f32 v[6:7], v[16:17], v[2:3] op_sel_hi:[1,0]
	v_pk_mul_f32 v[8:9], v[18:19], v[2:3] op_sel_hi:[1,0]
	v_cvt_pk_bf16_f32 v6, v6, v7
	v_cvt_pk_bf16_f32 v7, v8, v9
	ds_write2_b64 v1, v[4:5], v[6:7] offset0:4 offset1:6
	v_pk_mul_f32 v[4:5], v[20:21], v[2:3] op_sel_hi:[1,0]
	v_pk_mul_f32 v[6:7], v[22:23], v[2:3] op_sel_hi:[1,0]
	v_cvt_pk_bf16_f32 v4, v4, v5
	v_cvt_pk_bf16_f32 v5, v6, v7
	v_pk_mul_f32 v[6:7], v[24:25], v[2:3] op_sel_hi:[1,0]
	v_pk_mul_f32 v[8:9], v[26:27], v[2:3] op_sel_hi:[1,0]
	v_cvt_pk_bf16_f32 v6, v6, v7
	v_cvt_pk_bf16_f32 v7, v8, v9
	ds_write2_b64 v1, v[4:5], v[6:7] offset0:8 offset1:10
	v_pk_mul_f32 v[4:5], v[28:29], v[2:3] op_sel_hi:[1,0]
	v_pk_mul_f32 v[6:7], v[30:31], v[2:3] op_sel_hi:[1,0]
	v_cvt_pk_bf16_f32 v4, v4, v5
	v_cvt_pk_bf16_f32 v5, v6, v7
	v_pk_mul_f32 v[6:7], v[32:33], v[2:3] op_sel_hi:[1,0]
	v_pk_mul_f32 v[2:3], v[34:35], v[2:3] op_sel_hi:[1,0]
	v_cvt_pk_bf16_f32 v6, v6, v7
	v_cvt_pk_bf16_f32 v7, v2, v3
	ds_write2_b64 v1, v[4:5], v[6:7] offset0:12 offset1:14
	s_lshl_b64 s[0:1], s[78:79], 11
	v_readlane_b32 s6, v249, 53
	s_waitcnt lgkmcnt(0)
	v_readlane_b32 s7, v249, 54
	s_add_u32 s0, s6, s0
	v_add3_u32 v1, s2, v110, v111
	s_addc_u32 s1, s7, s1
	ds_read_b128 v[4:7], v1 offset:36864
	s_add_u32 s0, s0, s74
	v_mov_b32_e32 v3, 0
	ds_read_b128 v[8:11], v1 offset:38016
	s_addc_u32 s1, s1, 0
	v_mov_b32_e32 v119, v3
	v_lshl_add_u64 v[12:13], s[0:1], 0, v[118:119]
	v_mov_b32_e32 v121, v3
	v_lshl_add_u64 v[14:15], v[12:13], 0, v[120:121]
	v_mov_b32_e32 v115, v3
	s_waitcnt lgkmcnt(0)
	global_store_dwordx4 v[14:15], v[4:7], off
	v_lshl_add_u64 v[14:15], v[12:13], 0, v[114:115]
	ds_read_b128 v[4:7], v1 offset:39168
	v_readlane_b32 s0, v248, 6
	global_store_dwordx4 v[14:15], v[8:11], off
	ds_read_b128 v[8:11], v1 offset:40320
	s_or_b32 s2, s0, 8
	v_readfirstlane_b32 s4, v222
	s_lshr_b32 s70, s4, 6
	s_lshl_b32 s3, s2, 8
	v_readlane_b32 s8, v248, 7
	v_mov_b32_e32 v113, v3
	s_lshl_b32 s76, s70, 5
	s_or_b32 s0, s8, s3
	v_lshl_add_u64 v[14:15], v[12:13], 0, v[112:113]
	v_mov_b32_e32 v117, v3
	v_readlane_b32 s9, v248, 8
	s_add_u32 s78, s0, s76
	s_waitcnt lgkmcnt(0)
	global_store_dwordx4 v[14:15], v[4:7], off
	s_addc_u32 s79, s9, 0
	s_mov_b32 s77, 0
	v_lshl_add_u64 v[4:5], v[12:13], 0, v[116:117]
	global_store_dwordx4 v[4:5], v[8:11], off
	v_mov_b32_e32 v5, s79
	v_or_b32_e32 v4, s78, v133
	v_lshlrev_b64 v[4:5], 11, v[4:5]
	s_mov_b32 s75, s77
	v_lshl_add_u64 v[4:5], s[6:7], 0, v[4:5]
	v_lshl_add_u64 v[4:5], v[4:5], 0, s[74:75]
	v_mov_b32_e32 v1, v3
	v_lshl_add_u64 v[4:5], v[4:5], 0, v[0:1]
	global_load_dwordx4 v[88:91], v[4:5], off
	global_load_dwordx4 v[92:95], v[4:5], off offset:32
	global_load_dwordx4 v[96:99], v[4:5], off offset:64
	global_load_dwordx4 v[100:103], v[4:5], off offset:96
	s_cmp_gt_u32 s4, 63
	s_mov_b32 s71, 0x9000
	s_cbranch_scc1 .LBB0_888
	v_cmp_gt_u32_e32 vcc, 32, v134
	v_mov_b32_e32 v1, 0
	s_and_saveexec_b64 s[0:1], vcc
	s_cbranch_execz .LBB0_885
	v_lshlrev_b32_e32 v1, 4, v133
	v_readlane_b32 s6, v249, 62
	v_readlane_b32 s7, v249, 63
	v_readlane_b32 s5, v249, 60
	v_lshl_or_b32 v1, s6, 9, v1
	v_readlane_b32 s6, v249, 51
	v_or_b32_e32 v4, s5, v1
	v_ashrrev_i32_e32 v5, 31, v4
	v_readlane_b32 s7, v249, 52
	s_nop 1
	v_lshl_add_u64 v[4:5], v[4:5], 2, s[6:7]
	global_load_dword v1, v[4:5], off

.LBB0_910:
	s_nop 2
	v_mov_b32_e32 v1, v36
	s_nop 1
	v_permlane32_swap_b32_e32 v36, v1
	v_add_f32_e32 v1, v36, v1
	v_div_scale_f32 v2, s[0:1], v1, v1, 1.0
	v_rcp_f32_e32 v3, v2
	s_mulk_i32 s70, 0x1200
	s_add_i32 s2, s70, 0
	s_waitcnt vmcnt(0) lgkmcnt(0)
	s_barrier
	v_fma_f32 v36, -v2, v3, 1.0
	v_fmac_f32_e32 v3, v36, v3
	v_div_scale_f32 v36, vcc, 1.0, v1, 1.0
	v_mul_f32_e32 v37, v36, v3
	v_fma_f32 v38, -v2, v37, v36
	v_fmac_f32_e32 v37, v38, v3
	v_fma_f32 v2, -v2, v37, v36
	v_div_fmas_f32 v2, v2, v3, v37
	v_div_fixup_f32 v2, v2, v1, 1.0
	v_pk_mul_f32 v[4:5], v[4:5], v[2:3] op_sel_hi:[1,0]
	v_pk_mul_f32 v[6:7], v[6:7], v[2:3] op_sel_hi:[1,0]
	v_add3_u32 v1, s2, v136, v124
	v_cvt_pk_bf16_f32 v4, v4, v5
	v_cvt_pk_bf16_f32 v5, v6, v7
	v_pk_mul_f32 v[6:7], v[8:9], v[2:3] op_sel_hi:[1,0]
	v_pk_mul_f32 v[8:9], v[10:11], v[2:3] op_sel_hi:[1,0]
	v_cvt_pk_bf16_f32 v6, v6, v7
	v_cvt_pk_bf16_f32 v7, v8, v9
	v_add_u32_e32 v1, 0x9000, v1
	ds_write2_b64 v1, v[4:5], v[6:7] offset1:2
	v_pk_mul_f32 v[4:5], v[12:13], v[2:3] op_sel_hi:[1,0]
	v_pk_mul_f32 v[6:7], v[14:15], v[2:3] op_sel_hi:[1,0]
	v_cvt_pk_bf16_f32 v4, v4, v5
	v_cvt_pk_bf16_f32 v5, v6, v7
	v_pk_mul_f32 v[6:7], v[16:17], v[2:3] op_sel_hi:[1,0]
	v_pk_mul_f32 v[8:9], v[18:19], v[2:3] op_sel_hi:[1,0]
	v_cvt_pk_bf16_f32 v6, v6, v7
	v_cvt_pk_bf16_f32 v7, v8, v9
	ds_write2_b64 v1, v[4:5], v[6:7] offset0:4 offset1:6
	v_pk_mul_f32 v[4:5], v[20:21], v[2:3] op_sel_hi:[1,0]
	v_pk_mul_f32 v[6:7], v[22:23], v[2:3] op_sel_hi:[1,0]
	v_cvt_pk_bf16_f32 v4, v4, v5
	v_cvt_pk_bf16_f32 v5, v6, v7
	v_pk_mul_f32 v[6:7], v[24:25], v[2:3] op_sel_hi:[1,0]
	v_pk_mul_f32 v[8:9], v[26:27], v[2:3] op_sel_hi:[1,0]
	v_cvt_pk_bf16_f32 v6, v6, v7
	v_cvt_pk_bf16_f32 v7, v8, v9
	ds_write2_b64 v1, v[4:5], v[6:7] offset0:8 offset1:10
	v_pk_mul_f32 v[4:5], v[28:29], v[2:3] op_sel_hi:[1,0]
	v_pk_mul_f32 v[6:7], v[30:31], v[2:3] op_sel_hi:[1,0]
	v_cvt_pk_bf16_f32 v4, v4, v5
	v_cvt_pk_bf16_f32 v5, v6, v7
	v_pk_mul_f32 v[6:7], v[32:33], v[2:3] op_sel_hi:[1,0]
	v_pk_mul_f32 v[2:3], v[34:35], v[2:3] op_sel_hi:[1,0]
	v_cvt_pk_bf16_f32 v6, v6, v7
	v_cvt_pk_bf16_f32 v7, v2, v3
	ds_write2_b64 v1, v[4:5], v[6:7] offset0:12 offset1:14
	s_lshl_b64 s[0:1], s[78:79], 11
	v_readlane_b32 s4, v249, 53
	s_waitcnt lgkmcnt(0)
	v_readlane_b32 s5, v249, 54
	s_add_u32 s0, s4, s0
	v_add3_u32 v1, s2, v110, v111
	s_addc_u32 s1, s5, s1
	ds_read_b128 v[4:7], v1 offset:36864
	s_add_u32 s0, s0, s74
	v_mov_b32_e32 v3, 0
	ds_read_b128 v[8:11], v1 offset:38016
	s_addc_u32 s1, s1, 0
	v_mov_b32_e32 v119, v3
	v_lshl_add_u64 v[12:13], s[0:1], 0, v[118:119]
	v_mov_b32_e32 v121, v3
	v_lshl_add_u64 v[14:15], v[12:13], 0, v[120:121]
	v_mov_b32_e32 v115, v3
	s_waitcnt lgkmcnt(0)
	global_store_dwordx4 v[14:15], v[4:7], off
	v_lshl_add_u64 v[14:15], v[12:13], 0, v[114:115]
	ds_read_b128 v[4:7], v1 offset:39168
	v_readlane_b32 s0, v248, 6
	global_store_dwordx4 v[14:15], v[8:11], off
	ds_read_b128 v[8:11], v1 offset:40320
	s_xor_b32 s68, s0, 7
	v_readfirstlane_b32 s3, v222
	s_lshr_b32 s70, s3, 6
	s_lshl_b32 s2, s68, 8
	v_readlane_b32 s8, v248, 7
	v_mov_b32_e32 v113, v3
	s_lshl_b32 s76, s70, 5
	s_or_b32 s0, s8, s2
	v_lshl_add_u64 v[14:15], v[12:13], 0, v[112:113]
	v_mov_b32_e32 v117, v3
	v_readlane_b32 s9, v248, 8
	s_add_u32 s78, s0, s76
	s_waitcnt lgkmcnt(0)
	global_store_dwordx4 v[14:15], v[4:7], off
	s_addc_u32 s79, s9, 0
	s_mov_b32 s77, 0
	v_lshl_add_u64 v[4:5], v[12:13], 0, v[116:117]
	global_store_dwordx4 v[4:5], v[8:11], off
	v_mov_b32_e32 v5, s79
	v_or_b32_e32 v4, s78, v133
	v_lshlrev_b64 v[4:5], 11, v[4:5]
	s_mov_b32 s75, s77
	v_lshl_add_u64 v[4:5], s[4:5], 0, v[4:5]
	v_lshl_add_u64 v[4:5], v[4:5], 0, s[74:75]
	v_mov_b32_e32 v1, v3
	v_lshl_add_u64 v[4:5], v[4:5], 0, v[0:1]
	global_load_dwordx4 v[88:91], v[4:5], off
	global_load_dwordx4 v[92:95], v[4:5], off offset:32
	global_load_dwordx4 v[96:99], v[4:5], off offset:64
	global_load_dwordx4 v[100:103], v[4:5], off offset:96
	s_cmp_gt_u32 s3, 63
	s_mov_b32 s71, 0x9000
	s_cbranch_scc1 .LBB0_916
	v_cmp_gt_u32_e32 vcc, 32, v134
	v_mov_b32_e32 v1, 0
	s_and_saveexec_b64 s[0:1], vcc
	s_cbranch_execz .LBB0_913
	v_lshlrev_b32_e32 v1, 4, v133
	v_readlane_b32 s4, v249, 62
	v_readlane_b32 s5, v249, 63
	s_nop 0
	v_lshl_or_b32 v1, s4, 9, v1
	v_readlane_b32 s4, v249, 60
	s_nop 1
	v_or_b32_e32 v4, s4, v1
	v_readlane_b32 s4, v249, 51
	v_ashrrev_i32_e32 v5, 31, v4
	v_readlane_b32 s5, v249, 52
	s_nop 1
	v_lshl_add_u64 v[4:5], v[4:5], 2, s[4:5]
	global_load_dword v1, v[4:5], off

.LBB0_938:
	s_nop 2
	v_mov_b32_e32 v1, v36
	s_nop 1
	v_permlane32_swap_b32_e32 v36, v1
	v_add_f32_e32 v1, v36, v1
	v_div_scale_f32 v2, s[0:1], v1, v1, 1.0
	v_rcp_f32_e32 v3, v2
	s_mulk_i32 s70, 0x1200
	s_add_i32 s2, s70, 0
	s_waitcnt vmcnt(0) lgkmcnt(0)
	s_barrier
	v_fma_f32 v36, -v2, v3, 1.0
	v_fmac_f32_e32 v3, v36, v3
	v_div_scale_f32 v36, vcc, 1.0, v1, 1.0
	v_mul_f32_e32 v37, v36, v3
	v_fma_f32 v38, -v2, v37, v36
	v_fmac_f32_e32 v37, v38, v3
	v_fma_f32 v2, -v2, v37, v36
	v_div_fmas_f32 v2, v2, v3, v37
	v_div_fixup_f32 v2, v2, v1, 1.0
	v_pk_mul_f32 v[4:5], v[4:5], v[2:3] op_sel_hi:[1,0]
	v_pk_mul_f32 v[6:7], v[6:7], v[2:3] op_sel_hi:[1,0]
	v_add3_u32 v1, s2, v136, v124
	v_cvt_pk_bf16_f32 v4, v4, v5
	v_cvt_pk_bf16_f32 v5, v6, v7
	v_pk_mul_f32 v[6:7], v[8:9], v[2:3] op_sel_hi:[1,0]
	v_pk_mul_f32 v[8:9], v[10:11], v[2:3] op_sel_hi:[1,0]
	v_cvt_pk_bf16_f32 v6, v6, v7
	v_cvt_pk_bf16_f32 v7, v8, v9
	v_add_u32_e32 v1, 0x9000, v1
	ds_write2_b64 v1, v[4:5], v[6:7] offset1:2
	v_pk_mul_f32 v[4:5], v[12:13], v[2:3] op_sel_hi:[1,0]
	v_pk_mul_f32 v[6:7], v[14:15], v[2:3] op_sel_hi:[1,0]
	v_cvt_pk_bf16_f32 v4, v4, v5
	v_cvt_pk_bf16_f32 v5, v6, v7
	v_pk_mul_f32 v[6:7], v[16:17], v[2:3] op_sel_hi:[1,0]
	v_pk_mul_f32 v[8:9], v[18:19], v[2:3] op_sel_hi:[1,0]
	v_cvt_pk_bf16_f32 v6, v6, v7
	v_cvt_pk_bf16_f32 v7, v8, v9
	ds_write2_b64 v1, v[4:5], v[6:7] offset0:4 offset1:6
	v_pk_mul_f32 v[4:5], v[20:21], v[2:3] op_sel_hi:[1,0]
	v_pk_mul_f32 v[6:7], v[22:23], v[2:3] op_sel_hi:[1,0]
	v_cvt_pk_bf16_f32 v4, v4, v5
	v_cvt_pk_bf16_f32 v5, v6, v7
	v_pk_mul_f32 v[6:7], v[24:25], v[2:3] op_sel_hi:[1,0]
	v_pk_mul_f32 v[8:9], v[26:27], v[2:3] op_sel_hi:[1,0]
	v_cvt_pk_bf16_f32 v6, v6, v7
	v_cvt_pk_bf16_f32 v7, v8, v9
	ds_write2_b64 v1, v[4:5], v[6:7] offset0:8 offset1:10
	v_pk_mul_f32 v[4:5], v[28:29], v[2:3] op_sel_hi:[1,0]
	v_pk_mul_f32 v[6:7], v[30:31], v[2:3] op_sel_hi:[1,0]
	v_cvt_pk_bf16_f32 v4, v4, v5
	v_cvt_pk_bf16_f32 v5, v6, v7
	v_pk_mul_f32 v[6:7], v[32:33], v[2:3] op_sel_hi:[1,0]
	v_pk_mul_f32 v[2:3], v[34:35], v[2:3] op_sel_hi:[1,0]
	v_cvt_pk_bf16_f32 v6, v6, v7
	v_cvt_pk_bf16_f32 v7, v2, v3
	ds_write2_b64 v1, v[4:5], v[6:7] offset0:12 offset1:14
	s_lshl_b64 s[0:1], s[78:79], 11
	v_readlane_b32 s4, v249, 53
	s_waitcnt lgkmcnt(0)
	v_readlane_b32 s5, v249, 54
	s_add_u32 s0, s4, s0
	v_add3_u32 v14, s2, v110, v111
	s_addc_u32 s1, s5, s1
	ds_read_b128 v[2:5], v14 offset:36864
	s_add_u32 s0, s0, s74
	v_mov_b32_e32 v1, 0
	ds_read_b128 v[6:9], v14 offset:38016
	s_addc_u32 s1, s1, 0
	v_mov_b32_e32 v119, v1
	v_lshl_add_u64 v[10:11], s[0:1], 0, v[118:119]
	v_mov_b32_e32 v121, v1
	v_lshl_add_u64 v[12:13], v[10:11], 0, v[120:121]
	v_mov_b32_e32 v115, v1
	s_waitcnt lgkmcnt(0)
	global_store_dwordx4 v[12:13], v[2:5], off
	v_lshl_add_u64 v[12:13], v[10:11], 0, v[114:115]
	ds_read_b128 v[2:5], v14 offset:39168
	global_store_dwordx4 v[12:13], v[6:9], off
	ds_read_b128 v[6:9], v14 offset:40320
	v_readfirstlane_b32 s2, v222
	s_lshr_b32 s70, s2, 6
	v_readlane_b32 s8, v248, 7
	v_readlane_b32 s0, v249, 58
	v_mov_b32_e32 v113, v1
	s_lshl_b32 s76, s70, 5
	s_or_b32 s0, s8, s0
	v_lshl_add_u64 v[12:13], v[10:11], 0, v[112:113]
	v_mov_b32_e32 v117, v1
	v_readlane_b32 s9, v248, 8
	s_add_u32 s78, s0, s76
	s_waitcnt lgkmcnt(0)
	global_store_dwordx4 v[12:13], v[2:5], off
	s_addc_u32 s79, s9, 0
	s_mov_b32 s77, 0
	v_lshl_add_u64 v[2:3], v[10:11], 0, v[116:117]
	global_store_dwordx4 v[2:3], v[6:9], off
	v_mov_b32_e32 v3, s79
	v_or_b32_e32 v2, s78, v133
	v_lshlrev_b64 v[2:3], 11, v[2:3]
	s_mov_b32 s75, s77
	v_lshl_add_u64 v[2:3], s[4:5], 0, v[2:3]
	v_lshl_add_u64 v[2:3], v[2:3], 0, s[74:75]
	v_lshl_add_u64 v[2:3], v[2:3], 0, v[0:1]
	global_load_dwordx4 v[88:91], v[2:3], off
	global_load_dwordx4 v[92:95], v[2:3], off offset:32
	global_load_dwordx4 v[96:99], v[2:3], off offset:64
	global_load_dwordx4 v[100:103], v[2:3], off offset:96
	s_cmp_gt_u32 s2, 63
	s_mov_b32 s69, 0x9000
	s_cbranch_scc1 .LBB0_944
	v_cmp_gt_u32_e32 vcc, 32, v134
	v_mov_b32_e32 v0, 0
	s_and_saveexec_b64 s[0:1], vcc
	s_cbranch_execz .LBB0_941
	v_lshlrev_b32_e32 v0, 4, v133
	v_readlane_b32 s4, v249, 62
	v_readlane_b32 s5, v249, 63
	v_readlane_b32 s3, v249, 60
	v_lshl_or_b32 v0, s4, 9, v0
	v_readlane_b32 s4, v249, 51
	v_or_b32_e32 v2, s3, v0
	v_ashrrev_i32_e32 v3, 31, v2
	v_readlane_b32 s5, v249, 52
	s_nop 1
	v_lshl_add_u64 v[2:3], v[2:3], 2, s[4:5]
	global_load_dword v0, v[2:3], off

.LBB0_946:
	s_add_i32 s93, s0, 0
	s_lshl_b32 s0, s1, 1
	s_and_b32 s0, s0, -4
	s_add_i32 s94, s0, 0
	s_add_i32 s94, s94, 0x1b000
	s_cmp_le_u32 s77, s33
	v_lshl_add_u32 v121, v132, 2, s93
	s_cselect_b64 s[0:1], -1, 0
	s_cmp_gt_u32 s77, s33
	v_add_u32_e32 v119, s93, v125
	v_add_u32_e32 v117, s93, v126
	v_add_u32_e32 v115, s93, v127
	v_add_u32_e32 v0, s93, v128
	s_cbranch_scc1 .LBB0_949
	v_mov_b32_e32 v50, s94
	ds_read_b32 v58, v50
	v_sub_f32_e32 v59, v82, v113
	ds_read_b128 v[74:77], v121 offset:32832
	ds_read_b128 v[50:53], v121 offset:32768
	ds_read_b128 v[54:57], v121 offset:32800
	s_waitcnt lgkmcnt(0)
	v_sub_f32_e32 v122, v59, v58
	ds_read_b128 v[58:61], v121 offset:32864
	ds_read_b128 v[142:145], v117
	v_sub_f32_e32 v53, v122, v53
	v_sub_f32_e32 v57, v122, v57
	v_sub_f32_e32 v56, v122, v56
	s_waitcnt lgkmcnt(0)
	v_sub_f32_e32 v65, v122, v61
	v_sub_f32_e32 v64, v122, v60
	v_sub_f32_e32 v63, v122, v59
	v_sub_f32_e32 v62, v122, v58
	v_sub_f32_e32 v61, v122, v77
	v_sub_f32_e32 v60, v122, v76
	v_sub_f32_e32 v59, v122, v75
	v_sub_f32_e32 v58, v122, v74
	ds_read_b128 v[74:77], v119
	v_sub_f32_e32 v55, v122, v55
	v_sub_f32_e32 v54, v122, v54
	v_sub_f32_e32 v52, v122, v52
	v_sub_f32_e32 v51, v122, v51
	v_sub_f32_e32 v50, v122, v50
	ds_read_b128 v[66:69], v121 offset:32896
	ds_read_b128 v[70:73], v121 offset:32928
	ds_read_b128 v[138:141], v121 offset:32960
	ds_read_b128 v[78:81], v121 offset:32992
	ds_read_b128 v[146:149], v115
	s_waitcnt lgkmcnt(0)
	v_mfma_f32_32x32x16_bf16 v[50:65], v[74:77], v[88:91], v[50:65]
	ds_read_b128 v[150:153], v0
	v_sub_f32_e32 v77, v122, v141
	v_sub_f32_e32 v76, v122, v140
	v_sub_f32_e32 v75, v122, v139
	v_sub_f32_e32 v74, v122, v138
	v_sub_f32_e32 v81, v122, v81
	v_sub_f32_e32 v80, v122, v80
	v_mfma_f32_32x32x16_bf16 v[50:65], v[142:145], v[92:95], v[50:65]
	ds_read_b128 v[138:141], v119 offset:4096
	v_sub_f32_e32 v79, v122, v79
	v_sub_f32_e32 v78, v122, v78
	v_sub_f32_e32 v73, v122, v73
	v_sub_f32_e32 v72, v122, v72
	v_sub_f32_e32 v71, v122, v71
	v_sub_f32_e32 v70, v122, v70
	v_mfma_f32_32x32x16_bf16 v[50:65], v[146:149], v[96:99], v[50:65]
	v_sub_f32_e32 v69, v122, v69
	v_sub_f32_e32 v68, v122, v68
	v_sub_f32_e32 v67, v122, v67
	v_sub_f32_e32 v66, v122, v66
	ds_read_b128 v[142:145], v117 offset:4096
	s_cmp_lg_u32 s33, s77
	s_waitcnt lgkmcnt(0)
	v_mfma_f32_32x32x16_bf16 v[66:81], v[138:141], v[88:91], v[66:81]
	ds_read_b128 v[138:141], v115 offset:4096
	v_mfma_f32_32x32x16_bf16 v[66:81], v[142:145], v[92:95], v[66:81]
	s_waitcnt lgkmcnt(0)
	v_mfma_f32_32x32x16_bf16 v[66:81], v[138:141], v[96:99], v[66:81]
	ds_read_b128 v[138:141], v0 offset:4096
	s_waitcnt lgkmcnt(0)
	v_mfma_f32_32x32x16_bf16 v[66:81], v[138:141], v[100:103], v[66:81]
	v_mfma_f32_32x32x16_bf16 v[50:65], v[150:153], v[100:103], v[50:65]
	s_cbranch_scc1 .LBB0_949
	s_nop 10
	v_cndmask_b32_e64 v122, v50, v109, s[2:3]
	v_cndmask_b32_e64 v66, v66, v109, s[4:5]
	v_cndmask_b32_e64 v50, v122, v50, s[6:7]
	v_cndmask_b32_e64 v51, v109, v51, s[6:7]
	v_cndmask_b32_e64 v67, v67, v109, s[8:9]
	v_cndmask_b32_e64 v52, v52, v109, s[10:11]
	v_cndmask_b32_e64 v68, v68, v109, s[12:13]
	v_cndmask_b32_e64 v53, v53, v109, s[14:15]
	v_cndmask_b32_e64 v69, v69, v109, s[16:17]
	v_cndmask_b32_e64 v54, v54, v109, s[18:19]
	v_cndmask_b32_e64 v70, v70, v109, s[20:21]
	v_cndmask_b32_e64 v55, v55, v109, s[22:23]
	v_cndmask_b32_e64 v71, v71, v109, s[24:25]
	v_cndmask_b32_e64 v56, v56, v109, s[26:27]
	v_cndmask_b32_e64 v72, v72, v109, s[28:29]
	v_cndmask_b32_e64 v57, v57, v109, s[30:31]
	v_cndmask_b32_e64 v73, v73, v109, s[34:35]
	v_cndmask_b32_e64 v58, v58, v109, s[36:37]
	v_cndmask_b32_e64 v74, v74, v109, s[38:39]
	v_cndmask_b32_e64 v59, v59, v109, s[40:41]
	v_cndmask_b32_e64 v75, v75, v109, s[42:43]
	v_cndmask_b32_e64 v60, v60, v109, s[44:45]
	v_cndmask_b32_e64 v76, v76, v109, s[46:47]
	v_cndmask_b32_e64 v61, v61, v109, s[48:49]
	v_cndmask_b32_e64 v77, v77, v109, s[50:51]
	v_cndmask_b32_e64 v62, v62, v109, s[52:53]
	v_cndmask_b32_e64 v78, v78, v109, s[54:55]
	v_cndmask_b32_e64 v63, v63, v109, s[56:57]
	v_cndmask_b32_e64 v79, v79, v109, s[58:59]
	v_cndmask_b32_e64 v64, v64, v109, s[60:61]
	v_cndmask_b32_e64 v80, v80, v109, s[62:63]
	v_cndmask_b32_e64 v65, v65, v109, s[64:65]
	v_cndmask_b32_e64 v81, v81, v109, s[66:67]

.LBB0_954:
	v_exp_f32_e32 v66, v66
	v_exp_f32_e32 v67, v67
	v_exp_f32_e32 v68, v68
	v_exp_f32_e32 v69, v69
	ds_read_b64_tr_b16 v[138:139], v123 offset:20480
	ds_read_b64_tr_b16 v[140:141], v123 offset:21504
	v_exp_f32_e32 v70, v70
	v_exp_f32_e32 v71, v71
	v_exp_f32_e32 v72, v72
	v_exp_f32_e32 v73, v73
	v_cvt_pk_bf16_f32 v142, v66, v67
	v_cvt_pk_bf16_f32 v143, v68, v69
	v_cvt_pk_bf16_f32 v144, v70, v71
	v_cvt_pk_bf16_f32 v145, v72, v73
	v_exp_f32_e32 v74, v74
	v_exp_f32_e32 v75, v75
	s_waitcnt lgkmcnt(0)
	v_mfma_f32_32x32x16_bf16 v[2:17], v[138:141], v[142:145], v[2:17]
	ds_read_b64_tr_b16 v[138:139], v122 offset:20480
	ds_read_b64_tr_b16 v[140:141], v122 offset:21504
	v_exp_f32_e32 v76, v76
	v_exp_f32_e32 v77, v77
	v_exp_f32_e32 v78, v78
	v_exp_f32_e32 v79, v79
	v_exp_f32_e32 v80, v80
	v_exp_f32_e32 v81, v81
	s_waitcnt lgkmcnt(0)
	v_mfma_f32_32x32x16_bf16 v[18:33], v[138:141], v[142:145], v[18:33]
	ds_read_b64_tr_b16 v[138:139], v123 offset:22528
	ds_read_b64_tr_b16 v[140:141], v123 offset:23552
	v_mfma_f32_32x32x16_bf16 v[34:49], v[84:87], v[142:145], v[34:49]
	v_cvt_pk_bf16_f32 v142, v74, v75
	v_cvt_pk_bf16_f32 v143, v76, v77
	v_cvt_pk_bf16_f32 v144, v78, v79
	v_cvt_pk_bf16_f32 v145, v80, v81
	s_waitcnt lgkmcnt(0)
	s_nop 0
	v_mfma_f32_32x32x16_bf16 v[2:17], v[138:141], v[142:145], v[2:17]
	ds_read_b64_tr_b16 v[138:139], v122 offset:22528
	ds_read_b64_tr_b16 v[140:141], v122 offset:23552
	s_waitcnt lgkmcnt(0)
	v_mfma_f32_32x32x16_bf16 v[18:33], v[138:141], v[142:145], v[18:33]
	v_mfma_f32_32x32x16_bf16 v[34:49], v[84:87], v[142:145], v[34:49]
.LBB0_955:
	s_cmp_lt_u32 s77, s33
	s_cselect_b64 s[0:1], -1, 0
	s_cmp_ge_u32 s77, s33
	s_cbranch_scc1 .LBB0_958
	s_nop 4
	v_mov_b32_e32 v50, s94
	ds_read_b32 v58, v50
	v_sub_f32_e32 v59, v82, v113
	ds_read_b128 v[74:77], v121 offset:33088
	ds_read_b128 v[50:53], v121 offset:33024
	ds_read_b128 v[54:57], v121 offset:33056
	s_waitcnt lgkmcnt(0)
	v_sub_f32_e32 v122, v59, v58
	ds_read_b128 v[58:61], v121 offset:33120
	ds_read_b128 v[142:145], v117 offset:8192
	v_sub_f32_e32 v53, v122, v53
	v_sub_f32_e32 v57, v122, v57
	v_sub_f32_e32 v56, v122, v56
	s_waitcnt lgkmcnt(0)
	v_sub_f32_e32 v65, v122, v61
	v_sub_f32_e32 v64, v122, v60
	v_sub_f32_e32 v63, v122, v59
	v_sub_f32_e32 v62, v122, v58
	v_sub_f32_e32 v61, v122, v77
	v_sub_f32_e32 v60, v122, v76
	v_sub_f32_e32 v59, v122, v75
	v_sub_f32_e32 v58, v122, v74
	ds_read_b128 v[74:77], v119 offset:8192
	v_sub_f32_e32 v55, v122, v55
	v_sub_f32_e32 v54, v122, v54
	v_sub_f32_e32 v52, v122, v52
	v_sub_f32_e32 v51, v122, v51
	v_sub_f32_e32 v50, v122, v50
	ds_read_b128 v[66:69], v121 offset:33152
	ds_read_b128 v[70:73], v121 offset:33184
	ds_read_b128 v[138:141], v121 offset:33216
	ds_read_b128 v[78:81], v121 offset:33248
	ds_read_b128 v[146:149], v115 offset:8192
	s_waitcnt lgkmcnt(0)
	v_mfma_f32_32x32x16_bf16 v[50:65], v[74:77], v[88:91], v[50:65]
	ds_read_b128 v[150:153], v0 offset:8192
	v_sub_f32_e32 v77, v122, v141
	v_sub_f32_e32 v76, v122, v140
	v_sub_f32_e32 v75, v122, v139
	v_sub_f32_e32 v74, v122, v138
	v_sub_f32_e32 v81, v122, v81
	v_sub_f32_e32 v80, v122, v80
	v_mfma_f32_32x32x16_bf16 v[50:65], v[142:145], v[92:95], v[50:65]
	ds_read_b128 v[138:141], v119 offset:12288
	v_sub_f32_e32 v79, v122, v79
	v_sub_f32_e32 v78, v122, v78
	v_sub_f32_e32 v73, v122, v73
	v_sub_f32_e32 v72, v122, v72
	v_sub_f32_e32 v71, v122, v71
	v_sub_f32_e32 v70, v122, v70
	v_mfma_f32_32x32x16_bf16 v[50:65], v[146:149], v[96:99], v[50:65]
	v_sub_f32_e32 v69, v122, v69
	v_sub_f32_e32 v68, v122, v68
	v_sub_f32_e32 v67, v122, v67
	v_sub_f32_e32 v66, v122, v66
	ds_read_b128 v[142:145], v117 offset:12288
	s_cmp_lg_u32 s68, s77
	s_waitcnt lgkmcnt(0)
	v_mfma_f32_32x32x16_bf16 v[66:81], v[138:141], v[88:91], v[66:81]
	ds_read_b128 v[138:141], v115 offset:12288
	v_mfma_f32_32x32x16_bf16 v[66:81], v[142:145], v[92:95], v[66:81]
	s_waitcnt lgkmcnt(0)
	v_mfma_f32_32x32x16_bf16 v[66:81], v[138:141], v[96:99], v[66:81]
	ds_read_b128 v[138:141], v0 offset:12288
	s_waitcnt lgkmcnt(0)
	v_mfma_f32_32x32x16_bf16 v[66:81], v[138:141], v[100:103], v[66:81]
	v_mfma_f32_32x32x16_bf16 v[50:65], v[150:153], v[100:103], v[50:65]
	s_cbranch_scc1 .LBB0_958
	s_nop 10
	v_cndmask_b32_e64 v0, v50, v109, s[2:3]
	v_cndmask_b32_e64 v66, v66, v109, s[4:5]
	v_cndmask_b32_e64 v50, v0, v50, s[6:7]
	v_cndmask_b32_e64 v51, v109, v51, s[6:7]
	v_cndmask_b32_e64 v67, v67, v109, s[8:9]
	v_cndmask_b32_e64 v52, v52, v109, s[10:11]
	v_cndmask_b32_e64 v68, v68, v109, s[12:13]
	v_cndmask_b32_e64 v53, v53, v109, s[14:15]
	v_cndmask_b32_e64 v69, v69, v109, s[16:17]
	v_cndmask_b32_e64 v54, v54, v109, s[18:19]
	v_cndmask_b32_e64 v70, v70, v109, s[20:21]
	v_cndmask_b32_e64 v55, v55, v109, s[22:23]
	v_cndmask_b32_e64 v71, v71, v109, s[24:25]
	v_cndmask_b32_e64 v56, v56, v109, s[26:27]
	v_cndmask_b32_e64 v72, v72, v109, s[28:29]
	v_cndmask_b32_e64 v57, v57, v109, s[30:31]
	v_cndmask_b32_e64 v73, v73, v109, s[34:35]
	v_cndmask_b32_e64 v58, v58, v109, s[36:37]
	v_cndmask_b32_e64 v74, v74, v109, s[38:39]
	v_cndmask_b32_e64 v59, v59, v109, s[40:41]
	v_cndmask_b32_e64 v75, v75, v109, s[42:43]
	v_cndmask_b32_e64 v60, v60, v109, s[44:45]
	v_cndmask_b32_e64 v76, v76, v109, s[46:47]
	v_cndmask_b32_e64 v61, v61, v109, s[48:49]
	v_cndmask_b32_e64 v77, v77, v109, s[50:51]
	v_cndmask_b32_e64 v62, v62, v109, s[52:53]
	v_cndmask_b32_e64 v78, v78, v109, s[54:55]
	v_cndmask_b32_e64 v63, v63, v109, s[56:57]
	v_cndmask_b32_e64 v79, v79, v109, s[58:59]
	v_cndmask_b32_e64 v64, v64, v109, s[60:61]
	v_cndmask_b32_e64 v80, v80, v109, s[62:63]
	v_cndmask_b32_e64 v65, v65, v109, s[64:65]
	v_cndmask_b32_e64 v81, v81, v109, s[66:67]

.LBB0_963:
	v_exp_f32_e32 v66, v66
	v_exp_f32_e32 v67, v67
	v_exp_f32_e32 v68, v68
	v_exp_f32_e32 v69, v69
	ds_read_b64_tr_b16 v[138:139], v115 offset:28672
	ds_read_b64_tr_b16 v[140:141], v115 offset:29696
	v_exp_f32_e32 v70, v70
	v_exp_f32_e32 v71, v71
	v_exp_f32_e32 v72, v72
	v_exp_f32_e32 v73, v73
	v_cvt_pk_bf16_f32 v142, v66, v67
	v_cvt_pk_bf16_f32 v143, v68, v69
	v_cvt_pk_bf16_f32 v144, v70, v71
	v_cvt_pk_bf16_f32 v145, v72, v73
	v_exp_f32_e32 v74, v74
	v_exp_f32_e32 v75, v75
	s_waitcnt lgkmcnt(0)
	v_mfma_f32_32x32x16_bf16 v[2:17], v[138:141], v[142:145], v[2:17]
	ds_read_b64_tr_b16 v[138:139], v0 offset:28672
	ds_read_b64_tr_b16 v[140:141], v0 offset:29696
	v_exp_f32_e32 v76, v76
	v_exp_f32_e32 v77, v77
	v_exp_f32_e32 v78, v78
	v_exp_f32_e32 v79, v79
	v_exp_f32_e32 v80, v80
	v_exp_f32_e32 v81, v81
	s_waitcnt lgkmcnt(0)
	v_mfma_f32_32x32x16_bf16 v[18:33], v[138:141], v[142:145], v[18:33]
	ds_read_b64_tr_b16 v[138:139], v115 offset:30720
	ds_read_b64_tr_b16 v[140:141], v115 offset:31744
	v_mfma_f32_32x32x16_bf16 v[34:49], v[84:87], v[142:145], v[34:49]
	v_cvt_pk_bf16_f32 v142, v74, v75
	v_cvt_pk_bf16_f32 v143, v76, v77
	v_cvt_pk_bf16_f32 v144, v78, v79
	v_cvt_pk_bf16_f32 v145, v80, v81
	s_waitcnt lgkmcnt(0)
	s_nop 0
	v_mfma_f32_32x32x16_bf16 v[2:17], v[138:141], v[142:145], v[2:17]
	ds_read_b64_tr_b16 v[138:139], v0 offset:30720
	ds_read_b64_tr_b16 v[140:141], v0 offset:31744
	s_waitcnt lgkmcnt(0)
	v_mfma_f32_32x32x16_bf16 v[18:33], v[138:141], v[142:145], v[18:33]
	v_mfma_f32_32x32x16_bf16 v[34:49], v[84:87], v[142:145], v[34:49]

.LBB0_966:
	s_nop 2
	v_mov_b32_e32 v0, v34
	s_nop 1
	v_permlane32_swap_b32_e32 v34, v0
	v_add_f32_e32 v0, v34, v0
	v_div_scale_f32 v1, s[0:1], v0, v0, 1.0
	v_rcp_f32_e32 v34, v1
	s_mulk_i32 s70, 0x1200
	s_add_i32 s2, s70, 0
	s_waitcnt vmcnt(0) lgkmcnt(0)
	s_barrier
	v_fma_f32 v35, -v1, v34, 1.0
	v_fmac_f32_e32 v34, v35, v34
	v_div_scale_f32 v35, vcc, 1.0, v0, 1.0
	v_mul_f32_e32 v36, v35, v34
	v_fma_f32 v37, -v1, v36, v35
	v_fmac_f32_e32 v36, v37, v34
	v_fma_f32 v1, -v1, v36, v35
	v_div_fmas_f32 v1, v1, v34, v36
	v_div_fixup_f32 v0, v1, v0, 1.0
	v_add3_u32 v1, s2, v136, v124
	v_pk_mul_f32 v[2:3], v[2:3], v[0:1] op_sel_hi:[1,0]
	v_pk_mul_f32 v[4:5], v[4:5], v[0:1] op_sel_hi:[1,0]
	v_cvt_pk_bf16_f32 v2, v2, v3
	v_cvt_pk_bf16_f32 v3, v4, v5
	v_pk_mul_f32 v[4:5], v[6:7], v[0:1] op_sel_hi:[1,0]
	v_pk_mul_f32 v[6:7], v[8:9], v[0:1] op_sel_hi:[1,0]
	v_cvt_pk_bf16_f32 v4, v4, v5
	v_cvt_pk_bf16_f32 v5, v6, v7
	v_add_u32_e32 v8, 0x9000, v1
	ds_write2_b64 v8, v[2:3], v[4:5] offset1:2
	v_pk_mul_f32 v[2:3], v[10:11], v[0:1] op_sel_hi:[1,0]
	v_pk_mul_f32 v[4:5], v[12:13], v[0:1] op_sel_hi:[1,0]
	v_cvt_pk_bf16_f32 v2, v2, v3
	v_cvt_pk_bf16_f32 v3, v4, v5
	v_pk_mul_f32 v[4:5], v[14:15], v[0:1] op_sel_hi:[1,0]
	v_pk_mul_f32 v[6:7], v[16:17], v[0:1] op_sel_hi:[1,0]
	v_cvt_pk_bf16_f32 v4, v4, v5
	v_cvt_pk_bf16_f32 v5, v6, v7
	ds_write2_b64 v8, v[2:3], v[4:5] offset0:4 offset1:6
	v_pk_mul_f32 v[2:3], v[18:19], v[0:1] op_sel_hi:[1,0]
	v_pk_mul_f32 v[4:5], v[20:21], v[0:1] op_sel_hi:[1,0]
	v_cvt_pk_bf16_f32 v2, v2, v3
	v_cvt_pk_bf16_f32 v3, v4, v5
	v_pk_mul_f32 v[4:5], v[22:23], v[0:1] op_sel_hi:[1,0]
	v_pk_mul_f32 v[6:7], v[24:25], v[0:1] op_sel_hi:[1,0]
	v_cvt_pk_bf16_f32 v4, v4, v5
	v_cvt_pk_bf16_f32 v5, v6, v7
	ds_write2_b64 v8, v[2:3], v[4:5] offset0:8 offset1:10
	v_pk_mul_f32 v[2:3], v[26:27], v[0:1] op_sel_hi:[1,0]
	v_pk_mul_f32 v[4:5], v[28:29], v[0:1] op_sel_hi:[1,0]
	v_cvt_pk_bf16_f32 v2, v2, v3
	v_cvt_pk_bf16_f32 v3, v4, v5
	v_pk_mul_f32 v[4:5], v[30:31], v[0:1] op_sel_hi:[1,0]
	v_pk_mul_f32 v[0:1], v[32:33], v[0:1] op_sel_hi:[1,0]
	v_cvt_pk_bf16_f32 v4, v4, v5
	v_cvt_pk_bf16_f32 v5, v0, v1
	ds_write2_b64 v8, v[2:3], v[4:5] offset0:12 offset1:14
	s_lshl_b64 s[0:1], s[78:79], 11
	v_readlane_b32 s4, v249, 53
	s_waitcnt lgkmcnt(0)
	v_readlane_b32 s5, v249, 54
	s_add_u32 s0, s4, s0
	v_add3_u32 v12, s2, v110, v111
	s_addc_u32 s1, s5, s1
	ds_read_b128 v[0:3], v12 offset:36864
	s_add_u32 s0, s0, s74
	ds_read_b128 v[4:7], v12 offset:38016
	s_addc_u32 s1, s1, 0
	v_mov_b32_e32 v119, 0
	v_lshl_add_u64 v[8:9], s[0:1], 0, v[118:119]
	v_mov_b32_e32 v121, v119
	v_lshl_add_u64 v[10:11], v[8:9], 0, v[120:121]
	v_mov_b32_e32 v115, v119
	s_waitcnt lgkmcnt(0)
	global_store_dwordx4 v[10:11], v[0:3], off
	v_lshl_add_u64 v[10:11], v[8:9], 0, v[114:115]
	ds_read_b128 v[0:3], v12 offset:39168
	global_store_dwordx4 v[10:11], v[4:7], off
	ds_read_b128 v[4:7], v12 offset:40320
	v_mov_b32_e32 v113, v119
	v_lshl_add_u64 v[10:11], v[8:9], 0, v[112:113]
	v_mov_b32_e32 v117, v119
	v_readlane_b32 s74, v249, 28
	v_readlane_b32 s2, v249, 56
	s_waitcnt lgkmcnt(0)
	global_store_dwordx4 v[10:11], v[0:3], off
	v_readlane_b32 s90, v249, 55
	v_readlane_b32 s68, v249, 27
	v_lshl_add_u64 v[0:1], v[8:9], 0, v[116:117]
	v_readlane_b32 s75, v249, 29
	v_readlane_b32 s3, v249, 57
	global_store_dwordx4 v[0:1], v[4:7], off

.LBB0_1758:
	v_mov_b32_e32 v48, v163
	s_nop 1
	v_permlane32_swap_b32_e32 v163, v48
	v_add_f32_e32 v48, v163, v48
	v_div_scale_f32 v49, s[2:3], v48, v48, 1.0
	v_rcp_f32_e32 v50, v49
	s_mulk_i32 s24, 0x2200
	s_add_i32 s8, s24, 0
	s_waitcnt vmcnt(0) lgkmcnt(0)
	s_barrier
	v_fma_f32 v51, -v49, v50, 1.0
	v_fmac_f32_e32 v50, v51, v50
	v_div_scale_f32 v51, vcc, 1.0, v48, 1.0
	v_mul_f32_e32 v52, v51, v50
	v_fma_f32 v53, -v49, v52, v51
	v_fmac_f32_e32 v52, v53, v50
	v_fma_f32 v49, -v49, v52, v51
	v_div_fmas_f32 v49, v49, v50, v52
	v_div_fixup_f32 v48, v49, v48, 1.0
	v_add3_u32 v49, s8, v184, v148
	v_pk_mul_f32 v[50:51], v[64:65], v[48:49] op_sel_hi:[1,0]
	v_pk_mul_f32 v[52:53], v[66:67], v[48:49] op_sel_hi:[1,0]
	v_cvt_pk_bf16_f32 v50, v50, v51
	v_cvt_pk_bf16_f32 v51, v52, v53
	v_pk_mul_f32 v[52:53], v[68:69], v[48:49] op_sel_hi:[1,0]
	v_pk_mul_f32 v[54:55], v[70:71], v[48:49] op_sel_hi:[1,0]
	v_add_u32_e32 v49, 0xa000, v49
	v_pk_mul_f32 v[32:33], v[32:33], v[48:49] op_sel_hi:[1,0]
	v_pk_mul_f32 v[34:35], v[34:35], v[48:49] op_sel_hi:[1,0]
	v_pk_mul_f32 v[16:17], v[16:17], v[48:49] op_sel_hi:[1,0]
	v_pk_mul_f32 v[18:19], v[18:19], v[48:49] op_sel_hi:[1,0]
	v_pk_mul_f32 v[0:1], v[0:1], v[48:49] op_sel_hi:[1,0]
	v_pk_mul_f32 v[2:3], v[2:3], v[48:49] op_sel_hi:[1,0]
	v_cvt_pk_bf16_f32 v32, v32, v33
	v_cvt_pk_bf16_f32 v33, v34, v35
	v_pk_mul_f32 v[34:35], v[36:37], v[48:49] op_sel_hi:[1,0]
	v_pk_mul_f32 v[36:37], v[38:39], v[48:49] op_sel_hi:[1,0]
	v_cvt_pk_bf16_f32 v16, v16, v17
	v_cvt_pk_bf16_f32 v17, v18, v19
	v_pk_mul_f32 v[18:19], v[20:21], v[48:49] op_sel_hi:[1,0]
	v_pk_mul_f32 v[20:21], v[22:23], v[48:49] op_sel_hi:[1,0]
	v_cvt_pk_bf16_f32 v0, v0, v1
	v_cvt_pk_bf16_f32 v1, v2, v3
	v_pk_mul_f32 v[2:3], v[4:5], v[48:49] op_sel_hi:[1,0]
	v_pk_mul_f32 v[4:5], v[6:7], v[48:49] op_sel_hi:[1,0]
	v_cvt_pk_bf16_f32 v52, v52, v53
	v_cvt_pk_bf16_f32 v53, v54, v55
	v_cvt_pk_bf16_f32 v34, v34, v35
	v_cvt_pk_bf16_f32 v35, v36, v37
	v_cvt_pk_bf16_f32 v18, v18, v19
	v_cvt_pk_bf16_f32 v19, v20, v21
	v_cvt_pk_bf16_f32 v2, v2, v3
	v_cvt_pk_bf16_f32 v3, v4, v5
	ds_write2_b64 v49, v[50:51], v[52:53] offset1:2
	v_pk_mul_f32 v[50:51], v[72:73], v[48:49] op_sel_hi:[1,0]
	v_pk_mul_f32 v[52:53], v[74:75], v[48:49] op_sel_hi:[1,0]
	ds_write2_b64 v49, v[32:33], v[34:35] offset0:8 offset1:10
	v_pk_mul_f32 v[32:33], v[40:41], v[48:49] op_sel_hi:[1,0]
	v_pk_mul_f32 v[34:35], v[42:43], v[48:49] op_sel_hi:[1,0]
	ds_write2_b64 v49, v[16:17], v[18:19] offset0:16 offset1:18
	v_pk_mul_f32 v[16:17], v[24:25], v[48:49] op_sel_hi:[1,0]
	v_pk_mul_f32 v[18:19], v[26:27], v[48:49] op_sel_hi:[1,0]
	ds_write2_b64 v49, v[0:1], v[2:3] offset0:24 offset1:26
	v_pk_mul_f32 v[0:1], v[8:9], v[48:49] op_sel_hi:[1,0]
	v_pk_mul_f32 v[2:3], v[10:11], v[48:49] op_sel_hi:[1,0]
	v_cvt_pk_bf16_f32 v50, v50, v51
	v_cvt_pk_bf16_f32 v51, v52, v53
	v_pk_mul_f32 v[52:53], v[76:77], v[48:49] op_sel_hi:[1,0]
	v_pk_mul_f32 v[54:55], v[78:79], v[48:49] op_sel_hi:[1,0]
	v_cvt_pk_bf16_f32 v32, v32, v33
	v_cvt_pk_bf16_f32 v33, v34, v35
	v_pk_mul_f32 v[34:35], v[44:45], v[48:49] op_sel_hi:[1,0]
	v_pk_mul_f32 v[36:37], v[46:47], v[48:49] op_sel_hi:[1,0]
	v_cvt_pk_bf16_f32 v16, v16, v17
	v_cvt_pk_bf16_f32 v17, v18, v19
	v_pk_mul_f32 v[18:19], v[28:29], v[48:49] op_sel_hi:[1,0]
	v_pk_mul_f32 v[20:21], v[30:31], v[48:49] op_sel_hi:[1,0]
	v_cvt_pk_bf16_f32 v0, v0, v1
	v_cvt_pk_bf16_f32 v1, v2, v3
	v_pk_mul_f32 v[2:3], v[12:13], v[48:49] op_sel_hi:[1,0]
	v_pk_mul_f32 v[4:5], v[14:15], v[48:49] op_sel_hi:[1,0]
	v_cvt_pk_bf16_f32 v52, v52, v53
	v_cvt_pk_bf16_f32 v53, v54, v55
	v_cvt_pk_bf16_f32 v34, v34, v35
	v_cvt_pk_bf16_f32 v35, v36, v37
	v_cvt_pk_bf16_f32 v18, v18, v19
	v_cvt_pk_bf16_f32 v19, v20, v21
	v_cvt_pk_bf16_f32 v2, v2, v3
	v_cvt_pk_bf16_f32 v3, v4, v5
	s_mulk_i32 s23, 0x1800
	s_mul_hi_u32 s2, s22, 0x1800
	ds_write2_b64 v49, v[50:51], v[52:53] offset0:4 offset1:6
	ds_write2_b64 v49, v[32:33], v[34:35] offset0:12 offset1:14
	ds_write2_b64 v49, v[16:17], v[18:19] offset0:20 offset1:22
	ds_write2_b64 v49, v[0:1], v[2:3] offset0:28 offset1:30
	s_add_i32 s2, s2, s23
	s_mulk_i32 s22, 0x1800
	s_waitcnt lgkmcnt(0)
	s_add_u32 s3, s4, s22
	v_add3_u32 v14, s8, v185, v186
	s_addc_u32 s9, s5, s2
	ds_read_b128 v[0:3], v14 offset:40960
	s_add_u32 s2, s3, s6
	s_addc_u32 s3, s9, 0
	v_mov_b32_e32 v153, v147
	ds_read_b128 v[4:7], v14 offset:42048
	v_lshl_add_u64 v[8:9], s[2:3], 0, v[152:153]
	v_mov_b32_e32 v155, v147
	v_lshl_add_u64 v[10:11], v[8:9], 0, v[154:155]
	s_waitcnt lgkmcnt(0)
	global_store_dwordx4 v[10:11], v[0:3], off
	v_mov_b32_e32 v157, v147
	v_mov_b32_e32 v159, v147
	v_add_co_u32_e32 v0, vcc, s19, v10
	v_mov_b32_e32 v161, v147
	s_nop 0
	v_addc_co_u32_e32 v1, vcc, 0, v11, vcc
	global_store_dwordx4 v[0:1], v[4:7], off
	ds_read_b128 v[0:3], v14 offset:43136
	ds_read_b128 v[4:7], v14 offset:44224
	v_add_co_u32_e32 v12, vcc, s14, v10
	v_mov_b32_e32 v163, v147
	s_nop 0
	v_addc_co_u32_e32 v13, vcc, 0, v11, vcc
	v_add_co_u32_e32 v10, vcc, s15, v10
	s_waitcnt lgkmcnt(0)
	global_store_dwordx4 v[12:13], v[0:3], off
	v_addc_co_u32_e32 v11, vcc, 0, v11, vcc
	ds_read_b128 v[0:3], v14 offset:45312
	global_store_dwordx4 v[10:11], v[4:7], off
	ds_read_b128 v[4:7], v14 offset:46400
	v_lshl_add_u64 v[10:11], v[8:9], 0, v[156:157]
	s_add_i32 s21, s21, s96
	s_waitcnt lgkmcnt(0)
	global_store_dwordx4 v[10:11], v[0:3], off
	v_lshl_add_u64 v[10:11], v[8:9], 0, v[158:159]
	ds_read_b128 v[0:3], v14 offset:47488
	global_store_dwordx4 v[10:11], v[4:7], off
	ds_read_b128 v[4:7], v14 offset:48576
	v_lshl_add_u64 v[10:11], v[8:9], 0, v[160:161]
	s_cmpk_lt_i32 s21, 0x800
	s_waitcnt lgkmcnt(0)
	global_store_dwordx4 v[10:11], v[0:3], off
	s_nop 1
	v_lshl_add_u64 v[0:1], v[8:9], 0, v[162:163]
	global_store_dwordx4 v[0:1], v[4:7], off
	s_cbranch_scc0 .LBB0_1793
.LBB0_1759:
	s_setprio 0
	v_readfirstlane_b32 s12, v222
	s_and_b32 s6, s12, 0xffffffc0
	v_or_b32_e32 v0, s6, v145
	v_mul_hi_i32 v1, v0, s16
	v_lshrrev_b32_e32 v2, 31, v1
	v_ashrrev_i32_e32 v1, 2, v1
	v_add_u32_e32 v2, v1, v2
	s_ashr_i32 s10, s21, 9
	v_lshrrev_b32_e32 v163, 1, v2
	s_ashr_i32 s11, s10, 31
	v_mad_u64_u32 v[164:165], s[8:9], v2, s17, v[0:1]
	v_xor_b32_e32 v1, v163, v222
	s_lshl_b64 s[2:3], s[10:11], 13
	v_bfi_b32 v1, -8, v164, v1
	v_cmp_lt_i32_e32 vcc, 15, v1
	v_add_u32_e32 v2, s2, v2
	s_and_saveexec_b64 s[8:9], vcc
	s_xor_b64 s[8:9], exec, s[8:9]
	v_lshl_add_u32 v159, v2, 6, v187
	s_or_saveexec_b64 s[8:9], s[8:9]
	s_bfe_u32 s6, s21, 0x40005
	s_lshl_b32 s13, s6, 7
	v_mov_b32_e32 v153, 0x1000
	s_xor_b64 exec, exec, s[8:9]
	v_lshl_or_b32 v2, v2, 11, s13
	v_add_u32_e32 v159, 0x8000000, v2
	v_mov_b32_e32 v153, 0x20000
	s_or_b64 exec, exec, s[8:9]
	v_add_u32_e32 v2, 0x200, v0
	v_mul_hi_i32 v3, v2, s16
	v_lshrrev_b32_e32 v4, 31, v3
	v_ashrrev_i32_e32 v3, 2, v3
	v_add_u32_e32 v4, v3, v4
	v_mad_u64_u32 v[166:167], s[8:9], v4, s17, v[2:3]
	v_lshrrev_b32_e32 v167, 1, v4
	v_xor_b32_e32 v3, v167, v222
	v_bfi_b32 v3, -8, v166, v3
	v_cmp_lt_i32_e32 vcc, 15, v3
	v_add_u32_e32 v4, s2, v4
	s_and_saveexec_b64 s[8:9], vcc
	s_xor_b64 s[8:9], exec, s[8:9]
	v_lshl_add_u32 v161, v4, 6, v187
	s_or_saveexec_b64 s[8:9], s[8:9]
	v_mov_b32_e32 v155, 0x1000
	s_xor_b64 exec, exec, s[8:9]
	v_lshl_or_b32 v4, v4, 11, s13
	v_add_u32_e32 v161, 0x8000000, v4
	v_mov_b32_e32 v155, 0x20000
	s_or_b64 exec, exec, s[8:9]
	v_add_u32_e32 v4, 0x400, v0
	v_mul_hi_i32 v5, v4, s16
	v_lshrrev_b32_e32 v6, 31, v5
	v_ashrrev_i32_e32 v5, 2, v5
	v_add_u32_e32 v5, v5, v6
	v_mad_u64_u32 v[168:169], s[8:9], v5, s17, v[4:5]
	v_lshrrev_b32_e32 v169, 1, v5
	v_xor_b32_e32 v4, v169, v222
	v_bfi_b32 v4, -8, v168, v4
	v_cmp_lt_i32_e32 vcc, 15, v4
	v_add_u32_e32 v5, s2, v5
	s_and_saveexec_b64 s[8:9], vcc
	s_xor_b64 s[8:9], exec, s[8:9]
	v_lshl_add_u32 v165, v5, 6, v187
	s_or_saveexec_b64 s[8:9], s[8:9]
	v_mov_b32_e32 v157, 0x1000
	s_xor_b64 exec, exec, s[8:9]
	v_lshl_or_b32 v5, v5, 11, s13
	v_add_u32_e32 v165, 0x8000000, v5
	v_mov_b32_e32 v157, 0x20000
	s_or_b64 exec, exec, s[8:9]
	s_not_b32 s8, s21
	s_lshl_b32 s8, s8, 8
	s_lshr_b32 s24, s12, 6
	s_and_b32 s11, s8, 0x1f00
	s_lshl_b32 s26, s24, 5
	s_or_b32 s13, s13, 0xc000000
	s_or_b32 s8, s2, s11
	s_add_u32 s22, s8, s26
	v_or_b32_e32 v5, s22, v144
	v_mov_b64_e32 v[6:7], s[4:5]
	s_addc_u32 s23, s3, 0
	v_mad_u64_u32 v[6:7], s[8:9], v5, s18, v[6:7]
	s_mulk_i32 s6, 0xc0
	v_mad_i32_i24 v7, s23, v188, v7
	s_lshl_b32 s6, s6, 1
	v_lshl_add_u64 v[6:7], v[6:7], 0, s[6:7]
	v_mov_b32_e32 v151, v147
	v_lshl_add_u64 v[6:7], v[6:7], 0, v[150:151]
	v_ashrrev_i32_e32 v8, 31, v0
	v_ashrrev_i32_e32 v9, 31, v2
	global_load_dwordx4 v[96:99], v[6:7], off
	global_load_dwordx4 v[100:103], v[6:7], off offset:32
	global_load_dwordx4 v[104:107], v[6:7], off offset:64
	global_load_dwordx4 v[108:111], v[6:7], off offset:96
	global_load_dwordx4 v[112:115], v[6:7], off offset:128
	global_load_dwordx4 v[116:119], v[6:7], off offset:160
	global_load_dwordx4 v[120:123], v[6:7], off offset:192
	global_load_dwordx4 v[124:127], v[6:7], off offset:224
	global_load_dwordx4 v[128:131], v[6:7], off offset:256
	global_load_dwordx4 v[132:135], v[6:7], off offset:288
	global_load_dwordx4 v[136:139], v[6:7], off offset:320
	global_load_dwordx4 v[140:143], v[6:7], off offset:352
	v_lshl_add_u32 v6, v3, 3, v161
	v_lshl_add_u32 v4, v4, 3, v165
	v_mov_b32_e32 v7, v147
	v_mov_b32_e32 v5, v147
	v_lshrrev_b32_e32 v14, 28, v8
	v_lshrrev_b32_e32 v15, 28, v9
	v_lshl_add_u64 v[10:11], v[6:7], 1, s[84:85]
	v_lshl_add_u64 v[12:13], v[4:5], 1, s[84:85]
	v_add_u32_e32 v5, v0, v14
	v_add_u32_e32 v7, v2, v15
	v_ashrrev_i32_e32 v170, 4, v5
	v_and_b32_e32 v5, 0x1ffffff0, v5
	v_ashrrev_i32_e32 v171, 4, v7
	v_sub_u32_e32 v0, v0, v5
	v_lshlrev_b32_e32 v5, 2, v170
	v_add_lshl_u32 v15, v170, s2, 11
	v_add_lshl_u32 v17, v171, s2, 11
	s_lshl_b32 s2, s24, 10
	v_lshl_add_u32 v146, v1, 3, v159
	v_bfe_u32 v14, v170, 2, 2
	v_and_b32_e32 v5, 12, v5
	s_add_i32 s25, s2, 0
	v_lshl_add_u64 v[8:9], v[146:147], 1, s[84:85]
	v_and_b32_e32 v7, 0x1ffffff0, v7
	v_bitop3_b32 v0, v5, v0, v14 bitop3:0x36
	s_mov_b32 m0, s25
	v_sub_u32_e32 v2, v2, v7
	v_lshlrev_b32_e32 v7, 2, v171
	v_lshlrev_b32_e32 v189, 3, v0
	global_load_lds_dwordx4 v[8:9], off
	s_add_i32 m0, s25, 0x2000
	v_mov_b32_e32 v1, v147
	v_bfe_u32 v16, v171, 2, 2
	v_and_b32_e32 v7, 12, v7
	v_add3_u32 v0, s13, v15, v189
	global_load_lds_dwordx4 v[10:11], off
	s_add_i32 m0, s25, 0x4000
	v_bitop3_b32 v2, v7, v2, v16 bitop3:0x36
	v_lshl_add_u64 v[8:9], v[0:1], 1, s[84:85]
	global_load_lds_dwordx4 v[12:13], off
	s_add_i32 m0, s25, 0x6000
	v_lshlrev_b32_e32 v190, 3, v2
	global_load_lds_dwordx4 v[8:9], off
	s_add_i32 m0, s25, 0x8000
	v_mov_b32_e32 v3, v147
	v_add3_u32 v2, s13, v17, v190
	s_cmpk_gt_u32 s12, 0xff
	v_lshl_add_u64 v[10:11], v[2:3], 1, s[84:85]
	s_cselect_b64 s[8:9], -1, 0
	s_cmpk_lt_u32 s12, 0x100
	v_add_u32_e32 v146, v146, v153
	global_load_lds_dwordx4 v[10:11], off
	s_cselect_b64 s[12:13], -1, 0
	s_add_i32 m0, s25, 0xa000
	v_lshl_add_u64 v[8:9], v[146:147], 1, s[84:85]
	v_add_u32_e32 v146, v6, v155
	s_waitcnt vmcnt(0) lgkmcnt(0)
	s_barrier
	s_waitcnt vmcnt(0)
	global_load_lds_dwordx4 v[8:9], off
	v_lshl_add_u64 v[6:7], v[146:147], 1, s[84:85]
	s_add_i32 m0, s25, 0xc000
	v_add_u32_e32 v146, v4, v157
	global_load_lds_dwordx4 v[6:7], off
	v_lshl_add_u64 v[4:5], v[146:147], 1, s[84:85]
	s_add_i32 m0, s25, 0xe000
	v_add_u32_e32 v146, 0x20000, v0
	global_load_lds_dwordx4 v[4:5], off
	s_add_i32 m0, s25, 0x10000
	v_lshl_add_u64 v[0:1], v[146:147], 1, s[84:85]
	v_add_u32_e32 v146, 0x20000, v2
	global_load_lds_dwordx4 v[0:1], off
	v_lshl_add_u64 v[0:1], v[146:147], 1, s[84:85]
	s_add_i32 m0, s25, 0x12000
	v_add_u32_e32 v36, 0, v149
	global_load_lds_dwordx4 v[0:1], off
	ds_read_b128 v[0:3], v36
	v_add_u32_e32 v40, 0, v172
	ds_read_b128 v[4:7], v40
	v_add_u32_e32 v44, 0, v173
	v_add_u32_e32 v64, 0, v174
	ds_read_b128 v[8:11], v44
	ds_read_b128 v[12:15], v64
	s_waitcnt lgkmcnt(0)
	v_mfma_f32_32x32x16_bf16 v[48:63], v[0:3], v[96:99], 0
	ds_read_b128 v[0:3], v36 offset:128
	s_and_b64 vcc, exec, s[12:13]
	v_mfma_f32_32x32x16_bf16 v[48:63], v[4:7], v[100:103], v[48:63]
	ds_read_b128 v[4:7], v40 offset:128
	v_mfma_f32_32x32x16_bf16 v[48:63], v[8:11], v[104:107], v[48:63]
	ds_read_b128 v[8:11], v44 offset:128
	v_mfma_f32_32x32x16_bf16 v[48:63], v[12:15], v[108:111], v[48:63]
	ds_read_b128 v[12:15], v64 offset:128
	s_waitcnt lgkmcnt(0)
	v_mfma_f32_32x32x16_bf16 v[48:63], v[0:3], v[112:115], v[48:63]
	ds_read_b128 v[0:3], v36 offset:256
	v_mfma_f32_32x32x16_bf16 v[48:63], v[4:7], v[116:119], v[48:63]
	ds_read_b128 v[4:7], v40 offset:256
	v_mfma_f32_32x32x16_bf16 v[48:63], v[8:11], v[120:123], v[48:63]
	ds_read_b128 v[8:11], v44 offset:256
	v_mfma_f32_32x32x16_bf16 v[48:63], v[12:15], v[124:127], v[48:63]
	ds_read_b128 v[12:15], v64 offset:256
	s_waitcnt lgkmcnt(0)
	v_mfma_f32_32x32x16_bf16 v[48:63], v[0:3], v[128:131], v[48:63]
	ds_read_b128 v[0:3], v36 offset:12288
	v_mfma_f32_32x32x16_bf16 v[48:63], v[4:7], v[132:135], v[48:63]
	ds_read_b128 v[4:7], v40 offset:12288
	v_mfma_f32_32x32x16_bf16 v[48:63], v[8:11], v[136:139], v[48:63]
	ds_read_b128 v[8:11], v44 offset:12288
	s_waitcnt lgkmcnt(0)
	v_mfma_f32_32x32x16_bf16 v[80:95], v[0:3], v[96:99], 0
	ds_read_b128 v[16:19], v64 offset:12288
	v_mfma_f32_32x32x16_bf16 v[80:95], v[4:7], v[100:103], v[80:95]
	ds_read_b128 v[20:23], v36 offset:12416
	v_mfma_f32_32x32x16_bf16 v[80:95], v[8:11], v[104:107], v[80:95]
	ds_read_b128 v[24:27], v40 offset:12416
	s_waitcnt lgkmcnt(0)
	v_mfma_f32_32x32x16_bf16 v[80:95], v[16:19], v[108:111], v[80:95]
	ds_read_b128 v[28:31], v44 offset:12416
	v_mfma_f32_32x32x16_bf16 v[80:95], v[20:23], v[112:115], v[80:95]
	ds_read_b128 v[32:35], v64 offset:12416
	v_mfma_f32_32x32x16_bf16 v[80:95], v[24:27], v[116:119], v[80:95]
	ds_read_b128 v[36:39], v36 offset:12544
	s_waitcnt lgkmcnt(0)
	v_mfma_f32_32x32x16_bf16 v[80:95], v[28:31], v[120:123], v[80:95]
	ds_read_b128 v[40:43], v40 offset:12544
	v_mfma_f32_32x32x16_bf16 v[80:95], v[32:35], v[124:127], v[80:95]
	ds_read_b128 v[44:47], v44 offset:12544
	v_mfma_f32_32x32x16_bf16 v[80:95], v[36:39], v[128:131], v[80:95]
	ds_read_b128 v[64:67], v64 offset:12544
	s_waitcnt lgkmcnt(0)
	v_mfma_f32_32x32x16_bf16 v[80:95], v[40:43], v[132:135], v[80:95]
	v_mfma_f32_32x32x16_bf16 v[80:95], v[44:47], v[136:139], v[80:95]
	v_mfma_f32_32x32x16_bf16 v[80:95], v[64:67], v[140:143], v[80:95]
	v_mfma_f32_32x32x16_bf16 v[48:63], v[12:15], v[140:143], v[48:63]
	s_cbranch_vccnz .LBB0_1773
	s_waitcnt vmcnt(0) lgkmcnt(0)
	s_barrier
.LBB0_1773:
	s_nop 10
	v_max_f32_e32 v0, v49, v49
	v_max_f32_e32 v1, v48, v48
	v_max_f32_e32 v0, v1, v0
	v_max3_f32 v0, v0, v50, v51
	v_max3_f32 v0, v0, v52, v53
	v_max3_f32 v0, v0, v54, v55
	v_max3_f32 v0, v0, v56, v57
	v_max3_f32 v0, v0, v58, v59
	v_max3_f32 v0, v0, v60, v61
	v_max3_f32 v0, v0, v62, v63
	v_mov_b32_e32 v1, v0
	s_nop 1
	v_permlane32_swap_b32_e32 v0, v1
	v_max_f32_e32 v1, v1, v1
	v_max_f32_e32 v0, v0, v0
	v_max_f32_e32 v0, v0, v1
	s_cmp_lg_u64 exec, 0
	v_add_f32_e32 v0, 0, v0
	s_cselect_b64 vcc, -1, 0
	v_cndmask_b32_e32 v151, 0, v0, vcc
	v_sub_f32_e32 v0, v48, v151
	v_exp_f32_e32 v48, v0
	v_sub_f32_e32 v0, v49, v151
	v_exp_f32_e32 v49, v0
	v_sub_f32_e32 v0, v50, v151
	v_exp_f32_e32 v50, v0
	v_sub_f32_e32 v0, v51, v151
	v_exp_f32_e32 v51, v0
	v_sub_f32_e32 v0, v52, v151
	v_exp_f32_e32 v52, v0
	v_sub_f32_e32 v0, v53, v151
	v_exp_f32_e32 v53, v0
	v_sub_f32_e32 v0, v54, v151
	v_exp_f32_e32 v54, v0
	v_sub_f32_e32 v0, v55, v151
	v_add_u32_e32 v191, v182, v178
	v_exp_f32_e32 v55, v0
	v_add_u32_e32 v193, v183, v178
	ds_read_b64_tr_b16 v[4:5], v191 offset:24576
	ds_read_b64_tr_b16 v[6:7], v193 offset:26624
	v_sub_f32_e32 v0, v56, v151
	v_exp_f32_e32 v56, v0
	v_sub_f32_e32 v0, v57, v151
	v_exp_f32_e32 v57, v0
	v_sub_f32_e32 v0, v58, v151
	v_exp_f32_e32 v58, v0
	v_cvt_pk_bf16_f32 v0, v48, v49
	v_cvt_pk_bf16_f32 v1, v50, v51
	v_cvt_pk_bf16_f32 v2, v52, v53
	v_cvt_pk_bf16_f32 v3, v54, v55
	v_add_u32_e32 v146, v182, v179
	v_add_u32_e32 v195, v182, v180
	v_add_u32_e32 v192, v183, v179
	ds_read_b64_tr_b16 v[8:9], v146 offset:24576
	ds_read_b64_tr_b16 v[10:11], v192 offset:26624
	ds_read_b64_tr_b16 v[202:203], v193 offset:30720
	ds_read_b64_tr_b16 v[200:201], v191 offset:28672
	s_waitcnt lgkmcnt(0)
	v_mfma_f32_32x32x16_bf16 v[64:79], v[4:7], v[0:3], 0
	v_add_u32_e32 v197, v183, v180
	ds_read_b64_tr_b16 v[4:5], v195 offset:24576
	ds_read_b64_tr_b16 v[6:7], v197 offset:26624
	ds_read_b64_tr_b16 v[206:207], v192 offset:30720
	ds_read_b64_tr_b16 v[204:205], v146 offset:28672
	v_sub_f32_e32 v12, v59, v151
	v_sub_f32_e32 v62, v62, v151
	v_sub_f32_e32 v63, v63, v151
	v_exp_f32_e32 v59, v12
	v_add_u32_e32 v196, v182, v181
	s_waitcnt lgkmcnt(0)
	v_mfma_f32_32x32x16_bf16 v[16:31], v[4:7], v[0:3], 0
	v_sub_f32_e32 v4, v60, v151
	v_exp_f32_e32 v60, v4
	v_sub_f32_e32 v4, v61, v151
	v_exp_f32_e32 v61, v4
	v_exp_f32_e32 v62, v62
	v_exp_f32_e32 v63, v63
	v_add_u32_e32 v198, v183, v181
	v_mfma_f32_32x32x16_bf16 v[32:47], v[8:11], v[0:3], 0
	ds_read_b64_tr_b16 v[8:9], v196 offset:24576
	ds_read_b64_tr_b16 v[10:11], v198 offset:26624
	ds_read_b64_tr_b16 v[210:211], v197 offset:30720
	ds_read_b64_tr_b16 v[208:209], v195 offset:28672
	v_add_f32_e32 v194, 0, v48
	v_cvt_pk_bf16_f32 v216, v56, v57
	v_cvt_pk_bf16_f32 v217, v58, v59
	v_cvt_pk_bf16_f32 v218, v60, v61
	v_cvt_pk_bf16_f32 v219, v62, v63
	v_add_f32_e32 v194, v49, v194
	s_waitcnt lgkmcnt(0)
	v_mfma_f32_32x32x16_bf16 v[0:15], v[8:11], v[0:3], 0
	v_add_f32_e32 v194, v50, v194
	v_max_f32_e32 v199, v81, v81
	v_add_f32_e32 v194, v51, v194
	ds_read_b64_tr_b16 v[214:215], v198 offset:30720
	ds_read_b64_tr_b16 v[212:213], v196 offset:28672
	v_add_f32_e32 v194, v52, v194
	v_add_f32_e32 v194, v53, v194
	v_add_f32_e32 v194, v54, v194
	v_mfma_f32_32x32x16_bf16 v[64:79], v[200:203], v[216:219], v[64:79]
	v_max_f32_e32 v200, v80, v80
	v_max_f32_e32 v199, v200, v199
	v_max3_f32 v199, v199, v82, v83
	v_max3_f32 v199, v199, v84, v85
	v_max3_f32 v199, v199, v86, v87
	v_add_f32_e32 v194, v55, v194
	v_max3_f32 v199, v199, v88, v89
	v_add_f32_e32 v194, v56, v194
	v_max3_f32 v199, v199, v90, v91
	v_mfma_f32_32x32x16_bf16 v[32:47], v[204:207], v[216:219], v[32:47]
	v_add_f32_e32 v194, v57, v194
	v_max3_f32 v199, v199, v92, v93
	v_add_f32_e32 v194, v58, v194
	v_max3_f32 v199, v199, v94, v95
	v_add_f32_e32 v194, v59, v194
	v_mov_b32_e32 v200, v199
	v_add_f32_e32 v194, v60, v194
	v_mfma_f32_32x32x16_bf16 v[16:31], v[208:211], v[216:219], v[16:31]
	v_permlane32_swap_b32_e32 v199, v200
	v_add_f32_e32 v194, v61, v194
	v_max_f32_e32 v200, v200, v200
	v_max_f32_e32 v199, v199, v199
	v_add_f32_e32 v194, v62, v194
	v_max_f32_e32 v199, v199, v200
	s_waitcnt lgkmcnt(0)
	v_mfma_f32_32x32x16_bf16 v[0:15], v[212:215], v[216:219], v[0:15]
	v_add_f32_e32 v194, v63, v194
	v_sub_f32_e32 v199, v199, v151
	v_add_f32_e32 v194, 0, v194
	v_cmp_lt_f32_e32 vcc, s20, v199
	s_cbranch_vccz .LBB0_1775
	v_max_f32_e32 v199, v199, v199
	v_max_f32_e32 v199, 0, v199
	v_exp_f32_e64 v200, -v199
	v_add_f32_e32 v151, v151, v199
	v_pk_mul_f32 v[78:79], v[78:79], v[200:201] op_sel_hi:[1,0]
	v_pk_mul_f32 v[76:77], v[76:77], v[200:201] op_sel_hi:[1,0]
	v_pk_mul_f32 v[74:75], v[74:75], v[200:201] op_sel_hi:[1,0]
	v_pk_mul_f32 v[72:73], v[72:73], v[200:201] op_sel_hi:[1,0]
	v_pk_mul_f32 v[70:71], v[70:71], v[200:201] op_sel_hi:[1,0]
	v_pk_mul_f32 v[68:69], v[68:69], v[200:201] op_sel_hi:[1,0]
	v_pk_mul_f32 v[66:67], v[66:67], v[200:201] op_sel_hi:[1,0]
	v_pk_mul_f32 v[64:65], v[64:65], v[200:201] op_sel_hi:[1,0]
	v_pk_mul_f32 v[46:47], v[46:47], v[200:201] op_sel_hi:[1,0]
	v_pk_mul_f32 v[44:45], v[44:45], v[200:201] op_sel_hi:[1,0]
	v_pk_mul_f32 v[42:43], v[42:43], v[200:201] op_sel_hi:[1,0]
	v_pk_mul_f32 v[40:41], v[40:41], v[200:201] op_sel_hi:[1,0]
	v_pk_mul_f32 v[38:39], v[38:39], v[200:201] op_sel_hi:[1,0]
	v_pk_mul_f32 v[36:37], v[36:37], v[200:201] op_sel_hi:[1,0]
	v_pk_mul_f32 v[34:35], v[34:35], v[200:201] op_sel_hi:[1,0]
	v_pk_mul_f32 v[32:33], v[32:33], v[200:201] op_sel_hi:[1,0]
	v_pk_mul_f32 v[30:31], v[30:31], v[200:201] op_sel_hi:[1,0]
	v_pk_mul_f32 v[28:29], v[28:29], v[200:201] op_sel_hi:[1,0]
	v_pk_mul_f32 v[26:27], v[26:27], v[200:201] op_sel_hi:[1,0]
	v_pk_mul_f32 v[24:25], v[24:25], v[200:201] op_sel_hi:[1,0]
	v_pk_mul_f32 v[22:23], v[22:23], v[200:201] op_sel_hi:[1,0]
	v_pk_mul_f32 v[20:21], v[20:21], v[200:201] op_sel_hi:[1,0]
	v_pk_mul_f32 v[18:19], v[18:19], v[200:201] op_sel_hi:[1,0]
	v_pk_mul_f32 v[16:17], v[16:17], v[200:201] op_sel_hi:[1,0]
	v_pk_mul_f32 v[14:15], v[14:15], v[200:201] op_sel_hi:[1,0]
	v_pk_mul_f32 v[12:13], v[12:13], v[200:201] op_sel_hi:[1,0]
	v_pk_mul_f32 v[10:11], v[10:11], v[200:201] op_sel_hi:[1,0]
	v_pk_mul_f32 v[8:9], v[8:9], v[200:201] op_sel_hi:[1,0]
	v_pk_mul_f32 v[6:7], v[6:7], v[200:201] op_sel_hi:[1,0]
	v_pk_mul_f32 v[4:5], v[4:5], v[200:201] op_sel_hi:[1,0]
	v_pk_mul_f32 v[2:3], v[2:3], v[200:201] op_sel_hi:[1,0]
	v_pk_mul_f32 v[0:1], v[0:1], v[200:201] op_sel_hi:[1,0]
	v_mul_f32_e32 v194, v194, v200
.LBB0_1775:
	v_sub_f32_e32 v80, v80, v151
	v_sub_f32_e32 v81, v81, v151
	v_sub_f32_e32 v82, v82, v151
	v_sub_f32_e32 v83, v83, v151
	v_sub_f32_e32 v84, v84, v151
	v_sub_f32_e32 v85, v85, v151
	v_sub_f32_e32 v86, v86, v151
	v_sub_f32_e32 v87, v87, v151
	v_exp_f32_e32 v80, v80
	v_exp_f32_e32 v81, v81
	v_exp_f32_e32 v82, v82
	v_exp_f32_e32 v83, v83
	v_exp_f32_e32 v84, v84
	v_exp_f32_e32 v85, v85
	v_exp_f32_e32 v86, v86
	v_exp_f32_e32 v87, v87
	ds_read_b64_tr_b16 v[200:201], v191 offset:32768
	ds_read_b64_tr_b16 v[202:203], v193 offset:34816
	ds_read_b64_tr_b16 v[208:209], v146 offset:32768
	ds_read_b64_tr_b16 v[210:211], v192 offset:34816
	ds_read_b64_tr_b16 v[214:215], v193 offset:38912
	ds_read_b64_tr_b16 v[212:213], v191 offset:36864
	v_cvt_pk_bf16_f32 v204, v80, v81
	v_cvt_pk_bf16_f32 v205, v82, v83
	v_cvt_pk_bf16_f32 v206, v84, v85
	v_cvt_pk_bf16_f32 v207, v86, v87
	v_sub_f32_e32 v88, v88, v151
	v_sub_f32_e32 v89, v89, v151
	s_waitcnt lgkmcnt(0)
	v_mfma_f32_32x32x16_bf16 v[64:79], v[200:203], v[204:207], v[64:79]
	ds_read_b64_tr_b16 v[200:201], v195 offset:32768
	ds_read_b64_tr_b16 v[202:203], v197 offset:34816
	ds_read_b64_tr_b16 v[218:219], v192 offset:38912
	ds_read_b64_tr_b16 v[216:217], v146 offset:36864
	v_sub_f32_e32 v90, v90, v151
	v_sub_f32_e32 v91, v91, v151
	v_sub_f32_e32 v92, v92, v151
	v_sub_f32_e32 v93, v93, v151
	v_sub_f32_e32 v94, v94, v151
	v_sub_f32_e32 v95, v95, v151
	v_mfma_f32_32x32x16_bf16 v[32:47], v[208:211], v[204:207], v[32:47]
	ds_read_b64_tr_b16 v[208:209], v196 offset:32768
	ds_read_b64_tr_b16 v[210:211], v198 offset:34816
	ds_read_b64_tr_b16 v[226:227], v197 offset:38912
	ds_read_b64_tr_b16 v[224:225], v195 offset:36864
	v_exp_f32_e32 v88, v88
	v_exp_f32_e32 v89, v89
	v_exp_f32_e32 v90, v90
	v_exp_f32_e32 v91, v91
	v_exp_f32_e32 v92, v92
	v_exp_f32_e32 v93, v93
	s_waitcnt lgkmcnt(0)
	v_mfma_f32_32x32x16_bf16 v[16:31], v[200:203], v[204:207], v[16:31]
	ds_read_b64_tr_b16 v[198:199], v198 offset:38912
	ds_read_b64_tr_b16 v[196:197], v196 offset:36864
	v_exp_f32_e32 v94, v94
	v_exp_f32_e32 v95, v95
	v_cvt_pk_bf16_f32 v200, v88, v89
	v_cvt_pk_bf16_f32 v201, v90, v91
	v_cvt_pk_bf16_f32 v202, v92, v93
	v_cvt_pk_bf16_f32 v203, v94, v95
	v_mfma_f32_32x32x16_bf16 v[0:15], v[208:211], v[204:207], v[0:15]
	v_cndmask_b32_e64 v146, 0, 1, s[12:13]
	v_cmp_ne_u32_e64 s[2:3], 1, v146
	s_andn2_b64 vcc, exec, s[12:13]
	v_mfma_f32_32x32x16_bf16 v[64:79], v[212:215], v[200:203], v[64:79]
	v_mfma_f32_32x32x16_bf16 v[32:47], v[216:219], v[200:203], v[32:47]
	v_mfma_f32_32x32x16_bf16 v[16:31], v[224:227], v[200:203], v[16:31]
	s_waitcnt lgkmcnt(0)
	v_mfma_f32_32x32x16_bf16 v[0:15], v[196:199], v[200:203], v[0:15]
	s_cbranch_vccnz .LBB0_1777
	s_waitcnt vmcnt(0) lgkmcnt(0)
	s_barrier

.LBB0_1786:
	s_setprio 0
	v_add_u32_e32 v159, s28, v149
	ds_read_b128 v[48:51], v159
	v_add_u32_e32 v161, s28, v172
	v_add_u32_e32 v165, s28, v173
	v_add_u32_e32 v167, s28, v174
	ds_read_b128 v[80:83], v161
	ds_read_b128 v[84:87], v165
	ds_read_b128 v[88:91], v167
	s_waitcnt lgkmcnt(0)
	v_mfma_f32_32x32x16_bf16 v[48:63], v[48:51], v[96:99], 0
	ds_read_b128 v[92:95], v159 offset:128
	v_mfma_f32_32x32x16_bf16 v[48:63], v[80:83], v[100:103], v[48:63]
	ds_read_b128 v[80:83], v161 offset:128
	v_mfma_f32_32x32x16_bf16 v[48:63], v[84:87], v[104:107], v[48:63]
	ds_read_b128 v[84:87], v165 offset:128
	v_mfma_f32_32x32x16_bf16 v[48:63], v[88:91], v[108:111], v[48:63]
	ds_read_b128 v[88:91], v167 offset:128
	s_waitcnt lgkmcnt(0)
	v_mfma_f32_32x32x16_bf16 v[48:63], v[92:95], v[112:115], v[48:63]
	ds_read_b128 v[92:95], v159 offset:256
	v_mfma_f32_32x32x16_bf16 v[48:63], v[80:83], v[116:119], v[48:63]
	ds_read_b128 v[80:83], v161 offset:256
	v_mfma_f32_32x32x16_bf16 v[48:63], v[84:87], v[120:123], v[48:63]
	ds_read_b128 v[84:87], v165 offset:256
	v_mfma_f32_32x32x16_bf16 v[48:63], v[88:91], v[124:127], v[48:63]
	ds_read_b128 v[190:193], v167 offset:256
	s_waitcnt lgkmcnt(0)
	v_mfma_f32_32x32x16_bf16 v[48:63], v[92:95], v[128:131], v[48:63]
	ds_read_b128 v[88:91], v159 offset:12288
	v_mfma_f32_32x32x16_bf16 v[48:63], v[80:83], v[132:135], v[48:63]
	ds_read_b128 v[194:197], v161 offset:12288
	v_mfma_f32_32x32x16_bf16 v[48:63], v[84:87], v[136:139], v[48:63]
	ds_read_b128 v[198:201], v165 offset:12288
	s_waitcnt lgkmcnt(0)
	v_mfma_f32_32x32x16_bf16 v[80:95], v[88:91], v[96:99], 0
	ds_read_b128 v[202:205], v167 offset:12288
	v_mfma_f32_32x32x16_bf16 v[80:95], v[194:197], v[100:103], v[80:95]
	ds_read_b128 v[206:209], v159 offset:12416
	v_mfma_f32_32x32x16_bf16 v[80:95], v[198:201], v[104:107], v[80:95]
	ds_read_b128 v[210:213], v161 offset:12416
	s_waitcnt lgkmcnt(0)
	v_mfma_f32_32x32x16_bf16 v[80:95], v[202:205], v[108:111], v[80:95]
	ds_read_b128 v[214:217], v165 offset:12416
	v_mfma_f32_32x32x16_bf16 v[80:95], v[206:209], v[112:115], v[80:95]
	ds_read_b128 v[218:221], v167 offset:12416
	v_mfma_f32_32x32x16_bf16 v[80:95], v[210:213], v[116:119], v[80:95]
	ds_read_b128 v[224:227], v159 offset:12544
	s_waitcnt lgkmcnt(0)
	v_mfma_f32_32x32x16_bf16 v[80:95], v[214:217], v[120:123], v[80:95]
	ds_read_b128 v[228:231], v161 offset:12544
	v_mfma_f32_32x32x16_bf16 v[80:95], v[218:221], v[124:127], v[80:95]
	ds_read_b128 v[232:235], v165 offset:12544
	v_mfma_f32_32x32x16_bf16 v[80:95], v[224:227], v[128:131], v[80:95]
	ds_read_b128 v[236:239], v167 offset:12544
	s_waitcnt lgkmcnt(0)
	v_mfma_f32_32x32x16_bf16 v[80:95], v[228:231], v[132:135], v[80:95]
	v_mfma_f32_32x32x16_bf16 v[80:95], v[232:235], v[136:139], v[80:95]
	v_mfma_f32_32x32x16_bf16 v[80:95], v[236:239], v[140:143], v[80:95]
	v_mfma_f32_32x32x16_bf16 v[48:63], v[190:193], v[140:143], v[48:63]
	s_andn2_b64 vcc, exec, s[8:9]
	s_cbranch_vccnz .LBB0_1781

.LBB0_1788:
	s_setprio 1
	s_nop 7
	v_max_f32_e32 v159, v49, v49
	v_max_f32_e32 v161, v48, v48
	v_max_f32_e32 v159, v161, v159
	v_max3_f32 v159, v159, v50, v51
	v_max3_f32 v159, v159, v52, v53
	v_max3_f32 v159, v159, v54, v55
	v_max3_f32 v159, v159, v56, v57
	v_max3_f32 v159, v159, v58, v59
	v_max3_f32 v159, v159, v60, v61
	v_max3_f32 v159, v159, v62, v63
	v_mov_b32_e32 v161, v159
	s_nop 1
	v_permlane32_swap_b32_e32 v159, v161
	v_max_f32_e32 v161, v161, v161
	v_max_f32_e32 v159, v159, v159
	v_max_f32_e32 v159, v159, v161
	v_sub_f32_e32 v159, v159, v151
	v_cmp_lt_f32_e32 vcc, s20, v159
	s_cbranch_vccz .LBB0_1790
	v_max_f32_e32 v159, v159, v159
	v_max_f32_e32 v159, 0, v159
	v_exp_f32_e64 v190, -v159
	v_add_f32_e32 v151, v151, v159
	v_pk_mul_f32 v[78:79], v[78:79], v[190:191] op_sel_hi:[1,0]
	v_pk_mul_f32 v[76:77], v[76:77], v[190:191] op_sel_hi:[1,0]
	v_pk_mul_f32 v[74:75], v[74:75], v[190:191] op_sel_hi:[1,0]
	v_pk_mul_f32 v[72:73], v[72:73], v[190:191] op_sel_hi:[1,0]
	v_pk_mul_f32 v[70:71], v[70:71], v[190:191] op_sel_hi:[1,0]
	v_pk_mul_f32 v[68:69], v[68:69], v[190:191] op_sel_hi:[1,0]
	v_pk_mul_f32 v[66:67], v[66:67], v[190:191] op_sel_hi:[1,0]
	v_pk_mul_f32 v[64:65], v[64:65], v[190:191] op_sel_hi:[1,0]
	v_pk_mul_f32 v[46:47], v[46:47], v[190:191] op_sel_hi:[1,0]
	v_pk_mul_f32 v[44:45], v[44:45], v[190:191] op_sel_hi:[1,0]
	v_pk_mul_f32 v[42:43], v[42:43], v[190:191] op_sel_hi:[1,0]
	v_pk_mul_f32 v[40:41], v[40:41], v[190:191] op_sel_hi:[1,0]
	v_pk_mul_f32 v[38:39], v[38:39], v[190:191] op_sel_hi:[1,0]
	v_pk_mul_f32 v[36:37], v[36:37], v[190:191] op_sel_hi:[1,0]
	v_pk_mul_f32 v[34:35], v[34:35], v[190:191] op_sel_hi:[1,0]
	v_pk_mul_f32 v[32:33], v[32:33], v[190:191] op_sel_hi:[1,0]
	v_pk_mul_f32 v[30:31], v[30:31], v[190:191] op_sel_hi:[1,0]
	v_pk_mul_f32 v[28:29], v[28:29], v[190:191] op_sel_hi:[1,0]
	v_pk_mul_f32 v[26:27], v[26:27], v[190:191] op_sel_hi:[1,0]
	v_pk_mul_f32 v[24:25], v[24:25], v[190:191] op_sel_hi:[1,0]
	v_pk_mul_f32 v[22:23], v[22:23], v[190:191] op_sel_hi:[1,0]
	v_pk_mul_f32 v[20:21], v[20:21], v[190:191] op_sel_hi:[1,0]
	v_pk_mul_f32 v[18:19], v[18:19], v[190:191] op_sel_hi:[1,0]
	v_pk_mul_f32 v[16:17], v[16:17], v[190:191] op_sel_hi:[1,0]
	v_pk_mul_f32 v[14:15], v[14:15], v[190:191] op_sel_hi:[1,0]
	v_pk_mul_f32 v[12:13], v[12:13], v[190:191] op_sel_hi:[1,0]
	v_pk_mul_f32 v[10:11], v[10:11], v[190:191] op_sel_hi:[1,0]
	v_pk_mul_f32 v[8:9], v[8:9], v[190:191] op_sel_hi:[1,0]
	v_pk_mul_f32 v[6:7], v[6:7], v[190:191] op_sel_hi:[1,0]
	v_pk_mul_f32 v[4:5], v[4:5], v[190:191] op_sel_hi:[1,0]
	v_pk_mul_f32 v[2:3], v[2:3], v[190:191] op_sel_hi:[1,0]
	v_pk_mul_f32 v[0:1], v[0:1], v[190:191] op_sel_hi:[1,0]
	v_mul_f32_e32 v163, v163, v190
.LBB0_1790:
	v_add_u32_e32 v171, s28, v175
	v_add_u32_e32 v190, s28, v177
	v_sub_f32_e32 v48, v48, v151
	v_sub_f32_e32 v49, v49, v151
	v_sub_f32_e32 v50, v50, v151
	v_sub_f32_e32 v51, v51, v151
	v_sub_f32_e32 v52, v52, v151
	v_sub_f32_e32 v53, v53, v151
	v_sub_f32_e32 v54, v54, v151
	v_sub_f32_e32 v55, v55, v151
	v_add_u32_e32 v161, v171, v178
	v_exp_f32_e32 v48, v48
	v_exp_f32_e32 v49, v49
	v_exp_f32_e32 v50, v50
	v_exp_f32_e32 v51, v51
	v_exp_f32_e32 v52, v52
	v_exp_f32_e32 v53, v53
	v_exp_f32_e32 v54, v54
	v_exp_f32_e32 v55, v55
	v_add_u32_e32 v167, v190, v178
	ds_read_b64_tr_b16 v[196:197], v161 offset:24576
	ds_read_b64_tr_b16 v[198:199], v167 offset:26624
	v_add_u32_e32 v159, v171, v179
	v_add_u32_e32 v165, v190, v179
	ds_read_b64_tr_b16 v[200:201], v159 offset:24576
	ds_read_b64_tr_b16 v[202:203], v165 offset:26624
	ds_read_b64_tr_b16 v[206:207], v167 offset:30720
	ds_read_b64_tr_b16 v[204:205], v161 offset:28672
	v_cvt_pk_bf16_f32 v192, v48, v49
	v_cvt_pk_bf16_f32 v193, v50, v51
	v_cvt_pk_bf16_f32 v194, v52, v53
	v_cvt_pk_bf16_f32 v195, v54, v55
	v_add_u32_e32 v169, v171, v180
	v_add_u32_e32 v171, v171, v181
	s_waitcnt lgkmcnt(0)
	v_mfma_f32_32x32x16_bf16 v[64:79], v[196:199], v[192:195], v[64:79]
	v_add_u32_e32 v189, v190, v180
	ds_read_b64_tr_b16 v[196:197], v169 offset:24576
	ds_read_b64_tr_b16 v[198:199], v189 offset:26624
	ds_read_b64_tr_b16 v[210:211], v165 offset:30720
	ds_read_b64_tr_b16 v[208:209], v159 offset:28672
	v_add_u32_e32 v190, v190, v181
	v_add_f32_e32 v191, 0, v48
	v_sub_f32_e32 v56, v56, v151
	v_sub_f32_e32 v57, v57, v151
	v_sub_f32_e32 v58, v58, v151
	v_mfma_f32_32x32x16_bf16 v[32:47], v[200:203], v[192:195], v[32:47]
	ds_read_b64_tr_b16 v[200:201], v171 offset:24576
	ds_read_b64_tr_b16 v[202:203], v190 offset:26624
	ds_read_b64_tr_b16 v[214:215], v189 offset:30720
	ds_read_b64_tr_b16 v[212:213], v169 offset:28672
	v_sub_f32_e32 v59, v59, v151
	v_sub_f32_e32 v60, v60, v151
	v_sub_f32_e32 v61, v61, v151
	v_sub_f32_e32 v62, v62, v151
	v_sub_f32_e32 v63, v63, v151
	v_add_f32_e32 v191, v49, v191
	s_waitcnt lgkmcnt(0)
	v_mfma_f32_32x32x16_bf16 v[16:31], v[196:199], v[192:195], v[16:31]
	v_exp_f32_e32 v56, v56
	v_exp_f32_e32 v57, v57
	v_exp_f32_e32 v58, v58
	v_exp_f32_e32 v59, v59
	v_exp_f32_e32 v60, v60
	v_exp_f32_e32 v61, v61
	ds_read_b64_tr_b16 v[198:199], v190 offset:30720
	ds_read_b64_tr_b16 v[196:197], v171 offset:28672
	v_mfma_f32_32x32x16_bf16 v[0:15], v[200:203], v[192:195], v[0:15]
	v_exp_f32_e32 v62, v62
	v_exp_f32_e32 v63, v63
	v_add_f32_e32 v191, v50, v191
	v_add_f32_e32 v191, v51, v191
	v_add_f32_e32 v191, v52, v191
	v_add_f32_e32 v191, v53, v191
	v_cvt_pk_bf16_f32 v192, v56, v57
	v_cvt_pk_bf16_f32 v193, v58, v59
	v_cvt_pk_bf16_f32 v194, v60, v61
	v_cvt_pk_bf16_f32 v195, v62, v63
	v_add_f32_e32 v191, v54, v191
	v_add_f32_e32 v191, v55, v191
	v_mfma_f32_32x32x16_bf16 v[64:79], v[204:207], v[192:195], v[64:79]
	v_add_f32_e32 v191, v56, v191
	v_add_f32_e32 v191, v57, v191
	v_add_f32_e32 v191, v58, v191
	v_add_f32_e32 v191, v59, v191
	v_add_f32_e32 v191, v60, v191
	v_add_f32_e32 v191, v61, v191
	v_add_f32_e32 v191, v62, v191
	v_mfma_f32_32x32x16_bf16 v[32:47], v[208:211], v[192:195], v[32:47]
	v_add_f32_e32 v191, v63, v191
	v_add_f32_e32 v163, v163, v191
	v_mfma_f32_32x32x16_bf16 v[16:31], v[212:215], v[192:195], v[16:31]
	s_waitcnt lgkmcnt(0)
	v_mfma_f32_32x32x16_bf16 v[0:15], v[196:199], v[192:195], v[0:15]
	v_max_f32_e32 v192, v81, v81
	v_max_f32_e32 v193, v80, v80
	v_max_f32_e32 v192, v193, v192
	v_max3_f32 v192, v192, v82, v83
	v_max3_f32 v192, v192, v84, v85
	v_max3_f32 v192, v192, v86, v87
	v_max3_f32 v192, v192, v88, v89
	v_max3_f32 v192, v192, v90, v91
	v_max3_f32 v192, v192, v92, v93
	v_max3_f32 v192, v192, v94, v95
	v_mov_b32_e32 v191, v192
	s_nop 1
	v_permlane32_swap_b32_e32 v192, v191
	v_max_f32_e32 v191, v191, v191
	v_max_f32_e32 v192, v192, v192
	v_max_f32_e32 v191, v192, v191
	v_sub_f32_e32 v191, v191, v151
	v_cmp_lt_f32_e32 vcc, s20, v191
	s_cbranch_vccz .LBB0_1792
	v_max_f32_e32 v191, v191, v191
	v_max_f32_e32 v191, 0, v191
	v_exp_f32_e64 v192, -v191
	v_add_f32_e32 v151, v151, v191
	v_pk_mul_f32 v[78:79], v[78:79], v[192:193] op_sel_hi:[1,0]
	v_pk_mul_f32 v[76:77], v[76:77], v[192:193] op_sel_hi:[1,0]
	v_pk_mul_f32 v[74:75], v[74:75], v[192:193] op_sel_hi:[1,0]
	v_pk_mul_f32 v[72:73], v[72:73], v[192:193] op_sel_hi:[1,0]
	v_pk_mul_f32 v[70:71], v[70:71], v[192:193] op_sel_hi:[1,0]
	v_pk_mul_f32 v[68:69], v[68:69], v[192:193] op_sel_hi:[1,0]
	v_pk_mul_f32 v[66:67], v[66:67], v[192:193] op_sel_hi:[1,0]
	v_pk_mul_f32 v[64:65], v[64:65], v[192:193] op_sel_hi:[1,0]
	v_pk_mul_f32 v[46:47], v[46:47], v[192:193] op_sel_hi:[1,0]
	v_pk_mul_f32 v[44:45], v[44:45], v[192:193] op_sel_hi:[1,0]
	v_pk_mul_f32 v[42:43], v[42:43], v[192:193] op_sel_hi:[1,0]
	v_pk_mul_f32 v[40:41], v[40:41], v[192:193] op_sel_hi:[1,0]
	v_pk_mul_f32 v[38:39], v[38:39], v[192:193] op_sel_hi:[1,0]
	v_pk_mul_f32 v[36:37], v[36:37], v[192:193] op_sel_hi:[1,0]
	v_pk_mul_f32 v[34:35], v[34:35], v[192:193] op_sel_hi:[1,0]
	v_pk_mul_f32 v[32:33], v[32:33], v[192:193] op_sel_hi:[1,0]
	v_pk_mul_f32 v[30:31], v[30:31], v[192:193] op_sel_hi:[1,0]
	v_pk_mul_f32 v[28:29], v[28:29], v[192:193] op_sel_hi:[1,0]
	v_pk_mul_f32 v[26:27], v[26:27], v[192:193] op_sel_hi:[1,0]
	v_pk_mul_f32 v[24:25], v[24:25], v[192:193] op_sel_hi:[1,0]
	v_pk_mul_f32 v[22:23], v[22:23], v[192:193] op_sel_hi:[1,0]
	v_pk_mul_f32 v[20:21], v[20:21], v[192:193] op_sel_hi:[1,0]
	v_pk_mul_f32 v[18:19], v[18:19], v[192:193] op_sel_hi:[1,0]
	v_pk_mul_f32 v[16:17], v[16:17], v[192:193] op_sel_hi:[1,0]
	v_pk_mul_f32 v[14:15], v[14:15], v[192:193] op_sel_hi:[1,0]
	v_pk_mul_f32 v[12:13], v[12:13], v[192:193] op_sel_hi:[1,0]
	v_pk_mul_f32 v[10:11], v[10:11], v[192:193] op_sel_hi:[1,0]
	v_pk_mul_f32 v[8:9], v[8:9], v[192:193] op_sel_hi:[1,0]
	v_pk_mul_f32 v[6:7], v[6:7], v[192:193] op_sel_hi:[1,0]
	v_pk_mul_f32 v[4:5], v[4:5], v[192:193] op_sel_hi:[1,0]
	v_pk_mul_f32 v[2:3], v[2:3], v[192:193] op_sel_hi:[1,0]
	v_pk_mul_f32 v[0:1], v[0:1], v[192:193] op_sel_hi:[1,0]
	v_mul_f32_e32 v163, v163, v192
.LBB0_1792:
	v_sub_f32_e32 v80, v80, v151
	v_sub_f32_e32 v81, v81, v151
	v_sub_f32_e32 v82, v82, v151
	v_sub_f32_e32 v83, v83, v151
	v_sub_f32_e32 v84, v84, v151
	v_sub_f32_e32 v85, v85, v151
	v_sub_f32_e32 v86, v86, v151
	v_sub_f32_e32 v87, v87, v151
	v_exp_f32_e32 v80, v80
	v_exp_f32_e32 v81, v81
	v_exp_f32_e32 v82, v82
	v_exp_f32_e32 v83, v83
	v_exp_f32_e32 v84, v84
	v_exp_f32_e32 v85, v85
	v_exp_f32_e32 v86, v86
	v_exp_f32_e32 v87, v87
	ds_read_b64_tr_b16 v[192:193], v161 offset:32768
	ds_read_b64_tr_b16 v[194:195], v167 offset:34816
	ds_read_b64_tr_b16 v[200:201], v159 offset:32768
	ds_read_b64_tr_b16 v[202:203], v165 offset:34816
	ds_read_b64_tr_b16 v[206:207], v167 offset:38912
	ds_read_b64_tr_b16 v[204:205], v161 offset:36864
	v_cvt_pk_bf16_f32 v196, v80, v81
	v_cvt_pk_bf16_f32 v197, v82, v83
	v_cvt_pk_bf16_f32 v198, v84, v85
	v_cvt_pk_bf16_f32 v199, v86, v87
	v_sub_f32_e32 v88, v88, v151
	v_sub_f32_e32 v89, v89, v151
	s_waitcnt lgkmcnt(0)
	v_mfma_f32_32x32x16_bf16 v[64:79], v[192:195], v[196:199], v[64:79]
	ds_read_b64_tr_b16 v[192:193], v169 offset:32768
	ds_read_b64_tr_b16 v[194:195], v189 offset:34816
	ds_read_b64_tr_b16 v[210:211], v165 offset:38912
	ds_read_b64_tr_b16 v[208:209], v159 offset:36864
	v_add_f32_e32 v159, 0, v80
	v_add_f32_e32 v159, v81, v159
	v_add_f32_e32 v159, v82, v159
	v_sub_f32_e32 v90, v90, v151
	v_sub_f32_e32 v91, v91, v151
	v_sub_f32_e32 v92, v92, v151
	v_mfma_f32_32x32x16_bf16 v[32:47], v[200:203], v[196:199], v[32:47]
	ds_read_b64_tr_b16 v[200:201], v171 offset:32768
	ds_read_b64_tr_b16 v[202:203], v190 offset:34816
	ds_read_b64_tr_b16 v[214:215], v189 offset:38912
	ds_read_b64_tr_b16 v[212:213], v169 offset:36864
	v_sub_f32_e32 v93, v93, v151
	v_sub_f32_e32 v94, v94, v151
	v_sub_f32_e32 v95, v95, v151
	v_add_f32_e32 v159, v83, v159
	v_exp_f32_e32 v88, v88
	v_exp_f32_e32 v89, v89
	s_waitcnt lgkmcnt(0)
	v_mfma_f32_32x32x16_bf16 v[16:31], v[192:195], v[196:199], v[16:31]
	v_exp_f32_e32 v90, v90
	v_exp_f32_e32 v91, v91
	v_exp_f32_e32 v92, v92
	v_exp_f32_e32 v93, v93
	ds_read_b64_tr_b16 v[192:193], v190 offset:38912
	ds_read_b64_tr_b16 v[190:191], v171 offset:36864
	v_exp_f32_e32 v94, v94
	v_exp_f32_e32 v95, v95
	v_mfma_f32_32x32x16_bf16 v[0:15], v[200:203], v[196:199], v[0:15]
	v_add_f32_e32 v159, v84, v159
	v_add_f32_e32 v159, v85, v159
	v_add_f32_e32 v159, v86, v159
	v_add_f32_e32 v159, v87, v159
	v_cvt_pk_bf16_f32 v194, v88, v89
	v_cvt_pk_bf16_f32 v195, v90, v91
	v_cvt_pk_bf16_f32 v196, v92, v93
	v_cvt_pk_bf16_f32 v197, v94, v95
	v_add_f32_e32 v159, v88, v159
	v_add_f32_e32 v159, v89, v159
	v_mfma_f32_32x32x16_bf16 v[64:79], v[204:207], v[194:197], v[64:79]
	v_add_f32_e32 v159, v90, v159
	v_add_f32_e32 v159, v91, v159
	v_add_f32_e32 v159, v92, v159
	v_add_f32_e32 v159, v93, v159
	v_add_f32_e32 v159, v94, v159
	v_add_f32_e32 v159, v95, v159
	v_add_f32_e32 v163, v163, v159
	v_mfma_f32_32x32x16_bf16 v[32:47], v[208:211], v[194:197], v[32:47]
	v_mfma_f32_32x32x16_bf16 v[16:31], v[212:215], v[194:197], v[16:31]
	s_waitcnt lgkmcnt(0)
	v_mfma_f32_32x32x16_bf16 v[0:15], v[190:193], v[194:197], v[0:15]
	s_and_b64 vcc, exec, s[2:3]
	s_cbranch_vccz .LBB0_1783
	s_branch .LBB0_1784

.LBB0_1794:
	s_andn2_b64 vcc, exec, s[2:3]
	s_cbranch_vccnz .LBB0_2068
	s_lshl_b32 s2, s68, 5
	s_and_b32 s2, s2, 0xe0
	s_ashr_i32 s7, s68, 3
	s_add_i32 s2, s2, s7
	v_readfirstlane_b32 s14, v222
	s_ashr_i32 s12, s2, 6
	s_bfe_u32 s6, s2, 0x40002
	s_movk_i32 s2, 0xffc0
	v_mov_b32_e32 v0, s14
	v_bfi_b32 v0, s2, v0, v222
	s_mov_b32 s2, 0x2aaaaaab
	s_waitcnt lgkmcnt(0)
	v_mul_hi_i32 v1, v0, s2
	v_lshrrev_b32_e32 v2, 31, v1
	v_ashrrev_i32_e32 v1, 2, v1
	v_add_u32_e32 v2, v1, v2
	s_movk_i32 s2, 0xffe8
	v_lshrrev_b32_e32 v150, 1, v2
	s_ashr_i32 s13, s12, 31
	v_mad_u64_u32 v[144:145], s[2:3], v2, s2, v[0:1]
	v_xor_b32_e32 v1, v150, v222
	s_lshl_b64 s[8:9], s[12:13], 13
	v_bfi_b32 v1, -8, v144, v1
	v_cmp_lt_i32_e32 vcc, 15, v1
	v_add_u32_e32 v2, s8, v2
	s_and_saveexec_b64 s[2:3], vcc
	s_xor_b64 s[2:3], exec, s[2:3]
	v_mov_b32_e32 v3, 0xbfff80
	v_lshl_add_u32 v145, v2, 6, v3
	s_or_saveexec_b64 s[2:3], s[2:3]
	s_lshl_b32 s17, s6, 7
	v_mov_b32_e32 v154, 0x1000
	s_xor_b64 exec, exec, s[2:3]
	v_lshl_or_b32 v2, v2, 11, s17
	v_add_u32_e32 v145, 0x8000000, v2
	v_mov_b32_e32 v154, 0x20000
	s_or_b64 exec, exec, s[2:3]
	v_add_u32_e32 v2, 0x200, v0
	s_mov_b32 s2, 0x2aaaaaab
	v_mul_hi_i32 v3, v2, s2
	v_lshrrev_b32_e32 v4, 31, v3
	v_ashrrev_i32_e32 v3, 2, v3
	v_add_u32_e32 v4, v3, v4
	s_movk_i32 s2, 0xffe8
	v_lshrrev_b32_e32 v151, 1, v4
	v_mad_u64_u32 v[146:147], s[2:3], v4, s2, v[2:3]
	v_xor_b32_e32 v3, v151, v222
	v_bfi_b32 v3, -8, v146, v3
	v_cmp_lt_i32_e32 vcc, 15, v3
	v_add_u32_e32 v4, s8, v4
	s_and_saveexec_b64 s[2:3], vcc
	s_xor_b64 s[2:3], exec, s[2:3]
	v_mov_b32_e32 v5, 0xbfff80
	v_lshl_add_u32 v147, v4, 6, v5
	s_or_saveexec_b64 s[2:3], s[2:3]
	v_mov_b32_e32 v155, 0x1000
	s_xor_b64 exec, exec, s[2:3]
	v_lshl_or_b32 v4, v4, 11, s17
	v_add_u32_e32 v147, 0x8000000, v4
	v_mov_b32_e32 v155, 0x20000
	s_or_b64 exec, exec, s[2:3]
	v_add_u32_e32 v4, 0x400, v0
	s_mov_b32 s2, 0x2aaaaaab
	v_mul_hi_i32 v5, v4, s2
	v_lshrrev_b32_e32 v6, 31, v5
	v_ashrrev_i32_e32 v5, 2, v5
	v_add_u32_e32 v5, v5, v6
	s_movk_i32 s2, 0xffe8
	v_lshrrev_b32_e32 v152, 1, v5
	v_mad_u64_u32 v[148:149], s[2:3], v5, s2, v[4:5]
	v_xor_b32_e32 v4, v152, v222
	v_bfi_b32 v4, -8, v148, v4
	v_cmp_lt_i32_e32 vcc, 15, v4
	v_add_u32_e32 v5, s8, v5
	s_and_saveexec_b64 s[2:3], vcc
	s_xor_b64 s[2:3], exec, s[2:3]
	v_mov_b32_e32 v6, 0xbfff80
	v_lshl_add_u32 v149, v5, 6, v6
	s_or_saveexec_b64 s[2:3], s[2:3]
	v_and_b32_e32 v197, 63, v222
	v_mov_b32_e32 v156, 0x1000
	s_xor_b64 exec, exec, s[2:3]
	v_lshl_or_b32 v5, v5, 11, s17
	v_add_u32_e32 v149, 0x8000000, v5
	v_mov_b32_e32 v156, 0x20000
	s_or_b64 exec, exec, s[2:3]
	s_lshl_b32 s2, s7, 8
	s_and_b32 s16, s2, 0x300
	s_lshr_b32 s21, s14, 6
	s_xor_b32 s13, s16, 0x1f00
	s_lshl_b32 s22, s21, 5
	s_or_b32 s18, s17, 0xc000000
	s_or_b32 s2, s8, s13
	v_and_b32_e32 v194, 31, v222
	s_add_u32 s19, s2, s22
	v_or_b32_e32 v5, s19, v194
	s_movk_i32 s2, 0x1800
	v_mov_b64_e32 v[8:9], s[4:5]
	v_lshl_add_u32 v10, v1, 3, v145
	v_ashrrev_i32_e32 v1, 31, v0
	s_addc_u32 s20, s9, 0
	v_mad_u64_u32 v[8:9], s[2:3], v5, s2, v[8:9]
	v_mov_b32_e32 v5, 0x1800
	s_mulk_i32 s6, 0xc0
	v_lshrrev_b32_e32 v1, 28, v1
	v_lshrrev_b32_e32 v161, 5, v197
	s_mov_b32 s7, 0
	v_mad_i32_i24 v9, s20, v5, v9
	s_lshl_b32 s6, s6, 1
	v_add_u32_e32 v1, v0, v1
	v_mov_b32_e32 v7, 0
	v_lshl_add_u64 v[8:9], v[8:9], 0, s[6:7]
	v_lshlrev_b32_e32 v6, 4, v161
	v_ashrrev_i32_e32 v153, 4, v1
	v_and_b32_e32 v1, 0x1ffffff0, v1
	v_lshl_add_u64 v[8:9], v[8:9], 0, v[6:7]
	v_sub_u32_e32 v0, v0, v1
	v_lshlrev_b32_e32 v1, 2, v153
	global_load_dwordx4 v[96:99], v[8:9], off
	global_load_dwordx4 v[100:103], v[8:9], off offset:32
	global_load_dwordx4 v[104:107], v[8:9], off offset:64
	global_load_dwordx4 v[108:111], v[8:9], off offset:96
	global_load_dwordx4 v[112:115], v[8:9], off offset:128
	global_load_dwordx4 v[116:119], v[8:9], off offset:160
	global_load_dwordx4 v[120:123], v[8:9], off offset:192
	global_load_dwordx4 v[124:127], v[8:9], off offset:224
	global_load_dwordx4 v[128:131], v[8:9], off offset:256
	global_load_dwordx4 v[132:135], v[8:9], off offset:288
	global_load_dwordx4 v[136:139], v[8:9], off offset:320
	global_load_dwordx4 v[140:143], v[8:9], off offset:352
	v_lshl_add_u32 v8, v3, 3, v147
	v_and_b32_e32 v1, 12, v1
	v_bfe_u32 v3, v153, 2, 2
	v_bitop3_b32 v0, v1, v0, v3 bitop3:0x36
	v_lshlrev_b32_e32 v158, 3, v0
	v_add_lshl_u32 v0, v153, s8, 11
	v_add3_u32 v12, s18, v0, v158
	v_ashrrev_i32_e32 v0, 31, v2
	v_lshrrev_b32_e32 v0, 28, v0
	v_add_u32_e32 v0, v2, v0
	v_ashrrev_i32_e32 v159, 4, v0
	v_and_b32_e32 v0, 0x1ffffff0, v0
	v_lshlrev_b32_e32 v1, 2, v159
	v_sub_u32_e32 v0, v2, v0
	v_and_b32_e32 v1, 12, v1
	v_bfe_u32 v2, v159, 2, 2
	v_bitop3_b32 v0, v1, v0, v2 bitop3:0x36
	s_lshl_b32 s2, s21, 10
	v_lshlrev_b32_e32 v160, 3, v0
	v_add_lshl_u32 v0, v159, s8, 11
	s_add_i32 s7, s2, 0
	v_mov_b32_e32 v11, v7
	v_add3_u32 v2, s18, v0, v160
	v_lshl_add_u64 v[0:1], v[10:11], 1, s[84:85]
	s_mov_b32 m0, s7
	v_mov_b32_e32 v9, v7
	v_lshl_add_u32 v4, v4, 3, v149
	global_load_lds_dwordx4 v[0:1], off
	v_lshl_add_u64 v[0:1], v[8:9], 1, s[84:85]
	s_add_i32 m0, s7, 0x2000
	v_mov_b32_e32 v5, v7
	global_load_lds_dwordx4 v[0:1], off
	v_lshl_add_u64 v[0:1], v[4:5], 1, s[84:85]
	s_add_i32 m0, s7, 0x4000
	v_mov_b32_e32 v13, v7
	global_load_lds_dwordx4 v[0:1], off
	s_add_i32 m0, s7, 0x6000
	v_lshl_add_u64 v[0:1], v[12:13], 1, s[84:85]
	v_mov_b32_e32 v3, v7
	global_load_lds_dwordx4 v[0:1], off
	v_lshl_add_u64 v[0:1], v[2:3], 1, s[84:85]
	s_add_i32 m0, s7, 0x8000
	s_cmpk_gt_u32 s14, 0xff
	global_load_lds_dwordx4 v[0:1], off
	v_mov_b32_e32 v0, v7
	s_waitcnt vmcnt(0) lgkmcnt(0)
	s_barrier
	s_waitcnt vmcnt(0)
	s_cselect_b64 s[10:11], -1, 0
	s_cmpk_lt_u32 s14, 0x100
	v_add_u32_e32 v6, v10, v154
	v_lshrrev_b32_e32 v0, 1, v222
	s_cselect_b64 s[14:15], -1, 0
	s_add_i32 m0, s7, 0xa000
	v_lshl_add_u64 v[10:11], v[6:7], 1, s[84:85]
	v_add_u32_e32 v6, v8, v155
	v_bfe_u32 v1, v222, 1, 3
	v_mul_u32_u24_e32 v13, 0x180, v194
	v_bitop3_b32 v3, v161, v0, 7 bitop3:0x78
	global_load_lds_dwordx4 v[10:11], off
	v_lshl_add_u64 v[8:9], v[6:7], 1, s[84:85]
	s_add_i32 m0, s7, 0xc000
	v_add_u32_e32 v6, v4, v156
	v_lshl_or_b32 v170, v3, 4, v13
	v_bitop3_b32 v3, v161, v1, 2 bitop3:0x36
	global_load_lds_dwordx4 v[8:9], off
	v_lshl_add_u64 v[4:5], v[6:7], 1, s[84:85]
	s_add_i32 m0, s7, 0xe000
	v_add_u32_e32 v6, 0x20000, v12
	v_lshl_or_b32 v171, v3, 4, v13
	v_bitop3_b32 v3, v161, v1, 4 bitop3:0x36
	global_load_lds_dwordx4 v[4:5], off
	s_add_i32 m0, s7, 0x10000
	v_lshl_add_u64 v[4:5], v[6:7], 1, s[84:85]
	v_add_u32_e32 v6, 0x20000, v2
	v_lshl_or_b32 v172, v3, 4, v13
	global_load_lds_dwordx4 v[4:5], off
	v_lshl_add_u64 v[2:3], v[6:7], 1, s[84:85]
	s_add_i32 m0, s7, 0x12000
	v_add_u32_e32 v190, 0, v170
	global_load_lds_dwordx4 v[2:3], off
	ds_read_b128 v[2:5], v190
	v_bitop3_b32 v1, v161, v1, 6 bitop3:0x36
	v_lshl_or_b32 v173, v1, 4, v13
	v_add_u32_e32 v191, 0, v171
	ds_read_b128 v[6:9], v191
	v_add_u32_e32 v192, 0, v172
	v_add_u32_e32 v193, 0, v173
	ds_read_b128 v[10:13], v192
	ds_read_b128 v[14:17], v193
	s_waitcnt lgkmcnt(0)
	v_mfma_f32_32x32x16_bf16 v[48:63], v[2:5], v[96:99], 0
	ds_read_b128 v[2:5], v190 offset:128
	v_or_b32_e32 v1, 2, v161
	s_and_b64 vcc, exec, s[14:15]
	v_mfma_f32_32x32x16_bf16 v[48:63], v[6:9], v[100:103], v[48:63]
	ds_read_b128 v[6:9], v191 offset:128
	v_mfma_f32_32x32x16_bf16 v[48:63], v[10:13], v[104:107], v[48:63]
	ds_read_b128 v[10:13], v192 offset:128
	v_mfma_f32_32x32x16_bf16 v[48:63], v[14:17], v[108:111], v[48:63]
	ds_read_b128 v[14:17], v193 offset:128
	s_waitcnt lgkmcnt(0)
	v_mfma_f32_32x32x16_bf16 v[48:63], v[2:5], v[112:115], v[48:63]
	ds_read_b128 v[2:5], v190 offset:256
	v_mfma_f32_32x32x16_bf16 v[48:63], v[6:9], v[116:119], v[48:63]
	ds_read_b128 v[6:9], v191 offset:256
	v_mfma_f32_32x32x16_bf16 v[48:63], v[10:13], v[120:123], v[48:63]
	ds_read_b128 v[10:13], v192 offset:256
	v_mfma_f32_32x32x16_bf16 v[48:63], v[14:17], v[124:127], v[48:63]
	ds_read_b128 v[14:17], v193 offset:256
	s_waitcnt lgkmcnt(0)
	v_mfma_f32_32x32x16_bf16 v[48:63], v[2:5], v[128:131], v[48:63]
	ds_read_b128 v[2:5], v190 offset:12288
	v_mfma_f32_32x32x16_bf16 v[48:63], v[6:9], v[132:135], v[48:63]
	ds_read_b128 v[6:9], v191 offset:12288
	v_mfma_f32_32x32x16_bf16 v[48:63], v[10:13], v[136:139], v[48:63]
	ds_read_b128 v[10:13], v192 offset:12288
	s_waitcnt lgkmcnt(0)
	v_mfma_f32_32x32x16_bf16 v[80:95], v[2:5], v[96:99], 0
	ds_read_b128 v[18:21], v193 offset:12288
	v_mfma_f32_32x32x16_bf16 v[80:95], v[6:9], v[100:103], v[80:95]
	ds_read_b128 v[22:25], v190 offset:12416
	v_mfma_f32_32x32x16_bf16 v[80:95], v[10:13], v[104:107], v[80:95]
	ds_read_b128 v[26:29], v191 offset:12416
	s_waitcnt lgkmcnt(0)
	v_mfma_f32_32x32x16_bf16 v[80:95], v[18:21], v[108:111], v[80:95]
	ds_read_b128 v[30:33], v192 offset:12416
	v_mfma_f32_32x32x16_bf16 v[80:95], v[22:25], v[112:115], v[80:95]
	ds_read_b128 v[34:37], v193 offset:12416
	v_mfma_f32_32x32x16_bf16 v[80:95], v[26:29], v[116:119], v[80:95]
	ds_read_b128 v[38:41], v190 offset:12544
	s_waitcnt lgkmcnt(0)
	v_mfma_f32_32x32x16_bf16 v[80:95], v[30:33], v[120:123], v[80:95]
	ds_read_b128 v[42:45], v191 offset:12544
	v_mfma_f32_32x32x16_bf16 v[80:95], v[34:37], v[124:127], v[80:95]
	ds_read_b128 v[64:67], v192 offset:12544
	v_mfma_f32_32x32x16_bf16 v[80:95], v[38:41], v[128:131], v[80:95]
	ds_read_b128 v[68:71], v193 offset:12544
	s_waitcnt lgkmcnt(0)
	v_mfma_f32_32x32x16_bf16 v[80:95], v[42:45], v[132:135], v[80:95]
	v_mfma_f32_32x32x16_bf16 v[80:95], v[64:67], v[136:139], v[80:95]
	v_mfma_f32_32x32x16_bf16 v[80:95], v[68:71], v[140:143], v[80:95]
	v_mfma_f32_32x32x16_bf16 v[48:63], v[14:17], v[140:143], v[48:63]
	s_cbranch_vccnz .LBB0_1809
	s_waitcnt vmcnt(0) lgkmcnt(0)
	s_barrier
.LBB0_1809:
	v_bfe_u32 v2, v222, 2, 2
	v_lshrrev_b32_e32 v5, 3, v222
	v_lshlrev_b32_e32 v6, 3, v222
	v_lshlrev_b32_e32 v3, 10, v161
	v_lshlrev_b32_e32 v4, 8, v2
	v_and_b32_e32 v5, 2, v5
	v_and_b32_e32 v0, 1, v0
	v_and_b32_e32 v6, 8, v6
	v_or3_b32 v3, v4, v6, v3
	v_bitop3_b32 v4, v5, v161, v0 bitop3:0x36
	v_bitop3_b32 v0, v1, v5, v0 bitop3:0x1e
	v_lshl_or_b32 v175, v0, 4, v3
	v_max_f32_e32 v0, v49, v49
	v_max_f32_e32 v1, v48, v48
	v_max_f32_e32 v0, v1, v0
	v_max3_f32 v0, v0, v50, v51
	v_max3_f32 v0, v0, v52, v53
	v_max3_f32 v0, v0, v54, v55
	v_max3_f32 v0, v0, v56, v57
	v_max3_f32 v0, v0, v58, v59
	v_max3_f32 v0, v0, v60, v61
	v_max3_f32 v0, v0, v62, v63
	v_mov_b32_e32 v1, v0
	s_nop 1
	v_permlane32_swap_b32_e32 v0, v1
	v_max_f32_e32 v1, v1, v1
	v_max_f32_e32 v0, v0, v0
	v_max_f32_e32 v0, v0, v1
	s_cmp_lg_u64 exec, 0
	v_add_f32_e32 v0, 0, v0
	s_cselect_b64 vcc, -1, 0
	v_cndmask_b32_e32 v157, 0, v0, vcc
	v_sub_f32_e32 v0, v48, v157
	v_exp_f32_e32 v48, v0
	v_sub_f32_e32 v0, v49, v157
	v_exp_f32_e32 v49, v0
	v_sub_f32_e32 v0, v50, v157
	v_exp_f32_e32 v50, v0
	v_sub_f32_e32 v0, v51, v157
	v_exp_f32_e32 v51, v0
	v_sub_f32_e32 v0, v52, v157
	v_lshl_or_b32 v174, v4, 4, v3
	v_exp_f32_e32 v52, v0
	v_sub_f32_e32 v0, v53, v157
	v_lshlrev_b32_e32 v177, 6, v2
	v_add_u32_e32 v12, 0, v174
	v_exp_f32_e32 v53, v0
	v_sub_f32_e32 v0, v54, v157
	v_add_u32_e32 v13, 0, v175
	v_exp_f32_e32 v54, v0
	v_sub_f32_e32 v0, v55, v157
	v_add_u32_e32 v183, v12, v177
	v_exp_f32_e32 v55, v0
	v_add_u32_e32 v185, v13, v177
	ds_read_b64_tr_b16 v[4:5], v183 offset:24576
	ds_read_b64_tr_b16 v[6:7], v185 offset:26624
	v_sub_f32_e32 v0, v56, v157
	v_exp_f32_e32 v56, v0
	v_sub_f32_e32 v0, v57, v157
	v_xor_b32_e32 v178, 64, v177
	v_xor_b32_e32 v179, 0x80, v177
	v_exp_f32_e32 v57, v0
	v_sub_f32_e32 v0, v58, v157
	v_exp_f32_e32 v58, v0
	v_cvt_pk_bf16_f32 v0, v48, v49
	v_cvt_pk_bf16_f32 v1, v50, v51
	v_cvt_pk_bf16_f32 v2, v52, v53
	v_cvt_pk_bf16_f32 v3, v54, v55
	v_add_u32_e32 v182, v12, v178
	v_add_u32_e32 v186, v12, v179
	v_add_u32_e32 v184, v13, v178
	ds_read_b64_tr_b16 v[8:9], v182 offset:24576
	ds_read_b64_tr_b16 v[10:11], v184 offset:26624
	ds_read_b64_tr_b16 v[164:165], v185 offset:30720
	ds_read_b64_tr_b16 v[162:163], v183 offset:28672
	s_waitcnt lgkmcnt(0)
	v_mfma_f32_32x32x16_bf16 v[64:79], v[4:7], v[0:3], 0
	v_add_u32_e32 v188, v13, v179
	ds_read_b64_tr_b16 v[4:5], v186 offset:24576
	ds_read_b64_tr_b16 v[6:7], v188 offset:26624
	ds_read_b64_tr_b16 v[168:169], v184 offset:30720
	ds_read_b64_tr_b16 v[166:167], v182 offset:28672
	v_sub_f32_e32 v14, v59, v157
	v_sub_f32_e32 v62, v62, v157
	v_sub_f32_e32 v63, v63, v157
	v_exp_f32_e32 v59, v14
	v_exp_f32_e32 v62, v62
	s_waitcnt lgkmcnt(0)
	v_mfma_f32_32x32x16_bf16 v[16:31], v[4:7], v[0:3], 0
	v_sub_f32_e32 v4, v60, v157
	v_exp_f32_e32 v60, v4
	v_sub_f32_e32 v4, v61, v157
	v_exp_f32_e32 v61, v4
	v_exp_f32_e32 v63, v63
	v_xor_b32_e32 v180, 0xc0, v177
	v_add_u32_e32 v187, v12, v180
	v_mfma_f32_32x32x16_bf16 v[32:47], v[8:11], v[0:3], 0
	v_add_u32_e32 v189, v13, v180
	ds_read_b64_tr_b16 v[8:9], v187 offset:24576
	ds_read_b64_tr_b16 v[10:11], v189 offset:26624
	ds_read_b64_tr_b16 v[200:201], v188 offset:30720
	ds_read_b64_tr_b16 v[198:199], v186 offset:28672
	v_cvt_pk_bf16_f32 v206, v56, v57
	v_cvt_pk_bf16_f32 v207, v58, v59
	v_cvt_pk_bf16_f32 v208, v60, v61
	v_cvt_pk_bf16_f32 v209, v62, v63
	ds_read_b64_tr_b16 v[204:205], v189 offset:30720
	ds_read_b64_tr_b16 v[202:203], v187 offset:28672
	v_mfma_f32_32x32x16_bf16 v[64:79], v[162:165], v[206:209], v[64:79]
	v_add_f32_e32 v162, 0, v48
	v_add_f32_e32 v162, v49, v162
	v_add_f32_e32 v162, v50, v162
	v_max_f32_e32 v163, v81, v81
	v_max_f32_e32 v164, v80, v80
	v_add_f32_e32 v162, v51, v162
	v_max_f32_e32 v163, v164, v163
	s_waitcnt lgkmcnt(0)
	v_mfma_f32_32x32x16_bf16 v[0:15], v[8:11], v[0:3], 0
	v_add_f32_e32 v162, v52, v162
	v_max3_f32 v163, v163, v82, v83
	v_add_f32_e32 v162, v53, v162
	v_max3_f32 v163, v163, v84, v85
	v_add_f32_e32 v162, v54, v162
	v_max3_f32 v163, v163, v86, v87
	v_add_f32_e32 v162, v55, v162
	v_max3_f32 v163, v163, v88, v89
	v_add_f32_e32 v162, v56, v162
	v_max3_f32 v163, v163, v90, v91
	v_mfma_f32_32x32x16_bf16 v[32:47], v[166:169], v[206:209], v[32:47]
	v_add_f32_e32 v162, v57, v162
	v_max3_f32 v163, v163, v92, v93
	v_add_f32_e32 v162, v58, v162
	v_max3_f32 v163, v163, v94, v95
	v_add_f32_e32 v162, v59, v162
	v_mov_b32_e32 v164, v163
	v_add_f32_e32 v162, v60, v162
	v_mfma_f32_32x32x16_bf16 v[16:31], v[198:201], v[206:209], v[16:31]
	v_permlane32_swap_b32_e32 v163, v164
	v_add_f32_e32 v162, v61, v162
	v_max_f32_e32 v164, v164, v164
	v_max_f32_e32 v163, v163, v163
	v_add_f32_e32 v162, v62, v162
	v_max_f32_e32 v163, v163, v164
	v_mfma_f32_32x32x16_bf16 v[0:15], v[202:205], v[206:209], v[0:15]
	v_add_f32_e32 v162, v63, v162
	v_sub_f32_e32 v163, v163, v157
	s_mov_b32 s2, 0x41000000
	v_add_f32_e32 v162, 0, v162
	v_cmp_lt_f32_e32 vcc, s2, v163
	s_cbranch_vccz .LBB0_1811
	v_max_f32_e32 v163, v163, v163
	v_max_f32_e32 v163, 0, v163
	v_exp_f32_e64 v164, -v163
	v_add_f32_e32 v157, v157, v163
	v_pk_mul_f32 v[78:79], v[78:79], v[164:165] op_sel_hi:[1,0]
	v_pk_mul_f32 v[76:77], v[76:77], v[164:165] op_sel_hi:[1,0]
	v_pk_mul_f32 v[74:75], v[74:75], v[164:165] op_sel_hi:[1,0]
	v_pk_mul_f32 v[72:73], v[72:73], v[164:165] op_sel_hi:[1,0]
	v_pk_mul_f32 v[70:71], v[70:71], v[164:165] op_sel_hi:[1,0]
	v_pk_mul_f32 v[68:69], v[68:69], v[164:165] op_sel_hi:[1,0]
	v_pk_mul_f32 v[66:67], v[66:67], v[164:165] op_sel_hi:[1,0]
	v_pk_mul_f32 v[64:65], v[64:65], v[164:165] op_sel_hi:[1,0]
	v_pk_mul_f32 v[46:47], v[46:47], v[164:165] op_sel_hi:[1,0]
	v_pk_mul_f32 v[44:45], v[44:45], v[164:165] op_sel_hi:[1,0]
	v_pk_mul_f32 v[42:43], v[42:43], v[164:165] op_sel_hi:[1,0]
	v_pk_mul_f32 v[40:41], v[40:41], v[164:165] op_sel_hi:[1,0]
	v_pk_mul_f32 v[38:39], v[38:39], v[164:165] op_sel_hi:[1,0]
	v_pk_mul_f32 v[36:37], v[36:37], v[164:165] op_sel_hi:[1,0]
	v_pk_mul_f32 v[34:35], v[34:35], v[164:165] op_sel_hi:[1,0]
	v_pk_mul_f32 v[32:33], v[32:33], v[164:165] op_sel_hi:[1,0]
	v_pk_mul_f32 v[30:31], v[30:31], v[164:165] op_sel_hi:[1,0]
	v_pk_mul_f32 v[28:29], v[28:29], v[164:165] op_sel_hi:[1,0]
	v_pk_mul_f32 v[26:27], v[26:27], v[164:165] op_sel_hi:[1,0]
	v_pk_mul_f32 v[24:25], v[24:25], v[164:165] op_sel_hi:[1,0]
	v_pk_mul_f32 v[22:23], v[22:23], v[164:165] op_sel_hi:[1,0]
	v_pk_mul_f32 v[20:21], v[20:21], v[164:165] op_sel_hi:[1,0]
	v_pk_mul_f32 v[18:19], v[18:19], v[164:165] op_sel_hi:[1,0]
	v_pk_mul_f32 v[16:17], v[16:17], v[164:165] op_sel_hi:[1,0]
	v_pk_mul_f32 v[14:15], v[14:15], v[164:165] op_sel_hi:[1,0]
	v_pk_mul_f32 v[12:13], v[12:13], v[164:165] op_sel_hi:[1,0]
	v_pk_mul_f32 v[10:11], v[10:11], v[164:165] op_sel_hi:[1,0]
	v_pk_mul_f32 v[8:9], v[8:9], v[164:165] op_sel_hi:[1,0]
	v_pk_mul_f32 v[6:7], v[6:7], v[164:165] op_sel_hi:[1,0]
	v_pk_mul_f32 v[4:5], v[4:5], v[164:165] op_sel_hi:[1,0]
	v_pk_mul_f32 v[2:3], v[2:3], v[164:165] op_sel_hi:[1,0]
	v_pk_mul_f32 v[0:1], v[0:1], v[164:165] op_sel_hi:[1,0]
	v_mul_f32_e32 v162, v162, v164
.LBB0_1811:
	v_sub_f32_e32 v80, v80, v157
	v_sub_f32_e32 v81, v81, v157
	v_sub_f32_e32 v82, v82, v157
	v_sub_f32_e32 v83, v83, v157
	v_sub_f32_e32 v84, v84, v157
	v_sub_f32_e32 v85, v85, v157
	v_sub_f32_e32 v86, v86, v157
	v_sub_f32_e32 v87, v87, v157
	v_exp_f32_e32 v80, v80
	v_exp_f32_e32 v81, v81
	v_exp_f32_e32 v82, v82
	v_exp_f32_e32 v83, v83
	v_exp_f32_e32 v84, v84
	v_exp_f32_e32 v85, v85
	v_exp_f32_e32 v86, v86
	v_exp_f32_e32 v87, v87
	ds_read_b64_tr_b16 v[164:165], v183 offset:32768
	ds_read_b64_tr_b16 v[166:167], v185 offset:34816
	ds_read_b64_tr_b16 v[202:203], v182 offset:32768
	ds_read_b64_tr_b16 v[204:205], v184 offset:34816
	ds_read_b64_tr_b16 v[208:209], v185 offset:38912
	ds_read_b64_tr_b16 v[206:207], v183 offset:36864
	v_cvt_pk_bf16_f32 v198, v80, v81
	v_cvt_pk_bf16_f32 v199, v82, v83
	v_cvt_pk_bf16_f32 v200, v84, v85
	v_cvt_pk_bf16_f32 v201, v86, v87
	v_sub_f32_e32 v88, v88, v157
	v_sub_f32_e32 v89, v89, v157
	s_waitcnt lgkmcnt(0)
	v_mfma_f32_32x32x16_bf16 v[64:79], v[164:167], v[198:201], v[64:79]
	ds_read_b64_tr_b16 v[164:165], v186 offset:32768
	ds_read_b64_tr_b16 v[166:167], v188 offset:34816
	ds_read_b64_tr_b16 v[212:213], v184 offset:38912
	ds_read_b64_tr_b16 v[210:211], v182 offset:36864
	v_sub_f32_e32 v90, v90, v157
	v_sub_f32_e32 v91, v91, v157
	v_sub_f32_e32 v92, v92, v157
	v_sub_f32_e32 v93, v93, v157
	v_sub_f32_e32 v94, v94, v157
	v_sub_f32_e32 v95, v95, v157
	v_mfma_f32_32x32x16_bf16 v[32:47], v[202:205], v[198:201], v[32:47]
	ds_read_b64_tr_b16 v[202:203], v187 offset:32768
	ds_read_b64_tr_b16 v[204:205], v189 offset:34816
	ds_read_b64_tr_b16 v[216:217], v188 offset:38912
	ds_read_b64_tr_b16 v[214:215], v186 offset:36864
	v_exp_f32_e32 v88, v88
	v_exp_f32_e32 v89, v89
	v_exp_f32_e32 v90, v90
	v_exp_f32_e32 v91, v91
	v_exp_f32_e32 v92, v92
	v_exp_f32_e32 v93, v93
	s_waitcnt lgkmcnt(0)
	v_mfma_f32_32x32x16_bf16 v[16:31], v[164:167], v[198:201], v[16:31]
	ds_read_b64_tr_b16 v[166:167], v189 offset:38912
	ds_read_b64_tr_b16 v[164:165], v187 offset:36864
	v_exp_f32_e32 v94, v94
	v_exp_f32_e32 v95, v95
	v_bitop3_b32 v163, v150, 7, v222 bitop3:0x48
	v_bitop3_b32 v150, v152, 7, v222 bitop3:0x48
	v_cndmask_b32_e64 v152, 0, 1, s[14:15]
	v_lshlrev_b32_e32 v181, 3, v161
	v_mfma_f32_32x32x16_bf16 v[0:15], v[202:205], v[198:201], v[0:15]
	v_cvt_pk_bf16_f32 v198, v88, v89
	v_cvt_pk_bf16_f32 v199, v90, v91
	v_cvt_pk_bf16_f32 v200, v92, v93
	v_cvt_pk_bf16_f32 v201, v94, v95
	v_bitop3_b32 v151, v151, 7, v222 bitop3:0x48
	v_cmp_ne_u32_e64 s[2:3], 1, v152
	s_andn2_b64 vcc, exec, s[14:15]
	v_mfma_f32_32x32x16_bf16 v[64:79], v[206:209], v[198:201], v[64:79]
	s_mov_b32 s27, 1
	v_mfma_f32_32x32x16_bf16 v[32:47], v[210:213], v[198:201], v[32:47]
	v_mfma_f32_32x32x16_bf16 v[16:31], v[214:217], v[198:201], v[16:31]
	s_waitcnt lgkmcnt(0)
	v_mfma_f32_32x32x16_bf16 v[0:15], v[164:167], v[198:201], v[0:15]
	s_cbranch_vccnz .LBB0_1813
	s_waitcnt vmcnt(0) lgkmcnt(0)
	s_barrier

.LBB0_1822:
	s_setprio 0
	v_add_u32_e32 v147, s26, v170
	ds_read_b128 v[48:51], v147
	v_add_u32_e32 v149, s26, v171
	v_add_u32_e32 v151, s26, v172
	v_add_u32_e32 v153, s26, v173
	ds_read_b128 v[80:83], v149
	ds_read_b128 v[84:87], v151
	ds_read_b128 v[88:91], v153
	s_waitcnt lgkmcnt(0)
	v_mfma_f32_32x32x16_bf16 v[48:63], v[48:51], v[96:99], 0
	ds_read_b128 v[92:95], v147 offset:128
	v_mfma_f32_32x32x16_bf16 v[48:63], v[80:83], v[100:103], v[48:63]
	ds_read_b128 v[80:83], v149 offset:128
	v_mfma_f32_32x32x16_bf16 v[48:63], v[84:87], v[104:107], v[48:63]
	ds_read_b128 v[84:87], v151 offset:128
	v_mfma_f32_32x32x16_bf16 v[48:63], v[88:91], v[108:111], v[48:63]
	ds_read_b128 v[88:91], v153 offset:128
	s_waitcnt lgkmcnt(0)
	v_mfma_f32_32x32x16_bf16 v[48:63], v[92:95], v[112:115], v[48:63]
	ds_read_b128 v[92:95], v147 offset:256
	v_mfma_f32_32x32x16_bf16 v[48:63], v[80:83], v[116:119], v[48:63]
	ds_read_b128 v[80:83], v149 offset:256
	v_mfma_f32_32x32x16_bf16 v[48:63], v[84:87], v[120:123], v[48:63]
	ds_read_b128 v[84:87], v151 offset:256
	v_mfma_f32_32x32x16_bf16 v[48:63], v[88:91], v[124:127], v[48:63]
	ds_read_b128 v[162:165], v153 offset:256
	s_waitcnt lgkmcnt(0)
	v_mfma_f32_32x32x16_bf16 v[48:63], v[92:95], v[128:131], v[48:63]
	ds_read_b128 v[88:91], v147 offset:12288
	v_mfma_f32_32x32x16_bf16 v[48:63], v[80:83], v[132:135], v[48:63]
	ds_read_b128 v[166:169], v149 offset:12288
	v_mfma_f32_32x32x16_bf16 v[48:63], v[84:87], v[136:139], v[48:63]
	ds_read_b128 v[198:201], v151 offset:12288
	s_waitcnt lgkmcnt(0)
	v_mfma_f32_32x32x16_bf16 v[80:95], v[88:91], v[96:99], 0
	ds_read_b128 v[202:205], v153 offset:12288
	v_mfma_f32_32x32x16_bf16 v[80:95], v[166:169], v[100:103], v[80:95]
	ds_read_b128 v[206:209], v147 offset:12416
	v_mfma_f32_32x32x16_bf16 v[80:95], v[198:201], v[104:107], v[80:95]
	ds_read_b128 v[210:213], v149 offset:12416
	s_waitcnt lgkmcnt(0)
	v_mfma_f32_32x32x16_bf16 v[80:95], v[202:205], v[108:111], v[80:95]
	ds_read_b128 v[214:217], v151 offset:12416
	v_mfma_f32_32x32x16_bf16 v[80:95], v[206:209], v[112:115], v[80:95]
	ds_read_b128 v[218:221], v153 offset:12416
	v_mfma_f32_32x32x16_bf16 v[80:95], v[210:213], v[116:119], v[80:95]
	ds_read_b128 v[224:227], v147 offset:12544
	s_waitcnt lgkmcnt(0)
	v_mfma_f32_32x32x16_bf16 v[80:95], v[214:217], v[120:123], v[80:95]
	ds_read_b128 v[228:231], v149 offset:12544
	v_mfma_f32_32x32x16_bf16 v[80:95], v[218:221], v[124:127], v[80:95]
	ds_read_b128 v[232:235], v151 offset:12544
	v_mfma_f32_32x32x16_bf16 v[80:95], v[224:227], v[128:131], v[80:95]
	ds_read_b128 v[236:239], v153 offset:12544
	s_waitcnt lgkmcnt(0)
	v_mfma_f32_32x32x16_bf16 v[80:95], v[228:231], v[132:135], v[80:95]
	v_mfma_f32_32x32x16_bf16 v[80:95], v[232:235], v[136:139], v[80:95]
	v_mfma_f32_32x32x16_bf16 v[80:95], v[236:239], v[140:143], v[80:95]
	v_mfma_f32_32x32x16_bf16 v[48:63], v[162:165], v[140:143], v[48:63]
	s_andn2_b64 vcc, exec, s[10:11]
	s_cbranch_vccnz .LBB0_1817

.LBB0_1824:
	s_setprio 1
	s_nop 7
	v_max_f32_e32 v147, v49, v49
	v_max_f32_e32 v149, v48, v48
	v_max_f32_e32 v147, v149, v147
	v_max3_f32 v147, v147, v50, v51
	v_max3_f32 v147, v147, v52, v53
	v_max3_f32 v147, v147, v54, v55
	v_max3_f32 v147, v147, v56, v57
	v_max3_f32 v147, v147, v58, v59
	v_max3_f32 v147, v147, v60, v61
	v_max3_f32 v147, v147, v62, v63
	v_mov_b32_e32 v149, v147
	s_nop 1
	v_permlane32_swap_b32_e32 v147, v149
	v_max_f32_e32 v149, v149, v149
	v_max_f32_e32 v147, v147, v147
	v_max_f32_e32 v147, v147, v149
	v_sub_f32_e32 v147, v147, v157
	v_cmp_lt_f32_e32 vcc, s24, v147
	s_cbranch_vccz .LBB0_1826
	v_max_f32_e32 v147, v147, v147
	v_max_f32_e32 v147, 0, v147
	v_exp_f32_e64 v158, -v147
	v_add_f32_e32 v157, v157, v147
	v_pk_mul_f32 v[78:79], v[78:79], v[158:159] op_sel_hi:[1,0]
	v_pk_mul_f32 v[76:77], v[76:77], v[158:159] op_sel_hi:[1,0]
	v_pk_mul_f32 v[74:75], v[74:75], v[158:159] op_sel_hi:[1,0]
	v_pk_mul_f32 v[72:73], v[72:73], v[158:159] op_sel_hi:[1,0]
	v_pk_mul_f32 v[70:71], v[70:71], v[158:159] op_sel_hi:[1,0]
	v_pk_mul_f32 v[68:69], v[68:69], v[158:159] op_sel_hi:[1,0]
	v_pk_mul_f32 v[66:67], v[66:67], v[158:159] op_sel_hi:[1,0]
	v_pk_mul_f32 v[64:65], v[64:65], v[158:159] op_sel_hi:[1,0]
	v_pk_mul_f32 v[46:47], v[46:47], v[158:159] op_sel_hi:[1,0]
	v_pk_mul_f32 v[44:45], v[44:45], v[158:159] op_sel_hi:[1,0]
	v_pk_mul_f32 v[42:43], v[42:43], v[158:159] op_sel_hi:[1,0]
	v_pk_mul_f32 v[40:41], v[40:41], v[158:159] op_sel_hi:[1,0]
	v_pk_mul_f32 v[38:39], v[38:39], v[158:159] op_sel_hi:[1,0]
	v_pk_mul_f32 v[36:37], v[36:37], v[158:159] op_sel_hi:[1,0]
	v_pk_mul_f32 v[34:35], v[34:35], v[158:159] op_sel_hi:[1,0]
	v_pk_mul_f32 v[32:33], v[32:33], v[158:159] op_sel_hi:[1,0]
	v_pk_mul_f32 v[30:31], v[30:31], v[158:159] op_sel_hi:[1,0]
	v_pk_mul_f32 v[28:29], v[28:29], v[158:159] op_sel_hi:[1,0]
	v_pk_mul_f32 v[26:27], v[26:27], v[158:159] op_sel_hi:[1,0]
	v_pk_mul_f32 v[24:25], v[24:25], v[158:159] op_sel_hi:[1,0]
	v_pk_mul_f32 v[22:23], v[22:23], v[158:159] op_sel_hi:[1,0]
	v_pk_mul_f32 v[20:21], v[20:21], v[158:159] op_sel_hi:[1,0]
	v_pk_mul_f32 v[18:19], v[18:19], v[158:159] op_sel_hi:[1,0]
	v_pk_mul_f32 v[16:17], v[16:17], v[158:159] op_sel_hi:[1,0]
	v_pk_mul_f32 v[14:15], v[14:15], v[158:159] op_sel_hi:[1,0]
	v_pk_mul_f32 v[12:13], v[12:13], v[158:159] op_sel_hi:[1,0]
	v_pk_mul_f32 v[10:11], v[10:11], v[158:159] op_sel_hi:[1,0]
	v_pk_mul_f32 v[8:9], v[8:9], v[158:159] op_sel_hi:[1,0]
	v_pk_mul_f32 v[6:7], v[6:7], v[158:159] op_sel_hi:[1,0]
	v_pk_mul_f32 v[4:5], v[4:5], v[158:159] op_sel_hi:[1,0]
	v_pk_mul_f32 v[2:3], v[2:3], v[158:159] op_sel_hi:[1,0]
	v_pk_mul_f32 v[0:1], v[0:1], v[158:159] op_sel_hi:[1,0]
	v_mul_f32_e32 v161, v161, v158
.LBB0_1826:
	v_add_u32_e32 v159, s26, v174
	v_add_u32_e32 v162, s26, v175
	v_sub_f32_e32 v48, v48, v157
	v_sub_f32_e32 v49, v49, v157
	v_sub_f32_e32 v50, v50, v157
	v_sub_f32_e32 v51, v51, v157
	v_sub_f32_e32 v52, v52, v157
	v_sub_f32_e32 v53, v53, v157
	v_sub_f32_e32 v54, v54, v157
	v_sub_f32_e32 v55, v55, v157
	v_add_u32_e32 v149, v159, v177
	v_exp_f32_e32 v48, v48
	v_exp_f32_e32 v49, v49
	v_exp_f32_e32 v50, v50
	v_exp_f32_e32 v51, v51
	v_exp_f32_e32 v52, v52
	v_exp_f32_e32 v53, v53
	v_exp_f32_e32 v54, v54
	v_exp_f32_e32 v55, v55
	v_add_u32_e32 v153, v162, v177
	ds_read_b64_tr_b16 v[198:199], v149 offset:24576
	ds_read_b64_tr_b16 v[200:201], v153 offset:26624
	v_add_u32_e32 v147, v159, v178
	v_add_u32_e32 v151, v162, v178
	ds_read_b64_tr_b16 v[202:203], v147 offset:24576
	ds_read_b64_tr_b16 v[204:205], v151 offset:26624
	ds_read_b64_tr_b16 v[208:209], v153 offset:30720
	ds_read_b64_tr_b16 v[206:207], v149 offset:28672
	v_cvt_pk_bf16_f32 v164, v48, v49
	v_cvt_pk_bf16_f32 v165, v50, v51
	v_cvt_pk_bf16_f32 v166, v52, v53
	v_cvt_pk_bf16_f32 v167, v54, v55
	v_add_u32_e32 v158, v159, v179
	v_add_u32_e32 v159, v159, v180
	s_waitcnt lgkmcnt(0)
	v_mfma_f32_32x32x16_bf16 v[64:79], v[198:201], v[164:167], v[64:79]
	v_add_u32_e32 v160, v162, v179
	ds_read_b64_tr_b16 v[198:199], v158 offset:24576
	ds_read_b64_tr_b16 v[200:201], v160 offset:26624
	ds_read_b64_tr_b16 v[212:213], v151 offset:30720
	ds_read_b64_tr_b16 v[210:211], v147 offset:28672
	v_add_u32_e32 v162, v162, v180
	v_add_f32_e32 v163, 0, v48
	v_sub_f32_e32 v56, v56, v157
	v_sub_f32_e32 v57, v57, v157
	v_sub_f32_e32 v58, v58, v157
	v_mfma_f32_32x32x16_bf16 v[32:47], v[202:205], v[164:167], v[32:47]
	ds_read_b64_tr_b16 v[202:203], v159 offset:24576
	ds_read_b64_tr_b16 v[204:205], v162 offset:26624
	ds_read_b64_tr_b16 v[216:217], v160 offset:30720
	ds_read_b64_tr_b16 v[214:215], v158 offset:28672
	v_sub_f32_e32 v59, v59, v157
	v_sub_f32_e32 v60, v60, v157
	v_sub_f32_e32 v61, v61, v157
	v_sub_f32_e32 v62, v62, v157
	v_sub_f32_e32 v63, v63, v157
	v_add_f32_e32 v163, v49, v163
	s_waitcnt lgkmcnt(0)
	v_mfma_f32_32x32x16_bf16 v[16:31], v[198:201], v[164:167], v[16:31]
	v_exp_f32_e32 v56, v56
	v_exp_f32_e32 v57, v57
	v_exp_f32_e32 v58, v58
	v_exp_f32_e32 v59, v59
	v_exp_f32_e32 v60, v60
	v_exp_f32_e32 v61, v61
	ds_read_b64_tr_b16 v[200:201], v162 offset:30720
	ds_read_b64_tr_b16 v[198:199], v159 offset:28672
	v_mfma_f32_32x32x16_bf16 v[0:15], v[202:205], v[164:167], v[0:15]
	v_exp_f32_e32 v62, v62
	v_exp_f32_e32 v63, v63
	v_add_f32_e32 v163, v50, v163
	v_add_f32_e32 v163, v51, v163
	v_add_f32_e32 v163, v52, v163
	v_add_f32_e32 v163, v53, v163
	v_cvt_pk_bf16_f32 v164, v56, v57
	v_cvt_pk_bf16_f32 v165, v58, v59
	v_cvt_pk_bf16_f32 v166, v60, v61
	v_cvt_pk_bf16_f32 v167, v62, v63
	v_add_f32_e32 v163, v54, v163
	v_add_f32_e32 v163, v55, v163
	v_mfma_f32_32x32x16_bf16 v[64:79], v[206:209], v[164:167], v[64:79]
	v_add_f32_e32 v163, v56, v163
	v_add_f32_e32 v163, v57, v163
	v_add_f32_e32 v163, v58, v163
	v_add_f32_e32 v163, v59, v163
	v_add_f32_e32 v163, v60, v163
	v_add_f32_e32 v163, v61, v163
	v_add_f32_e32 v163, v62, v163
	v_mfma_f32_32x32x16_bf16 v[32:47], v[210:213], v[164:167], v[32:47]
	v_add_f32_e32 v163, v63, v163
	v_add_f32_e32 v161, v161, v163
	v_mfma_f32_32x32x16_bf16 v[16:31], v[214:217], v[164:167], v[16:31]
	s_waitcnt lgkmcnt(0)
	v_mfma_f32_32x32x16_bf16 v[0:15], v[198:201], v[164:167], v[0:15]
	v_max_f32_e32 v164, v81, v81
	v_max_f32_e32 v165, v80, v80
	v_max_f32_e32 v164, v165, v164
	v_max3_f32 v164, v164, v82, v83
	v_max3_f32 v164, v164, v84, v85
	v_max3_f32 v164, v164, v86, v87
	v_max3_f32 v164, v164, v88, v89
	v_max3_f32 v164, v164, v90, v91
	v_max3_f32 v164, v164, v92, v93
	v_max3_f32 v164, v164, v94, v95
	v_mov_b32_e32 v163, v164
	s_nop 1
	v_permlane32_swap_b32_e32 v164, v163
	v_max_f32_e32 v163, v163, v163
	v_max_f32_e32 v164, v164, v164
	v_max_f32_e32 v163, v164, v163
	v_sub_f32_e32 v163, v163, v157
	v_cmp_lt_f32_e32 vcc, s24, v163
	s_cbranch_vccz .LBB0_1828
	v_max_f32_e32 v163, v163, v163
	v_max_f32_e32 v163, 0, v163
	v_exp_f32_e64 v164, -v163
	v_add_f32_e32 v157, v157, v163
	v_pk_mul_f32 v[78:79], v[78:79], v[164:165] op_sel_hi:[1,0]
	v_pk_mul_f32 v[76:77], v[76:77], v[164:165] op_sel_hi:[1,0]
	v_pk_mul_f32 v[74:75], v[74:75], v[164:165] op_sel_hi:[1,0]
	v_pk_mul_f32 v[72:73], v[72:73], v[164:165] op_sel_hi:[1,0]
	v_pk_mul_f32 v[70:71], v[70:71], v[164:165] op_sel_hi:[1,0]
	v_pk_mul_f32 v[68:69], v[68:69], v[164:165] op_sel_hi:[1,0]
	v_pk_mul_f32 v[66:67], v[66:67], v[164:165] op_sel_hi:[1,0]
	v_pk_mul_f32 v[64:65], v[64:65], v[164:165] op_sel_hi:[1,0]
	v_pk_mul_f32 v[46:47], v[46:47], v[164:165] op_sel_hi:[1,0]
	v_pk_mul_f32 v[44:45], v[44:45], v[164:165] op_sel_hi:[1,0]
	v_pk_mul_f32 v[42:43], v[42:43], v[164:165] op_sel_hi:[1,0]
	v_pk_mul_f32 v[40:41], v[40:41], v[164:165] op_sel_hi:[1,0]
	v_pk_mul_f32 v[38:39], v[38:39], v[164:165] op_sel_hi:[1,0]
	v_pk_mul_f32 v[36:37], v[36:37], v[164:165] op_sel_hi:[1,0]
	v_pk_mul_f32 v[34:35], v[34:35], v[164:165] op_sel_hi:[1,0]
	v_pk_mul_f32 v[32:33], v[32:33], v[164:165] op_sel_hi:[1,0]
	v_pk_mul_f32 v[30:31], v[30:31], v[164:165] op_sel_hi:[1,0]
	v_pk_mul_f32 v[28:29], v[28:29], v[164:165] op_sel_hi:[1,0]
	v_pk_mul_f32 v[26:27], v[26:27], v[164:165] op_sel_hi:[1,0]
	v_pk_mul_f32 v[24:25], v[24:25], v[164:165] op_sel_hi:[1,0]
	v_pk_mul_f32 v[22:23], v[22:23], v[164:165] op_sel_hi:[1,0]
	v_pk_mul_f32 v[20:21], v[20:21], v[164:165] op_sel_hi:[1,0]
	v_pk_mul_f32 v[18:19], v[18:19], v[164:165] op_sel_hi:[1,0]
	v_pk_mul_f32 v[16:17], v[16:17], v[164:165] op_sel_hi:[1,0]
	v_pk_mul_f32 v[14:15], v[14:15], v[164:165] op_sel_hi:[1,0]
	v_pk_mul_f32 v[12:13], v[12:13], v[164:165] op_sel_hi:[1,0]
	v_pk_mul_f32 v[10:11], v[10:11], v[164:165] op_sel_hi:[1,0]
	v_pk_mul_f32 v[8:9], v[8:9], v[164:165] op_sel_hi:[1,0]
	v_pk_mul_f32 v[6:7], v[6:7], v[164:165] op_sel_hi:[1,0]
	v_pk_mul_f32 v[4:5], v[4:5], v[164:165] op_sel_hi:[1,0]
	v_pk_mul_f32 v[2:3], v[2:3], v[164:165] op_sel_hi:[1,0]
	v_pk_mul_f32 v[0:1], v[0:1], v[164:165] op_sel_hi:[1,0]
	v_mul_f32_e32 v161, v161, v164
.LBB0_1828:
	v_sub_f32_e32 v80, v80, v157
	v_sub_f32_e32 v81, v81, v157
	v_sub_f32_e32 v82, v82, v157
	v_sub_f32_e32 v83, v83, v157
	v_sub_f32_e32 v84, v84, v157
	v_sub_f32_e32 v85, v85, v157
	v_sub_f32_e32 v86, v86, v157
	v_sub_f32_e32 v87, v87, v157
	v_exp_f32_e32 v80, v80
	v_exp_f32_e32 v81, v81
	v_exp_f32_e32 v82, v82
	v_exp_f32_e32 v83, v83
	v_exp_f32_e32 v84, v84
	v_exp_f32_e32 v85, v85
	v_exp_f32_e32 v86, v86
	v_exp_f32_e32 v87, v87
	ds_read_b64_tr_b16 v[164:165], v149 offset:32768
	ds_read_b64_tr_b16 v[166:167], v153 offset:34816
	ds_read_b64_tr_b16 v[202:203], v147 offset:32768
	ds_read_b64_tr_b16 v[204:205], v151 offset:34816
	ds_read_b64_tr_b16 v[208:209], v153 offset:38912
	ds_read_b64_tr_b16 v[206:207], v149 offset:36864
	v_cvt_pk_bf16_f32 v198, v80, v81
	v_cvt_pk_bf16_f32 v199, v82, v83
	v_cvt_pk_bf16_f32 v200, v84, v85
	v_cvt_pk_bf16_f32 v201, v86, v87
	v_sub_f32_e32 v88, v88, v157
	v_sub_f32_e32 v89, v89, v157
	s_waitcnt lgkmcnt(0)
	v_mfma_f32_32x32x16_bf16 v[64:79], v[164:167], v[198:201], v[64:79]
	ds_read_b64_tr_b16 v[164:165], v158 offset:32768
	ds_read_b64_tr_b16 v[166:167], v160 offset:34816
	ds_read_b64_tr_b16 v[212:213], v151 offset:38912
	ds_read_b64_tr_b16 v[210:211], v147 offset:36864
	v_add_f32_e32 v147, 0, v80
	v_add_f32_e32 v147, v81, v147
	v_add_f32_e32 v147, v82, v147
	v_sub_f32_e32 v90, v90, v157
	v_sub_f32_e32 v91, v91, v157
	v_sub_f32_e32 v92, v92, v157
	v_mfma_f32_32x32x16_bf16 v[32:47], v[202:205], v[198:201], v[32:47]
	ds_read_b64_tr_b16 v[202:203], v159 offset:32768
	ds_read_b64_tr_b16 v[204:205], v162 offset:34816
	ds_read_b64_tr_b16 v[216:217], v160 offset:38912
	ds_read_b64_tr_b16 v[214:215], v158 offset:36864
	v_sub_f32_e32 v93, v93, v157
	v_sub_f32_e32 v94, v94, v157
	v_sub_f32_e32 v95, v95, v157
	v_add_f32_e32 v147, v83, v147
	v_exp_f32_e32 v88, v88
	v_exp_f32_e32 v89, v89
	s_waitcnt lgkmcnt(0)
	v_mfma_f32_32x32x16_bf16 v[16:31], v[164:167], v[198:201], v[16:31]
	v_exp_f32_e32 v90, v90
	v_exp_f32_e32 v91, v91
	v_exp_f32_e32 v92, v92
	v_exp_f32_e32 v93, v93
	ds_read_b64_tr_b16 v[164:165], v162 offset:38912
	ds_read_b64_tr_b16 v[162:163], v159 offset:36864
	v_exp_f32_e32 v94, v94
	v_exp_f32_e32 v95, v95
	v_mfma_f32_32x32x16_bf16 v[0:15], v[202:205], v[198:201], v[0:15]
	v_add_f32_e32 v147, v84, v147
	v_add_f32_e32 v147, v85, v147
	v_add_f32_e32 v147, v86, v147
	v_add_f32_e32 v147, v87, v147
	v_cvt_pk_bf16_f32 v166, v88, v89
	v_cvt_pk_bf16_f32 v167, v90, v91
	v_cvt_pk_bf16_f32 v168, v92, v93
	v_cvt_pk_bf16_f32 v169, v94, v95
	v_add_f32_e32 v147, v88, v147
	v_add_f32_e32 v147, v89, v147
	v_mfma_f32_32x32x16_bf16 v[64:79], v[206:209], v[166:169], v[64:79]
	v_add_f32_e32 v147, v90, v147
	v_add_f32_e32 v147, v91, v147
	v_add_f32_e32 v147, v92, v147
	v_add_f32_e32 v147, v93, v147
	v_add_f32_e32 v147, v94, v147
	v_add_f32_e32 v147, v95, v147
	v_add_f32_e32 v161, v161, v147
	v_mfma_f32_32x32x16_bf16 v[32:47], v[210:213], v[166:169], v[32:47]
	v_mfma_f32_32x32x16_bf16 v[16:31], v[214:217], v[166:169], v[16:31]
	s_waitcnt lgkmcnt(0)
	v_mfma_f32_32x32x16_bf16 v[0:15], v[162:165], v[166:169], v[0:15]
	s_and_b64 vcc, exec, s[2:3]
	s_cbranch_vccz .LBB0_1819
	s_branch .LBB0_1820
.LBB0_1829:
	s_setprio 0
	v_mov_b32_e32 v48, v161
	s_nop 1
	v_permlane32_swap_b32_e32 v161, v48
	v_add_f32_e32 v48, v161, v48
	v_div_scale_f32 v49, s[2:3], v48, v48, 1.0
	v_rcp_f32_e32 v50, v49
	s_mulk_i32 s21, 0x2200
	s_add_i32 s7, s21, 0
	v_mul_u32_u24_e32 v195, 0x110, v194
	v_fma_f32 v51, -v49, v50, 1.0
	v_fmac_f32_e32 v50, v51, v50
	v_div_scale_f32 v51, vcc, 1.0, v48, 1.0
	v_mul_f32_e32 v52, v51, v50
	v_fma_f32 v53, -v49, v52, v51
	v_fmac_f32_e32 v52, v53, v50
	v_fma_f32 v49, -v49, v52, v51
	v_div_fmas_f32 v49, v49, v50, v52
	v_div_fixup_f32 v48, v49, v48, 1.0
	v_add3_u32 v49, s7, v195, v181
	v_pk_mul_f32 v[50:51], v[64:65], v[48:49] op_sel_hi:[1,0]
	v_pk_mul_f32 v[52:53], v[66:67], v[48:49] op_sel_hi:[1,0]
	v_cvt_pk_bf16_f32 v50, v50, v51
	v_cvt_pk_bf16_f32 v51, v52, v53
	v_pk_mul_f32 v[52:53], v[68:69], v[48:49] op_sel_hi:[1,0]
	v_pk_mul_f32 v[54:55], v[70:71], v[48:49] op_sel_hi:[1,0]
	v_add_u32_e32 v49, 0xa000, v49
	v_pk_mul_f32 v[32:33], v[32:33], v[48:49] op_sel_hi:[1,0]
	v_pk_mul_f32 v[34:35], v[34:35], v[48:49] op_sel_hi:[1,0]
	v_pk_mul_f32 v[16:17], v[16:17], v[48:49] op_sel_hi:[1,0]
	v_pk_mul_f32 v[18:19], v[18:19], v[48:49] op_sel_hi:[1,0]
	v_pk_mul_f32 v[0:1], v[0:1], v[48:49] op_sel_hi:[1,0]
	v_pk_mul_f32 v[2:3], v[2:3], v[48:49] op_sel_hi:[1,0]
	v_cvt_pk_bf16_f32 v32, v32, v33
	v_cvt_pk_bf16_f32 v33, v34, v35
	v_pk_mul_f32 v[34:35], v[36:37], v[48:49] op_sel_hi:[1,0]
	v_pk_mul_f32 v[36:37], v[38:39], v[48:49] op_sel_hi:[1,0]
	v_cvt_pk_bf16_f32 v16, v16, v17
	v_cvt_pk_bf16_f32 v17, v18, v19
	v_pk_mul_f32 v[18:19], v[20:21], v[48:49] op_sel_hi:[1,0]
	v_pk_mul_f32 v[20:21], v[22:23], v[48:49] op_sel_hi:[1,0]
	v_cvt_pk_bf16_f32 v0, v0, v1
	v_cvt_pk_bf16_f32 v1, v2, v3
	v_pk_mul_f32 v[2:3], v[4:5], v[48:49] op_sel_hi:[1,0]
	v_pk_mul_f32 v[4:5], v[6:7], v[48:49] op_sel_hi:[1,0]
	v_cvt_pk_bf16_f32 v52, v52, v53
	v_cvt_pk_bf16_f32 v53, v54, v55
	v_cvt_pk_bf16_f32 v34, v34, v35
	v_cvt_pk_bf16_f32 v35, v36, v37
	v_cvt_pk_bf16_f32 v18, v18, v19
	v_cvt_pk_bf16_f32 v19, v20, v21
	v_cvt_pk_bf16_f32 v2, v2, v3
	v_cvt_pk_bf16_f32 v3, v4, v5
	s_waitcnt vmcnt(0) lgkmcnt(0)
	s_barrier
	ds_write2_b64 v49, v[50:51], v[52:53] offset1:2
	v_pk_mul_f32 v[50:51], v[72:73], v[48:49] op_sel_hi:[1,0]
	v_pk_mul_f32 v[52:53], v[74:75], v[48:49] op_sel_hi:[1,0]
	ds_write2_b64 v49, v[32:33], v[34:35] offset0:8 offset1:10
	v_pk_mul_f32 v[32:33], v[40:41], v[48:49] op_sel_hi:[1,0]
	v_pk_mul_f32 v[34:35], v[42:43], v[48:49] op_sel_hi:[1,0]
	ds_write2_b64 v49, v[16:17], v[18:19] offset0:16 offset1:18
	v_pk_mul_f32 v[16:17], v[24:25], v[48:49] op_sel_hi:[1,0]
	v_pk_mul_f32 v[18:19], v[26:27], v[48:49] op_sel_hi:[1,0]
	ds_write2_b64 v49, v[0:1], v[2:3] offset0:24 offset1:26
	v_pk_mul_f32 v[0:1], v[8:9], v[48:49] op_sel_hi:[1,0]
	v_pk_mul_f32 v[2:3], v[10:11], v[48:49] op_sel_hi:[1,0]
	v_cvt_pk_bf16_f32 v50, v50, v51
	v_cvt_pk_bf16_f32 v51, v52, v53
	v_pk_mul_f32 v[52:53], v[76:77], v[48:49] op_sel_hi:[1,0]
	v_pk_mul_f32 v[54:55], v[78:79], v[48:49] op_sel_hi:[1,0]
	v_cvt_pk_bf16_f32 v32, v32, v33
	v_cvt_pk_bf16_f32 v33, v34, v35
	v_pk_mul_f32 v[34:35], v[44:45], v[48:49] op_sel_hi:[1,0]
	v_pk_mul_f32 v[36:37], v[46:47], v[48:49] op_sel_hi:[1,0]
	v_cvt_pk_bf16_f32 v16, v16, v17
	v_cvt_pk_bf16_f32 v17, v18, v19
	v_pk_mul_f32 v[18:19], v[28:29], v[48:49] op_sel_hi:[1,0]
	v_pk_mul_f32 v[20:21], v[30:31], v[48:49] op_sel_hi:[1,0]
	v_cvt_pk_bf16_f32 v0, v0, v1
	v_cvt_pk_bf16_f32 v1, v2, v3
	v_pk_mul_f32 v[2:3], v[12:13], v[48:49] op_sel_hi:[1,0]
	v_pk_mul_f32 v[4:5], v[14:15], v[48:49] op_sel_hi:[1,0]
	v_cvt_pk_bf16_f32 v52, v52, v53
	v_cvt_pk_bf16_f32 v53, v54, v55
	v_cvt_pk_bf16_f32 v34, v34, v35
	v_cvt_pk_bf16_f32 v35, v36, v37
	v_cvt_pk_bf16_f32 v18, v18, v19
	v_cvt_pk_bf16_f32 v19, v20, v21
	v_cvt_pk_bf16_f32 v2, v2, v3
	v_cvt_pk_bf16_f32 v3, v4, v5
	s_mulk_i32 s20, 0x1800
	s_mul_hi_u32 s2, s19, 0x1800
	v_lshrrev_b32_e32 v14, 4, v197
	v_and_b32_e32 v164, 15, v222
	ds_write2_b64 v49, v[50:51], v[52:53] offset0:4 offset1:6
	ds_write2_b64 v49, v[32:33], v[34:35] offset0:12 offset1:14
	ds_write2_b64 v49, v[16:17], v[18:19] offset0:20 offset1:22
	ds_write2_b64 v49, v[0:1], v[2:3] offset0:28 offset1:30
	s_add_i32 s2, s2, s20
	s_mulk_i32 s19, 0x1800
	v_lshlrev_b32_e32 v144, 4, v164
	v_mul_u32_u24_e32 v196, 0x110, v14
	s_waitcnt lgkmcnt(0)
	s_add_u32 s3, s4, s19
	v_add3_u32 v15, s7, v144, v196
	s_addc_u32 s10, s5, s2
	ds_read_b128 v[0:3], v15 offset:40960
	s_add_u32 s2, s3, s6
	s_addc_u32 s3, s10, 0
	v_mov_b32_e32 v145, 0
	v_mul_u32_u24_e32 v16, 0xc00, v14
	ds_read_b128 v[4:7], v15 offset:42048
	v_lshl_add_u64 v[8:9], s[2:3], 0, v[144:145]
	v_lshlrev_b32_e32 v146, 1, v16
	v_mov_b32_e32 v147, v145
	v_lshl_add_u64 v[10:11], v[8:9], 0, v[146:147]
	s_movk_i32 s3, 0x6000
	s_waitcnt lgkmcnt(0)
	global_store_dwordx4 v[10:11], v[0:3], off
	v_mov_b32_e32 v149, v145
	s_movk_i32 s2, 0xc00
	v_add_co_u32_e32 v0, vcc, s3, v10
	s_mov_b32 s3, 0xc000
	s_nop 0
	v_addc_co_u32_e32 v1, vcc, 0, v11, vcc
	global_store_dwordx4 v[0:1], v[4:7], off
	ds_read_b128 v[0:3], v15 offset:43136
	ds_read_b128 v[4:7], v15 offset:44224
	v_add_co_u32_e32 v12, vcc, s3, v10
	s_mov_b32 s3, 0x12000
	s_nop 0
	v_addc_co_u32_e32 v13, vcc, 0, v11, vcc
	s_waitcnt lgkmcnt(0)
	global_store_dwordx4 v[12:13], v[0:3], off
	v_mov_b32_e32 v153, v145
	v_mov_b32_e32 v151, v145
	v_add_co_u32_e32 v0, vcc, s3, v10
	v_mov_b32_e32 v155, v145
	s_nop 0
	v_addc_co_u32_e32 v1, vcc, 0, v11, vcc
	global_store_dwordx4 v[0:1], v[4:7], off
	ds_read_b128 v[0:3], v15 offset:45312
	v_readfirstlane_b32 s12, v222
	v_or_b32_e32 v4, 0xc000, v16
	v_lshlrev_b32_e32 v148, 1, v4
	v_lshl_add_u64 v[10:11], v[8:9], 0, v[148:149]
	ds_read_b128 v[4:7], v15 offset:46400
	s_waitcnt lgkmcnt(0)
	global_store_dwordx4 v[10:11], v[0:3], off
	s_nop 1
	v_mov_b32_e32 v0, 0xf000
	v_mad_u32_u24 v0, v14, s2, v0
	v_lshlrev_b32_e32 v152, 1, v0
	v_lshl_add_u64 v[0:1], v[8:9], 0, v[152:153]
	global_store_dwordx4 v[0:1], v[4:7], off
	ds_read_b128 v[0:3], v15 offset:47488
	s_nop 0
	v_mov_b32_e32 v4, 0x12000
	v_mad_u32_u24 v4, v14, s2, v4
	v_lshlrev_b32_e32 v150, 1, v4
	v_lshl_add_u64 v[10:11], v[8:9], 0, v[150:151]
	ds_read_b128 v[4:7], v15 offset:48576
	s_waitcnt lgkmcnt(0)
	global_store_dwordx4 v[10:11], v[0:3], off
	s_nop 1
	v_mov_b32_e32 v0, 0x15000
	v_mad_u32_u24 v0, v14, s2, v0
	v_lshlrev_b32_e32 v154, 1, v0
	v_lshl_add_u64 v[0:1], v[8:9], 0, v[154:155]
	s_and_b32 s2, s12, 0xffffffc0
	global_store_dwordx4 v[0:1], v[4:7], off
	v_or_b32_e32 v0, s2, v197
	s_mov_b32 s2, 0x2aaaaaab
	v_mul_hi_i32 v1, v0, s2
	v_lshrrev_b32_e32 v2, 31, v1
	v_ashrrev_i32_e32 v1, 2, v1
	v_add_u32_e32 v2, v1, v2
	s_movk_i32 s2, 0xffe8
	v_lshrrev_b32_e32 v165, 1, v2
	v_mad_u64_u32 v[158:159], s[2:3], v2, s2, v[0:1]
	v_xor_b32_e32 v1, v165, v222
	v_bfi_b32 v1, -8, v158, v1
	v_cmp_lt_i32_e32 vcc, 15, v1
	v_add_u32_e32 v2, s8, v2
	s_and_saveexec_b64 s[2:3], vcc
	s_xor_b64 s[2:3], exec, s[2:3]
	v_mov_b32_e32 v3, 0xbfff80
	v_lshl_add_u32 v155, v2, 6, v3
	s_or_saveexec_b64 s[2:3], s[2:3]
	v_mov_b32_e32 v145, 0x1000
	s_xor_b64 exec, exec, s[2:3]
	v_lshl_or_b32 v2, v2, 11, s17
	v_add_u32_e32 v155, 0x8000000, v2
	v_mov_b32_e32 v145, 0x20000
	s_or_b64 exec, exec, s[2:3]
	v_add_u32_e32 v2, 0x200, v0
	s_mov_b32 s2, 0x2aaaaaab
	v_mul_hi_i32 v3, v2, s2
	v_lshrrev_b32_e32 v4, 31, v3
	v_ashrrev_i32_e32 v3, 2, v3
	v_add_u32_e32 v4, v3, v4
	s_movk_i32 s2, 0xffe8
	v_lshrrev_b32_e32 v166, 1, v4
	v_mad_u64_u32 v[160:161], s[2:3], v4, s2, v[2:3]
	v_xor_b32_e32 v3, v166, v222
	v_bfi_b32 v3, -8, v160, v3
	v_cmp_lt_i32_e32 vcc, 15, v3
	v_add_u32_e32 v4, s8, v4
	s_and_saveexec_b64 s[2:3], vcc
	s_xor_b64 s[2:3], exec, s[2:3]
	v_mov_b32_e32 v5, 0xbfff80
	v_lshl_add_u32 v159, v4, 6, v5
	s_or_saveexec_b64 s[2:3], s[2:3]
	v_mov_b32_e32 v147, 0x1000
	s_xor_b64 exec, exec, s[2:3]
	v_lshl_or_b32 v4, v4, 11, s17
	v_add_u32_e32 v159, 0x8000000, v4
	v_mov_b32_e32 v147, 0x20000
	s_or_b64 exec, exec, s[2:3]
	v_add_u32_e32 v4, 0x400, v0
	s_mov_b32 s2, 0x2aaaaaab
	v_mul_hi_i32 v5, v4, s2
	v_lshrrev_b32_e32 v6, 31, v5
	v_ashrrev_i32_e32 v5, 2, v5
	v_add_u32_e32 v5, v5, v6
	s_movk_i32 s2, 0xffe8
	v_mad_u64_u32 v[162:163], s[2:3], v5, s2, v[4:5]
	v_lshrrev_b32_e32 v163, 1, v5
	v_xor_b32_e32 v4, v163, v222
	v_bfi_b32 v4, -8, v162, v4
	v_cmp_lt_i32_e32 vcc, 15, v4
	v_add_u32_e32 v5, s8, v5
	s_and_saveexec_b64 s[2:3], vcc
	s_xor_b64 s[2:3], exec, s[2:3]
	v_mov_b32_e32 v6, 0xbfff80
	v_lshl_add_u32 v161, v5, 6, v6
	s_or_saveexec_b64 s[2:3], s[2:3]
	v_mov_b32_e32 v149, 0x1000
	s_xor_b64 exec, exec, s[2:3]
	v_lshl_or_b32 v5, v5, 11, s17
	v_add_u32_e32 v161, 0x8000000, v5
	v_mov_b32_e32 v149, 0x20000
	s_or_b64 exec, exec, s[2:3]
	s_lshr_b32 s21, s12, 6
	s_or_b32 s15, s16, 0x1800
	s_lshl_b32 s22, s21, 5
	s_or_b32 s3, s8, s15
	s_add_u32 s19, s3, s22
	s_movk_i32 s2, 0x1800
	v_or_b32_e32 v5, s19, v194
	v_mov_b64_e32 v[6:7], s[4:5]
	s_addc_u32 s20, s9, 0
	v_mad_u64_u32 v[6:7], s[2:3], v5, s2, v[6:7]
	v_mov_b32_e32 v5, 0x1800
	s_mov_b32 s7, 0
	v_mad_i32_i24 v7, s20, v5, v7
	v_lshl_add_u32 v8, v1, 3, v155
	v_ashrrev_i32_e32 v1, 31, v0
	v_lshl_add_u64 v[6:7], v[6:7], 0, s[6:7]
	v_lshlrev_b32_e32 v156, 1, v181
	v_mov_b32_e32 v157, 0
	v_lshrrev_b32_e32 v10, 28, v1
	v_lshl_add_u64 v[6:7], v[6:7], 0, v[156:157]
	v_lshl_add_u32 v4, v4, 3, v161
	v_mov_b32_e32 v5, v157
	v_add_u32_e32 v16, v0, v10
	global_load_dwordx4 v[96:99], v[6:7], off
	global_load_dwordx4 v[100:103], v[6:7], off offset:32
	global_load_dwordx4 v[104:107], v[6:7], off offset:64
	global_load_dwordx4 v[108:111], v[6:7], off offset:96
	global_load_dwordx4 v[112:115], v[6:7], off offset:128
	global_load_dwordx4 v[116:119], v[6:7], off offset:160
	global_load_dwordx4 v[120:123], v[6:7], off offset:192
	global_load_dwordx4 v[124:127], v[6:7], off offset:224
	global_load_dwordx4 v[128:131], v[6:7], off offset:256
	global_load_dwordx4 v[132:135], v[6:7], off offset:288
	global_load_dwordx4 v[136:139], v[6:7], off offset:320
	global_load_dwordx4 v[140:143], v[6:7], off offset:352
	v_lshl_add_u32 v6, v3, 3, v159
	v_ashrrev_i32_e32 v3, 31, v2
	v_lshl_add_u64 v[14:15], v[4:5], 1, s[84:85]
	v_ashrrev_i32_e32 v167, 4, v16
	v_and_b32_e32 v5, 0x1ffffff0, v16
	v_lshrrev_b32_e32 v11, 28, v3
	v_mov_b32_e32 v9, v157
	s_lshl_b32 s2, s21, 10
	v_sub_u32_e32 v0, v0, v5
	v_lshlrev_b32_e32 v5, 2, v167
	v_mov_b32_e32 v7, v157
	v_add_u32_e32 v17, v2, v11
	v_lshl_add_u64 v[10:11], v[8:9], 1, s[84:85]
	v_bfe_u32 v9, v167, 2, 2
	s_add_i32 s7, s2, 0
	v_and_b32_e32 v5, 12, v5
	v_lshl_add_u64 v[12:13], v[6:7], 1, s[84:85]
	v_ashrrev_i32_e32 v168, 4, v17
	v_and_b32_e32 v7, 0x1ffffff0, v17
	v_bitop3_b32 v0, v5, v0, v9 bitop3:0x36
	s_mov_b32 m0, s7
	v_add_lshl_u32 v16, v167, s8, 11
	v_sub_u32_e32 v2, v2, v7
	v_lshlrev_b32_e32 v7, 2, v168
	global_load_lds_dwordx4 v[10:11], off
	s_add_i32 m0, s7, 0x2000
	v_lshlrev_b32_e32 v169, 3, v0
	v_mov_b32_e32 v1, v157
	v_bfe_u32 v17, v168, 2, 2
	v_and_b32_e32 v7, 12, v7
	global_load_lds_dwordx4 v[12:13], off
	s_add_i32 m0, s7, 0x4000
	v_add3_u32 v0, s18, v16, v169
	v_bitop3_b32 v2, v7, v2, v17 bitop3:0x36
	global_load_lds_dwordx4 v[14:15], off
	s_add_i32 m0, s7, 0x6000
	v_lshl_add_u64 v[10:11], v[0:1], 1, s[84:85]
	v_add_lshl_u32 v18, v168, s8, 11
	v_lshlrev_b32_e32 v198, 3, v2
	global_load_lds_dwordx4 v[10:11], off
	s_add_i32 m0, s7, 0x8000
	v_mov_b32_e32 v3, v157
	v_add3_u32 v2, s18, v18, v198
	s_cmpk_gt_u32 s12, 0xff
	v_lshl_add_u64 v[12:13], v[2:3], 1, s[84:85]
	s_cselect_b64 s[10:11], -1, 0
	s_cmpk_lt_u32 s12, 0x100
	v_add_u32_e32 v8, v8, v145
	v_mov_b32_e32 v9, v157
	global_load_lds_dwordx4 v[12:13], off
	s_cselect_b64 s[12:13], -1, 0
	s_add_i32 m0, s7, 0xa000
	v_lshl_add_u64 v[8:9], v[8:9], 1, s[84:85]
	v_add_u32_e32 v6, v6, v147
	v_mov_b32_e32 v7, v157
	s_waitcnt vmcnt(0) lgkmcnt(0)
	s_barrier
	s_waitcnt vmcnt(0)
	global_load_lds_dwordx4 v[8:9], off
	v_lshl_add_u64 v[6:7], v[6:7], 1, s[84:85]
	s_add_i32 m0, s7, 0xc000
	v_add_u32_e32 v4, v4, v149
	v_mov_b32_e32 v5, v157
	global_load_lds_dwordx4 v[6:7], off
	v_lshl_add_u64 v[4:5], v[4:5], 1, s[84:85]
	s_add_i32 m0, s7, 0xe000
	v_add_u32_e32 v0, 0x20000, v0
	v_mov_b32_e32 v1, v157
	global_load_lds_dwordx4 v[4:5], off
	s_add_i32 m0, s7, 0x10000
	v_lshl_add_u64 v[0:1], v[0:1], 1, s[84:85]
	global_load_lds_dwordx4 v[0:1], off
	v_add_u32_e32 v0, 0x20000, v2
	v_mov_b32_e32 v1, v157
	v_lshl_add_u64 v[0:1], v[0:1], 1, s[84:85]
	s_add_i32 m0, s7, 0x12000
	s_and_b64 vcc, exec, s[12:13]
	global_load_lds_dwordx4 v[0:1], off
	ds_read_b128 v[0:3], v190
	ds_read_b128 v[4:7], v191
	ds_read_b128 v[8:11], v192
	ds_read_b128 v[12:15], v193
	s_waitcnt lgkmcnt(0)
	v_mfma_f32_32x32x16_bf16 v[48:63], v[0:3], v[96:99], 0
	ds_read_b128 v[0:3], v190 offset:128
	v_mfma_f32_32x32x16_bf16 v[48:63], v[4:7], v[100:103], v[48:63]
	ds_read_b128 v[4:7], v191 offset:128
	v_mfma_f32_32x32x16_bf16 v[48:63], v[8:11], v[104:107], v[48:63]
	ds_read_b128 v[8:11], v192 offset:128
	v_mfma_f32_32x32x16_bf16 v[48:63], v[12:15], v[108:111], v[48:63]
	ds_read_b128 v[12:15], v193 offset:128
	s_waitcnt lgkmcnt(0)
	v_mfma_f32_32x32x16_bf16 v[48:63], v[0:3], v[112:115], v[48:63]
	ds_read_b128 v[0:3], v190 offset:256
	v_mfma_f32_32x32x16_bf16 v[48:63], v[4:7], v[116:119], v[48:63]
	ds_read_b128 v[4:7], v191 offset:256
	v_mfma_f32_32x32x16_bf16 v[48:63], v[8:11], v[120:123], v[48:63]
	ds_read_b128 v[8:11], v192 offset:256
	v_mfma_f32_32x32x16_bf16 v[48:63], v[12:15], v[124:127], v[48:63]
	ds_read_b128 v[12:15], v193 offset:256
	s_waitcnt lgkmcnt(0)
	v_mfma_f32_32x32x16_bf16 v[48:63], v[0:3], v[128:131], v[48:63]
	ds_read_b128 v[0:3], v190 offset:12288
	v_mfma_f32_32x32x16_bf16 v[48:63], v[4:7], v[132:135], v[48:63]
	ds_read_b128 v[4:7], v191 offset:12288
	v_mfma_f32_32x32x16_bf16 v[48:63], v[8:11], v[136:139], v[48:63]
	ds_read_b128 v[8:11], v192 offset:12288
	s_waitcnt lgkmcnt(0)
	v_mfma_f32_32x32x16_bf16 v[80:95], v[0:3], v[96:99], 0
	ds_read_b128 v[16:19], v193 offset:12288
	v_mfma_f32_32x32x16_bf16 v[80:95], v[4:7], v[100:103], v[80:95]
	ds_read_b128 v[20:23], v190 offset:12416
	v_mfma_f32_32x32x16_bf16 v[80:95], v[8:11], v[104:107], v[80:95]
	ds_read_b128 v[24:27], v191 offset:12416
	s_waitcnt lgkmcnt(0)
	v_mfma_f32_32x32x16_bf16 v[80:95], v[16:19], v[108:111], v[80:95]
	ds_read_b128 v[28:31], v192 offset:12416
	v_mfma_f32_32x32x16_bf16 v[80:95], v[20:23], v[112:115], v[80:95]
	ds_read_b128 v[32:35], v193 offset:12416
	v_mfma_f32_32x32x16_bf16 v[80:95], v[24:27], v[116:119], v[80:95]
	ds_read_b128 v[36:39], v190 offset:12544
	s_waitcnt lgkmcnt(0)
	v_mfma_f32_32x32x16_bf16 v[80:95], v[28:31], v[120:123], v[80:95]
	ds_read_b128 v[40:43], v191 offset:12544
	v_mfma_f32_32x32x16_bf16 v[80:95], v[32:35], v[124:127], v[80:95]
	ds_read_b128 v[44:47], v192 offset:12544
	v_mfma_f32_32x32x16_bf16 v[80:95], v[36:39], v[128:131], v[80:95]
	ds_read_b128 v[64:67], v193 offset:12544
	s_waitcnt lgkmcnt(0)
	v_mfma_f32_32x32x16_bf16 v[80:95], v[40:43], v[132:135], v[80:95]
	v_mfma_f32_32x32x16_bf16 v[80:95], v[44:47], v[136:139], v[80:95]
	v_mfma_f32_32x32x16_bf16 v[80:95], v[64:67], v[140:143], v[80:95]
	v_mfma_f32_32x32x16_bf16 v[48:63], v[12:15], v[140:143], v[48:63]
	s_cbranch_vccnz .LBB0_1843
	s_waitcnt vmcnt(0) lgkmcnt(0)
	s_barrier
.LBB0_1843:
	s_nop 10
	v_max_f32_e32 v0, v49, v49
	v_max_f32_e32 v1, v48, v48
	v_max_f32_e32 v0, v1, v0
	v_max3_f32 v0, v0, v50, v51
	v_max3_f32 v0, v0, v52, v53
	v_max3_f32 v0, v0, v54, v55
	v_max3_f32 v0, v0, v56, v57
	v_max3_f32 v0, v0, v58, v59
	v_max3_f32 v0, v0, v60, v61
	v_max3_f32 v0, v0, v62, v63
	v_mov_b32_e32 v1, v0
	s_nop 1
	v_permlane32_swap_b32_e32 v0, v1
	v_max_f32_e32 v1, v1, v1
	v_max_f32_e32 v0, v0, v0
	v_max_f32_e32 v0, v0, v1
	s_cmp_lg_u64 exec, 0
	v_add_f32_e32 v0, 0, v0
	s_cselect_b64 vcc, -1, 0
	v_cndmask_b32_e32 v151, 0, v0, vcc
	v_sub_f32_e32 v0, v48, v151
	v_exp_f32_e32 v48, v0
	v_sub_f32_e32 v0, v49, v151
	v_exp_f32_e32 v49, v0
	v_sub_f32_e32 v0, v50, v151
	v_exp_f32_e32 v50, v0
	v_sub_f32_e32 v0, v51, v151
	v_exp_f32_e32 v51, v0
	v_sub_f32_e32 v0, v52, v151
	v_exp_f32_e32 v52, v0
	v_sub_f32_e32 v0, v53, v151
	v_exp_f32_e32 v53, v0
	v_sub_f32_e32 v0, v54, v151
	v_exp_f32_e32 v54, v0
	v_sub_f32_e32 v0, v55, v151
	v_exp_f32_e32 v55, v0
	v_sub_f32_e32 v0, v56, v151
	v_exp_f32_e32 v56, v0
	ds_read_b64_tr_b16 v[0:1], v183 offset:24576
	ds_read_b64_tr_b16 v[2:3], v185 offset:26624
	v_cvt_pk_bf16_f32 v4, v48, v49
	v_cvt_pk_bf16_f32 v5, v50, v51
	v_cvt_pk_bf16_f32 v6, v52, v53
	v_cvt_pk_bf16_f32 v7, v54, v55
	ds_read_b64_tr_b16 v[8:9], v182 offset:24576
	ds_read_b64_tr_b16 v[10:11], v184 offset:26624
	ds_read_b64_tr_b16 v[202:203], v185 offset:30720
	ds_read_b64_tr_b16 v[200:201], v183 offset:28672
	s_waitcnt lgkmcnt(0)
	v_mfma_f32_32x32x16_bf16 v[64:79], v[0:3], v[4:7], 0
	v_sub_f32_e32 v0, v57, v151
	v_add_f32_e32 v153, 0, v48
	v_exp_f32_e32 v57, v0
	ds_read_b64_tr_b16 v[0:1], v186 offset:24576
	ds_read_b64_tr_b16 v[2:3], v188 offset:26624
	ds_read_b64_tr_b16 v[206:207], v184 offset:30720
	ds_read_b64_tr_b16 v[204:205], v182 offset:28672
	v_add_f32_e32 v153, v49, v153
	v_add_f32_e32 v153, v50, v153
	v_add_f32_e32 v153, v51, v153
	v_mfma_f32_32x32x16_bf16 v[32:47], v[8:11], v[4:7], 0
	v_sub_f32_e32 v8, v59, v151
	v_exp_f32_e32 v59, v8
	ds_read_b64_tr_b16 v[8:9], v187 offset:24576
	ds_read_b64_tr_b16 v[10:11], v189 offset:26624
	ds_read_b64_tr_b16 v[210:211], v188 offset:30720
	ds_read_b64_tr_b16 v[208:209], v186 offset:28672
	v_add_f32_e32 v153, v52, v153
	v_sub_f32_e32 v12, v58, v151
	v_add_f32_e32 v153, v53, v153
	v_exp_f32_e32 v58, v12
	s_waitcnt lgkmcnt(0)
	v_mfma_f32_32x32x16_bf16 v[16:31], v[0:3], v[4:7], 0
	v_sub_f32_e32 v0, v60, v151
	v_exp_f32_e32 v60, v0
	v_sub_f32_e32 v0, v61, v151
	v_exp_f32_e32 v61, v0
	v_add_f32_e32 v153, v54, v153
	v_add_f32_e32 v153, v55, v153
	v_max_f32_e32 v157, v81, v81
	v_mfma_f32_32x32x16_bf16 v[0:15], v[8:11], v[4:7], 0
	v_max_f32_e32 v199, v80, v80
	v_sub_f32_e32 v62, v62, v151
	v_sub_f32_e32 v63, v63, v151
	v_add_f32_e32 v153, v56, v153
	v_max_f32_e32 v157, v199, v157
	ds_read_b64_tr_b16 v[214:215], v189 offset:30720
	ds_read_b64_tr_b16 v[212:213], v187 offset:28672
	v_exp_f32_e32 v62, v62
	v_exp_f32_e32 v63, v63
	v_add_f32_e32 v153, v57, v153
	v_max3_f32 v157, v157, v82, v83
	v_add_f32_e32 v153, v58, v153
	v_max3_f32 v157, v157, v84, v85
	v_add_f32_e32 v153, v59, v153
	v_max3_f32 v157, v157, v86, v87
	v_add_f32_e32 v153, v60, v153
	v_max3_f32 v157, v157, v88, v89
	v_cvt_pk_bf16_f32 v216, v56, v57
	v_cvt_pk_bf16_f32 v217, v58, v59
	v_cvt_pk_bf16_f32 v218, v60, v61
	v_cvt_pk_bf16_f32 v219, v62, v63
	v_add_f32_e32 v153, v61, v153
	v_max3_f32 v157, v157, v90, v91
	v_mfma_f32_32x32x16_bf16 v[64:79], v[200:203], v[216:219], v[64:79]
	v_add_f32_e32 v153, v62, v153
	v_max3_f32 v157, v157, v92, v93
	v_add_f32_e32 v153, v63, v153
	v_max3_f32 v199, v157, v94, v95
	v_add_f32_e32 v157, 0, v153
	v_mov_b32_e32 v153, v199
	s_nop 1
	v_permlane32_swap_b32_e32 v199, v153
	v_mfma_f32_32x32x16_bf16 v[32:47], v[204:207], v[216:219], v[32:47]
	v_max_f32_e32 v153, v153, v153
	v_max_f32_e32 v199, v199, v199
	v_max_f32_e32 v153, v199, v153
	v_sub_f32_e32 v153, v153, v151
	s_mov_b32 s2, 0x41000000
	v_cmp_lt_f32_e32 vcc, s2, v153
	v_mfma_f32_32x32x16_bf16 v[16:31], v[208:211], v[216:219], v[16:31]
	s_waitcnt lgkmcnt(0)
	v_mfma_f32_32x32x16_bf16 v[0:15], v[212:215], v[216:219], v[0:15]
	s_cbranch_vccz .LBB0_1845
	v_max_f32_e32 v153, v153, v153
	v_max_f32_e32 v153, 0, v153
	v_exp_f32_e64 v200, -v153
	v_add_f32_e32 v151, v151, v153
	v_pk_mul_f32 v[78:79], v[78:79], v[200:201] op_sel_hi:[1,0]
	v_pk_mul_f32 v[76:77], v[76:77], v[200:201] op_sel_hi:[1,0]
	v_pk_mul_f32 v[74:75], v[74:75], v[200:201] op_sel_hi:[1,0]
	v_pk_mul_f32 v[72:73], v[72:73], v[200:201] op_sel_hi:[1,0]
	v_pk_mul_f32 v[70:71], v[70:71], v[200:201] op_sel_hi:[1,0]
	v_pk_mul_f32 v[68:69], v[68:69], v[200:201] op_sel_hi:[1,0]
	v_pk_mul_f32 v[66:67], v[66:67], v[200:201] op_sel_hi:[1,0]
	v_pk_mul_f32 v[64:65], v[64:65], v[200:201] op_sel_hi:[1,0]
	v_pk_mul_f32 v[46:47], v[46:47], v[200:201] op_sel_hi:[1,0]
	v_pk_mul_f32 v[44:45], v[44:45], v[200:201] op_sel_hi:[1,0]
	v_pk_mul_f32 v[42:43], v[42:43], v[200:201] op_sel_hi:[1,0]
	v_pk_mul_f32 v[40:41], v[40:41], v[200:201] op_sel_hi:[1,0]
	v_pk_mul_f32 v[38:39], v[38:39], v[200:201] op_sel_hi:[1,0]
	v_pk_mul_f32 v[36:37], v[36:37], v[200:201] op_sel_hi:[1,0]
	v_pk_mul_f32 v[34:35], v[34:35], v[200:201] op_sel_hi:[1,0]
	v_pk_mul_f32 v[32:33], v[32:33], v[200:201] op_sel_hi:[1,0]
	v_pk_mul_f32 v[30:31], v[30:31], v[200:201] op_sel_hi:[1,0]
	v_pk_mul_f32 v[28:29], v[28:29], v[200:201] op_sel_hi:[1,0]
	v_pk_mul_f32 v[26:27], v[26:27], v[200:201] op_sel_hi:[1,0]
	v_pk_mul_f32 v[24:25], v[24:25], v[200:201] op_sel_hi:[1,0]
	v_pk_mul_f32 v[22:23], v[22:23], v[200:201] op_sel_hi:[1,0]
	v_pk_mul_f32 v[20:21], v[20:21], v[200:201] op_sel_hi:[1,0]
	v_pk_mul_f32 v[18:19], v[18:19], v[200:201] op_sel_hi:[1,0]
	v_pk_mul_f32 v[16:17], v[16:17], v[200:201] op_sel_hi:[1,0]
	v_pk_mul_f32 v[14:15], v[14:15], v[200:201] op_sel_hi:[1,0]
	v_pk_mul_f32 v[12:13], v[12:13], v[200:201] op_sel_hi:[1,0]
	v_pk_mul_f32 v[10:11], v[10:11], v[200:201] op_sel_hi:[1,0]
	v_pk_mul_f32 v[8:9], v[8:9], v[200:201] op_sel_hi:[1,0]
	v_pk_mul_f32 v[6:7], v[6:7], v[200:201] op_sel_hi:[1,0]
	v_pk_mul_f32 v[4:5], v[4:5], v[200:201] op_sel_hi:[1,0]
	v_pk_mul_f32 v[2:3], v[2:3], v[200:201] op_sel_hi:[1,0]
	v_pk_mul_f32 v[0:1], v[0:1], v[200:201] op_sel_hi:[1,0]
	v_mul_f32_e32 v157, v157, v200
.LBB0_1845:
	v_sub_f32_e32 v80, v80, v151
	v_sub_f32_e32 v81, v81, v151
	v_sub_f32_e32 v82, v82, v151
	v_sub_f32_e32 v83, v83, v151
	v_sub_f32_e32 v84, v84, v151
	v_sub_f32_e32 v85, v85, v151
	v_sub_f32_e32 v86, v86, v151
	v_sub_f32_e32 v87, v87, v151
	v_exp_f32_e32 v80, v80
	v_exp_f32_e32 v81, v81
	v_exp_f32_e32 v82, v82
	v_exp_f32_e32 v83, v83
	v_exp_f32_e32 v84, v84
	v_exp_f32_e32 v85, v85
	v_exp_f32_e32 v86, v86
	v_exp_f32_e32 v87, v87
	ds_read_b64_tr_b16 v[200:201], v183 offset:32768
	ds_read_b64_tr_b16 v[202:203], v185 offset:34816
	ds_read_b64_tr_b16 v[208:209], v182 offset:32768
	ds_read_b64_tr_b16 v[210:211], v184 offset:34816
	ds_read_b64_tr_b16 v[214:215], v185 offset:38912
	ds_read_b64_tr_b16 v[212:213], v183 offset:36864
	v_cvt_pk_bf16_f32 v204, v80, v81
	v_cvt_pk_bf16_f32 v205, v82, v83
	v_cvt_pk_bf16_f32 v206, v84, v85
	v_cvt_pk_bf16_f32 v207, v86, v87
	v_sub_f32_e32 v88, v88, v151
	v_sub_f32_e32 v89, v89, v151
	s_waitcnt lgkmcnt(0)
	v_mfma_f32_32x32x16_bf16 v[64:79], v[200:203], v[204:207], v[64:79]
	ds_read_b64_tr_b16 v[200:201], v186 offset:32768
	ds_read_b64_tr_b16 v[202:203], v188 offset:34816
	ds_read_b64_tr_b16 v[218:219], v184 offset:38912
	ds_read_b64_tr_b16 v[216:217], v182 offset:36864
	v_sub_f32_e32 v90, v90, v151
	v_sub_f32_e32 v91, v91, v151
	v_sub_f32_e32 v92, v92, v151
	v_sub_f32_e32 v93, v93, v151
	v_sub_f32_e32 v94, v94, v151
	v_sub_f32_e32 v95, v95, v151
	v_mfma_f32_32x32x16_bf16 v[32:47], v[208:211], v[204:207], v[32:47]
	ds_read_b64_tr_b16 v[208:209], v187 offset:32768
	ds_read_b64_tr_b16 v[210:211], v189 offset:34816
	ds_read_b64_tr_b16 v[226:227], v188 offset:38912
	ds_read_b64_tr_b16 v[224:225], v186 offset:36864
	v_exp_f32_e32 v88, v88
	v_exp_f32_e32 v89, v89
	v_exp_f32_e32 v90, v90
	v_exp_f32_e32 v91, v91
	v_exp_f32_e32 v92, v92
	v_exp_f32_e32 v93, v93
	s_waitcnt lgkmcnt(0)
	v_mfma_f32_32x32x16_bf16 v[16:31], v[200:203], v[204:207], v[16:31]
	ds_read_b64_tr_b16 v[202:203], v189 offset:38912
	ds_read_b64_tr_b16 v[200:201], v187 offset:36864
	v_exp_f32_e32 v94, v94
	v_exp_f32_e32 v95, v95
	v_lshlrev_b32_e32 v153, 3, v164
	v_bitop3_b32 v164, v166, 7, v222 bitop3:0x48
	v_cndmask_b32_e64 v166, 0, 1, s[12:13]
	v_bitop3_b32 v165, v165, 7, v222 bitop3:0x48
	v_mfma_f32_32x32x16_bf16 v[0:15], v[208:211], v[204:207], v[0:15]
	v_cvt_pk_bf16_f32 v204, v88, v89
	v_cvt_pk_bf16_f32 v205, v90, v91
	v_cvt_pk_bf16_f32 v206, v92, v93
	v_cvt_pk_bf16_f32 v207, v94, v95
	v_bitop3_b32 v163, v163, 7, v222 bitop3:0x48
	v_cmp_ne_u32_e64 s[2:3], 1, v166
	s_andn2_b64 vcc, exec, s[12:13]
	v_mfma_f32_32x32x16_bf16 v[64:79], v[212:215], v[204:207], v[64:79]
	v_mfma_f32_32x32x16_bf16 v[32:47], v[216:219], v[204:207], v[32:47]
	v_mfma_f32_32x32x16_bf16 v[16:31], v[224:227], v[204:207], v[16:31]
	s_waitcnt lgkmcnt(0)
	v_mfma_f32_32x32x16_bf16 v[0:15], v[200:203], v[204:207], v[0:15]
	s_cbranch_vccnz .LBB0_1847
	s_waitcnt vmcnt(0) lgkmcnt(0)
	s_barrier

.LBB0_1856:
	s_setprio 0
	v_add_u32_e32 v155, s27, v170
	ds_read_b128 v[48:51], v155
	v_add_u32_e32 v161, s27, v171
	v_add_u32_e32 v163, s27, v172
	v_add_u32_e32 v165, s27, v173
	ds_read_b128 v[80:83], v161
	ds_read_b128 v[84:87], v163
	ds_read_b128 v[88:91], v165
	s_waitcnt lgkmcnt(0)
	v_mfma_f32_32x32x16_bf16 v[48:63], v[48:51], v[96:99], 0
	ds_read_b128 v[92:95], v155 offset:128
	v_mfma_f32_32x32x16_bf16 v[48:63], v[80:83], v[100:103], v[48:63]
	ds_read_b128 v[80:83], v161 offset:128
	v_mfma_f32_32x32x16_bf16 v[48:63], v[84:87], v[104:107], v[48:63]
	ds_read_b128 v[84:87], v163 offset:128
	v_mfma_f32_32x32x16_bf16 v[48:63], v[88:91], v[108:111], v[48:63]
	ds_read_b128 v[88:91], v165 offset:128
	s_waitcnt lgkmcnt(0)
	v_mfma_f32_32x32x16_bf16 v[48:63], v[92:95], v[112:115], v[48:63]
	ds_read_b128 v[92:95], v155 offset:256
	v_mfma_f32_32x32x16_bf16 v[48:63], v[80:83], v[116:119], v[48:63]
	ds_read_b128 v[80:83], v161 offset:256
	v_mfma_f32_32x32x16_bf16 v[48:63], v[84:87], v[120:123], v[48:63]
	ds_read_b128 v[84:87], v163 offset:256
	v_mfma_f32_32x32x16_bf16 v[48:63], v[88:91], v[124:127], v[48:63]
	ds_read_b128 v[198:201], v165 offset:256
	s_waitcnt lgkmcnt(0)
	v_mfma_f32_32x32x16_bf16 v[48:63], v[92:95], v[128:131], v[48:63]
	ds_read_b128 v[88:91], v155 offset:12288
	v_mfma_f32_32x32x16_bf16 v[48:63], v[80:83], v[132:135], v[48:63]
	ds_read_b128 v[202:205], v161 offset:12288
	v_mfma_f32_32x32x16_bf16 v[48:63], v[84:87], v[136:139], v[48:63]
	ds_read_b128 v[206:209], v163 offset:12288
	s_waitcnt lgkmcnt(0)
	v_mfma_f32_32x32x16_bf16 v[80:95], v[88:91], v[96:99], 0
	ds_read_b128 v[210:213], v165 offset:12288
	v_mfma_f32_32x32x16_bf16 v[80:95], v[202:205], v[100:103], v[80:95]
	ds_read_b128 v[214:217], v155 offset:12416
	v_mfma_f32_32x32x16_bf16 v[80:95], v[206:209], v[104:107], v[80:95]
	ds_read_b128 v[218:221], v161 offset:12416
	s_waitcnt lgkmcnt(0)
	v_mfma_f32_32x32x16_bf16 v[80:95], v[210:213], v[108:111], v[80:95]
	ds_read_b128 v[224:227], v163 offset:12416
	v_mfma_f32_32x32x16_bf16 v[80:95], v[214:217], v[112:115], v[80:95]
	ds_read_b128 v[228:231], v165 offset:12416
	v_mfma_f32_32x32x16_bf16 v[80:95], v[218:221], v[116:119], v[80:95]
	ds_read_b128 v[232:235], v155 offset:12544
	s_waitcnt lgkmcnt(0)
	v_mfma_f32_32x32x16_bf16 v[80:95], v[224:227], v[120:123], v[80:95]
	ds_read_b128 v[236:239], v161 offset:12544
	v_mfma_f32_32x32x16_bf16 v[80:95], v[228:231], v[124:127], v[80:95]
	ds_read_b128 v[240:243], v163 offset:12544
	v_mfma_f32_32x32x16_bf16 v[80:95], v[232:235], v[128:131], v[80:95]
	ds_read_b128 v[244:247], v165 offset:12544
	s_waitcnt lgkmcnt(0)
	v_mfma_f32_32x32x16_bf16 v[80:95], v[236:239], v[132:135], v[80:95]
	v_mfma_f32_32x32x16_bf16 v[80:95], v[240:243], v[136:139], v[80:95]
	v_mfma_f32_32x32x16_bf16 v[80:95], v[244:247], v[140:143], v[80:95]
	v_mfma_f32_32x32x16_bf16 v[48:63], v[198:201], v[140:143], v[48:63]
	s_andn2_b64 vcc, exec, s[10:11]
	s_cbranch_vccnz .LBB0_1851

.LBB0_1858:
	s_setprio 1
	s_nop 7
	v_max_f32_e32 v155, v49, v49
	v_max_f32_e32 v161, v48, v48
	v_max_f32_e32 v155, v161, v155
	v_max3_f32 v155, v155, v50, v51
	v_max3_f32 v155, v155, v52, v53
	v_max3_f32 v155, v155, v54, v55
	v_max3_f32 v155, v155, v56, v57
	v_max3_f32 v155, v155, v58, v59
	v_max3_f32 v155, v155, v60, v61
	v_max3_f32 v155, v155, v62, v63
	v_mov_b32_e32 v161, v155
	s_nop 1
	v_permlane32_swap_b32_e32 v155, v161
	v_max_f32_e32 v161, v161, v161
	v_max_f32_e32 v155, v155, v155
	v_max_f32_e32 v155, v155, v161
	v_sub_f32_e32 v155, v155, v151
	v_cmp_lt_f32_e32 vcc, s26, v155
	s_cbranch_vccz .LBB0_1860
	v_max_f32_e32 v155, v155, v155
	v_max_f32_e32 v155, 0, v155
	v_exp_f32_e64 v168, -v155
	v_add_f32_e32 v151, v151, v155
	v_pk_mul_f32 v[78:79], v[78:79], v[168:169] op_sel_hi:[1,0]
	v_pk_mul_f32 v[76:77], v[76:77], v[168:169] op_sel_hi:[1,0]
	v_pk_mul_f32 v[74:75], v[74:75], v[168:169] op_sel_hi:[1,0]
	v_pk_mul_f32 v[72:73], v[72:73], v[168:169] op_sel_hi:[1,0]
	v_pk_mul_f32 v[70:71], v[70:71], v[168:169] op_sel_hi:[1,0]
	v_pk_mul_f32 v[68:69], v[68:69], v[168:169] op_sel_hi:[1,0]
	v_pk_mul_f32 v[66:67], v[66:67], v[168:169] op_sel_hi:[1,0]
	v_pk_mul_f32 v[64:65], v[64:65], v[168:169] op_sel_hi:[1,0]
	v_pk_mul_f32 v[46:47], v[46:47], v[168:169] op_sel_hi:[1,0]
	v_pk_mul_f32 v[44:45], v[44:45], v[168:169] op_sel_hi:[1,0]
	v_pk_mul_f32 v[42:43], v[42:43], v[168:169] op_sel_hi:[1,0]
	v_pk_mul_f32 v[40:41], v[40:41], v[168:169] op_sel_hi:[1,0]
	v_pk_mul_f32 v[38:39], v[38:39], v[168:169] op_sel_hi:[1,0]
	v_pk_mul_f32 v[36:37], v[36:37], v[168:169] op_sel_hi:[1,0]
	v_pk_mul_f32 v[34:35], v[34:35], v[168:169] op_sel_hi:[1,0]
	v_pk_mul_f32 v[32:33], v[32:33], v[168:169] op_sel_hi:[1,0]
	v_pk_mul_f32 v[30:31], v[30:31], v[168:169] op_sel_hi:[1,0]
	v_pk_mul_f32 v[28:29], v[28:29], v[168:169] op_sel_hi:[1,0]
	v_pk_mul_f32 v[26:27], v[26:27], v[168:169] op_sel_hi:[1,0]
	v_pk_mul_f32 v[24:25], v[24:25], v[168:169] op_sel_hi:[1,0]
	v_pk_mul_f32 v[22:23], v[22:23], v[168:169] op_sel_hi:[1,0]
	v_pk_mul_f32 v[20:21], v[20:21], v[168:169] op_sel_hi:[1,0]
	v_pk_mul_f32 v[18:19], v[18:19], v[168:169] op_sel_hi:[1,0]
	v_pk_mul_f32 v[16:17], v[16:17], v[168:169] op_sel_hi:[1,0]
	v_pk_mul_f32 v[14:15], v[14:15], v[168:169] op_sel_hi:[1,0]
	v_pk_mul_f32 v[12:13], v[12:13], v[168:169] op_sel_hi:[1,0]
	v_pk_mul_f32 v[10:11], v[10:11], v[168:169] op_sel_hi:[1,0]
	v_pk_mul_f32 v[8:9], v[8:9], v[168:169] op_sel_hi:[1,0]
	v_pk_mul_f32 v[6:7], v[6:7], v[168:169] op_sel_hi:[1,0]
	v_pk_mul_f32 v[4:5], v[4:5], v[168:169] op_sel_hi:[1,0]
	v_pk_mul_f32 v[2:3], v[2:3], v[168:169] op_sel_hi:[1,0]
	v_pk_mul_f32 v[0:1], v[0:1], v[168:169] op_sel_hi:[1,0]
	v_mul_f32_e32 v157, v157, v168
.LBB0_1860:
	v_add_u32_e32 v168, s27, v174
	v_add_u32_e32 v198, s27, v175
	v_sub_f32_e32 v48, v48, v151
	v_sub_f32_e32 v49, v49, v151
	v_sub_f32_e32 v50, v50, v151
	v_sub_f32_e32 v51, v51, v151
	v_sub_f32_e32 v52, v52, v151
	v_sub_f32_e32 v53, v53, v151
	v_sub_f32_e32 v54, v54, v151
	v_sub_f32_e32 v55, v55, v151
	v_add_u32_e32 v161, v168, v177
	v_exp_f32_e32 v48, v48
	v_exp_f32_e32 v49, v49
	v_exp_f32_e32 v50, v50
	v_exp_f32_e32 v51, v51
	v_exp_f32_e32 v52, v52
	v_exp_f32_e32 v53, v53
	v_exp_f32_e32 v54, v54
	v_exp_f32_e32 v55, v55
	v_add_u32_e32 v165, v198, v177
	ds_read_b64_tr_b16 v[204:205], v161 offset:24576
	ds_read_b64_tr_b16 v[206:207], v165 offset:26624
	v_add_u32_e32 v155, v168, v178
	v_add_u32_e32 v163, v198, v178
	ds_read_b64_tr_b16 v[208:209], v155 offset:24576
	ds_read_b64_tr_b16 v[210:211], v163 offset:26624
	ds_read_b64_tr_b16 v[214:215], v165 offset:30720
	ds_read_b64_tr_b16 v[212:213], v161 offset:28672
	v_cvt_pk_bf16_f32 v200, v48, v49
	v_cvt_pk_bf16_f32 v201, v50, v51
	v_cvt_pk_bf16_f32 v202, v52, v53
	v_cvt_pk_bf16_f32 v203, v54, v55
	v_add_u32_e32 v167, v168, v179
	v_add_u32_e32 v168, v168, v180
	s_waitcnt lgkmcnt(0)
	v_mfma_f32_32x32x16_bf16 v[64:79], v[204:207], v[200:203], v[64:79]
	v_add_u32_e32 v169, v198, v179
	ds_read_b64_tr_b16 v[204:205], v167 offset:24576
	ds_read_b64_tr_b16 v[206:207], v169 offset:26624
	ds_read_b64_tr_b16 v[218:219], v163 offset:30720
	ds_read_b64_tr_b16 v[216:217], v155 offset:28672
	v_add_u32_e32 v198, v198, v180
	v_add_f32_e32 v199, 0, v48
	v_sub_f32_e32 v56, v56, v151
	v_sub_f32_e32 v57, v57, v151
	v_sub_f32_e32 v58, v58, v151
	v_mfma_f32_32x32x16_bf16 v[32:47], v[208:211], v[200:203], v[32:47]
	ds_read_b64_tr_b16 v[208:209], v168 offset:24576
	ds_read_b64_tr_b16 v[210:211], v198 offset:26624
	ds_read_b64_tr_b16 v[226:227], v169 offset:30720
	ds_read_b64_tr_b16 v[224:225], v167 offset:28672
	v_sub_f32_e32 v59, v59, v151
	v_sub_f32_e32 v60, v60, v151
	v_sub_f32_e32 v61, v61, v151
	v_sub_f32_e32 v62, v62, v151
	v_sub_f32_e32 v63, v63, v151
	v_add_f32_e32 v199, v49, v199
	s_waitcnt lgkmcnt(0)
	v_mfma_f32_32x32x16_bf16 v[16:31], v[204:207], v[200:203], v[16:31]
	v_exp_f32_e32 v56, v56
	v_exp_f32_e32 v57, v57
	v_exp_f32_e32 v58, v58
	v_exp_f32_e32 v59, v59
	v_exp_f32_e32 v60, v60
	v_exp_f32_e32 v61, v61
	ds_read_b64_tr_b16 v[206:207], v198 offset:30720
	ds_read_b64_tr_b16 v[204:205], v168 offset:28672
	v_mfma_f32_32x32x16_bf16 v[0:15], v[208:211], v[200:203], v[0:15]
	v_exp_f32_e32 v62, v62
	v_exp_f32_e32 v63, v63
	v_add_f32_e32 v199, v50, v199
	v_add_f32_e32 v199, v51, v199
	v_add_f32_e32 v199, v52, v199
	v_add_f32_e32 v199, v53, v199
	v_cvt_pk_bf16_f32 v200, v56, v57
	v_cvt_pk_bf16_f32 v201, v58, v59
	v_cvt_pk_bf16_f32 v202, v60, v61
	v_cvt_pk_bf16_f32 v203, v62, v63
	v_add_f32_e32 v199, v54, v199
	v_add_f32_e32 v199, v55, v199
	v_mfma_f32_32x32x16_bf16 v[64:79], v[212:215], v[200:203], v[64:79]
	v_add_f32_e32 v199, v56, v199
	v_add_f32_e32 v199, v57, v199
	v_add_f32_e32 v199, v58, v199
	v_add_f32_e32 v199, v59, v199
	v_add_f32_e32 v199, v60, v199
	v_add_f32_e32 v199, v61, v199
	v_add_f32_e32 v199, v62, v199
	v_mfma_f32_32x32x16_bf16 v[32:47], v[216:219], v[200:203], v[32:47]
	v_add_f32_e32 v199, v63, v199
	v_add_f32_e32 v157, v157, v199
	v_mfma_f32_32x32x16_bf16 v[16:31], v[224:227], v[200:203], v[16:31]
	s_waitcnt lgkmcnt(0)
	v_mfma_f32_32x32x16_bf16 v[0:15], v[204:207], v[200:203], v[0:15]
	v_max_f32_e32 v200, v81, v81
	v_max_f32_e32 v201, v80, v80
	v_max_f32_e32 v200, v201, v200
	v_max3_f32 v200, v200, v82, v83
	v_max3_f32 v200, v200, v84, v85
	v_max3_f32 v200, v200, v86, v87
	v_max3_f32 v200, v200, v88, v89
	v_max3_f32 v200, v200, v90, v91
	v_max3_f32 v200, v200, v92, v93
	v_max3_f32 v200, v200, v94, v95
	v_mov_b32_e32 v199, v200
	s_nop 1
	v_permlane32_swap_b32_e32 v200, v199
	v_max_f32_e32 v199, v199, v199
	v_max_f32_e32 v200, v200, v200
	v_max_f32_e32 v199, v200, v199
	v_sub_f32_e32 v199, v199, v151
	v_cmp_lt_f32_e32 vcc, s26, v199
	s_cbranch_vccz .LBB0_1862
	v_max_f32_e32 v199, v199, v199
	v_max_f32_e32 v199, 0, v199
	v_exp_f32_e64 v200, -v199
	v_add_f32_e32 v151, v151, v199
	v_pk_mul_f32 v[78:79], v[78:79], v[200:201] op_sel_hi:[1,0]
	v_pk_mul_f32 v[76:77], v[76:77], v[200:201] op_sel_hi:[1,0]
	v_pk_mul_f32 v[74:75], v[74:75], v[200:201] op_sel_hi:[1,0]
	v_pk_mul_f32 v[72:73], v[72:73], v[200:201] op_sel_hi:[1,0]
	v_pk_mul_f32 v[70:71], v[70:71], v[200:201] op_sel_hi:[1,0]
	v_pk_mul_f32 v[68:69], v[68:69], v[200:201] op_sel_hi:[1,0]
	v_pk_mul_f32 v[66:67], v[66:67], v[200:201] op_sel_hi:[1,0]
	v_pk_mul_f32 v[64:65], v[64:65], v[200:201] op_sel_hi:[1,0]
	v_pk_mul_f32 v[46:47], v[46:47], v[200:201] op_sel_hi:[1,0]
	v_pk_mul_f32 v[44:45], v[44:45], v[200:201] op_sel_hi:[1,0]
	v_pk_mul_f32 v[42:43], v[42:43], v[200:201] op_sel_hi:[1,0]
	v_pk_mul_f32 v[40:41], v[40:41], v[200:201] op_sel_hi:[1,0]
	v_pk_mul_f32 v[38:39], v[38:39], v[200:201] op_sel_hi:[1,0]
	v_pk_mul_f32 v[36:37], v[36:37], v[200:201] op_sel_hi:[1,0]
	v_pk_mul_f32 v[34:35], v[34:35], v[200:201] op_sel_hi:[1,0]
	v_pk_mul_f32 v[32:33], v[32:33], v[200:201] op_sel_hi:[1,0]
	v_pk_mul_f32 v[30:31], v[30:31], v[200:201] op_sel_hi:[1,0]
	v_pk_mul_f32 v[28:29], v[28:29], v[200:201] op_sel_hi:[1,0]
	v_pk_mul_f32 v[26:27], v[26:27], v[200:201] op_sel_hi:[1,0]
	v_pk_mul_f32 v[24:25], v[24:25], v[200:201] op_sel_hi:[1,0]
	v_pk_mul_f32 v[22:23], v[22:23], v[200:201] op_sel_hi:[1,0]
	v_pk_mul_f32 v[20:21], v[20:21], v[200:201] op_sel_hi:[1,0]
	v_pk_mul_f32 v[18:19], v[18:19], v[200:201] op_sel_hi:[1,0]
	v_pk_mul_f32 v[16:17], v[16:17], v[200:201] op_sel_hi:[1,0]
	v_pk_mul_f32 v[14:15], v[14:15], v[200:201] op_sel_hi:[1,0]
	v_pk_mul_f32 v[12:13], v[12:13], v[200:201] op_sel_hi:[1,0]
	v_pk_mul_f32 v[10:11], v[10:11], v[200:201] op_sel_hi:[1,0]
	v_pk_mul_f32 v[8:9], v[8:9], v[200:201] op_sel_hi:[1,0]
	v_pk_mul_f32 v[6:7], v[6:7], v[200:201] op_sel_hi:[1,0]
	v_pk_mul_f32 v[4:5], v[4:5], v[200:201] op_sel_hi:[1,0]
	v_pk_mul_f32 v[2:3], v[2:3], v[200:201] op_sel_hi:[1,0]
	v_pk_mul_f32 v[0:1], v[0:1], v[200:201] op_sel_hi:[1,0]
	v_mul_f32_e32 v157, v157, v200
.LBB0_1862:
	v_sub_f32_e32 v80, v80, v151
	v_sub_f32_e32 v81, v81, v151
	v_sub_f32_e32 v82, v82, v151
	v_sub_f32_e32 v83, v83, v151
	v_sub_f32_e32 v84, v84, v151
	v_sub_f32_e32 v85, v85, v151
	v_sub_f32_e32 v86, v86, v151
	v_sub_f32_e32 v87, v87, v151
	v_exp_f32_e32 v80, v80
	v_exp_f32_e32 v81, v81
	v_exp_f32_e32 v82, v82
	v_exp_f32_e32 v83, v83
	v_exp_f32_e32 v84, v84
	v_exp_f32_e32 v85, v85
	v_exp_f32_e32 v86, v86
	v_exp_f32_e32 v87, v87
	ds_read_b64_tr_b16 v[200:201], v161 offset:32768
	ds_read_b64_tr_b16 v[202:203], v165 offset:34816
	ds_read_b64_tr_b16 v[208:209], v155 offset:32768
	ds_read_b64_tr_b16 v[210:211], v163 offset:34816
	ds_read_b64_tr_b16 v[214:215], v165 offset:38912
	ds_read_b64_tr_b16 v[212:213], v161 offset:36864
	v_cvt_pk_bf16_f32 v204, v80, v81
	v_cvt_pk_bf16_f32 v205, v82, v83
	v_cvt_pk_bf16_f32 v206, v84, v85
	v_cvt_pk_bf16_f32 v207, v86, v87
	v_sub_f32_e32 v88, v88, v151
	v_sub_f32_e32 v89, v89, v151
	s_waitcnt lgkmcnt(0)
	v_mfma_f32_32x32x16_bf16 v[64:79], v[200:203], v[204:207], v[64:79]
	ds_read_b64_tr_b16 v[200:201], v167 offset:32768
	ds_read_b64_tr_b16 v[202:203], v169 offset:34816
	ds_read_b64_tr_b16 v[218:219], v163 offset:38912
	ds_read_b64_tr_b16 v[216:217], v155 offset:36864
	v_add_f32_e32 v155, 0, v80
	v_add_f32_e32 v155, v81, v155
	v_add_f32_e32 v155, v82, v155
	v_sub_f32_e32 v90, v90, v151
	v_sub_f32_e32 v91, v91, v151
	v_sub_f32_e32 v92, v92, v151
	v_mfma_f32_32x32x16_bf16 v[32:47], v[208:211], v[204:207], v[32:47]
	ds_read_b64_tr_b16 v[208:209], v168 offset:32768
	ds_read_b64_tr_b16 v[210:211], v198 offset:34816
	ds_read_b64_tr_b16 v[226:227], v169 offset:38912
	ds_read_b64_tr_b16 v[224:225], v167 offset:36864
	v_sub_f32_e32 v93, v93, v151
	v_sub_f32_e32 v94, v94, v151
	v_sub_f32_e32 v95, v95, v151
	v_add_f32_e32 v155, v83, v155
	v_exp_f32_e32 v88, v88
	v_exp_f32_e32 v89, v89
	s_waitcnt lgkmcnt(0)
	v_mfma_f32_32x32x16_bf16 v[16:31], v[200:203], v[204:207], v[16:31]
	v_exp_f32_e32 v90, v90
	v_exp_f32_e32 v91, v91
	v_exp_f32_e32 v92, v92
	v_exp_f32_e32 v93, v93
	ds_read_b64_tr_b16 v[200:201], v198 offset:38912
	ds_read_b64_tr_b16 v[198:199], v168 offset:36864
	v_exp_f32_e32 v94, v94
	v_exp_f32_e32 v95, v95
	v_mfma_f32_32x32x16_bf16 v[0:15], v[208:211], v[204:207], v[0:15]
	v_add_f32_e32 v155, v84, v155
	v_add_f32_e32 v155, v85, v155
	v_add_f32_e32 v155, v86, v155
	v_add_f32_e32 v155, v87, v155
	v_cvt_pk_bf16_f32 v202, v88, v89
	v_cvt_pk_bf16_f32 v203, v90, v91
	v_cvt_pk_bf16_f32 v204, v92, v93
	v_cvt_pk_bf16_f32 v205, v94, v95
	v_add_f32_e32 v155, v88, v155
	v_add_f32_e32 v155, v89, v155
	v_mfma_f32_32x32x16_bf16 v[64:79], v[212:215], v[202:205], v[64:79]
	v_add_f32_e32 v155, v90, v155
	v_add_f32_e32 v155, v91, v155
	v_add_f32_e32 v155, v92, v155
	v_add_f32_e32 v155, v93, v155
	v_add_f32_e32 v155, v94, v155
	v_add_f32_e32 v155, v95, v155
	v_add_f32_e32 v157, v157, v155
	v_mfma_f32_32x32x16_bf16 v[32:47], v[216:219], v[202:205], v[32:47]
	v_mfma_f32_32x32x16_bf16 v[16:31], v[224:227], v[202:205], v[16:31]
	s_waitcnt lgkmcnt(0)
	v_mfma_f32_32x32x16_bf16 v[0:15], v[198:201], v[202:205], v[0:15]
	s_and_b64 vcc, exec, s[2:3]
	s_cbranch_vccz .LBB0_1853
	s_branch .LBB0_1854
.LBB0_1863:
	s_setprio 0
	v_mov_b32_e32 v48, v157
	s_nop 1
	v_permlane32_swap_b32_e32 v157, v48
	v_add_f32_e32 v48, v157, v48
	v_div_scale_f32 v49, s[2:3], v48, v48, 1.0
	v_rcp_f32_e32 v50, v49
	s_mulk_i32 s21, 0x2200
	s_add_i32 s7, s21, 0
	s_waitcnt vmcnt(0) lgkmcnt(0)
	s_barrier
	v_fma_f32 v51, -v49, v50, 1.0
	v_fmac_f32_e32 v50, v51, v50
	v_div_scale_f32 v51, vcc, 1.0, v48, 1.0
	v_mul_f32_e32 v52, v51, v50
	v_fma_f32 v53, -v49, v52, v51
	v_fmac_f32_e32 v52, v53, v50
	v_fma_f32 v49, -v49, v52, v51
	v_div_fmas_f32 v49, v49, v50, v52
	v_div_fixup_f32 v48, v49, v48, 1.0
	v_add3_u32 v49, s7, v195, v181
	v_pk_mul_f32 v[50:51], v[64:65], v[48:49] op_sel_hi:[1,0]
	v_pk_mul_f32 v[52:53], v[66:67], v[48:49] op_sel_hi:[1,0]
	v_cvt_pk_bf16_f32 v50, v50, v51
	v_cvt_pk_bf16_f32 v51, v52, v53
	v_pk_mul_f32 v[52:53], v[68:69], v[48:49] op_sel_hi:[1,0]
	v_pk_mul_f32 v[54:55], v[70:71], v[48:49] op_sel_hi:[1,0]
	v_add_u32_e32 v49, 0xa000, v49
	v_pk_mul_f32 v[32:33], v[32:33], v[48:49] op_sel_hi:[1,0]
	v_pk_mul_f32 v[34:35], v[34:35], v[48:49] op_sel_hi:[1,0]
	v_pk_mul_f32 v[16:17], v[16:17], v[48:49] op_sel_hi:[1,0]
	v_pk_mul_f32 v[18:19], v[18:19], v[48:49] op_sel_hi:[1,0]
	v_pk_mul_f32 v[0:1], v[0:1], v[48:49] op_sel_hi:[1,0]
	v_pk_mul_f32 v[2:3], v[2:3], v[48:49] op_sel_hi:[1,0]
	v_cvt_pk_bf16_f32 v32, v32, v33
	v_cvt_pk_bf16_f32 v33, v34, v35
	v_pk_mul_f32 v[34:35], v[36:37], v[48:49] op_sel_hi:[1,0]
	v_pk_mul_f32 v[36:37], v[38:39], v[48:49] op_sel_hi:[1,0]
	v_cvt_pk_bf16_f32 v16, v16, v17
	v_cvt_pk_bf16_f32 v17, v18, v19
	v_pk_mul_f32 v[18:19], v[20:21], v[48:49] op_sel_hi:[1,0]
	v_pk_mul_f32 v[20:21], v[22:23], v[48:49] op_sel_hi:[1,0]
	v_cvt_pk_bf16_f32 v0, v0, v1
	v_cvt_pk_bf16_f32 v1, v2, v3
	v_pk_mul_f32 v[2:3], v[4:5], v[48:49] op_sel_hi:[1,0]
	v_pk_mul_f32 v[4:5], v[6:7], v[48:49] op_sel_hi:[1,0]
	v_cvt_pk_bf16_f32 v52, v52, v53
	v_cvt_pk_bf16_f32 v53, v54, v55
	v_cvt_pk_bf16_f32 v34, v34, v35
	v_cvt_pk_bf16_f32 v35, v36, v37
	v_cvt_pk_bf16_f32 v18, v18, v19
	v_cvt_pk_bf16_f32 v19, v20, v21
	v_cvt_pk_bf16_f32 v2, v2, v3
	v_cvt_pk_bf16_f32 v3, v4, v5
	ds_write2_b64 v49, v[50:51], v[52:53] offset1:2
	v_pk_mul_f32 v[50:51], v[72:73], v[48:49] op_sel_hi:[1,0]
	v_pk_mul_f32 v[52:53], v[74:75], v[48:49] op_sel_hi:[1,0]
	ds_write2_b64 v49, v[32:33], v[34:35] offset0:8 offset1:10
	v_pk_mul_f32 v[32:33], v[40:41], v[48:49] op_sel_hi:[1,0]
	v_pk_mul_f32 v[34:35], v[42:43], v[48:49] op_sel_hi:[1,0]
	ds_write2_b64 v49, v[16:17], v[18:19] offset0:16 offset1:18
	v_pk_mul_f32 v[16:17], v[24:25], v[48:49] op_sel_hi:[1,0]
	v_pk_mul_f32 v[18:19], v[26:27], v[48:49] op_sel_hi:[1,0]
	ds_write2_b64 v49, v[0:1], v[2:3] offset0:24 offset1:26
	v_pk_mul_f32 v[0:1], v[8:9], v[48:49] op_sel_hi:[1,0]
	v_pk_mul_f32 v[2:3], v[10:11], v[48:49] op_sel_hi:[1,0]
	v_cvt_pk_bf16_f32 v50, v50, v51
	v_cvt_pk_bf16_f32 v51, v52, v53
	v_pk_mul_f32 v[52:53], v[76:77], v[48:49] op_sel_hi:[1,0]
	v_pk_mul_f32 v[54:55], v[78:79], v[48:49] op_sel_hi:[1,0]
	v_cvt_pk_bf16_f32 v32, v32, v33
	v_cvt_pk_bf16_f32 v33, v34, v35
	v_pk_mul_f32 v[34:35], v[44:45], v[48:49] op_sel_hi:[1,0]
	v_pk_mul_f32 v[36:37], v[46:47], v[48:49] op_sel_hi:[1,0]
	v_cvt_pk_bf16_f32 v16, v16, v17
	v_cvt_pk_bf16_f32 v17, v18, v19
	v_pk_mul_f32 v[18:19], v[28:29], v[48:49] op_sel_hi:[1,0]
	v_pk_mul_f32 v[20:21], v[30:31], v[48:49] op_sel_hi:[1,0]
	v_cvt_pk_bf16_f32 v0, v0, v1
	v_cvt_pk_bf16_f32 v1, v2, v3
	v_pk_mul_f32 v[2:3], v[12:13], v[48:49] op_sel_hi:[1,0]
	v_pk_mul_f32 v[4:5], v[14:15], v[48:49] op_sel_hi:[1,0]
	v_cvt_pk_bf16_f32 v52, v52, v53
	v_cvt_pk_bf16_f32 v53, v54, v55
	v_cvt_pk_bf16_f32 v34, v34, v35
	v_cvt_pk_bf16_f32 v35, v36, v37
	v_cvt_pk_bf16_f32 v18, v18, v19
	v_cvt_pk_bf16_f32 v19, v20, v21
	v_cvt_pk_bf16_f32 v2, v2, v3
	v_cvt_pk_bf16_f32 v3, v4, v5
	s_mulk_i32 s20, 0x1800
	s_mul_hi_u32 s2, s19, 0x1800
	ds_write2_b64 v49, v[50:51], v[52:53] offset0:4 offset1:6
	ds_write2_b64 v49, v[32:33], v[34:35] offset0:12 offset1:14
	ds_write2_b64 v49, v[16:17], v[18:19] offset0:20 offset1:22
	ds_write2_b64 v49, v[0:1], v[2:3] offset0:28 offset1:30
	s_add_i32 s2, s2, s20
	s_mulk_i32 s19, 0x1800
	s_waitcnt lgkmcnt(0)
	s_add_u32 s3, s4, s19
	v_add3_u32 v14, s7, v144, v196
	s_addc_u32 s10, s5, s2
	ds_read_b128 v[0:3], v14 offset:40960
	s_add_u32 s2, s3, s6
	s_addc_u32 s3, s10, 0
	v_lshlrev_b32_e32 v158, 1, v153
	v_mov_b32_e32 v159, 0
	ds_read_b128 v[4:7], v14 offset:42048
	v_lshl_add_u64 v[8:9], s[2:3], 0, v[158:159]
	v_mov_b32_e32 v147, v159
	v_lshl_add_u64 v[10:11], v[8:9], 0, v[146:147]
	s_movk_i32 s2, 0x6000
	s_waitcnt lgkmcnt(0)
	global_store_dwordx4 v[10:11], v[0:3], off
	v_mov_b32_e32 v149, v159
	v_mov_b32_e32 v153, v159
	v_add_co_u32_e32 v0, vcc, s2, v10
	s_mov_b32 s2, 0xc000
	s_nop 0
	v_addc_co_u32_e32 v1, vcc, 0, v11, vcc
	global_store_dwordx4 v[0:1], v[4:7], off
	ds_read_b128 v[0:3], v14 offset:43136
	ds_read_b128 v[4:7], v14 offset:44224
	v_add_co_u32_e32 v12, vcc, s2, v10
	s_mov_b32 s2, 0x12000
	s_nop 0
	v_addc_co_u32_e32 v13, vcc, 0, v11, vcc
	v_add_co_u32_e32 v10, vcc, s2, v10
	s_waitcnt lgkmcnt(0)
	global_store_dwordx4 v[12:13], v[0:3], off
	v_addc_co_u32_e32 v11, vcc, 0, v11, vcc
	ds_read_b128 v[0:3], v14 offset:45312
	global_store_dwordx4 v[10:11], v[4:7], off
	ds_read_b128 v[4:7], v14 offset:46400
	v_lshl_add_u64 v[10:11], v[8:9], 0, v[148:149]
	v_mov_b32_e32 v151, v159
	s_waitcnt lgkmcnt(0)
	global_store_dwordx4 v[10:11], v[0:3], off
	v_lshl_add_u64 v[10:11], v[8:9], 0, v[152:153]
	ds_read_b128 v[0:3], v14 offset:47488
	global_store_dwordx4 v[10:11], v[4:7], off
	ds_read_b128 v[4:7], v14 offset:48576
	v_lshl_add_u64 v[10:11], v[8:9], 0, v[150:151]
	v_mov_b32_e32 v155, v159
	v_readfirstlane_b32 s12, v222
	s_waitcnt lgkmcnt(0)
	global_store_dwordx4 v[10:11], v[0:3], off
	s_and_b32 s2, s12, 0xffffffc0
	s_nop 0
	v_lshl_add_u64 v[0:1], v[8:9], 0, v[154:155]
	global_store_dwordx4 v[0:1], v[4:7], off
	v_or_b32_e32 v0, s2, v197
	s_mov_b32 s2, 0x2aaaaaab
	v_mul_hi_i32 v1, v0, s2
	v_lshrrev_b32_e32 v2, 31, v1
	v_ashrrev_i32_e32 v1, 2, v1
	v_add_u32_e32 v2, v1, v2
	s_movk_i32 s2, 0xffe8
	v_lshrrev_b32_e32 v159, 1, v2
	v_mad_u64_u32 v[160:161], s[2:3], v2, s2, v[0:1]
	v_xor_b32_e32 v1, v159, v222
	v_bfi_b32 v1, -8, v160, v1
	v_cmp_lt_i32_e32 vcc, 15, v1
	v_add_u32_e32 v2, s8, v2
	s_and_saveexec_b64 s[2:3], vcc
	s_xor_b64 s[2:3], exec, s[2:3]
	v_mov_b32_e32 v3, 0xbfff80
	v_lshl_add_u32 v153, v2, 6, v3
	s_or_saveexec_b64 s[2:3], s[2:3]
	v_mov_b32_e32 v145, 0x1000
	s_xor_b64 exec, exec, s[2:3]
	v_lshl_or_b32 v2, v2, 11, s17
	v_add_u32_e32 v153, 0x8000000, v2
	v_mov_b32_e32 v145, 0x20000
	s_or_b64 exec, exec, s[2:3]
	v_add_u32_e32 v2, 0x200, v0
	s_mov_b32 s2, 0x2aaaaaab
	v_mul_hi_i32 v3, v2, s2
	v_lshrrev_b32_e32 v4, 31, v3
	v_ashrrev_i32_e32 v3, 2, v3
	v_add_u32_e32 v4, v3, v4
	s_movk_i32 s2, 0xffe8
	v_mad_u64_u32 v[162:163], s[2:3], v4, s2, v[2:3]
	v_lshrrev_b32_e32 v163, 1, v4
	v_xor_b32_e32 v3, v163, v222
	v_bfi_b32 v3, -8, v162, v3
	v_cmp_lt_i32_e32 vcc, 15, v3
	v_add_u32_e32 v4, s8, v4
	s_and_saveexec_b64 s[2:3], vcc
	s_xor_b64 s[2:3], exec, s[2:3]
	v_mov_b32_e32 v5, 0xbfff80
	v_lshl_add_u32 v155, v4, 6, v5
	s_or_saveexec_b64 s[2:3], s[2:3]
	v_mov_b32_e32 v147, 0x1000
	s_xor_b64 exec, exec, s[2:3]
	v_lshl_or_b32 v4, v4, 11, s17
	v_add_u32_e32 v155, 0x8000000, v4
	v_mov_b32_e32 v147, 0x20000
	s_or_b64 exec, exec, s[2:3]
	v_add_u32_e32 v4, 0x400, v0
	s_mov_b32 s2, 0x2aaaaaab
	v_mul_hi_i32 v5, v4, s2
	v_lshrrev_b32_e32 v6, 31, v5
	v_ashrrev_i32_e32 v5, 2, v5
	v_add_u32_e32 v5, v5, v6
	s_movk_i32 s2, 0xffe8
	v_mad_u64_u32 v[164:165], s[2:3], v5, s2, v[4:5]
	v_lshrrev_b32_e32 v165, 1, v5
	v_xor_b32_e32 v4, v165, v222
	v_bfi_b32 v4, -8, v164, v4
	v_cmp_lt_i32_e32 vcc, 15, v4
	v_add_u32_e32 v5, s8, v5
	s_and_saveexec_b64 s[2:3], vcc
	s_xor_b64 s[2:3], exec, s[2:3]
	v_mov_b32_e32 v6, 0xbfff80
	v_lshl_add_u32 v161, v5, 6, v6
	s_or_saveexec_b64 s[2:3], s[2:3]
	v_mov_b32_e32 v149, 0x1000
	s_xor_b64 exec, exec, s[2:3]
	v_lshl_or_b32 v5, v5, 11, s17
	v_add_u32_e32 v161, 0x8000000, v5
	v_mov_b32_e32 v149, 0x20000
	s_or_b64 exec, exec, s[2:3]
	s_lshr_b32 s21, s12, 6
	s_xor_b32 s22, s16, 0x1700
	s_lshl_b32 s23, s21, 5
	s_or_b32 s2, s8, s22
	s_add_u32 s19, s2, s23
	v_or_b32_e32 v5, s19, v194
	s_movk_i32 s2, 0x1800
	v_mov_b64_e32 v[6:7], s[4:5]
	s_addc_u32 s20, s9, 0
	v_mad_u64_u32 v[6:7], s[2:3], v5, s2, v[6:7]
	v_mov_b32_e32 v5, 0x1800
	s_mov_b32 s7, 0
	v_mad_i32_i24 v7, s20, v5, v7
	v_lshl_add_u32 v8, v1, 3, v153
	v_ashrrev_i32_e32 v1, 31, v0
	v_lshl_add_u64 v[6:7], v[6:7], 0, s[6:7]
	v_mov_b32_e32 v157, 0
	v_lshrrev_b32_e32 v10, 28, v1
	v_lshl_add_u64 v[6:7], v[6:7], 0, v[156:157]
	v_lshl_add_u32 v4, v4, 3, v161
	v_mov_b32_e32 v5, v157
	v_add_u32_e32 v16, v0, v10
	global_load_dwordx4 v[96:99], v[6:7], off
	global_load_dwordx4 v[100:103], v[6:7], off offset:32
	global_load_dwordx4 v[104:107], v[6:7], off offset:64
	global_load_dwordx4 v[108:111], v[6:7], off offset:96
	global_load_dwordx4 v[112:115], v[6:7], off offset:128
	global_load_dwordx4 v[116:119], v[6:7], off offset:160
	global_load_dwordx4 v[120:123], v[6:7], off offset:192
	global_load_dwordx4 v[124:127], v[6:7], off offset:224
	global_load_dwordx4 v[128:131], v[6:7], off offset:256
	global_load_dwordx4 v[132:135], v[6:7], off offset:288
	global_load_dwordx4 v[136:139], v[6:7], off offset:320
	global_load_dwordx4 v[140:143], v[6:7], off offset:352
	v_lshl_add_u32 v6, v3, 3, v155
	v_ashrrev_i32_e32 v3, 31, v2
	v_lshl_add_u64 v[14:15], v[4:5], 1, s[84:85]
	v_ashrrev_i32_e32 v167, 4, v16
	v_and_b32_e32 v5, 0x1ffffff0, v16
	v_lshrrev_b32_e32 v11, 28, v3
	v_mov_b32_e32 v9, v157
	s_lshl_b32 s2, s21, 10
	v_sub_u32_e32 v0, v0, v5
	v_lshlrev_b32_e32 v5, 2, v167
	v_mov_b32_e32 v7, v157
	v_add_u32_e32 v17, v2, v11
	v_lshl_add_u64 v[10:11], v[8:9], 1, s[84:85]
	v_bfe_u32 v9, v167, 2, 2
	s_add_i32 s7, s2, 0
	v_and_b32_e32 v5, 12, v5
	v_lshl_add_u64 v[12:13], v[6:7], 1, s[84:85]
	v_ashrrev_i32_e32 v166, 4, v17
	v_and_b32_e32 v7, 0x1ffffff0, v17
	v_bitop3_b32 v0, v5, v0, v9 bitop3:0x36
	s_mov_b32 m0, s7
	v_add_lshl_u32 v16, v167, s8, 11
	v_sub_u32_e32 v2, v2, v7
	v_lshlrev_b32_e32 v7, 2, v166
	global_load_lds_dwordx4 v[10:11], off
	s_add_i32 m0, s7, 0x2000
	v_lshlrev_b32_e32 v168, 3, v0
	v_mov_b32_e32 v1, v157
	v_bfe_u32 v17, v166, 2, 2
	v_and_b32_e32 v7, 12, v7
	global_load_lds_dwordx4 v[12:13], off
	s_add_i32 m0, s7, 0x4000
	v_add3_u32 v0, s18, v16, v168
	v_bitop3_b32 v2, v7, v2, v17 bitop3:0x36
	global_load_lds_dwordx4 v[14:15], off
	s_add_i32 m0, s7, 0x6000
	v_lshl_add_u64 v[10:11], v[0:1], 1, s[84:85]
	v_add_lshl_u32 v18, v166, s8, 11
	v_lshlrev_b32_e32 v169, 3, v2
	global_load_lds_dwordx4 v[10:11], off
	s_add_i32 m0, s7, 0x8000
	v_mov_b32_e32 v3, v157
	v_add3_u32 v2, s18, v18, v169
	s_cmpk_gt_u32 s12, 0xff
	v_lshl_add_u64 v[12:13], v[2:3], 1, s[84:85]
	s_cselect_b64 s[10:11], -1, 0
	s_cmpk_lt_u32 s12, 0x100
	v_add_u32_e32 v8, v8, v145
	v_mov_b32_e32 v9, v157
	global_load_lds_dwordx4 v[12:13], off
	s_cselect_b64 s[12:13], -1, 0
	s_add_i32 m0, s7, 0xa000
	v_lshl_add_u64 v[8:9], v[8:9], 1, s[84:85]
	v_add_u32_e32 v6, v6, v147
	v_mov_b32_e32 v7, v157
	s_waitcnt vmcnt(0) lgkmcnt(0)
	s_barrier
	s_waitcnt vmcnt(0)
	global_load_lds_dwordx4 v[8:9], off
	v_lshl_add_u64 v[6:7], v[6:7], 1, s[84:85]
	s_add_i32 m0, s7, 0xc000
	v_add_u32_e32 v4, v4, v149
	v_mov_b32_e32 v5, v157
	global_load_lds_dwordx4 v[6:7], off
	v_lshl_add_u64 v[4:5], v[4:5], 1, s[84:85]
	s_add_i32 m0, s7, 0xe000
	v_add_u32_e32 v0, 0x20000, v0
	v_mov_b32_e32 v1, v157
	global_load_lds_dwordx4 v[4:5], off
	s_add_i32 m0, s7, 0x10000
	v_lshl_add_u64 v[0:1], v[0:1], 1, s[84:85]
	global_load_lds_dwordx4 v[0:1], off
	v_add_u32_e32 v0, 0x20000, v2
	v_mov_b32_e32 v1, v157
	v_lshl_add_u64 v[0:1], v[0:1], 1, s[84:85]
	s_add_i32 m0, s7, 0x12000
	s_and_b64 vcc, exec, s[12:13]
	global_load_lds_dwordx4 v[0:1], off
	ds_read_b128 v[0:3], v190
	ds_read_b128 v[4:7], v191
	ds_read_b128 v[8:11], v192
	ds_read_b128 v[12:15], v193
	s_waitcnt lgkmcnt(0)
	v_mfma_f32_32x32x16_bf16 v[48:63], v[0:3], v[96:99], 0
	ds_read_b128 v[0:3], v190 offset:128
	v_mfma_f32_32x32x16_bf16 v[48:63], v[4:7], v[100:103], v[48:63]
	ds_read_b128 v[4:7], v191 offset:128
	v_mfma_f32_32x32x16_bf16 v[48:63], v[8:11], v[104:107], v[48:63]
	ds_read_b128 v[8:11], v192 offset:128
	v_mfma_f32_32x32x16_bf16 v[48:63], v[12:15], v[108:111], v[48:63]
	ds_read_b128 v[12:15], v193 offset:128
	s_waitcnt lgkmcnt(0)
	v_mfma_f32_32x32x16_bf16 v[48:63], v[0:3], v[112:115], v[48:63]
	ds_read_b128 v[0:3], v190 offset:256
	v_mfma_f32_32x32x16_bf16 v[48:63], v[4:7], v[116:119], v[48:63]
	ds_read_b128 v[4:7], v191 offset:256
	v_mfma_f32_32x32x16_bf16 v[48:63], v[8:11], v[120:123], v[48:63]
	ds_read_b128 v[8:11], v192 offset:256
	v_mfma_f32_32x32x16_bf16 v[48:63], v[12:15], v[124:127], v[48:63]
	ds_read_b128 v[12:15], v193 offset:256
	s_waitcnt lgkmcnt(0)
	v_mfma_f32_32x32x16_bf16 v[48:63], v[0:3], v[128:131], v[48:63]
	ds_read_b128 v[0:3], v190 offset:12288
	v_mfma_f32_32x32x16_bf16 v[48:63], v[4:7], v[132:135], v[48:63]
	ds_read_b128 v[4:7], v191 offset:12288
	v_mfma_f32_32x32x16_bf16 v[48:63], v[8:11], v[136:139], v[48:63]
	ds_read_b128 v[8:11], v192 offset:12288
	s_waitcnt lgkmcnt(0)
	v_mfma_f32_32x32x16_bf16 v[80:95], v[0:3], v[96:99], 0
	ds_read_b128 v[16:19], v193 offset:12288
	v_mfma_f32_32x32x16_bf16 v[80:95], v[4:7], v[100:103], v[80:95]
	ds_read_b128 v[20:23], v190 offset:12416
	v_mfma_f32_32x32x16_bf16 v[80:95], v[8:11], v[104:107], v[80:95]
	ds_read_b128 v[24:27], v191 offset:12416
	s_waitcnt lgkmcnt(0)
	v_mfma_f32_32x32x16_bf16 v[80:95], v[16:19], v[108:111], v[80:95]
	ds_read_b128 v[28:31], v192 offset:12416
	v_mfma_f32_32x32x16_bf16 v[80:95], v[20:23], v[112:115], v[80:95]
	ds_read_b128 v[32:35], v193 offset:12416
	v_mfma_f32_32x32x16_bf16 v[80:95], v[24:27], v[116:119], v[80:95]
	ds_read_b128 v[36:39], v190 offset:12544
	s_waitcnt lgkmcnt(0)
	v_mfma_f32_32x32x16_bf16 v[80:95], v[28:31], v[120:123], v[80:95]
	ds_read_b128 v[40:43], v191 offset:12544
	v_mfma_f32_32x32x16_bf16 v[80:95], v[32:35], v[124:127], v[80:95]
	ds_read_b128 v[44:47], v192 offset:12544
	v_mfma_f32_32x32x16_bf16 v[80:95], v[36:39], v[128:131], v[80:95]
	ds_read_b128 v[64:67], v193 offset:12544
	s_waitcnt lgkmcnt(0)
	v_mfma_f32_32x32x16_bf16 v[80:95], v[40:43], v[132:135], v[80:95]
	v_mfma_f32_32x32x16_bf16 v[80:95], v[44:47], v[136:139], v[80:95]
	v_mfma_f32_32x32x16_bf16 v[80:95], v[64:67], v[140:143], v[80:95]
	v_mfma_f32_32x32x16_bf16 v[48:63], v[12:15], v[140:143], v[48:63]
	s_cbranch_vccnz .LBB0_1877
	s_waitcnt vmcnt(0) lgkmcnt(0)
	s_barrier
.LBB0_1877:
	s_nop 10
	v_max_f32_e32 v0, v49, v49
	v_max_f32_e32 v1, v48, v48
	v_max_f32_e32 v0, v1, v0
	v_max3_f32 v0, v0, v50, v51
	v_max3_f32 v0, v0, v52, v53
	v_max3_f32 v0, v0, v54, v55
	v_max3_f32 v0, v0, v56, v57
	v_max3_f32 v0, v0, v58, v59
	v_max3_f32 v0, v0, v60, v61
	v_max3_f32 v0, v0, v62, v63
	v_mov_b32_e32 v1, v0
	s_nop 1
	v_permlane32_swap_b32_e32 v0, v1
	v_max_f32_e32 v1, v1, v1
	v_max_f32_e32 v0, v0, v0
	v_max_f32_e32 v0, v0, v1
	s_cmp_lg_u64 exec, 0
	v_add_f32_e32 v0, 0, v0
	s_cselect_b64 vcc, -1, 0
	v_cndmask_b32_e32 v151, 0, v0, vcc
	v_sub_f32_e32 v0, v48, v151
	v_exp_f32_e32 v48, v0
	v_sub_f32_e32 v0, v49, v151
	v_exp_f32_e32 v49, v0
	v_sub_f32_e32 v0, v50, v151
	v_exp_f32_e32 v50, v0
	v_sub_f32_e32 v0, v51, v151
	v_exp_f32_e32 v51, v0
	v_sub_f32_e32 v0, v52, v151
	v_exp_f32_e32 v52, v0
	v_sub_f32_e32 v0, v53, v151
	v_exp_f32_e32 v53, v0
	v_sub_f32_e32 v0, v54, v151
	v_exp_f32_e32 v54, v0
	v_sub_f32_e32 v0, v55, v151
	v_exp_f32_e32 v55, v0
	v_sub_f32_e32 v0, v56, v151
	v_exp_f32_e32 v56, v0
	ds_read_b64_tr_b16 v[0:1], v183 offset:24576
	ds_read_b64_tr_b16 v[2:3], v185 offset:26624
	v_cvt_pk_bf16_f32 v4, v48, v49
	v_cvt_pk_bf16_f32 v5, v50, v51
	v_cvt_pk_bf16_f32 v6, v52, v53
	v_cvt_pk_bf16_f32 v7, v54, v55
	ds_read_b64_tr_b16 v[8:9], v182 offset:24576
	ds_read_b64_tr_b16 v[10:11], v184 offset:26624
	ds_read_b64_tr_b16 v[200:201], v185 offset:30720
	ds_read_b64_tr_b16 v[198:199], v183 offset:28672
	s_waitcnt lgkmcnt(0)
	v_mfma_f32_32x32x16_bf16 v[64:79], v[0:3], v[4:7], 0
	v_sub_f32_e32 v0, v57, v151
	v_exp_f32_e32 v57, v0
	ds_read_b64_tr_b16 v[0:1], v186 offset:24576
	ds_read_b64_tr_b16 v[2:3], v188 offset:26624
	ds_read_b64_tr_b16 v[204:205], v184 offset:30720
	ds_read_b64_tr_b16 v[202:203], v182 offset:28672
	v_sub_f32_e32 v12, v58, v151
	v_sub_f32_e32 v62, v62, v151
	v_sub_f32_e32 v63, v63, v151
	v_exp_f32_e32 v58, v12
	s_waitcnt lgkmcnt(0)
	v_mfma_f32_32x32x16_bf16 v[16:31], v[0:3], v[4:7], 0
	v_sub_f32_e32 v0, v60, v151
	v_exp_f32_e32 v60, v0
	v_sub_f32_e32 v0, v61, v151
	v_exp_f32_e32 v61, v0
	v_exp_f32_e32 v62, v62
	v_exp_f32_e32 v63, v63
	v_add_f32_e32 v157, 0, v48
	v_mfma_f32_32x32x16_bf16 v[32:47], v[8:11], v[4:7], 0
	v_sub_f32_e32 v8, v59, v151
	v_exp_f32_e32 v59, v8
	ds_read_b64_tr_b16 v[8:9], v187 offset:24576
	ds_read_b64_tr_b16 v[10:11], v189 offset:26624
	ds_read_b64_tr_b16 v[208:209], v188 offset:30720
	ds_read_b64_tr_b16 v[206:207], v186 offset:28672
	v_cvt_pk_bf16_f32 v214, v56, v57
	v_cvt_pk_bf16_f32 v216, v60, v61
	v_cvt_pk_bf16_f32 v215, v58, v59
	v_cvt_pk_bf16_f32 v217, v62, v63
	s_waitcnt lgkmcnt(0)
	v_mfma_f32_32x32x16_bf16 v[0:15], v[8:11], v[4:7], 0
	v_add_f32_e32 v157, v49, v157
	v_add_f32_e32 v157, v50, v157
	v_add_f32_e32 v157, v51, v157
	ds_read_b64_tr_b16 v[212:213], v189 offset:30720
	ds_read_b64_tr_b16 v[210:211], v187 offset:28672
	v_add_f32_e32 v157, v52, v157
	v_add_f32_e32 v157, v53, v157
	v_add_f32_e32 v157, v54, v157
	v_mfma_f32_32x32x16_bf16 v[64:79], v[198:201], v[214:217], v[64:79]
	v_max_f32_e32 v198, v81, v81
	v_max_f32_e32 v199, v80, v80
	v_max_f32_e32 v198, v199, v198
	v_max3_f32 v198, v198, v82, v83
	v_max3_f32 v198, v198, v84, v85
	v_max3_f32 v198, v198, v86, v87
	v_add_f32_e32 v157, v55, v157
	v_max3_f32 v198, v198, v88, v89
	v_add_f32_e32 v157, v56, v157
	v_max3_f32 v198, v198, v90, v91
	v_mfma_f32_32x32x16_bf16 v[32:47], v[202:205], v[214:217], v[32:47]
	v_add_f32_e32 v157, v57, v157
	v_max3_f32 v198, v198, v92, v93
	v_add_f32_e32 v157, v58, v157
	v_max3_f32 v198, v198, v94, v95
	v_add_f32_e32 v157, v59, v157
	v_mov_b32_e32 v199, v198
	v_add_f32_e32 v157, v60, v157
	v_mfma_f32_32x32x16_bf16 v[16:31], v[206:209], v[214:217], v[16:31]
	v_permlane32_swap_b32_e32 v198, v199
	v_add_f32_e32 v157, v61, v157
	v_max_f32_e32 v199, v199, v199
	v_max_f32_e32 v198, v198, v198
	v_add_f32_e32 v157, v62, v157
	v_max_f32_e32 v198, v198, v199
	s_waitcnt lgkmcnt(0)
	v_mfma_f32_32x32x16_bf16 v[0:15], v[210:213], v[214:217], v[0:15]
	v_add_f32_e32 v157, v63, v157
	v_sub_f32_e32 v198, v198, v151
	s_mov_b32 s2, 0x41000000
	v_add_f32_e32 v157, 0, v157
	v_cmp_lt_f32_e32 vcc, s2, v198
	s_cbranch_vccz .LBB0_1879
	v_max_f32_e32 v198, v198, v198
	v_max_f32_e32 v199, 0, v198
	v_exp_f32_e64 v198, -v199
	v_add_f32_e32 v151, v151, v199
	v_pk_mul_f32 v[78:79], v[78:79], v[198:199] op_sel_hi:[1,0]
	v_pk_mul_f32 v[76:77], v[76:77], v[198:199] op_sel_hi:[1,0]
	v_pk_mul_f32 v[74:75], v[74:75], v[198:199] op_sel_hi:[1,0]
	v_pk_mul_f32 v[72:73], v[72:73], v[198:199] op_sel_hi:[1,0]
	v_pk_mul_f32 v[70:71], v[70:71], v[198:199] op_sel_hi:[1,0]
	v_pk_mul_f32 v[68:69], v[68:69], v[198:199] op_sel_hi:[1,0]
	v_pk_mul_f32 v[66:67], v[66:67], v[198:199] op_sel_hi:[1,0]
	v_pk_mul_f32 v[64:65], v[64:65], v[198:199] op_sel_hi:[1,0]
	v_pk_mul_f32 v[46:47], v[46:47], v[198:199] op_sel_hi:[1,0]
	v_pk_mul_f32 v[44:45], v[44:45], v[198:199] op_sel_hi:[1,0]
	v_pk_mul_f32 v[42:43], v[42:43], v[198:199] op_sel_hi:[1,0]
	v_pk_mul_f32 v[40:41], v[40:41], v[198:199] op_sel_hi:[1,0]
	v_pk_mul_f32 v[38:39], v[38:39], v[198:199] op_sel_hi:[1,0]
	v_pk_mul_f32 v[36:37], v[36:37], v[198:199] op_sel_hi:[1,0]
	v_pk_mul_f32 v[34:35], v[34:35], v[198:199] op_sel_hi:[1,0]
	v_pk_mul_f32 v[32:33], v[32:33], v[198:199] op_sel_hi:[1,0]
	v_pk_mul_f32 v[30:31], v[30:31], v[198:199] op_sel_hi:[1,0]
	v_pk_mul_f32 v[28:29], v[28:29], v[198:199] op_sel_hi:[1,0]
	v_pk_mul_f32 v[26:27], v[26:27], v[198:199] op_sel_hi:[1,0]
	v_pk_mul_f32 v[24:25], v[24:25], v[198:199] op_sel_hi:[1,0]
	v_pk_mul_f32 v[22:23], v[22:23], v[198:199] op_sel_hi:[1,0]
	v_pk_mul_f32 v[20:21], v[20:21], v[198:199] op_sel_hi:[1,0]
	v_pk_mul_f32 v[18:19], v[18:19], v[198:199] op_sel_hi:[1,0]
	v_pk_mul_f32 v[16:17], v[16:17], v[198:199] op_sel_hi:[1,0]
	v_pk_mul_f32 v[14:15], v[14:15], v[198:199] op_sel_hi:[1,0]
	v_pk_mul_f32 v[12:13], v[12:13], v[198:199] op_sel_hi:[1,0]
	v_pk_mul_f32 v[10:11], v[10:11], v[198:199] op_sel_hi:[1,0]
	v_pk_mul_f32 v[8:9], v[8:9], v[198:199] op_sel_hi:[1,0]
	v_pk_mul_f32 v[6:7], v[6:7], v[198:199] op_sel_hi:[1,0]
	v_pk_mul_f32 v[4:5], v[4:5], v[198:199] op_sel_hi:[1,0]
	v_pk_mul_f32 v[2:3], v[2:3], v[198:199] op_sel_hi:[1,0]
	v_pk_mul_f32 v[0:1], v[0:1], v[198:199] op_sel_hi:[1,0]
	v_mul_f32_e32 v157, v157, v198
.LBB0_1879:
	v_sub_f32_e32 v80, v80, v151
	v_sub_f32_e32 v81, v81, v151
	v_sub_f32_e32 v82, v82, v151
	v_sub_f32_e32 v83, v83, v151
	v_sub_f32_e32 v84, v84, v151
	v_sub_f32_e32 v85, v85, v151
	v_sub_f32_e32 v86, v86, v151
	v_sub_f32_e32 v87, v87, v151
	v_exp_f32_e32 v80, v80
	v_exp_f32_e32 v81, v81
	v_exp_f32_e32 v82, v82
	v_exp_f32_e32 v83, v83
	v_exp_f32_e32 v84, v84
	v_exp_f32_e32 v85, v85
	v_exp_f32_e32 v86, v86
	v_exp_f32_e32 v87, v87
	ds_read_b64_tr_b16 v[198:199], v183 offset:32768
	ds_read_b64_tr_b16 v[200:201], v185 offset:34816
	ds_read_b64_tr_b16 v[206:207], v182 offset:32768
	ds_read_b64_tr_b16 v[208:209], v184 offset:34816
	ds_read_b64_tr_b16 v[212:213], v185 offset:38912
	ds_read_b64_tr_b16 v[210:211], v183 offset:36864
	v_cvt_pk_bf16_f32 v202, v80, v81
	v_cvt_pk_bf16_f32 v203, v82, v83
	v_cvt_pk_bf16_f32 v204, v84, v85
	v_cvt_pk_bf16_f32 v205, v86, v87
	v_sub_f32_e32 v88, v88, v151
	v_sub_f32_e32 v89, v89, v151
	s_waitcnt lgkmcnt(0)
	v_mfma_f32_32x32x16_bf16 v[64:79], v[198:201], v[202:205], v[64:79]
	ds_read_b64_tr_b16 v[198:199], v186 offset:32768
	ds_read_b64_tr_b16 v[200:201], v188 offset:34816
	ds_read_b64_tr_b16 v[216:217], v184 offset:38912
	ds_read_b64_tr_b16 v[214:215], v182 offset:36864
	v_sub_f32_e32 v90, v90, v151
	v_sub_f32_e32 v91, v91, v151
	v_sub_f32_e32 v92, v92, v151
	v_sub_f32_e32 v93, v93, v151
	v_sub_f32_e32 v94, v94, v151
	v_sub_f32_e32 v95, v95, v151
	v_mfma_f32_32x32x16_bf16 v[32:47], v[206:209], v[202:205], v[32:47]
	ds_read_b64_tr_b16 v[206:207], v187 offset:32768
	ds_read_b64_tr_b16 v[208:209], v189 offset:34816
	ds_read_b64_tr_b16 v[220:221], v188 offset:38912
	ds_read_b64_tr_b16 v[218:219], v186 offset:36864
	v_exp_f32_e32 v88, v88
	v_exp_f32_e32 v89, v89
	v_exp_f32_e32 v90, v90
	v_exp_f32_e32 v91, v91
	v_exp_f32_e32 v92, v92
	v_exp_f32_e32 v93, v93
	s_waitcnt lgkmcnt(0)
	v_mfma_f32_32x32x16_bf16 v[16:31], v[198:201], v[202:205], v[16:31]
	ds_read_b64_tr_b16 v[226:227], v189 offset:38912
	ds_read_b64_tr_b16 v[224:225], v187 offset:36864
	v_exp_f32_e32 v94, v94
	v_exp_f32_e32 v95, v95
	v_cvt_pk_bf16_f32 v200, v88, v89
	v_cvt_pk_bf16_f32 v201, v90, v91
	v_bitop3_b32 v198, v159, 7, v222 bitop3:0x48
	v_bitop3_b32 v159, v165, 7, v222 bitop3:0x48
	v_mfma_f32_32x32x16_bf16 v[0:15], v[206:209], v[202:205], v[0:15]
	v_cvt_pk_bf16_f32 v202, v92, v93
	v_cvt_pk_bf16_f32 v203, v94, v95
	v_cndmask_b32_e64 v165, 0, 1, s[12:13]
	v_bitop3_b32 v163, v163, 7, v222 bitop3:0x48
	v_cmp_ne_u32_e64 s[2:3], 1, v165
	s_andn2_b64 vcc, exec, s[12:13]
	s_mov_b32 s28, 1
	v_mfma_f32_32x32x16_bf16 v[64:79], v[210:213], v[200:203], v[64:79]
	v_mfma_f32_32x32x16_bf16 v[32:47], v[214:217], v[200:203], v[32:47]
	v_mfma_f32_32x32x16_bf16 v[16:31], v[218:221], v[200:203], v[16:31]
	s_waitcnt lgkmcnt(0)
	v_mfma_f32_32x32x16_bf16 v[0:15], v[224:227], v[200:203], v[0:15]
	s_cbranch_vccnz .LBB0_1881
	s_waitcnt vmcnt(0) lgkmcnt(0)
	s_barrier

.LBB0_1890:
	s_setprio 0
	v_add_u32_e32 v153, s27, v170
	ds_read_b128 v[48:51], v153
	v_add_u32_e32 v155, s27, v171
	v_add_u32_e32 v159, s27, v172
	v_add_u32_e32 v163, s27, v173
	ds_read_b128 v[80:83], v155
	ds_read_b128 v[84:87], v159
	ds_read_b128 v[88:91], v163
	s_waitcnt lgkmcnt(0)
	v_mfma_f32_32x32x16_bf16 v[48:63], v[48:51], v[96:99], 0
	ds_read_b128 v[92:95], v153 offset:128
	v_mfma_f32_32x32x16_bf16 v[48:63], v[80:83], v[100:103], v[48:63]
	ds_read_b128 v[80:83], v155 offset:128
	v_mfma_f32_32x32x16_bf16 v[48:63], v[84:87], v[104:107], v[48:63]
	ds_read_b128 v[84:87], v159 offset:128
	v_mfma_f32_32x32x16_bf16 v[48:63], v[88:91], v[108:111], v[48:63]
	ds_read_b128 v[88:91], v163 offset:128
	s_waitcnt lgkmcnt(0)
	v_mfma_f32_32x32x16_bf16 v[48:63], v[92:95], v[112:115], v[48:63]
	ds_read_b128 v[92:95], v153 offset:256
	v_mfma_f32_32x32x16_bf16 v[48:63], v[80:83], v[116:119], v[48:63]
	ds_read_b128 v[80:83], v155 offset:256
	v_mfma_f32_32x32x16_bf16 v[48:63], v[84:87], v[120:123], v[48:63]
	ds_read_b128 v[84:87], v159 offset:256
	v_mfma_f32_32x32x16_bf16 v[48:63], v[88:91], v[124:127], v[48:63]
	ds_read_b128 v[198:201], v163 offset:256
	s_waitcnt lgkmcnt(0)
	v_mfma_f32_32x32x16_bf16 v[48:63], v[92:95], v[128:131], v[48:63]
	ds_read_b128 v[88:91], v153 offset:12288
	v_mfma_f32_32x32x16_bf16 v[48:63], v[80:83], v[132:135], v[48:63]
	ds_read_b128 v[202:205], v155 offset:12288
	v_mfma_f32_32x32x16_bf16 v[48:63], v[84:87], v[136:139], v[48:63]
	ds_read_b128 v[206:209], v159 offset:12288
	s_waitcnt lgkmcnt(0)
	v_mfma_f32_32x32x16_bf16 v[80:95], v[88:91], v[96:99], 0
	ds_read_b128 v[210:213], v163 offset:12288
	v_mfma_f32_32x32x16_bf16 v[80:95], v[202:205], v[100:103], v[80:95]
	ds_read_b128 v[214:217], v153 offset:12416
	v_mfma_f32_32x32x16_bf16 v[80:95], v[206:209], v[104:107], v[80:95]
	ds_read_b128 v[218:221], v155 offset:12416
	s_waitcnt lgkmcnt(0)
	v_mfma_f32_32x32x16_bf16 v[80:95], v[210:213], v[108:111], v[80:95]
	ds_read_b128 v[224:227], v159 offset:12416
	v_mfma_f32_32x32x16_bf16 v[80:95], v[214:217], v[112:115], v[80:95]
	ds_read_b128 v[228:231], v163 offset:12416
	v_mfma_f32_32x32x16_bf16 v[80:95], v[218:221], v[116:119], v[80:95]
	ds_read_b128 v[232:235], v153 offset:12544
	s_waitcnt lgkmcnt(0)
	v_mfma_f32_32x32x16_bf16 v[80:95], v[224:227], v[120:123], v[80:95]
	ds_read_b128 v[236:239], v155 offset:12544
	v_mfma_f32_32x32x16_bf16 v[80:95], v[228:231], v[124:127], v[80:95]
	ds_read_b128 v[240:243], v159 offset:12544
	v_mfma_f32_32x32x16_bf16 v[80:95], v[232:235], v[128:131], v[80:95]
	ds_read_b128 v[244:247], v163 offset:12544
	s_waitcnt lgkmcnt(0)
	v_mfma_f32_32x32x16_bf16 v[80:95], v[236:239], v[132:135], v[80:95]
	v_mfma_f32_32x32x16_bf16 v[80:95], v[240:243], v[136:139], v[80:95]
	v_mfma_f32_32x32x16_bf16 v[80:95], v[244:247], v[140:143], v[80:95]
	v_mfma_f32_32x32x16_bf16 v[48:63], v[198:201], v[140:143], v[48:63]
	s_andn2_b64 vcc, exec, s[10:11]
	s_cbranch_vccnz .LBB0_1885

.LBB0_1892:
	s_setprio 1
	s_nop 7
	v_max_f32_e32 v153, v49, v49
	v_max_f32_e32 v155, v48, v48
	v_max_f32_e32 v153, v155, v153
	v_max3_f32 v153, v153, v50, v51
	v_max3_f32 v153, v153, v52, v53
	v_max3_f32 v153, v153, v54, v55
	v_max3_f32 v153, v153, v56, v57
	v_max3_f32 v153, v153, v58, v59
	v_max3_f32 v153, v153, v60, v61
	v_max3_f32 v153, v153, v62, v63
	v_mov_b32_e32 v155, v153
	s_nop 1
	v_permlane32_swap_b32_e32 v153, v155
	v_max_f32_e32 v155, v155, v155
	v_max_f32_e32 v153, v153, v153
	v_max_f32_e32 v153, v153, v155
	v_sub_f32_e32 v153, v153, v151
	v_cmp_lt_f32_e32 vcc, s25, v153
	s_cbranch_vccz .LBB0_1894
	v_max_f32_e32 v153, v153, v153
	v_max_f32_e32 v153, 0, v153
	v_exp_f32_e64 v198, -v153
	v_add_f32_e32 v151, v151, v153
	v_pk_mul_f32 v[78:79], v[78:79], v[198:199] op_sel_hi:[1,0]
	v_pk_mul_f32 v[76:77], v[76:77], v[198:199] op_sel_hi:[1,0]
	v_pk_mul_f32 v[74:75], v[74:75], v[198:199] op_sel_hi:[1,0]
	v_pk_mul_f32 v[72:73], v[72:73], v[198:199] op_sel_hi:[1,0]
	v_pk_mul_f32 v[70:71], v[70:71], v[198:199] op_sel_hi:[1,0]
	v_pk_mul_f32 v[68:69], v[68:69], v[198:199] op_sel_hi:[1,0]
	v_pk_mul_f32 v[66:67], v[66:67], v[198:199] op_sel_hi:[1,0]
	v_pk_mul_f32 v[64:65], v[64:65], v[198:199] op_sel_hi:[1,0]
	v_pk_mul_f32 v[46:47], v[46:47], v[198:199] op_sel_hi:[1,0]
	v_pk_mul_f32 v[44:45], v[44:45], v[198:199] op_sel_hi:[1,0]
	v_pk_mul_f32 v[42:43], v[42:43], v[198:199] op_sel_hi:[1,0]
	v_pk_mul_f32 v[40:41], v[40:41], v[198:199] op_sel_hi:[1,0]
	v_pk_mul_f32 v[38:39], v[38:39], v[198:199] op_sel_hi:[1,0]
	v_pk_mul_f32 v[36:37], v[36:37], v[198:199] op_sel_hi:[1,0]
	v_pk_mul_f32 v[34:35], v[34:35], v[198:199] op_sel_hi:[1,0]
	v_pk_mul_f32 v[32:33], v[32:33], v[198:199] op_sel_hi:[1,0]
	v_pk_mul_f32 v[30:31], v[30:31], v[198:199] op_sel_hi:[1,0]
	v_pk_mul_f32 v[28:29], v[28:29], v[198:199] op_sel_hi:[1,0]
	v_pk_mul_f32 v[26:27], v[26:27], v[198:199] op_sel_hi:[1,0]
	v_pk_mul_f32 v[24:25], v[24:25], v[198:199] op_sel_hi:[1,0]
	v_pk_mul_f32 v[22:23], v[22:23], v[198:199] op_sel_hi:[1,0]
	v_pk_mul_f32 v[20:21], v[20:21], v[198:199] op_sel_hi:[1,0]
	v_pk_mul_f32 v[18:19], v[18:19], v[198:199] op_sel_hi:[1,0]
	v_pk_mul_f32 v[16:17], v[16:17], v[198:199] op_sel_hi:[1,0]
	v_pk_mul_f32 v[14:15], v[14:15], v[198:199] op_sel_hi:[1,0]
	v_pk_mul_f32 v[12:13], v[12:13], v[198:199] op_sel_hi:[1,0]
	v_pk_mul_f32 v[10:11], v[10:11], v[198:199] op_sel_hi:[1,0]
	v_pk_mul_f32 v[8:9], v[8:9], v[198:199] op_sel_hi:[1,0]
	v_pk_mul_f32 v[6:7], v[6:7], v[198:199] op_sel_hi:[1,0]
	v_pk_mul_f32 v[4:5], v[4:5], v[198:199] op_sel_hi:[1,0]
	v_pk_mul_f32 v[2:3], v[2:3], v[198:199] op_sel_hi:[1,0]
	v_pk_mul_f32 v[0:1], v[0:1], v[198:199] op_sel_hi:[1,0]
	v_mul_f32_e32 v157, v157, v198
.LBB0_1894:
	v_add_u32_e32 v167, s27, v174
	v_add_u32_e32 v198, s27, v175
	v_sub_f32_e32 v48, v48, v151
	v_sub_f32_e32 v49, v49, v151
	v_sub_f32_e32 v50, v50, v151
	v_sub_f32_e32 v51, v51, v151
	v_sub_f32_e32 v52, v52, v151
	v_sub_f32_e32 v53, v53, v151
	v_sub_f32_e32 v54, v54, v151
	v_sub_f32_e32 v55, v55, v151
	v_add_u32_e32 v155, v167, v177
	v_exp_f32_e32 v48, v48
	v_exp_f32_e32 v49, v49
	v_exp_f32_e32 v50, v50
	v_exp_f32_e32 v51, v51
	v_exp_f32_e32 v52, v52
	v_exp_f32_e32 v53, v53
	v_exp_f32_e32 v54, v54
	v_exp_f32_e32 v55, v55
	v_add_u32_e32 v163, v198, v177
	ds_read_b64_tr_b16 v[204:205], v155 offset:24576
	ds_read_b64_tr_b16 v[206:207], v163 offset:26624
	v_add_u32_e32 v153, v167, v178
	v_add_u32_e32 v159, v198, v178
	ds_read_b64_tr_b16 v[208:209], v153 offset:24576
	ds_read_b64_tr_b16 v[210:211], v159 offset:26624
	ds_read_b64_tr_b16 v[214:215], v163 offset:30720
	ds_read_b64_tr_b16 v[212:213], v155 offset:28672
	v_cvt_pk_bf16_f32 v200, v48, v49
	v_cvt_pk_bf16_f32 v201, v50, v51
	v_cvt_pk_bf16_f32 v202, v52, v53
	v_cvt_pk_bf16_f32 v203, v54, v55
	v_add_u32_e32 v165, v167, v179
	v_add_u32_e32 v167, v167, v180
	s_waitcnt lgkmcnt(0)
	v_mfma_f32_32x32x16_bf16 v[64:79], v[204:207], v[200:203], v[64:79]
	v_add_u32_e32 v169, v198, v179
	ds_read_b64_tr_b16 v[204:205], v165 offset:24576
	ds_read_b64_tr_b16 v[206:207], v169 offset:26624
	ds_read_b64_tr_b16 v[218:219], v159 offset:30720
	ds_read_b64_tr_b16 v[216:217], v153 offset:28672
	v_add_u32_e32 v198, v198, v180
	v_add_f32_e32 v199, 0, v48
	v_sub_f32_e32 v56, v56, v151
	v_sub_f32_e32 v57, v57, v151
	v_sub_f32_e32 v58, v58, v151
	v_mfma_f32_32x32x16_bf16 v[32:47], v[208:211], v[200:203], v[32:47]
	ds_read_b64_tr_b16 v[208:209], v167 offset:24576
	ds_read_b64_tr_b16 v[210:211], v198 offset:26624
	ds_read_b64_tr_b16 v[226:227], v169 offset:30720
	ds_read_b64_tr_b16 v[224:225], v165 offset:28672
	v_sub_f32_e32 v59, v59, v151
	v_sub_f32_e32 v60, v60, v151
	v_sub_f32_e32 v61, v61, v151
	v_sub_f32_e32 v62, v62, v151
	v_sub_f32_e32 v63, v63, v151
	v_add_f32_e32 v199, v49, v199
	s_waitcnt lgkmcnt(0)
	v_mfma_f32_32x32x16_bf16 v[16:31], v[204:207], v[200:203], v[16:31]
	v_exp_f32_e32 v56, v56
	v_exp_f32_e32 v57, v57
	v_exp_f32_e32 v58, v58
	v_exp_f32_e32 v59, v59
	v_exp_f32_e32 v60, v60
	v_exp_f32_e32 v61, v61
	ds_read_b64_tr_b16 v[206:207], v198 offset:30720
	ds_read_b64_tr_b16 v[204:205], v167 offset:28672
	v_mfma_f32_32x32x16_bf16 v[0:15], v[208:211], v[200:203], v[0:15]
	v_exp_f32_e32 v62, v62
	v_exp_f32_e32 v63, v63
	v_add_f32_e32 v199, v50, v199
	v_add_f32_e32 v199, v51, v199
	v_add_f32_e32 v199, v52, v199
	v_add_f32_e32 v199, v53, v199
	v_cvt_pk_bf16_f32 v200, v56, v57
	v_cvt_pk_bf16_f32 v201, v58, v59
	v_cvt_pk_bf16_f32 v202, v60, v61
	v_cvt_pk_bf16_f32 v203, v62, v63
	v_add_f32_e32 v199, v54, v199
	v_add_f32_e32 v199, v55, v199
	v_mfma_f32_32x32x16_bf16 v[64:79], v[212:215], v[200:203], v[64:79]
	v_add_f32_e32 v199, v56, v199
	v_add_f32_e32 v199, v57, v199
	v_add_f32_e32 v199, v58, v199
	v_add_f32_e32 v199, v59, v199
	v_add_f32_e32 v199, v60, v199
	v_add_f32_e32 v199, v61, v199
	v_add_f32_e32 v199, v62, v199
	v_mfma_f32_32x32x16_bf16 v[32:47], v[216:219], v[200:203], v[32:47]
	v_add_f32_e32 v199, v63, v199
	v_add_f32_e32 v157, v157, v199
	v_mfma_f32_32x32x16_bf16 v[16:31], v[224:227], v[200:203], v[16:31]
	s_waitcnt lgkmcnt(0)
	v_mfma_f32_32x32x16_bf16 v[0:15], v[204:207], v[200:203], v[0:15]
	v_max_f32_e32 v200, v81, v81
	v_max_f32_e32 v201, v80, v80
	v_max_f32_e32 v200, v201, v200
	v_max3_f32 v200, v200, v82, v83
	v_max3_f32 v200, v200, v84, v85
	v_max3_f32 v200, v200, v86, v87
	v_max3_f32 v200, v200, v88, v89
	v_max3_f32 v200, v200, v90, v91
	v_max3_f32 v200, v200, v92, v93
	v_max3_f32 v200, v200, v94, v95
	v_mov_b32_e32 v199, v200
	s_nop 1
	v_permlane32_swap_b32_e32 v200, v199
	v_max_f32_e32 v199, v199, v199
	v_max_f32_e32 v200, v200, v200
	v_max_f32_e32 v199, v200, v199
	v_sub_f32_e32 v199, v199, v151
	v_cmp_lt_f32_e32 vcc, s25, v199
	s_cbranch_vccz .LBB0_1896
	v_max_f32_e32 v199, v199, v199
	v_max_f32_e32 v199, 0, v199
	v_exp_f32_e64 v200, -v199
	v_add_f32_e32 v151, v151, v199
	v_pk_mul_f32 v[78:79], v[78:79], v[200:201] op_sel_hi:[1,0]
	v_pk_mul_f32 v[76:77], v[76:77], v[200:201] op_sel_hi:[1,0]
	v_pk_mul_f32 v[74:75], v[74:75], v[200:201] op_sel_hi:[1,0]
	v_pk_mul_f32 v[72:73], v[72:73], v[200:201] op_sel_hi:[1,0]
	v_pk_mul_f32 v[70:71], v[70:71], v[200:201] op_sel_hi:[1,0]
	v_pk_mul_f32 v[68:69], v[68:69], v[200:201] op_sel_hi:[1,0]
	v_pk_mul_f32 v[66:67], v[66:67], v[200:201] op_sel_hi:[1,0]
	v_pk_mul_f32 v[64:65], v[64:65], v[200:201] op_sel_hi:[1,0]
	v_pk_mul_f32 v[46:47], v[46:47], v[200:201] op_sel_hi:[1,0]
	v_pk_mul_f32 v[44:45], v[44:45], v[200:201] op_sel_hi:[1,0]
	v_pk_mul_f32 v[42:43], v[42:43], v[200:201] op_sel_hi:[1,0]
	v_pk_mul_f32 v[40:41], v[40:41], v[200:201] op_sel_hi:[1,0]
	v_pk_mul_f32 v[38:39], v[38:39], v[200:201] op_sel_hi:[1,0]
	v_pk_mul_f32 v[36:37], v[36:37], v[200:201] op_sel_hi:[1,0]
	v_pk_mul_f32 v[34:35], v[34:35], v[200:201] op_sel_hi:[1,0]
	v_pk_mul_f32 v[32:33], v[32:33], v[200:201] op_sel_hi:[1,0]
	v_pk_mul_f32 v[30:31], v[30:31], v[200:201] op_sel_hi:[1,0]
	v_pk_mul_f32 v[28:29], v[28:29], v[200:201] op_sel_hi:[1,0]
	v_pk_mul_f32 v[26:27], v[26:27], v[200:201] op_sel_hi:[1,0]
	v_pk_mul_f32 v[24:25], v[24:25], v[200:201] op_sel_hi:[1,0]
	v_pk_mul_f32 v[22:23], v[22:23], v[200:201] op_sel_hi:[1,0]
	v_pk_mul_f32 v[20:21], v[20:21], v[200:201] op_sel_hi:[1,0]
	v_pk_mul_f32 v[18:19], v[18:19], v[200:201] op_sel_hi:[1,0]
	v_pk_mul_f32 v[16:17], v[16:17], v[200:201] op_sel_hi:[1,0]
	v_pk_mul_f32 v[14:15], v[14:15], v[200:201] op_sel_hi:[1,0]
	v_pk_mul_f32 v[12:13], v[12:13], v[200:201] op_sel_hi:[1,0]
	v_pk_mul_f32 v[10:11], v[10:11], v[200:201] op_sel_hi:[1,0]
	v_pk_mul_f32 v[8:9], v[8:9], v[200:201] op_sel_hi:[1,0]
	v_pk_mul_f32 v[6:7], v[6:7], v[200:201] op_sel_hi:[1,0]
	v_pk_mul_f32 v[4:5], v[4:5], v[200:201] op_sel_hi:[1,0]
	v_pk_mul_f32 v[2:3], v[2:3], v[200:201] op_sel_hi:[1,0]
	v_pk_mul_f32 v[0:1], v[0:1], v[200:201] op_sel_hi:[1,0]
	v_mul_f32_e32 v157, v157, v200
.LBB0_1896:
	v_sub_f32_e32 v80, v80, v151
	v_sub_f32_e32 v81, v81, v151
	v_sub_f32_e32 v82, v82, v151
	v_sub_f32_e32 v83, v83, v151
	v_sub_f32_e32 v84, v84, v151
	v_sub_f32_e32 v85, v85, v151
	v_sub_f32_e32 v86, v86, v151
	v_sub_f32_e32 v87, v87, v151
	v_exp_f32_e32 v80, v80
	v_exp_f32_e32 v81, v81
	v_exp_f32_e32 v82, v82
	v_exp_f32_e32 v83, v83
	v_exp_f32_e32 v84, v84
	v_exp_f32_e32 v85, v85
	v_exp_f32_e32 v86, v86
	v_exp_f32_e32 v87, v87
	ds_read_b64_tr_b16 v[200:201], v155 offset:32768
	ds_read_b64_tr_b16 v[202:203], v163 offset:34816
	ds_read_b64_tr_b16 v[208:209], v153 offset:32768
	ds_read_b64_tr_b16 v[210:211], v159 offset:34816
	ds_read_b64_tr_b16 v[214:215], v163 offset:38912
	ds_read_b64_tr_b16 v[212:213], v155 offset:36864
	v_cvt_pk_bf16_f32 v204, v80, v81
	v_cvt_pk_bf16_f32 v205, v82, v83
	v_cvt_pk_bf16_f32 v206, v84, v85
	v_cvt_pk_bf16_f32 v207, v86, v87
	v_sub_f32_e32 v88, v88, v151
	v_sub_f32_e32 v89, v89, v151
	s_waitcnt lgkmcnt(0)
	v_mfma_f32_32x32x16_bf16 v[64:79], v[200:203], v[204:207], v[64:79]
	ds_read_b64_tr_b16 v[200:201], v165 offset:32768
	ds_read_b64_tr_b16 v[202:203], v169 offset:34816
	ds_read_b64_tr_b16 v[218:219], v159 offset:38912
	ds_read_b64_tr_b16 v[216:217], v153 offset:36864
	v_add_f32_e32 v153, 0, v80
	v_add_f32_e32 v153, v81, v153
	v_add_f32_e32 v153, v82, v153
	v_sub_f32_e32 v90, v90, v151
	v_sub_f32_e32 v91, v91, v151
	v_sub_f32_e32 v92, v92, v151
	v_mfma_f32_32x32x16_bf16 v[32:47], v[208:211], v[204:207], v[32:47]
	ds_read_b64_tr_b16 v[208:209], v167 offset:32768
	ds_read_b64_tr_b16 v[210:211], v198 offset:34816
	ds_read_b64_tr_b16 v[226:227], v169 offset:38912
	ds_read_b64_tr_b16 v[224:225], v165 offset:36864
	v_sub_f32_e32 v93, v93, v151
	v_sub_f32_e32 v94, v94, v151
	v_sub_f32_e32 v95, v95, v151
	v_add_f32_e32 v153, v83, v153
	v_exp_f32_e32 v88, v88
	v_exp_f32_e32 v89, v89
	s_waitcnt lgkmcnt(0)
	v_mfma_f32_32x32x16_bf16 v[16:31], v[200:203], v[204:207], v[16:31]
	v_exp_f32_e32 v90, v90
	v_exp_f32_e32 v91, v91
	v_exp_f32_e32 v92, v92
	v_exp_f32_e32 v93, v93
	ds_read_b64_tr_b16 v[200:201], v198 offset:38912
	ds_read_b64_tr_b16 v[198:199], v167 offset:36864
	v_exp_f32_e32 v94, v94
	v_exp_f32_e32 v95, v95
	v_mfma_f32_32x32x16_bf16 v[0:15], v[208:211], v[204:207], v[0:15]
	v_add_f32_e32 v153, v84, v153
	v_add_f32_e32 v153, v85, v153
	v_add_f32_e32 v153, v86, v153
	v_add_f32_e32 v153, v87, v153
	v_cvt_pk_bf16_f32 v202, v88, v89
	v_cvt_pk_bf16_f32 v203, v90, v91
	v_cvt_pk_bf16_f32 v204, v92, v93
	v_cvt_pk_bf16_f32 v205, v94, v95
	v_add_f32_e32 v153, v88, v153
	v_add_f32_e32 v153, v89, v153
	v_mfma_f32_32x32x16_bf16 v[64:79], v[212:215], v[202:205], v[64:79]
	v_add_f32_e32 v153, v90, v153
	v_add_f32_e32 v153, v91, v153
	v_add_f32_e32 v153, v92, v153
	v_add_f32_e32 v153, v93, v153
	v_add_f32_e32 v153, v94, v153
	v_add_f32_e32 v153, v95, v153
	v_add_f32_e32 v157, v157, v153
	v_mfma_f32_32x32x16_bf16 v[32:47], v[216:219], v[202:205], v[32:47]
	v_mfma_f32_32x32x16_bf16 v[16:31], v[224:227], v[202:205], v[16:31]
	s_waitcnt lgkmcnt(0)
	v_mfma_f32_32x32x16_bf16 v[0:15], v[198:201], v[202:205], v[0:15]
	s_and_b64 vcc, exec, s[2:3]
	s_cbranch_vccz .LBB0_1887
	s_branch .LBB0_1888
.LBB0_1897:
	s_setprio 0
	v_mov_b32_e32 v48, v157
	s_nop 1
	v_permlane32_swap_b32_e32 v157, v48
	v_add_f32_e32 v48, v157, v48
	v_div_scale_f32 v49, s[2:3], v48, v48, 1.0
	v_rcp_f32_e32 v50, v49
	s_mulk_i32 s21, 0x2200
	s_add_i32 s7, s21, 0
	s_waitcnt vmcnt(0) lgkmcnt(0)
	s_barrier
	v_fma_f32 v51, -v49, v50, 1.0
	v_fmac_f32_e32 v50, v51, v50
	v_div_scale_f32 v51, vcc, 1.0, v48, 1.0
	v_mul_f32_e32 v52, v51, v50
	v_fma_f32 v53, -v49, v52, v51
	v_fmac_f32_e32 v52, v53, v50
	v_fma_f32 v49, -v49, v52, v51
	v_div_fmas_f32 v49, v49, v50, v52
	v_div_fixup_f32 v48, v49, v48, 1.0
	v_add3_u32 v49, s7, v195, v181
	v_pk_mul_f32 v[50:51], v[64:65], v[48:49] op_sel_hi:[1,0]
	v_pk_mul_f32 v[52:53], v[66:67], v[48:49] op_sel_hi:[1,0]
	v_cvt_pk_bf16_f32 v50, v50, v51
	v_cvt_pk_bf16_f32 v51, v52, v53
	v_pk_mul_f32 v[52:53], v[68:69], v[48:49] op_sel_hi:[1,0]
	v_pk_mul_f32 v[54:55], v[70:71], v[48:49] op_sel_hi:[1,0]
	v_add_u32_e32 v49, 0xa000, v49
	v_pk_mul_f32 v[32:33], v[32:33], v[48:49] op_sel_hi:[1,0]
	v_pk_mul_f32 v[34:35], v[34:35], v[48:49] op_sel_hi:[1,0]
	v_pk_mul_f32 v[16:17], v[16:17], v[48:49] op_sel_hi:[1,0]
	v_pk_mul_f32 v[18:19], v[18:19], v[48:49] op_sel_hi:[1,0]
	v_pk_mul_f32 v[0:1], v[0:1], v[48:49] op_sel_hi:[1,0]
	v_pk_mul_f32 v[2:3], v[2:3], v[48:49] op_sel_hi:[1,0]
	v_cvt_pk_bf16_f32 v32, v32, v33
	v_cvt_pk_bf16_f32 v33, v34, v35
	v_pk_mul_f32 v[34:35], v[36:37], v[48:49] op_sel_hi:[1,0]
	v_pk_mul_f32 v[36:37], v[38:39], v[48:49] op_sel_hi:[1,0]
	v_cvt_pk_bf16_f32 v16, v16, v17
	v_cvt_pk_bf16_f32 v17, v18, v19
	v_pk_mul_f32 v[18:19], v[20:21], v[48:49] op_sel_hi:[1,0]
	v_pk_mul_f32 v[20:21], v[22:23], v[48:49] op_sel_hi:[1,0]
	v_cvt_pk_bf16_f32 v0, v0, v1
	v_cvt_pk_bf16_f32 v1, v2, v3
	v_pk_mul_f32 v[2:3], v[4:5], v[48:49] op_sel_hi:[1,0]
	v_pk_mul_f32 v[4:5], v[6:7], v[48:49] op_sel_hi:[1,0]
	v_cvt_pk_bf16_f32 v52, v52, v53
	v_cvt_pk_bf16_f32 v53, v54, v55
	v_cvt_pk_bf16_f32 v34, v34, v35
	v_cvt_pk_bf16_f32 v35, v36, v37
	v_cvt_pk_bf16_f32 v18, v18, v19
	v_cvt_pk_bf16_f32 v19, v20, v21
	v_cvt_pk_bf16_f32 v2, v2, v3
	v_cvt_pk_bf16_f32 v3, v4, v5
	ds_write2_b64 v49, v[50:51], v[52:53] offset1:2
	v_pk_mul_f32 v[50:51], v[72:73], v[48:49] op_sel_hi:[1,0]
	v_pk_mul_f32 v[52:53], v[74:75], v[48:49] op_sel_hi:[1,0]
	ds_write2_b64 v49, v[32:33], v[34:35] offset0:8 offset1:10
	v_pk_mul_f32 v[32:33], v[40:41], v[48:49] op_sel_hi:[1,0]
	v_pk_mul_f32 v[34:35], v[42:43], v[48:49] op_sel_hi:[1,0]
	ds_write2_b64 v49, v[16:17], v[18:19] offset0:16 offset1:18
	v_pk_mul_f32 v[16:17], v[24:25], v[48:49] op_sel_hi:[1,0]
	v_pk_mul_f32 v[18:19], v[26:27], v[48:49] op_sel_hi:[1,0]
	ds_write2_b64 v49, v[0:1], v[2:3] offset0:24 offset1:26
	v_pk_mul_f32 v[0:1], v[8:9], v[48:49] op_sel_hi:[1,0]
	v_pk_mul_f32 v[2:3], v[10:11], v[48:49] op_sel_hi:[1,0]
	v_cvt_pk_bf16_f32 v50, v50, v51
	v_cvt_pk_bf16_f32 v51, v52, v53
	v_pk_mul_f32 v[52:53], v[76:77], v[48:49] op_sel_hi:[1,0]
	v_pk_mul_f32 v[54:55], v[78:79], v[48:49] op_sel_hi:[1,0]
	v_cvt_pk_bf16_f32 v32, v32, v33
	v_cvt_pk_bf16_f32 v33, v34, v35
	v_pk_mul_f32 v[34:35], v[44:45], v[48:49] op_sel_hi:[1,0]
	v_pk_mul_f32 v[36:37], v[46:47], v[48:49] op_sel_hi:[1,0]
	v_cvt_pk_bf16_f32 v16, v16, v17
	v_cvt_pk_bf16_f32 v17, v18, v19
	v_pk_mul_f32 v[18:19], v[28:29], v[48:49] op_sel_hi:[1,0]
	v_pk_mul_f32 v[20:21], v[30:31], v[48:49] op_sel_hi:[1,0]
	v_cvt_pk_bf16_f32 v0, v0, v1
	v_cvt_pk_bf16_f32 v1, v2, v3
	v_pk_mul_f32 v[2:3], v[12:13], v[48:49] op_sel_hi:[1,0]
	v_pk_mul_f32 v[4:5], v[14:15], v[48:49] op_sel_hi:[1,0]
	v_cvt_pk_bf16_f32 v52, v52, v53
	v_cvt_pk_bf16_f32 v53, v54, v55
	v_cvt_pk_bf16_f32 v34, v34, v35
	v_cvt_pk_bf16_f32 v35, v36, v37
	v_cvt_pk_bf16_f32 v18, v18, v19
	v_cvt_pk_bf16_f32 v19, v20, v21
	v_cvt_pk_bf16_f32 v2, v2, v3
	v_cvt_pk_bf16_f32 v3, v4, v5
	s_mulk_i32 s20, 0x1800
	s_mul_hi_u32 s2, s19, 0x1800
	ds_write2_b64 v49, v[50:51], v[52:53] offset0:4 offset1:6
	ds_write2_b64 v49, v[32:33], v[34:35] offset0:12 offset1:14
	ds_write2_b64 v49, v[16:17], v[18:19] offset0:20 offset1:22
	ds_write2_b64 v49, v[0:1], v[2:3] offset0:28 offset1:30
	s_add_i32 s2, s2, s20
	s_mulk_i32 s19, 0x1800
	s_waitcnt lgkmcnt(0)
	s_add_u32 s3, s4, s19
	v_add3_u32 v14, s7, v144, v196
	s_addc_u32 s10, s5, s2
	ds_read_b128 v[0:3], v14 offset:40960
	s_add_u32 s2, s3, s6
	s_addc_u32 s3, s10, 0
	v_mov_b32_e32 v159, 0
	ds_read_b128 v[4:7], v14 offset:42048
	v_lshl_add_u64 v[8:9], s[2:3], 0, v[158:159]
	v_mov_b32_e32 v147, v159
	v_lshl_add_u64 v[10:11], v[8:9], 0, v[146:147]
	s_movk_i32 s2, 0x6000
	s_waitcnt lgkmcnt(0)
	global_store_dwordx4 v[10:11], v[0:3], off
	v_mov_b32_e32 v149, v159
	v_mov_b32_e32 v153, v159
	v_add_co_u32_e32 v0, vcc, s2, v10
	s_mov_b32 s2, 0xc000
	s_nop 0
	v_addc_co_u32_e32 v1, vcc, 0, v11, vcc
	global_store_dwordx4 v[0:1], v[4:7], off
	ds_read_b128 v[0:3], v14 offset:43136
	ds_read_b128 v[4:7], v14 offset:44224
	v_add_co_u32_e32 v12, vcc, s2, v10
	s_mov_b32 s2, 0x12000
	s_nop 0
	v_addc_co_u32_e32 v13, vcc, 0, v11, vcc
	v_add_co_u32_e32 v10, vcc, s2, v10
	s_waitcnt lgkmcnt(0)
	global_store_dwordx4 v[12:13], v[0:3], off
	v_addc_co_u32_e32 v11, vcc, 0, v11, vcc
	ds_read_b128 v[0:3], v14 offset:45312
	global_store_dwordx4 v[10:11], v[4:7], off
	ds_read_b128 v[4:7], v14 offset:46400
	v_lshl_add_u64 v[10:11], v[8:9], 0, v[148:149]
	v_mov_b32_e32 v151, v159
	s_waitcnt lgkmcnt(0)
	global_store_dwordx4 v[10:11], v[0:3], off
	v_lshl_add_u64 v[10:11], v[8:9], 0, v[152:153]
	ds_read_b128 v[0:3], v14 offset:47488
	global_store_dwordx4 v[10:11], v[4:7], off
	ds_read_b128 v[4:7], v14 offset:48576
	v_lshl_add_u64 v[10:11], v[8:9], 0, v[150:151]
	v_mov_b32_e32 v155, v159
	v_readfirstlane_b32 s12, v222
	s_waitcnt lgkmcnt(0)
	global_store_dwordx4 v[10:11], v[0:3], off
	s_and_b32 s2, s12, 0xffffffc0
	s_nop 0
	v_lshl_add_u64 v[0:1], v[8:9], 0, v[154:155]
	global_store_dwordx4 v[0:1], v[4:7], off
	v_or_b32_e32 v0, s2, v197
	s_mov_b32 s2, 0x2aaaaaab
	v_mul_hi_i32 v1, v0, s2
	v_lshrrev_b32_e32 v2, 31, v1
	v_ashrrev_i32_e32 v1, 2, v1
	v_add_u32_e32 v2, v1, v2
	s_movk_i32 s2, 0xffe8
	v_lshrrev_b32_e32 v159, 1, v2
	v_mad_u64_u32 v[160:161], s[2:3], v2, s2, v[0:1]
	v_xor_b32_e32 v1, v159, v222
	v_bfi_b32 v1, -8, v160, v1
	v_cmp_lt_i32_e32 vcc, 15, v1
	v_add_u32_e32 v2, s8, v2
	s_and_saveexec_b64 s[2:3], vcc
	s_xor_b64 s[2:3], exec, s[2:3]
	v_mov_b32_e32 v3, 0xbfff80
	v_lshl_add_u32 v153, v2, 6, v3
	s_or_saveexec_b64 s[2:3], s[2:3]
	v_mov_b32_e32 v145, 0x1000
	s_xor_b64 exec, exec, s[2:3]
	v_lshl_or_b32 v2, v2, 11, s17
	v_add_u32_e32 v153, 0x8000000, v2
	v_mov_b32_e32 v145, 0x20000
	s_or_b64 exec, exec, s[2:3]
	v_add_u32_e32 v2, 0x200, v0
	s_mov_b32 s2, 0x2aaaaaab
	v_mul_hi_i32 v3, v2, s2
	v_lshrrev_b32_e32 v4, 31, v3
	v_ashrrev_i32_e32 v3, 2, v3
	v_add_u32_e32 v4, v3, v4
	s_movk_i32 s2, 0xffe8
	v_mad_u64_u32 v[162:163], s[2:3], v4, s2, v[2:3]
	v_lshrrev_b32_e32 v163, 1, v4
	v_xor_b32_e32 v3, v163, v222
	v_bfi_b32 v3, -8, v162, v3
	v_cmp_lt_i32_e32 vcc, 15, v3
	v_add_u32_e32 v4, s8, v4
	s_and_saveexec_b64 s[2:3], vcc
	s_xor_b64 s[2:3], exec, s[2:3]
	v_mov_b32_e32 v5, 0xbfff80
	v_lshl_add_u32 v155, v4, 6, v5
	s_or_saveexec_b64 s[2:3], s[2:3]
	v_mov_b32_e32 v147, 0x1000
	s_xor_b64 exec, exec, s[2:3]
	v_lshl_or_b32 v4, v4, 11, s17
	v_add_u32_e32 v155, 0x8000000, v4
	v_mov_b32_e32 v147, 0x20000
	s_or_b64 exec, exec, s[2:3]
	v_add_u32_e32 v4, 0x400, v0
	s_mov_b32 s2, 0x2aaaaaab
	v_mul_hi_i32 v5, v4, s2
	v_lshrrev_b32_e32 v6, 31, v5
	v_ashrrev_i32_e32 v5, 2, v5
	v_add_u32_e32 v5, v5, v6
	s_movk_i32 s2, 0xffe8
	v_mad_u64_u32 v[164:165], s[2:3], v5, s2, v[4:5]
	v_lshrrev_b32_e32 v165, 1, v5
	v_xor_b32_e32 v4, v165, v222
	v_bfi_b32 v4, -8, v164, v4
	v_cmp_lt_i32_e32 vcc, 15, v4
	v_add_u32_e32 v5, s8, v5
	s_and_saveexec_b64 s[2:3], vcc
	s_xor_b64 s[2:3], exec, s[2:3]
	v_mov_b32_e32 v6, 0xbfff80
	v_lshl_add_u32 v161, v5, 6, v6
	s_or_saveexec_b64 s[2:3], s[2:3]
	v_mov_b32_e32 v149, 0x1000
	s_xor_b64 exec, exec, s[2:3]
	v_lshl_or_b32 v5, v5, 11, s17
	v_add_u32_e32 v161, 0x8000000, v5
	v_mov_b32_e32 v149, 0x20000
	s_or_b64 exec, exec, s[2:3]
	s_lshr_b32 s21, s12, 6
	s_or_b32 s22, s16, 0x1000
	s_lshl_b32 s23, s21, 5
	s_or_b32 s2, s8, s22
	s_add_u32 s19, s2, s23
	v_or_b32_e32 v5, s19, v194
	s_movk_i32 s2, 0x1800
	v_mov_b64_e32 v[6:7], s[4:5]
	s_addc_u32 s20, s9, 0
	v_mad_u64_u32 v[6:7], s[2:3], v5, s2, v[6:7]
	v_mov_b32_e32 v5, 0x1800
	s_mov_b32 s7, 0
	v_mad_i32_i24 v7, s20, v5, v7
	v_lshl_add_u32 v8, v1, 3, v153
	v_ashrrev_i32_e32 v1, 31, v0
	v_lshl_add_u64 v[6:7], v[6:7], 0, s[6:7]
	v_mov_b32_e32 v157, 0
	v_lshrrev_b32_e32 v10, 28, v1
	v_lshl_add_u64 v[6:7], v[6:7], 0, v[156:157]
	v_lshl_add_u32 v4, v4, 3, v161
	v_mov_b32_e32 v5, v157
	v_add_u32_e32 v16, v0, v10
	global_load_dwordx4 v[96:99], v[6:7], off
	global_load_dwordx4 v[100:103], v[6:7], off offset:32
	global_load_dwordx4 v[104:107], v[6:7], off offset:64
	global_load_dwordx4 v[108:111], v[6:7], off offset:96
	global_load_dwordx4 v[112:115], v[6:7], off offset:128
	global_load_dwordx4 v[116:119], v[6:7], off offset:160
	global_load_dwordx4 v[120:123], v[6:7], off offset:192
	global_load_dwordx4 v[124:127], v[6:7], off offset:224
	global_load_dwordx4 v[128:131], v[6:7], off offset:256
	global_load_dwordx4 v[132:135], v[6:7], off offset:288
	global_load_dwordx4 v[136:139], v[6:7], off offset:320
	global_load_dwordx4 v[140:143], v[6:7], off offset:352
	v_lshl_add_u32 v6, v3, 3, v155
	v_ashrrev_i32_e32 v3, 31, v2
	v_lshl_add_u64 v[14:15], v[4:5], 1, s[84:85]
	v_ashrrev_i32_e32 v167, 4, v16
	v_and_b32_e32 v5, 0x1ffffff0, v16
	v_lshrrev_b32_e32 v11, 28, v3
	v_mov_b32_e32 v9, v157
	s_lshl_b32 s2, s21, 10
	v_sub_u32_e32 v0, v0, v5
	v_lshlrev_b32_e32 v5, 2, v167
	v_mov_b32_e32 v7, v157
	v_add_u32_e32 v17, v2, v11
	v_lshl_add_u64 v[10:11], v[8:9], 1, s[84:85]
	v_bfe_u32 v9, v167, 2, 2
	s_add_i32 s7, s2, 0
	v_and_b32_e32 v5, 12, v5
	v_lshl_add_u64 v[12:13], v[6:7], 1, s[84:85]
	v_ashrrev_i32_e32 v166, 4, v17
	v_and_b32_e32 v7, 0x1ffffff0, v17
	v_bitop3_b32 v0, v5, v0, v9 bitop3:0x36
	s_mov_b32 m0, s7
	v_add_lshl_u32 v16, v167, s8, 11
	v_sub_u32_e32 v2, v2, v7
	v_lshlrev_b32_e32 v7, 2, v166
	global_load_lds_dwordx4 v[10:11], off
	s_add_i32 m0, s7, 0x2000
	v_lshlrev_b32_e32 v168, 3, v0
	v_mov_b32_e32 v1, v157
	v_bfe_u32 v17, v166, 2, 2
	v_and_b32_e32 v7, 12, v7
	global_load_lds_dwordx4 v[12:13], off
	s_add_i32 m0, s7, 0x4000
	v_add3_u32 v0, s18, v16, v168
	v_bitop3_b32 v2, v7, v2, v17 bitop3:0x36
	global_load_lds_dwordx4 v[14:15], off
	s_add_i32 m0, s7, 0x6000
	v_lshl_add_u64 v[10:11], v[0:1], 1, s[84:85]
	v_add_lshl_u32 v18, v166, s8, 11
	v_lshlrev_b32_e32 v169, 3, v2
	global_load_lds_dwordx4 v[10:11], off
	s_add_i32 m0, s7, 0x8000
	v_mov_b32_e32 v3, v157
	v_add3_u32 v2, s18, v18, v169
	s_cmpk_gt_u32 s12, 0xff
	v_lshl_add_u64 v[12:13], v[2:3], 1, s[84:85]
	s_cselect_b64 s[10:11], -1, 0
	s_cmpk_lt_u32 s12, 0x100
	v_add_u32_e32 v8, v8, v145
	v_mov_b32_e32 v9, v157
	global_load_lds_dwordx4 v[12:13], off
	s_cselect_b64 s[12:13], -1, 0
	s_add_i32 m0, s7, 0xa000
	v_lshl_add_u64 v[8:9], v[8:9], 1, s[84:85]
	v_add_u32_e32 v6, v6, v147
	v_mov_b32_e32 v7, v157
	s_waitcnt vmcnt(0) lgkmcnt(0)
	s_barrier
	s_waitcnt vmcnt(0)
	global_load_lds_dwordx4 v[8:9], off
	v_lshl_add_u64 v[6:7], v[6:7], 1, s[84:85]
	s_add_i32 m0, s7, 0xc000
	v_add_u32_e32 v4, v4, v149
	v_mov_b32_e32 v5, v157
	global_load_lds_dwordx4 v[6:7], off
	v_lshl_add_u64 v[4:5], v[4:5], 1, s[84:85]
	s_add_i32 m0, s7, 0xe000
	v_add_u32_e32 v0, 0x20000, v0
	v_mov_b32_e32 v1, v157
	global_load_lds_dwordx4 v[4:5], off
	s_add_i32 m0, s7, 0x10000
	v_lshl_add_u64 v[0:1], v[0:1], 1, s[84:85]
	global_load_lds_dwordx4 v[0:1], off
	v_add_u32_e32 v0, 0x20000, v2
	v_mov_b32_e32 v1, v157
	v_lshl_add_u64 v[0:1], v[0:1], 1, s[84:85]
	s_add_i32 m0, s7, 0x12000
	s_and_b64 vcc, exec, s[12:13]
	global_load_lds_dwordx4 v[0:1], off
	ds_read_b128 v[0:3], v190
	ds_read_b128 v[4:7], v191
	ds_read_b128 v[8:11], v192
	ds_read_b128 v[12:15], v193
	s_waitcnt lgkmcnt(0)
	v_mfma_f32_32x32x16_bf16 v[48:63], v[0:3], v[96:99], 0
	ds_read_b128 v[0:3], v190 offset:128
	v_mfma_f32_32x32x16_bf16 v[48:63], v[4:7], v[100:103], v[48:63]
	ds_read_b128 v[4:7], v191 offset:128
	v_mfma_f32_32x32x16_bf16 v[48:63], v[8:11], v[104:107], v[48:63]
	ds_read_b128 v[8:11], v192 offset:128
	v_mfma_f32_32x32x16_bf16 v[48:63], v[12:15], v[108:111], v[48:63]
	ds_read_b128 v[12:15], v193 offset:128
	s_waitcnt lgkmcnt(0)
	v_mfma_f32_32x32x16_bf16 v[48:63], v[0:3], v[112:115], v[48:63]
	ds_read_b128 v[0:3], v190 offset:256
	v_mfma_f32_32x32x16_bf16 v[48:63], v[4:7], v[116:119], v[48:63]
	ds_read_b128 v[4:7], v191 offset:256
	v_mfma_f32_32x32x16_bf16 v[48:63], v[8:11], v[120:123], v[48:63]
	ds_read_b128 v[8:11], v192 offset:256
	v_mfma_f32_32x32x16_bf16 v[48:63], v[12:15], v[124:127], v[48:63]
	ds_read_b128 v[12:15], v193 offset:256
	s_waitcnt lgkmcnt(0)
	v_mfma_f32_32x32x16_bf16 v[48:63], v[0:3], v[128:131], v[48:63]
	ds_read_b128 v[0:3], v190 offset:12288
	v_mfma_f32_32x32x16_bf16 v[48:63], v[4:7], v[132:135], v[48:63]
	ds_read_b128 v[4:7], v191 offset:12288
	v_mfma_f32_32x32x16_bf16 v[48:63], v[8:11], v[136:139], v[48:63]
	ds_read_b128 v[8:11], v192 offset:12288
	s_waitcnt lgkmcnt(0)
	v_mfma_f32_32x32x16_bf16 v[80:95], v[0:3], v[96:99], 0
	ds_read_b128 v[16:19], v193 offset:12288
	v_mfma_f32_32x32x16_bf16 v[80:95], v[4:7], v[100:103], v[80:95]
	ds_read_b128 v[20:23], v190 offset:12416
	v_mfma_f32_32x32x16_bf16 v[80:95], v[8:11], v[104:107], v[80:95]
	ds_read_b128 v[24:27], v191 offset:12416
	s_waitcnt lgkmcnt(0)
	v_mfma_f32_32x32x16_bf16 v[80:95], v[16:19], v[108:111], v[80:95]
	ds_read_b128 v[28:31], v192 offset:12416
	v_mfma_f32_32x32x16_bf16 v[80:95], v[20:23], v[112:115], v[80:95]
	ds_read_b128 v[32:35], v193 offset:12416
	v_mfma_f32_32x32x16_bf16 v[80:95], v[24:27], v[116:119], v[80:95]
	ds_read_b128 v[36:39], v190 offset:12544
	s_waitcnt lgkmcnt(0)
	v_mfma_f32_32x32x16_bf16 v[80:95], v[28:31], v[120:123], v[80:95]
	ds_read_b128 v[40:43], v191 offset:12544
	v_mfma_f32_32x32x16_bf16 v[80:95], v[32:35], v[124:127], v[80:95]
	ds_read_b128 v[44:47], v192 offset:12544
	v_mfma_f32_32x32x16_bf16 v[80:95], v[36:39], v[128:131], v[80:95]
	ds_read_b128 v[64:67], v193 offset:12544
	s_waitcnt lgkmcnt(0)
	v_mfma_f32_32x32x16_bf16 v[80:95], v[40:43], v[132:135], v[80:95]
	v_mfma_f32_32x32x16_bf16 v[80:95], v[44:47], v[136:139], v[80:95]
	v_mfma_f32_32x32x16_bf16 v[80:95], v[64:67], v[140:143], v[80:95]
	v_mfma_f32_32x32x16_bf16 v[48:63], v[12:15], v[140:143], v[48:63]
	s_cbranch_vccnz .LBB0_1911
	s_waitcnt vmcnt(0) lgkmcnt(0)
	s_barrier

.LBB0_1913:
	v_sub_f32_e32 v80, v80, v151
	v_sub_f32_e32 v81, v81, v151
	v_sub_f32_e32 v82, v82, v151
	v_sub_f32_e32 v83, v83, v151
	v_sub_f32_e32 v84, v84, v151
	v_sub_f32_e32 v85, v85, v151
	v_sub_f32_e32 v86, v86, v151
	v_sub_f32_e32 v87, v87, v151
	v_exp_f32_e32 v80, v80
	v_exp_f32_e32 v81, v81
	v_exp_f32_e32 v82, v82
	v_exp_f32_e32 v83, v83
	v_exp_f32_e32 v84, v84
	v_exp_f32_e32 v85, v85
	v_exp_f32_e32 v86, v86
	v_exp_f32_e32 v87, v87
	ds_read_b64_tr_b16 v[198:199], v183 offset:32768
	ds_read_b64_tr_b16 v[200:201], v185 offset:34816
	ds_read_b64_tr_b16 v[206:207], v182 offset:32768
	ds_read_b64_tr_b16 v[208:209], v184 offset:34816
	ds_read_b64_tr_b16 v[212:213], v185 offset:38912
	ds_read_b64_tr_b16 v[210:211], v183 offset:36864
	v_cvt_pk_bf16_f32 v202, v80, v81
	v_cvt_pk_bf16_f32 v203, v82, v83
	v_cvt_pk_bf16_f32 v204, v84, v85
	v_cvt_pk_bf16_f32 v205, v86, v87
	v_sub_f32_e32 v88, v88, v151
	v_sub_f32_e32 v89, v89, v151
	s_waitcnt lgkmcnt(0)
	v_mfma_f32_32x32x16_bf16 v[64:79], v[198:201], v[202:205], v[64:79]
	ds_read_b64_tr_b16 v[198:199], v186 offset:32768
	ds_read_b64_tr_b16 v[200:201], v188 offset:34816
	ds_read_b64_tr_b16 v[216:217], v184 offset:38912
	ds_read_b64_tr_b16 v[214:215], v182 offset:36864
	v_sub_f32_e32 v90, v90, v151
	v_sub_f32_e32 v91, v91, v151
	v_sub_f32_e32 v92, v92, v151
	v_sub_f32_e32 v93, v93, v151
	v_sub_f32_e32 v94, v94, v151
	v_sub_f32_e32 v95, v95, v151
	v_mfma_f32_32x32x16_bf16 v[32:47], v[206:209], v[202:205], v[32:47]
	ds_read_b64_tr_b16 v[206:207], v187 offset:32768
	ds_read_b64_tr_b16 v[208:209], v189 offset:34816
	ds_read_b64_tr_b16 v[220:221], v188 offset:38912
	ds_read_b64_tr_b16 v[218:219], v186 offset:36864
	v_exp_f32_e32 v88, v88
	v_exp_f32_e32 v89, v89
	v_exp_f32_e32 v90, v90
	v_exp_f32_e32 v91, v91
	v_exp_f32_e32 v92, v92
	v_exp_f32_e32 v93, v93
	s_waitcnt lgkmcnt(0)
	v_mfma_f32_32x32x16_bf16 v[16:31], v[198:201], v[202:205], v[16:31]
	ds_read_b64_tr_b16 v[226:227], v189 offset:38912
	ds_read_b64_tr_b16 v[224:225], v187 offset:36864
	v_exp_f32_e32 v94, v94
	v_exp_f32_e32 v95, v95
	v_cvt_pk_bf16_f32 v200, v88, v89
	v_cvt_pk_bf16_f32 v201, v90, v91
	v_bitop3_b32 v198, v159, 7, v222 bitop3:0x48
	v_bitop3_b32 v159, v165, 7, v222 bitop3:0x48
	v_mfma_f32_32x32x16_bf16 v[0:15], v[206:209], v[202:205], v[0:15]
	v_cvt_pk_bf16_f32 v202, v92, v93
	v_cvt_pk_bf16_f32 v203, v94, v95
	v_cndmask_b32_e64 v165, 0, 1, s[12:13]
	v_bitop3_b32 v163, v163, 7, v222 bitop3:0x48
	v_cmp_ne_u32_e64 s[2:3], 1, v165
	s_andn2_b64 vcc, exec, s[12:13]
	v_mfma_f32_32x32x16_bf16 v[64:79], v[210:213], v[200:203], v[64:79]
	v_mfma_f32_32x32x16_bf16 v[32:47], v[214:217], v[200:203], v[32:47]
	v_mfma_f32_32x32x16_bf16 v[16:31], v[218:221], v[200:203], v[16:31]
	s_waitcnt lgkmcnt(0)
	v_mfma_f32_32x32x16_bf16 v[0:15], v[224:227], v[200:203], v[0:15]
	s_cbranch_vccnz .LBB0_1915
	s_waitcnt vmcnt(0) lgkmcnt(0)
	s_barrier

.LBB0_1926:
	s_setprio 1
	s_nop 7
	v_max_f32_e32 v153, v49, v49
	v_max_f32_e32 v155, v48, v48
	v_max_f32_e32 v153, v155, v153
	v_max3_f32 v153, v153, v50, v51
	v_max3_f32 v153, v153, v52, v53
	v_max3_f32 v153, v153, v54, v55
	v_max3_f32 v153, v153, v56, v57
	v_max3_f32 v153, v153, v58, v59
	v_max3_f32 v153, v153, v60, v61
	v_max3_f32 v153, v153, v62, v63
	v_mov_b32_e32 v155, v153
	s_nop 1
	v_permlane32_swap_b32_e32 v153, v155
	v_max_f32_e32 v155, v155, v155
	v_max_f32_e32 v153, v153, v153
	v_max_f32_e32 v153, v153, v155
	v_sub_f32_e32 v153, v153, v151
	v_cmp_lt_f32_e32 vcc, s26, v153
	s_cbranch_vccz .LBB0_1928
	v_max_f32_e32 v153, v153, v153
	v_max_f32_e32 v153, 0, v153
	v_exp_f32_e64 v198, -v153
	v_add_f32_e32 v151, v151, v153
	v_pk_mul_f32 v[78:79], v[78:79], v[198:199] op_sel_hi:[1,0]
	v_pk_mul_f32 v[76:77], v[76:77], v[198:199] op_sel_hi:[1,0]
	v_pk_mul_f32 v[74:75], v[74:75], v[198:199] op_sel_hi:[1,0]
	v_pk_mul_f32 v[72:73], v[72:73], v[198:199] op_sel_hi:[1,0]
	v_pk_mul_f32 v[70:71], v[70:71], v[198:199] op_sel_hi:[1,0]
	v_pk_mul_f32 v[68:69], v[68:69], v[198:199] op_sel_hi:[1,0]
	v_pk_mul_f32 v[66:67], v[66:67], v[198:199] op_sel_hi:[1,0]
	v_pk_mul_f32 v[64:65], v[64:65], v[198:199] op_sel_hi:[1,0]
	v_pk_mul_f32 v[46:47], v[46:47], v[198:199] op_sel_hi:[1,0]
	v_pk_mul_f32 v[44:45], v[44:45], v[198:199] op_sel_hi:[1,0]
	v_pk_mul_f32 v[42:43], v[42:43], v[198:199] op_sel_hi:[1,0]
	v_pk_mul_f32 v[40:41], v[40:41], v[198:199] op_sel_hi:[1,0]
	v_pk_mul_f32 v[38:39], v[38:39], v[198:199] op_sel_hi:[1,0]
	v_pk_mul_f32 v[36:37], v[36:37], v[198:199] op_sel_hi:[1,0]
	v_pk_mul_f32 v[34:35], v[34:35], v[198:199] op_sel_hi:[1,0]
	v_pk_mul_f32 v[32:33], v[32:33], v[198:199] op_sel_hi:[1,0]
	v_pk_mul_f32 v[30:31], v[30:31], v[198:199] op_sel_hi:[1,0]
	v_pk_mul_f32 v[28:29], v[28:29], v[198:199] op_sel_hi:[1,0]
	v_pk_mul_f32 v[26:27], v[26:27], v[198:199] op_sel_hi:[1,0]
	v_pk_mul_f32 v[24:25], v[24:25], v[198:199] op_sel_hi:[1,0]
	v_pk_mul_f32 v[22:23], v[22:23], v[198:199] op_sel_hi:[1,0]
	v_pk_mul_f32 v[20:21], v[20:21], v[198:199] op_sel_hi:[1,0]
	v_pk_mul_f32 v[18:19], v[18:19], v[198:199] op_sel_hi:[1,0]
	v_pk_mul_f32 v[16:17], v[16:17], v[198:199] op_sel_hi:[1,0]
	v_pk_mul_f32 v[14:15], v[14:15], v[198:199] op_sel_hi:[1,0]
	v_pk_mul_f32 v[12:13], v[12:13], v[198:199] op_sel_hi:[1,0]
	v_pk_mul_f32 v[10:11], v[10:11], v[198:199] op_sel_hi:[1,0]
	v_pk_mul_f32 v[8:9], v[8:9], v[198:199] op_sel_hi:[1,0]
	v_pk_mul_f32 v[6:7], v[6:7], v[198:199] op_sel_hi:[1,0]
	v_pk_mul_f32 v[4:5], v[4:5], v[198:199] op_sel_hi:[1,0]
	v_pk_mul_f32 v[2:3], v[2:3], v[198:199] op_sel_hi:[1,0]
	v_pk_mul_f32 v[0:1], v[0:1], v[198:199] op_sel_hi:[1,0]
	v_mul_f32_e32 v157, v157, v198
.LBB0_1928:
	v_add_u32_e32 v167, s27, v174
	v_add_u32_e32 v198, s27, v175
	v_sub_f32_e32 v48, v48, v151
	v_sub_f32_e32 v49, v49, v151
	v_sub_f32_e32 v50, v50, v151
	v_sub_f32_e32 v51, v51, v151
	v_sub_f32_e32 v52, v52, v151
	v_sub_f32_e32 v53, v53, v151
	v_sub_f32_e32 v54, v54, v151
	v_sub_f32_e32 v55, v55, v151
	v_add_u32_e32 v155, v167, v177
	v_exp_f32_e32 v48, v48
	v_exp_f32_e32 v49, v49
	v_exp_f32_e32 v50, v50
	v_exp_f32_e32 v51, v51
	v_exp_f32_e32 v52, v52
	v_exp_f32_e32 v53, v53
	v_exp_f32_e32 v54, v54
	v_exp_f32_e32 v55, v55
	v_add_u32_e32 v163, v198, v177
	ds_read_b64_tr_b16 v[204:205], v155 offset:24576
	ds_read_b64_tr_b16 v[206:207], v163 offset:26624
	v_add_u32_e32 v153, v167, v178
	v_add_u32_e32 v159, v198, v178
	ds_read_b64_tr_b16 v[208:209], v153 offset:24576
	ds_read_b64_tr_b16 v[210:211], v159 offset:26624
	ds_read_b64_tr_b16 v[214:215], v163 offset:30720
	ds_read_b64_tr_b16 v[212:213], v155 offset:28672
	v_cvt_pk_bf16_f32 v200, v48, v49
	v_cvt_pk_bf16_f32 v201, v50, v51
	v_cvt_pk_bf16_f32 v202, v52, v53
	v_cvt_pk_bf16_f32 v203, v54, v55
	v_add_u32_e32 v165, v167, v179
	v_add_u32_e32 v167, v167, v180
	s_waitcnt lgkmcnt(0)
	v_mfma_f32_32x32x16_bf16 v[64:79], v[204:207], v[200:203], v[64:79]
	v_add_u32_e32 v169, v198, v179
	ds_read_b64_tr_b16 v[204:205], v165 offset:24576
	ds_read_b64_tr_b16 v[206:207], v169 offset:26624
	ds_read_b64_tr_b16 v[218:219], v159 offset:30720
	ds_read_b64_tr_b16 v[216:217], v153 offset:28672
	v_add_u32_e32 v198, v198, v180
	v_add_f32_e32 v199, 0, v48
	v_sub_f32_e32 v56, v56, v151
	v_sub_f32_e32 v57, v57, v151
	v_sub_f32_e32 v58, v58, v151
	v_mfma_f32_32x32x16_bf16 v[32:47], v[208:211], v[200:203], v[32:47]
	ds_read_b64_tr_b16 v[208:209], v167 offset:24576
	ds_read_b64_tr_b16 v[210:211], v198 offset:26624
	ds_read_b64_tr_b16 v[226:227], v169 offset:30720
	ds_read_b64_tr_b16 v[224:225], v165 offset:28672
	v_sub_f32_e32 v59, v59, v151
	v_sub_f32_e32 v60, v60, v151
	v_sub_f32_e32 v61, v61, v151
	v_sub_f32_e32 v62, v62, v151
	v_sub_f32_e32 v63, v63, v151
	v_add_f32_e32 v199, v49, v199
	s_waitcnt lgkmcnt(0)
	v_mfma_f32_32x32x16_bf16 v[16:31], v[204:207], v[200:203], v[16:31]
	v_exp_f32_e32 v56, v56
	v_exp_f32_e32 v57, v57
	v_exp_f32_e32 v58, v58
	v_exp_f32_e32 v59, v59
	v_exp_f32_e32 v60, v60
	v_exp_f32_e32 v61, v61
	ds_read_b64_tr_b16 v[206:207], v198 offset:30720
	ds_read_b64_tr_b16 v[204:205], v167 offset:28672
	v_mfma_f32_32x32x16_bf16 v[0:15], v[208:211], v[200:203], v[0:15]
	v_exp_f32_e32 v62, v62
	v_exp_f32_e32 v63, v63
	v_add_f32_e32 v199, v50, v199
	v_add_f32_e32 v199, v51, v199
	v_add_f32_e32 v199, v52, v199
	v_add_f32_e32 v199, v53, v199
	v_cvt_pk_bf16_f32 v200, v56, v57
	v_cvt_pk_bf16_f32 v201, v58, v59
	v_cvt_pk_bf16_f32 v202, v60, v61
	v_cvt_pk_bf16_f32 v203, v62, v63
	v_add_f32_e32 v199, v54, v199
	v_add_f32_e32 v199, v55, v199
	v_mfma_f32_32x32x16_bf16 v[64:79], v[212:215], v[200:203], v[64:79]
	v_add_f32_e32 v199, v56, v199
	v_add_f32_e32 v199, v57, v199
	v_add_f32_e32 v199, v58, v199
	v_add_f32_e32 v199, v59, v199
	v_add_f32_e32 v199, v60, v199
	v_add_f32_e32 v199, v61, v199
	v_add_f32_e32 v199, v62, v199
	v_mfma_f32_32x32x16_bf16 v[32:47], v[216:219], v[200:203], v[32:47]
	v_add_f32_e32 v199, v63, v199
	v_add_f32_e32 v157, v157, v199
	v_mfma_f32_32x32x16_bf16 v[16:31], v[224:227], v[200:203], v[16:31]
	s_waitcnt lgkmcnt(0)
	v_mfma_f32_32x32x16_bf16 v[0:15], v[204:207], v[200:203], v[0:15]
	v_max_f32_e32 v200, v81, v81
	v_max_f32_e32 v201, v80, v80
	v_max_f32_e32 v200, v201, v200
	v_max3_f32 v200, v200, v82, v83
	v_max3_f32 v200, v200, v84, v85
	v_max3_f32 v200, v200, v86, v87
	v_max3_f32 v200, v200, v88, v89
	v_max3_f32 v200, v200, v90, v91
	v_max3_f32 v200, v200, v92, v93
	v_max3_f32 v200, v200, v94, v95
	v_mov_b32_e32 v199, v200
	s_nop 1
	v_permlane32_swap_b32_e32 v200, v199
	v_max_f32_e32 v199, v199, v199
	v_max_f32_e32 v200, v200, v200
	v_max_f32_e32 v199, v200, v199
	v_sub_f32_e32 v199, v199, v151
	v_cmp_lt_f32_e32 vcc, s26, v199
	s_cbranch_vccz .LBB0_1930
	v_max_f32_e32 v199, v199, v199
	v_max_f32_e32 v199, 0, v199
	v_exp_f32_e64 v200, -v199
	v_add_f32_e32 v151, v151, v199
	v_pk_mul_f32 v[78:79], v[78:79], v[200:201] op_sel_hi:[1,0]
	v_pk_mul_f32 v[76:77], v[76:77], v[200:201] op_sel_hi:[1,0]
	v_pk_mul_f32 v[74:75], v[74:75], v[200:201] op_sel_hi:[1,0]
	v_pk_mul_f32 v[72:73], v[72:73], v[200:201] op_sel_hi:[1,0]
	v_pk_mul_f32 v[70:71], v[70:71], v[200:201] op_sel_hi:[1,0]
	v_pk_mul_f32 v[68:69], v[68:69], v[200:201] op_sel_hi:[1,0]
	v_pk_mul_f32 v[66:67], v[66:67], v[200:201] op_sel_hi:[1,0]
	v_pk_mul_f32 v[64:65], v[64:65], v[200:201] op_sel_hi:[1,0]
	v_pk_mul_f32 v[46:47], v[46:47], v[200:201] op_sel_hi:[1,0]
	v_pk_mul_f32 v[44:45], v[44:45], v[200:201] op_sel_hi:[1,0]
	v_pk_mul_f32 v[42:43], v[42:43], v[200:201] op_sel_hi:[1,0]
	v_pk_mul_f32 v[40:41], v[40:41], v[200:201] op_sel_hi:[1,0]
	v_pk_mul_f32 v[38:39], v[38:39], v[200:201] op_sel_hi:[1,0]
	v_pk_mul_f32 v[36:37], v[36:37], v[200:201] op_sel_hi:[1,0]
	v_pk_mul_f32 v[34:35], v[34:35], v[200:201] op_sel_hi:[1,0]
	v_pk_mul_f32 v[32:33], v[32:33], v[200:201] op_sel_hi:[1,0]
	v_pk_mul_f32 v[30:31], v[30:31], v[200:201] op_sel_hi:[1,0]
	v_pk_mul_f32 v[28:29], v[28:29], v[200:201] op_sel_hi:[1,0]
	v_pk_mul_f32 v[26:27], v[26:27], v[200:201] op_sel_hi:[1,0]
	v_pk_mul_f32 v[24:25], v[24:25], v[200:201] op_sel_hi:[1,0]
	v_pk_mul_f32 v[22:23], v[22:23], v[200:201] op_sel_hi:[1,0]
	v_pk_mul_f32 v[20:21], v[20:21], v[200:201] op_sel_hi:[1,0]
	v_pk_mul_f32 v[18:19], v[18:19], v[200:201] op_sel_hi:[1,0]
	v_pk_mul_f32 v[16:17], v[16:17], v[200:201] op_sel_hi:[1,0]
	v_pk_mul_f32 v[14:15], v[14:15], v[200:201] op_sel_hi:[1,0]
	v_pk_mul_f32 v[12:13], v[12:13], v[200:201] op_sel_hi:[1,0]
	v_pk_mul_f32 v[10:11], v[10:11], v[200:201] op_sel_hi:[1,0]
	v_pk_mul_f32 v[8:9], v[8:9], v[200:201] op_sel_hi:[1,0]
	v_pk_mul_f32 v[6:7], v[6:7], v[200:201] op_sel_hi:[1,0]
	v_pk_mul_f32 v[4:5], v[4:5], v[200:201] op_sel_hi:[1,0]
	v_pk_mul_f32 v[2:3], v[2:3], v[200:201] op_sel_hi:[1,0]
	v_pk_mul_f32 v[0:1], v[0:1], v[200:201] op_sel_hi:[1,0]
	v_mul_f32_e32 v157, v157, v200

.LBB0_1931:
	s_setprio 0
	v_mov_b32_e32 v48, v157
	s_nop 1
	v_permlane32_swap_b32_e32 v157, v48
	v_add_f32_e32 v48, v157, v48
	v_div_scale_f32 v49, s[2:3], v48, v48, 1.0
	v_rcp_f32_e32 v50, v49
	s_mulk_i32 s21, 0x2200
	s_add_i32 s7, s21, 0
	s_waitcnt vmcnt(0) lgkmcnt(0)
	s_barrier
	v_fma_f32 v51, -v49, v50, 1.0
	v_fmac_f32_e32 v50, v51, v50
	v_div_scale_f32 v51, vcc, 1.0, v48, 1.0
	v_mul_f32_e32 v52, v51, v50
	v_fma_f32 v53, -v49, v52, v51
	v_fmac_f32_e32 v52, v53, v50
	v_fma_f32 v49, -v49, v52, v51
	v_div_fmas_f32 v49, v49, v50, v52
	v_div_fixup_f32 v48, v49, v48, 1.0
	v_add3_u32 v49, s7, v195, v181
	v_pk_mul_f32 v[50:51], v[64:65], v[48:49] op_sel_hi:[1,0]
	v_pk_mul_f32 v[52:53], v[66:67], v[48:49] op_sel_hi:[1,0]
	v_cvt_pk_bf16_f32 v50, v50, v51
	v_cvt_pk_bf16_f32 v51, v52, v53
	v_pk_mul_f32 v[52:53], v[68:69], v[48:49] op_sel_hi:[1,0]
	v_pk_mul_f32 v[54:55], v[70:71], v[48:49] op_sel_hi:[1,0]
	v_add_u32_e32 v49, 0xa000, v49
	v_pk_mul_f32 v[32:33], v[32:33], v[48:49] op_sel_hi:[1,0]
	v_pk_mul_f32 v[34:35], v[34:35], v[48:49] op_sel_hi:[1,0]
	v_pk_mul_f32 v[16:17], v[16:17], v[48:49] op_sel_hi:[1,0]
	v_pk_mul_f32 v[18:19], v[18:19], v[48:49] op_sel_hi:[1,0]
	v_pk_mul_f32 v[0:1], v[0:1], v[48:49] op_sel_hi:[1,0]
	v_pk_mul_f32 v[2:3], v[2:3], v[48:49] op_sel_hi:[1,0]
	v_cvt_pk_bf16_f32 v32, v32, v33
	v_cvt_pk_bf16_f32 v33, v34, v35
	v_pk_mul_f32 v[34:35], v[36:37], v[48:49] op_sel_hi:[1,0]
	v_pk_mul_f32 v[36:37], v[38:39], v[48:49] op_sel_hi:[1,0]
	v_cvt_pk_bf16_f32 v16, v16, v17
	v_cvt_pk_bf16_f32 v17, v18, v19
	v_pk_mul_f32 v[18:19], v[20:21], v[48:49] op_sel_hi:[1,0]
	v_pk_mul_f32 v[20:21], v[22:23], v[48:49] op_sel_hi:[1,0]
	v_cvt_pk_bf16_f32 v0, v0, v1
	v_cvt_pk_bf16_f32 v1, v2, v3
	v_pk_mul_f32 v[2:3], v[4:5], v[48:49] op_sel_hi:[1,0]
	v_pk_mul_f32 v[4:5], v[6:7], v[48:49] op_sel_hi:[1,0]
	v_cvt_pk_bf16_f32 v52, v52, v53
	v_cvt_pk_bf16_f32 v53, v54, v55
	v_cvt_pk_bf16_f32 v34, v34, v35
	v_cvt_pk_bf16_f32 v35, v36, v37
	v_cvt_pk_bf16_f32 v18, v18, v19
	v_cvt_pk_bf16_f32 v19, v20, v21
	v_cvt_pk_bf16_f32 v2, v2, v3
	v_cvt_pk_bf16_f32 v3, v4, v5
	ds_write2_b64 v49, v[50:51], v[52:53] offset1:2
	v_pk_mul_f32 v[50:51], v[72:73], v[48:49] op_sel_hi:[1,0]
	v_pk_mul_f32 v[52:53], v[74:75], v[48:49] op_sel_hi:[1,0]
	ds_write2_b64 v49, v[32:33], v[34:35] offset0:8 offset1:10
	v_pk_mul_f32 v[32:33], v[40:41], v[48:49] op_sel_hi:[1,0]
	v_pk_mul_f32 v[34:35], v[42:43], v[48:49] op_sel_hi:[1,0]
	ds_write2_b64 v49, v[16:17], v[18:19] offset0:16 offset1:18
	v_pk_mul_f32 v[16:17], v[24:25], v[48:49] op_sel_hi:[1,0]
	v_pk_mul_f32 v[18:19], v[26:27], v[48:49] op_sel_hi:[1,0]
	ds_write2_b64 v49, v[0:1], v[2:3] offset0:24 offset1:26
	v_pk_mul_f32 v[0:1], v[8:9], v[48:49] op_sel_hi:[1,0]
	v_pk_mul_f32 v[2:3], v[10:11], v[48:49] op_sel_hi:[1,0]
	v_cvt_pk_bf16_f32 v50, v50, v51
	v_cvt_pk_bf16_f32 v51, v52, v53
	v_pk_mul_f32 v[52:53], v[76:77], v[48:49] op_sel_hi:[1,0]
	v_pk_mul_f32 v[54:55], v[78:79], v[48:49] op_sel_hi:[1,0]
	v_cvt_pk_bf16_f32 v32, v32, v33
	v_cvt_pk_bf16_f32 v33, v34, v35
	v_pk_mul_f32 v[34:35], v[44:45], v[48:49] op_sel_hi:[1,0]
	v_pk_mul_f32 v[36:37], v[46:47], v[48:49] op_sel_hi:[1,0]
	v_cvt_pk_bf16_f32 v16, v16, v17
	v_cvt_pk_bf16_f32 v17, v18, v19
	v_pk_mul_f32 v[18:19], v[28:29], v[48:49] op_sel_hi:[1,0]
	v_pk_mul_f32 v[20:21], v[30:31], v[48:49] op_sel_hi:[1,0]
	v_cvt_pk_bf16_f32 v0, v0, v1
	v_cvt_pk_bf16_f32 v1, v2, v3
	v_pk_mul_f32 v[2:3], v[12:13], v[48:49] op_sel_hi:[1,0]
	v_pk_mul_f32 v[4:5], v[14:15], v[48:49] op_sel_hi:[1,0]
	v_cvt_pk_bf16_f32 v52, v52, v53
	v_cvt_pk_bf16_f32 v53, v54, v55
	v_cvt_pk_bf16_f32 v34, v34, v35
	v_cvt_pk_bf16_f32 v35, v36, v37
	v_cvt_pk_bf16_f32 v18, v18, v19
	v_cvt_pk_bf16_f32 v19, v20, v21
	v_cvt_pk_bf16_f32 v2, v2, v3
	v_cvt_pk_bf16_f32 v3, v4, v5
	s_mulk_i32 s20, 0x1800
	s_mul_hi_u32 s2, s19, 0x1800
	ds_write2_b64 v49, v[50:51], v[52:53] offset0:4 offset1:6
	ds_write2_b64 v49, v[32:33], v[34:35] offset0:12 offset1:14
	ds_write2_b64 v49, v[16:17], v[18:19] offset0:20 offset1:22
	ds_write2_b64 v49, v[0:1], v[2:3] offset0:28 offset1:30
	s_add_i32 s2, s2, s20
	s_mulk_i32 s19, 0x1800
	s_waitcnt lgkmcnt(0)
	s_add_u32 s3, s4, s19
	v_add3_u32 v14, s7, v144, v196
	s_addc_u32 s10, s5, s2
	ds_read_b128 v[0:3], v14 offset:40960
	s_add_u32 s2, s3, s6
	s_addc_u32 s3, s10, 0
	v_mov_b32_e32 v159, 0
	ds_read_b128 v[4:7], v14 offset:42048
	v_lshl_add_u64 v[8:9], s[2:3], 0, v[158:159]
	v_mov_b32_e32 v147, v159
	v_lshl_add_u64 v[10:11], v[8:9], 0, v[146:147]
	s_movk_i32 s2, 0x6000
	s_waitcnt lgkmcnt(0)
	global_store_dwordx4 v[10:11], v[0:3], off
	v_mov_b32_e32 v149, v159
	v_mov_b32_e32 v153, v159
	v_add_co_u32_e32 v0, vcc, s2, v10
	s_mov_b32 s2, 0xc000
	s_nop 0
	v_addc_co_u32_e32 v1, vcc, 0, v11, vcc
	global_store_dwordx4 v[0:1], v[4:7], off
	ds_read_b128 v[0:3], v14 offset:43136
	ds_read_b128 v[4:7], v14 offset:44224
	v_add_co_u32_e32 v12, vcc, s2, v10
	s_mov_b32 s2, 0x12000
	s_nop 0
	v_addc_co_u32_e32 v13, vcc, 0, v11, vcc
	v_add_co_u32_e32 v10, vcc, s2, v10
	s_waitcnt lgkmcnt(0)
	global_store_dwordx4 v[12:13], v[0:3], off
	v_addc_co_u32_e32 v11, vcc, 0, v11, vcc
	ds_read_b128 v[0:3], v14 offset:45312
	global_store_dwordx4 v[10:11], v[4:7], off
	ds_read_b128 v[4:7], v14 offset:46400
	v_lshl_add_u64 v[10:11], v[8:9], 0, v[148:149]
	v_mov_b32_e32 v151, v159
	s_waitcnt lgkmcnt(0)
	global_store_dwordx4 v[10:11], v[0:3], off
	v_lshl_add_u64 v[10:11], v[8:9], 0, v[152:153]
	ds_read_b128 v[0:3], v14 offset:47488
	global_store_dwordx4 v[10:11], v[4:7], off
	ds_read_b128 v[4:7], v14 offset:48576
	v_lshl_add_u64 v[10:11], v[8:9], 0, v[150:151]
	v_mov_b32_e32 v155, v159
	v_readfirstlane_b32 s12, v222
	s_waitcnt lgkmcnt(0)
	global_store_dwordx4 v[10:11], v[0:3], off
	s_and_b32 s2, s12, 0xffffffc0
	s_nop 0
	v_lshl_add_u64 v[0:1], v[8:9], 0, v[154:155]
	global_store_dwordx4 v[0:1], v[4:7], off
	v_or_b32_e32 v0, s2, v197
	s_mov_b32 s2, 0x2aaaaaab
	v_mul_hi_i32 v1, v0, s2
	v_lshrrev_b32_e32 v2, 31, v1
	v_ashrrev_i32_e32 v1, 2, v1
	v_add_u32_e32 v2, v1, v2
	s_movk_i32 s2, 0xffe8
	v_lshrrev_b32_e32 v159, 1, v2
	v_mad_u64_u32 v[160:161], s[2:3], v2, s2, v[0:1]
	v_xor_b32_e32 v1, v159, v222
	v_bfi_b32 v1, -8, v160, v1
	v_cmp_lt_i32_e32 vcc, 15, v1
	v_add_u32_e32 v2, s8, v2
	s_and_saveexec_b64 s[2:3], vcc
	s_xor_b64 s[2:3], exec, s[2:3]
	v_mov_b32_e32 v3, 0xbfff80
	v_lshl_add_u32 v153, v2, 6, v3
	s_or_saveexec_b64 s[2:3], s[2:3]
	v_mov_b32_e32 v145, 0x1000
	s_xor_b64 exec, exec, s[2:3]
	v_lshl_or_b32 v2, v2, 11, s17
	v_add_u32_e32 v153, 0x8000000, v2
	v_mov_b32_e32 v145, 0x20000
	s_or_b64 exec, exec, s[2:3]
	v_add_u32_e32 v2, 0x200, v0
	s_mov_b32 s2, 0x2aaaaaab
	v_mul_hi_i32 v3, v2, s2
	v_lshrrev_b32_e32 v4, 31, v3
	v_ashrrev_i32_e32 v3, 2, v3
	v_add_u32_e32 v4, v3, v4
	s_movk_i32 s2, 0xffe8
	v_mad_u64_u32 v[162:163], s[2:3], v4, s2, v[2:3]
	v_lshrrev_b32_e32 v163, 1, v4
	v_xor_b32_e32 v3, v163, v222
	v_bfi_b32 v3, -8, v162, v3
	v_cmp_lt_i32_e32 vcc, 15, v3
	v_add_u32_e32 v4, s8, v4
	s_and_saveexec_b64 s[2:3], vcc
	s_xor_b64 s[2:3], exec, s[2:3]
	v_mov_b32_e32 v5, 0xbfff80
	v_lshl_add_u32 v155, v4, 6, v5
	s_or_saveexec_b64 s[2:3], s[2:3]
	v_mov_b32_e32 v147, 0x1000
	s_xor_b64 exec, exec, s[2:3]
	v_lshl_or_b32 v4, v4, 11, s17
	v_add_u32_e32 v155, 0x8000000, v4
	v_mov_b32_e32 v147, 0x20000
	s_or_b64 exec, exec, s[2:3]
	v_add_u32_e32 v4, 0x400, v0
	s_mov_b32 s2, 0x2aaaaaab
	v_mul_hi_i32 v5, v4, s2
	v_lshrrev_b32_e32 v6, 31, v5
	v_ashrrev_i32_e32 v5, 2, v5
	v_add_u32_e32 v5, v5, v6
	s_movk_i32 s2, 0xffe8
	v_mad_u64_u32 v[164:165], s[2:3], v5, s2, v[4:5]
	v_lshrrev_b32_e32 v165, 1, v5
	v_xor_b32_e32 v4, v165, v222
	v_bfi_b32 v4, -8, v164, v4
	v_cmp_lt_i32_e32 vcc, 15, v4
	v_add_u32_e32 v5, s8, v5
	s_and_saveexec_b64 s[2:3], vcc
	s_xor_b64 s[2:3], exec, s[2:3]
	v_mov_b32_e32 v6, 0xbfff80
	v_lshl_add_u32 v161, v5, 6, v6
	s_or_saveexec_b64 s[2:3], s[2:3]
	v_mov_b32_e32 v149, 0x1000
	s_xor_b64 exec, exec, s[2:3]
	v_lshl_or_b32 v5, v5, 11, s17
	v_add_u32_e32 v161, 0x8000000, v5
	v_mov_b32_e32 v149, 0x20000
	s_or_b64 exec, exec, s[2:3]
	s_lshr_b32 s21, s12, 6
	s_xor_b32 s22, s16, 0xf00
	s_lshl_b32 s23, s21, 5
	s_or_b32 s2, s8, s22
	s_add_u32 s19, s2, s23
	v_or_b32_e32 v5, s19, v194
	s_movk_i32 s2, 0x1800
	v_mov_b64_e32 v[6:7], s[4:5]
	s_addc_u32 s20, s9, 0
	v_mad_u64_u32 v[6:7], s[2:3], v5, s2, v[6:7]
	v_mov_b32_e32 v5, 0x1800
	s_mov_b32 s7, 0
	v_mad_i32_i24 v7, s20, v5, v7
	v_lshl_add_u32 v8, v1, 3, v153
	v_ashrrev_i32_e32 v1, 31, v0
	v_lshl_add_u64 v[6:7], v[6:7], 0, s[6:7]
	v_mov_b32_e32 v157, 0
	v_lshrrev_b32_e32 v10, 28, v1
	v_lshl_add_u64 v[6:7], v[6:7], 0, v[156:157]
	v_lshl_add_u32 v4, v4, 3, v161
	v_mov_b32_e32 v5, v157
	v_add_u32_e32 v16, v0, v10
	global_load_dwordx4 v[96:99], v[6:7], off
	global_load_dwordx4 v[100:103], v[6:7], off offset:32
	global_load_dwordx4 v[104:107], v[6:7], off offset:64
	global_load_dwordx4 v[108:111], v[6:7], off offset:96
	global_load_dwordx4 v[112:115], v[6:7], off offset:128
	global_load_dwordx4 v[116:119], v[6:7], off offset:160
	global_load_dwordx4 v[120:123], v[6:7], off offset:192
	global_load_dwordx4 v[124:127], v[6:7], off offset:224
	global_load_dwordx4 v[128:131], v[6:7], off offset:256
	global_load_dwordx4 v[132:135], v[6:7], off offset:288
	global_load_dwordx4 v[136:139], v[6:7], off offset:320
	global_load_dwordx4 v[140:143], v[6:7], off offset:352
	v_lshl_add_u32 v6, v3, 3, v155
	v_ashrrev_i32_e32 v3, 31, v2
	v_lshl_add_u64 v[14:15], v[4:5], 1, s[84:85]
	v_ashrrev_i32_e32 v167, 4, v16
	v_and_b32_e32 v5, 0x1ffffff0, v16
	v_lshrrev_b32_e32 v11, 28, v3
	v_mov_b32_e32 v9, v157
	s_lshl_b32 s2, s21, 10
	v_sub_u32_e32 v0, v0, v5
	v_lshlrev_b32_e32 v5, 2, v167
	v_mov_b32_e32 v7, v157
	v_add_u32_e32 v17, v2, v11
	v_lshl_add_u64 v[10:11], v[8:9], 1, s[84:85]
	v_bfe_u32 v9, v167, 2, 2
	s_add_i32 s7, s2, 0
	v_and_b32_e32 v5, 12, v5
	v_lshl_add_u64 v[12:13], v[6:7], 1, s[84:85]
	v_ashrrev_i32_e32 v166, 4, v17
	v_and_b32_e32 v7, 0x1ffffff0, v17
	v_bitop3_b32 v0, v5, v0, v9 bitop3:0x36
	s_mov_b32 m0, s7
	v_add_lshl_u32 v16, v167, s8, 11
	v_sub_u32_e32 v2, v2, v7
	v_lshlrev_b32_e32 v7, 2, v166
	global_load_lds_dwordx4 v[10:11], off
	s_add_i32 m0, s7, 0x2000
	v_lshlrev_b32_e32 v168, 3, v0
	v_mov_b32_e32 v1, v157
	v_bfe_u32 v17, v166, 2, 2
	v_and_b32_e32 v7, 12, v7
	global_load_lds_dwordx4 v[12:13], off
	s_add_i32 m0, s7, 0x4000
	v_add3_u32 v0, s18, v16, v168
	v_bitop3_b32 v2, v7, v2, v17 bitop3:0x36
	global_load_lds_dwordx4 v[14:15], off
	s_add_i32 m0, s7, 0x6000
	v_lshl_add_u64 v[10:11], v[0:1], 1, s[84:85]
	v_add_lshl_u32 v18, v166, s8, 11
	v_lshlrev_b32_e32 v169, 3, v2
	global_load_lds_dwordx4 v[10:11], off
	s_add_i32 m0, s7, 0x8000
	v_mov_b32_e32 v3, v157
	v_add3_u32 v2, s18, v18, v169
	s_cmpk_gt_u32 s12, 0xff
	v_lshl_add_u64 v[12:13], v[2:3], 1, s[84:85]
	s_cselect_b64 s[10:11], -1, 0
	s_cmpk_lt_u32 s12, 0x100
	v_add_u32_e32 v8, v8, v145
	v_mov_b32_e32 v9, v157
	global_load_lds_dwordx4 v[12:13], off
	s_cselect_b64 s[12:13], -1, 0
	s_add_i32 m0, s7, 0xa000
	v_lshl_add_u64 v[8:9], v[8:9], 1, s[84:85]
	v_add_u32_e32 v6, v6, v147
	v_mov_b32_e32 v7, v157
	s_waitcnt vmcnt(0) lgkmcnt(0)
	s_barrier
	s_waitcnt vmcnt(0)
	global_load_lds_dwordx4 v[8:9], off
	v_lshl_add_u64 v[6:7], v[6:7], 1, s[84:85]
	s_add_i32 m0, s7, 0xc000
	v_add_u32_e32 v4, v4, v149
	v_mov_b32_e32 v5, v157
	global_load_lds_dwordx4 v[6:7], off
	v_lshl_add_u64 v[4:5], v[4:5], 1, s[84:85]
	s_add_i32 m0, s7, 0xe000
	v_add_u32_e32 v0, 0x20000, v0
	v_mov_b32_e32 v1, v157
	global_load_lds_dwordx4 v[4:5], off
	s_add_i32 m0, s7, 0x10000
	v_lshl_add_u64 v[0:1], v[0:1], 1, s[84:85]
	global_load_lds_dwordx4 v[0:1], off
	v_add_u32_e32 v0, 0x20000, v2
	v_mov_b32_e32 v1, v157
	v_lshl_add_u64 v[0:1], v[0:1], 1, s[84:85]
	s_add_i32 m0, s7, 0x12000
	s_and_b64 vcc, exec, s[12:13]
	global_load_lds_dwordx4 v[0:1], off
	ds_read_b128 v[0:3], v190
	ds_read_b128 v[4:7], v191
	ds_read_b128 v[8:11], v192
	ds_read_b128 v[12:15], v193
	s_waitcnt lgkmcnt(0)
	v_mfma_f32_32x32x16_bf16 v[48:63], v[0:3], v[96:99], 0
	ds_read_b128 v[0:3], v190 offset:128
	v_mfma_f32_32x32x16_bf16 v[48:63], v[4:7], v[100:103], v[48:63]
	ds_read_b128 v[4:7], v191 offset:128
	v_mfma_f32_32x32x16_bf16 v[48:63], v[8:11], v[104:107], v[48:63]
	ds_read_b128 v[8:11], v192 offset:128
	v_mfma_f32_32x32x16_bf16 v[48:63], v[12:15], v[108:111], v[48:63]
	ds_read_b128 v[12:15], v193 offset:128
	s_waitcnt lgkmcnt(0)
	v_mfma_f32_32x32x16_bf16 v[48:63], v[0:3], v[112:115], v[48:63]
	ds_read_b128 v[0:3], v190 offset:256
	v_mfma_f32_32x32x16_bf16 v[48:63], v[4:7], v[116:119], v[48:63]
	ds_read_b128 v[4:7], v191 offset:256
	v_mfma_f32_32x32x16_bf16 v[48:63], v[8:11], v[120:123], v[48:63]
	ds_read_b128 v[8:11], v192 offset:256
	v_mfma_f32_32x32x16_bf16 v[48:63], v[12:15], v[124:127], v[48:63]
	ds_read_b128 v[12:15], v193 offset:256
	s_waitcnt lgkmcnt(0)
	v_mfma_f32_32x32x16_bf16 v[48:63], v[0:3], v[128:131], v[48:63]
	ds_read_b128 v[0:3], v190 offset:12288
	v_mfma_f32_32x32x16_bf16 v[48:63], v[4:7], v[132:135], v[48:63]
	ds_read_b128 v[4:7], v191 offset:12288
	v_mfma_f32_32x32x16_bf16 v[48:63], v[8:11], v[136:139], v[48:63]
	ds_read_b128 v[8:11], v192 offset:12288
	s_waitcnt lgkmcnt(0)
	v_mfma_f32_32x32x16_bf16 v[80:95], v[0:3], v[96:99], 0
	ds_read_b128 v[16:19], v193 offset:12288
	v_mfma_f32_32x32x16_bf16 v[80:95], v[4:7], v[100:103], v[80:95]
	ds_read_b128 v[20:23], v190 offset:12416
	v_mfma_f32_32x32x16_bf16 v[80:95], v[8:11], v[104:107], v[80:95]
	ds_read_b128 v[24:27], v191 offset:12416
	s_waitcnt lgkmcnt(0)
	v_mfma_f32_32x32x16_bf16 v[80:95], v[16:19], v[108:111], v[80:95]
	ds_read_b128 v[28:31], v192 offset:12416
	v_mfma_f32_32x32x16_bf16 v[80:95], v[20:23], v[112:115], v[80:95]
	ds_read_b128 v[32:35], v193 offset:12416
	v_mfma_f32_32x32x16_bf16 v[80:95], v[24:27], v[116:119], v[80:95]
	ds_read_b128 v[36:39], v190 offset:12544
	s_waitcnt lgkmcnt(0)
	v_mfma_f32_32x32x16_bf16 v[80:95], v[28:31], v[120:123], v[80:95]
	ds_read_b128 v[40:43], v191 offset:12544
	v_mfma_f32_32x32x16_bf16 v[80:95], v[32:35], v[124:127], v[80:95]
	ds_read_b128 v[44:47], v192 offset:12544
	v_mfma_f32_32x32x16_bf16 v[80:95], v[36:39], v[128:131], v[80:95]
	ds_read_b128 v[64:67], v193 offset:12544
	s_waitcnt lgkmcnt(0)
	v_mfma_f32_32x32x16_bf16 v[80:95], v[40:43], v[132:135], v[80:95]
	v_mfma_f32_32x32x16_bf16 v[80:95], v[44:47], v[136:139], v[80:95]
	v_mfma_f32_32x32x16_bf16 v[80:95], v[64:67], v[140:143], v[80:95]
	v_mfma_f32_32x32x16_bf16 v[48:63], v[12:15], v[140:143], v[48:63]
	s_cbranch_vccnz .LBB0_1945
	s_waitcnt vmcnt(0) lgkmcnt(0)
	s_barrier

.LBB0_1965:
	s_setprio 0
	v_mov_b32_e32 v48, v157
	s_nop 1
	v_permlane32_swap_b32_e32 v157, v48
	v_add_f32_e32 v48, v157, v48
	v_div_scale_f32 v49, s[2:3], v48, v48, 1.0
	v_rcp_f32_e32 v50, v49
	s_mulk_i32 s21, 0x2200
	s_add_i32 s7, s21, 0
	s_waitcnt vmcnt(0) lgkmcnt(0)
	s_barrier
	v_fma_f32 v51, -v49, v50, 1.0
	v_fmac_f32_e32 v50, v51, v50
	v_div_scale_f32 v51, vcc, 1.0, v48, 1.0
	v_mul_f32_e32 v52, v51, v50
	v_fma_f32 v53, -v49, v52, v51
	v_fmac_f32_e32 v52, v53, v50
	v_fma_f32 v49, -v49, v52, v51
	v_div_fmas_f32 v49, v49, v50, v52
	v_div_fixup_f32 v48, v49, v48, 1.0
	v_add3_u32 v49, s7, v195, v181
	v_pk_mul_f32 v[50:51], v[64:65], v[48:49] op_sel_hi:[1,0]
	v_pk_mul_f32 v[52:53], v[66:67], v[48:49] op_sel_hi:[1,0]
	v_cvt_pk_bf16_f32 v50, v50, v51
	v_cvt_pk_bf16_f32 v51, v52, v53
	v_pk_mul_f32 v[52:53], v[68:69], v[48:49] op_sel_hi:[1,0]
	v_pk_mul_f32 v[54:55], v[70:71], v[48:49] op_sel_hi:[1,0]
	v_add_u32_e32 v49, 0xa000, v49
	v_pk_mul_f32 v[32:33], v[32:33], v[48:49] op_sel_hi:[1,0]
	v_pk_mul_f32 v[34:35], v[34:35], v[48:49] op_sel_hi:[1,0]
	v_pk_mul_f32 v[16:17], v[16:17], v[48:49] op_sel_hi:[1,0]
	v_pk_mul_f32 v[18:19], v[18:19], v[48:49] op_sel_hi:[1,0]
	v_pk_mul_f32 v[0:1], v[0:1], v[48:49] op_sel_hi:[1,0]
	v_pk_mul_f32 v[2:3], v[2:3], v[48:49] op_sel_hi:[1,0]
	v_cvt_pk_bf16_f32 v32, v32, v33
	v_cvt_pk_bf16_f32 v33, v34, v35
	v_pk_mul_f32 v[34:35], v[36:37], v[48:49] op_sel_hi:[1,0]
	v_pk_mul_f32 v[36:37], v[38:39], v[48:49] op_sel_hi:[1,0]
	v_cvt_pk_bf16_f32 v16, v16, v17
	v_cvt_pk_bf16_f32 v17, v18, v19
	v_pk_mul_f32 v[18:19], v[20:21], v[48:49] op_sel_hi:[1,0]
	v_pk_mul_f32 v[20:21], v[22:23], v[48:49] op_sel_hi:[1,0]
	v_cvt_pk_bf16_f32 v0, v0, v1
	v_cvt_pk_bf16_f32 v1, v2, v3
	v_pk_mul_f32 v[2:3], v[4:5], v[48:49] op_sel_hi:[1,0]
	v_pk_mul_f32 v[4:5], v[6:7], v[48:49] op_sel_hi:[1,0]
	v_cvt_pk_bf16_f32 v52, v52, v53
	v_cvt_pk_bf16_f32 v53, v54, v55
	v_cvt_pk_bf16_f32 v34, v34, v35
	v_cvt_pk_bf16_f32 v35, v36, v37
	v_cvt_pk_bf16_f32 v18, v18, v19
	v_cvt_pk_bf16_f32 v19, v20, v21
	v_cvt_pk_bf16_f32 v2, v2, v3
	v_cvt_pk_bf16_f32 v3, v4, v5
	ds_write2_b64 v49, v[50:51], v[52:53] offset1:2
	v_pk_mul_f32 v[50:51], v[72:73], v[48:49] op_sel_hi:[1,0]
	v_pk_mul_f32 v[52:53], v[74:75], v[48:49] op_sel_hi:[1,0]
	ds_write2_b64 v49, v[32:33], v[34:35] offset0:8 offset1:10
	v_pk_mul_f32 v[32:33], v[40:41], v[48:49] op_sel_hi:[1,0]
	v_pk_mul_f32 v[34:35], v[42:43], v[48:49] op_sel_hi:[1,0]
	ds_write2_b64 v49, v[16:17], v[18:19] offset0:16 offset1:18
	v_pk_mul_f32 v[16:17], v[24:25], v[48:49] op_sel_hi:[1,0]
	v_pk_mul_f32 v[18:19], v[26:27], v[48:49] op_sel_hi:[1,0]
	ds_write2_b64 v49, v[0:1], v[2:3] offset0:24 offset1:26
	v_pk_mul_f32 v[0:1], v[8:9], v[48:49] op_sel_hi:[1,0]
	v_pk_mul_f32 v[2:3], v[10:11], v[48:49] op_sel_hi:[1,0]
	v_cvt_pk_bf16_f32 v50, v50, v51
	v_cvt_pk_bf16_f32 v51, v52, v53
	v_pk_mul_f32 v[52:53], v[76:77], v[48:49] op_sel_hi:[1,0]
	v_pk_mul_f32 v[54:55], v[78:79], v[48:49] op_sel_hi:[1,0]
	v_cvt_pk_bf16_f32 v32, v32, v33
	v_cvt_pk_bf16_f32 v33, v34, v35
	v_pk_mul_f32 v[34:35], v[44:45], v[48:49] op_sel_hi:[1,0]
	v_pk_mul_f32 v[36:37], v[46:47], v[48:49] op_sel_hi:[1,0]
	v_cvt_pk_bf16_f32 v16, v16, v17
	v_cvt_pk_bf16_f32 v17, v18, v19
	v_pk_mul_f32 v[18:19], v[28:29], v[48:49] op_sel_hi:[1,0]
	v_pk_mul_f32 v[20:21], v[30:31], v[48:49] op_sel_hi:[1,0]
	v_cvt_pk_bf16_f32 v0, v0, v1
	v_cvt_pk_bf16_f32 v1, v2, v3
	v_pk_mul_f32 v[2:3], v[12:13], v[48:49] op_sel_hi:[1,0]
	v_pk_mul_f32 v[4:5], v[14:15], v[48:49] op_sel_hi:[1,0]
	v_cvt_pk_bf16_f32 v52, v52, v53
	v_cvt_pk_bf16_f32 v53, v54, v55
	v_cvt_pk_bf16_f32 v34, v34, v35
	v_cvt_pk_bf16_f32 v35, v36, v37
	v_cvt_pk_bf16_f32 v18, v18, v19
	v_cvt_pk_bf16_f32 v19, v20, v21
	v_cvt_pk_bf16_f32 v2, v2, v3
	v_cvt_pk_bf16_f32 v3, v4, v5
	s_mulk_i32 s20, 0x1800
	s_mul_hi_u32 s2, s19, 0x1800
	ds_write2_b64 v49, v[50:51], v[52:53] offset0:4 offset1:6
	ds_write2_b64 v49, v[32:33], v[34:35] offset0:12 offset1:14
	ds_write2_b64 v49, v[16:17], v[18:19] offset0:20 offset1:22
	ds_write2_b64 v49, v[0:1], v[2:3] offset0:28 offset1:30
	s_add_i32 s2, s2, s20
	s_mulk_i32 s19, 0x1800
	s_waitcnt lgkmcnt(0)
	s_add_u32 s3, s4, s19
	v_add3_u32 v14, s7, v144, v196
	s_addc_u32 s10, s5, s2
	ds_read_b128 v[0:3], v14 offset:40960
	s_add_u32 s2, s3, s6
	s_addc_u32 s3, s10, 0
	v_mov_b32_e32 v159, 0
	ds_read_b128 v[4:7], v14 offset:42048
	v_lshl_add_u64 v[8:9], s[2:3], 0, v[158:159]
	v_mov_b32_e32 v147, v159
	v_lshl_add_u64 v[10:11], v[8:9], 0, v[146:147]
	s_movk_i32 s2, 0x6000
	s_waitcnt lgkmcnt(0)
	global_store_dwordx4 v[10:11], v[0:3], off
	v_mov_b32_e32 v149, v159
	v_mov_b32_e32 v153, v159
	v_add_co_u32_e32 v0, vcc, s2, v10
	s_mov_b32 s2, 0xc000
	s_nop 0
	v_addc_co_u32_e32 v1, vcc, 0, v11, vcc
	global_store_dwordx4 v[0:1], v[4:7], off
	ds_read_b128 v[0:3], v14 offset:43136
	ds_read_b128 v[4:7], v14 offset:44224
	v_add_co_u32_e32 v12, vcc, s2, v10
	s_mov_b32 s2, 0x12000
	s_nop 0
	v_addc_co_u32_e32 v13, vcc, 0, v11, vcc
	v_add_co_u32_e32 v10, vcc, s2, v10
	s_waitcnt lgkmcnt(0)
	global_store_dwordx4 v[12:13], v[0:3], off
	v_addc_co_u32_e32 v11, vcc, 0, v11, vcc
	ds_read_b128 v[0:3], v14 offset:45312
	global_store_dwordx4 v[10:11], v[4:7], off
	ds_read_b128 v[4:7], v14 offset:46400
	v_lshl_add_u64 v[10:11], v[8:9], 0, v[148:149]
	v_mov_b32_e32 v151, v159
	s_waitcnt lgkmcnt(0)
	global_store_dwordx4 v[10:11], v[0:3], off
	v_lshl_add_u64 v[10:11], v[8:9], 0, v[152:153]
	ds_read_b128 v[0:3], v14 offset:47488
	global_store_dwordx4 v[10:11], v[4:7], off
	ds_read_b128 v[4:7], v14 offset:48576
	v_lshl_add_u64 v[10:11], v[8:9], 0, v[150:151]
	v_mov_b32_e32 v155, v159
	v_readfirstlane_b32 s12, v222
	s_waitcnt lgkmcnt(0)
	global_store_dwordx4 v[10:11], v[0:3], off
	s_and_b32 s2, s12, 0xffffffc0
	s_nop 0
	v_lshl_add_u64 v[0:1], v[8:9], 0, v[154:155]
	global_store_dwordx4 v[0:1], v[4:7], off
	v_or_b32_e32 v0, s2, v197
	s_mov_b32 s2, 0x2aaaaaab
	v_mul_hi_i32 v1, v0, s2
	v_lshrrev_b32_e32 v2, 31, v1
	v_ashrrev_i32_e32 v1, 2, v1
	v_add_u32_e32 v2, v1, v2
	s_movk_i32 s2, 0xffe8
	v_lshrrev_b32_e32 v159, 1, v2
	v_mad_u64_u32 v[160:161], s[2:3], v2, s2, v[0:1]
	v_xor_b32_e32 v1, v159, v222
	v_bfi_b32 v1, -8, v160, v1
	v_cmp_lt_i32_e32 vcc, 15, v1
	v_add_u32_e32 v2, s8, v2
	s_and_saveexec_b64 s[2:3], vcc
	s_xor_b64 s[2:3], exec, s[2:3]
	v_mov_b32_e32 v3, 0xbfff80
	v_lshl_add_u32 v153, v2, 6, v3
	s_or_saveexec_b64 s[2:3], s[2:3]
	v_mov_b32_e32 v145, 0x1000
	s_xor_b64 exec, exec, s[2:3]
	v_lshl_or_b32 v2, v2, 11, s17
	v_add_u32_e32 v153, 0x8000000, v2
	v_mov_b32_e32 v145, 0x20000
	s_or_b64 exec, exec, s[2:3]
	v_add_u32_e32 v2, 0x200, v0
	s_mov_b32 s2, 0x2aaaaaab
	v_mul_hi_i32 v3, v2, s2
	v_lshrrev_b32_e32 v4, 31, v3
	v_ashrrev_i32_e32 v3, 2, v3
	v_add_u32_e32 v4, v3, v4
	s_movk_i32 s2, 0xffe8
	v_mad_u64_u32 v[162:163], s[2:3], v4, s2, v[2:3]
	v_lshrrev_b32_e32 v163, 1, v4
	v_xor_b32_e32 v3, v163, v222
	v_bfi_b32 v3, -8, v162, v3
	v_cmp_lt_i32_e32 vcc, 15, v3
	v_add_u32_e32 v4, s8, v4
	s_and_saveexec_b64 s[2:3], vcc
	s_xor_b64 s[2:3], exec, s[2:3]
	v_mov_b32_e32 v5, 0xbfff80
	v_lshl_add_u32 v155, v4, 6, v5
	s_or_saveexec_b64 s[2:3], s[2:3]
	v_mov_b32_e32 v147, 0x1000
	s_xor_b64 exec, exec, s[2:3]
	v_lshl_or_b32 v4, v4, 11, s17
	v_add_u32_e32 v155, 0x8000000, v4
	v_mov_b32_e32 v147, 0x20000
	s_or_b64 exec, exec, s[2:3]
	v_add_u32_e32 v4, 0x400, v0
	s_mov_b32 s2, 0x2aaaaaab
	v_mul_hi_i32 v5, v4, s2
	v_lshrrev_b32_e32 v6, 31, v5
	v_ashrrev_i32_e32 v5, 2, v5
	v_add_u32_e32 v5, v5, v6
	s_movk_i32 s2, 0xffe8
	v_mad_u64_u32 v[164:165], s[2:3], v5, s2, v[4:5]
	v_lshrrev_b32_e32 v165, 1, v5
	v_xor_b32_e32 v4, v165, v222
	v_bfi_b32 v4, -8, v164, v4
	v_cmp_lt_i32_e32 vcc, 15, v4
	v_add_u32_e32 v5, s8, v5
	s_and_saveexec_b64 s[2:3], vcc
	s_xor_b64 s[2:3], exec, s[2:3]
	v_mov_b32_e32 v6, 0xbfff80
	v_lshl_add_u32 v161, v5, 6, v6
	s_or_saveexec_b64 s[2:3], s[2:3]
	v_mov_b32_e32 v149, 0x1000
	s_xor_b64 exec, exec, s[2:3]
	v_lshl_or_b32 v5, v5, 11, s17
	v_add_u32_e32 v161, 0x8000000, v5
	v_mov_b32_e32 v149, 0x20000
	s_or_b64 exec, exec, s[2:3]
	s_lshr_b32 s21, s12, 6
	s_or_b32 s22, s16, 0x800
	s_lshl_b32 s23, s21, 5
	s_or_b32 s2, s8, s22
	s_add_u32 s19, s2, s23
	v_or_b32_e32 v5, s19, v194
	s_movk_i32 s2, 0x1800
	v_mov_b64_e32 v[6:7], s[4:5]
	s_addc_u32 s20, s9, 0
	v_mad_u64_u32 v[6:7], s[2:3], v5, s2, v[6:7]
	v_mov_b32_e32 v5, 0x1800
	s_mov_b32 s7, 0
	v_mad_i32_i24 v7, s20, v5, v7
	v_lshl_add_u32 v8, v1, 3, v153
	v_ashrrev_i32_e32 v1, 31, v0
	v_lshl_add_u64 v[6:7], v[6:7], 0, s[6:7]
	v_mov_b32_e32 v157, 0
	v_lshrrev_b32_e32 v10, 28, v1
	v_lshl_add_u64 v[6:7], v[6:7], 0, v[156:157]
	v_lshl_add_u32 v4, v4, 3, v161
	v_mov_b32_e32 v5, v157
	v_add_u32_e32 v16, v0, v10
	global_load_dwordx4 v[96:99], v[6:7], off
	global_load_dwordx4 v[100:103], v[6:7], off offset:32
	global_load_dwordx4 v[104:107], v[6:7], off offset:64
	global_load_dwordx4 v[108:111], v[6:7], off offset:96
	global_load_dwordx4 v[112:115], v[6:7], off offset:128
	global_load_dwordx4 v[116:119], v[6:7], off offset:160
	global_load_dwordx4 v[120:123], v[6:7], off offset:192
	global_load_dwordx4 v[124:127], v[6:7], off offset:224
	global_load_dwordx4 v[128:131], v[6:7], off offset:256
	global_load_dwordx4 v[132:135], v[6:7], off offset:288
	global_load_dwordx4 v[136:139], v[6:7], off offset:320
	global_load_dwordx4 v[140:143], v[6:7], off offset:352
	v_lshl_add_u32 v6, v3, 3, v155
	v_ashrrev_i32_e32 v3, 31, v2
	v_lshl_add_u64 v[14:15], v[4:5], 1, s[84:85]
	v_ashrrev_i32_e32 v167, 4, v16
	v_and_b32_e32 v5, 0x1ffffff0, v16
	v_lshrrev_b32_e32 v11, 28, v3
	v_mov_b32_e32 v9, v157
	s_lshl_b32 s2, s21, 10
	v_sub_u32_e32 v0, v0, v5
	v_lshlrev_b32_e32 v5, 2, v167
	v_mov_b32_e32 v7, v157
	v_add_u32_e32 v17, v2, v11
	v_lshl_add_u64 v[10:11], v[8:9], 1, s[84:85]
	v_bfe_u32 v9, v167, 2, 2
	s_add_i32 s7, s2, 0
	v_and_b32_e32 v5, 12, v5
	v_lshl_add_u64 v[12:13], v[6:7], 1, s[84:85]
	v_ashrrev_i32_e32 v166, 4, v17
	v_and_b32_e32 v7, 0x1ffffff0, v17
	v_bitop3_b32 v0, v5, v0, v9 bitop3:0x36
	s_mov_b32 m0, s7
	v_add_lshl_u32 v16, v167, s8, 11
	v_sub_u32_e32 v2, v2, v7
	v_lshlrev_b32_e32 v7, 2, v166
	global_load_lds_dwordx4 v[10:11], off
	s_add_i32 m0, s7, 0x2000
	v_lshlrev_b32_e32 v168, 3, v0
	v_mov_b32_e32 v1, v157
	v_bfe_u32 v17, v166, 2, 2
	v_and_b32_e32 v7, 12, v7
	global_load_lds_dwordx4 v[12:13], off
	s_add_i32 m0, s7, 0x4000
	v_add3_u32 v0, s18, v16, v168
	v_bitop3_b32 v2, v7, v2, v17 bitop3:0x36
	global_load_lds_dwordx4 v[14:15], off
	s_add_i32 m0, s7, 0x6000
	v_lshl_add_u64 v[10:11], v[0:1], 1, s[84:85]
	v_add_lshl_u32 v18, v166, s8, 11
	v_lshlrev_b32_e32 v169, 3, v2
	global_load_lds_dwordx4 v[10:11], off
	s_add_i32 m0, s7, 0x8000
	v_mov_b32_e32 v3, v157
	v_add3_u32 v2, s18, v18, v169
	s_cmpk_gt_u32 s12, 0xff
	v_lshl_add_u64 v[12:13], v[2:3], 1, s[84:85]
	s_cselect_b64 s[10:11], -1, 0
	s_cmpk_lt_u32 s12, 0x100
	v_add_u32_e32 v8, v8, v145
	v_mov_b32_e32 v9, v157
	global_load_lds_dwordx4 v[12:13], off
	s_cselect_b64 s[12:13], -1, 0
	s_add_i32 m0, s7, 0xa000
	v_lshl_add_u64 v[8:9], v[8:9], 1, s[84:85]
	v_add_u32_e32 v6, v6, v147
	v_mov_b32_e32 v7, v157
	s_waitcnt vmcnt(0) lgkmcnt(0)
	s_barrier
	s_waitcnt vmcnt(0)
	global_load_lds_dwordx4 v[8:9], off
	v_lshl_add_u64 v[6:7], v[6:7], 1, s[84:85]
	s_add_i32 m0, s7, 0xc000
	v_add_u32_e32 v4, v4, v149
	v_mov_b32_e32 v5, v157
	global_load_lds_dwordx4 v[6:7], off
	v_lshl_add_u64 v[4:5], v[4:5], 1, s[84:85]
	s_add_i32 m0, s7, 0xe000
	v_add_u32_e32 v0, 0x20000, v0
	v_mov_b32_e32 v1, v157
	global_load_lds_dwordx4 v[4:5], off
	s_add_i32 m0, s7, 0x10000
	v_lshl_add_u64 v[0:1], v[0:1], 1, s[84:85]
	global_load_lds_dwordx4 v[0:1], off
	v_add_u32_e32 v0, 0x20000, v2
	v_mov_b32_e32 v1, v157
	v_lshl_add_u64 v[0:1], v[0:1], 1, s[84:85]
	s_add_i32 m0, s7, 0x12000
	s_and_b64 vcc, exec, s[12:13]
	global_load_lds_dwordx4 v[0:1], off
	ds_read_b128 v[0:3], v190
	ds_read_b128 v[4:7], v191
	ds_read_b128 v[8:11], v192
	ds_read_b128 v[12:15], v193
	s_waitcnt lgkmcnt(0)
	v_mfma_f32_32x32x16_bf16 v[48:63], v[0:3], v[96:99], 0
	ds_read_b128 v[0:3], v190 offset:128
	v_mfma_f32_32x32x16_bf16 v[48:63], v[4:7], v[100:103], v[48:63]
	ds_read_b128 v[4:7], v191 offset:128
	v_mfma_f32_32x32x16_bf16 v[48:63], v[8:11], v[104:107], v[48:63]
	ds_read_b128 v[8:11], v192 offset:128
	v_mfma_f32_32x32x16_bf16 v[48:63], v[12:15], v[108:111], v[48:63]
	ds_read_b128 v[12:15], v193 offset:128
	s_waitcnt lgkmcnt(0)
	v_mfma_f32_32x32x16_bf16 v[48:63], v[0:3], v[112:115], v[48:63]
	ds_read_b128 v[0:3], v190 offset:256
	v_mfma_f32_32x32x16_bf16 v[48:63], v[4:7], v[116:119], v[48:63]
	ds_read_b128 v[4:7], v191 offset:256
	v_mfma_f32_32x32x16_bf16 v[48:63], v[8:11], v[120:123], v[48:63]
	ds_read_b128 v[8:11], v192 offset:256
	v_mfma_f32_32x32x16_bf16 v[48:63], v[12:15], v[124:127], v[48:63]
	ds_read_b128 v[12:15], v193 offset:256
	s_waitcnt lgkmcnt(0)
	v_mfma_f32_32x32x16_bf16 v[48:63], v[0:3], v[128:131], v[48:63]
	ds_read_b128 v[0:3], v190 offset:12288
	v_mfma_f32_32x32x16_bf16 v[48:63], v[4:7], v[132:135], v[48:63]
	ds_read_b128 v[4:7], v191 offset:12288
	v_mfma_f32_32x32x16_bf16 v[48:63], v[8:11], v[136:139], v[48:63]
	ds_read_b128 v[8:11], v192 offset:12288
	s_waitcnt lgkmcnt(0)
	v_mfma_f32_32x32x16_bf16 v[80:95], v[0:3], v[96:99], 0
	ds_read_b128 v[16:19], v193 offset:12288
	v_mfma_f32_32x32x16_bf16 v[80:95], v[4:7], v[100:103], v[80:95]
	ds_read_b128 v[20:23], v190 offset:12416
	v_mfma_f32_32x32x16_bf16 v[80:95], v[8:11], v[104:107], v[80:95]
	ds_read_b128 v[24:27], v191 offset:12416
	s_waitcnt lgkmcnt(0)
	v_mfma_f32_32x32x16_bf16 v[80:95], v[16:19], v[108:111], v[80:95]
	ds_read_b128 v[28:31], v192 offset:12416
	v_mfma_f32_32x32x16_bf16 v[80:95], v[20:23], v[112:115], v[80:95]
	ds_read_b128 v[32:35], v193 offset:12416
	v_mfma_f32_32x32x16_bf16 v[80:95], v[24:27], v[116:119], v[80:95]
	ds_read_b128 v[36:39], v190 offset:12544
	s_waitcnt lgkmcnt(0)
	v_mfma_f32_32x32x16_bf16 v[80:95], v[28:31], v[120:123], v[80:95]
	ds_read_b128 v[40:43], v191 offset:12544
	v_mfma_f32_32x32x16_bf16 v[80:95], v[32:35], v[124:127], v[80:95]
	ds_read_b128 v[44:47], v192 offset:12544
	v_mfma_f32_32x32x16_bf16 v[80:95], v[36:39], v[128:131], v[80:95]
	ds_read_b128 v[64:67], v193 offset:12544
	s_waitcnt lgkmcnt(0)
	v_mfma_f32_32x32x16_bf16 v[80:95], v[40:43], v[132:135], v[80:95]
	v_mfma_f32_32x32x16_bf16 v[80:95], v[44:47], v[136:139], v[80:95]
	v_mfma_f32_32x32x16_bf16 v[80:95], v[64:67], v[140:143], v[80:95]
	v_mfma_f32_32x32x16_bf16 v[48:63], v[12:15], v[140:143], v[48:63]
	s_cbranch_vccnz .LBB0_1979
	s_waitcnt vmcnt(0) lgkmcnt(0)
	s_barrier

.LBB0_1999:
	s_setprio 0
	v_mov_b32_e32 v48, v157
	s_nop 1
	v_permlane32_swap_b32_e32 v157, v48
	v_add_f32_e32 v48, v157, v48
	v_div_scale_f32 v49, s[2:3], v48, v48, 1.0
	v_rcp_f32_e32 v50, v49
	s_mulk_i32 s21, 0x2200
	s_add_i32 s7, s21, 0
	s_waitcnt vmcnt(0) lgkmcnt(0)
	s_barrier
	v_fma_f32 v51, -v49, v50, 1.0
	v_fmac_f32_e32 v50, v51, v50
	v_div_scale_f32 v51, vcc, 1.0, v48, 1.0
	v_mul_f32_e32 v52, v51, v50
	v_fma_f32 v53, -v49, v52, v51
	v_fmac_f32_e32 v52, v53, v50
	v_fma_f32 v49, -v49, v52, v51
	v_div_fmas_f32 v49, v49, v50, v52
	v_div_fixup_f32 v48, v49, v48, 1.0
	v_add3_u32 v49, s7, v195, v181
	v_pk_mul_f32 v[50:51], v[64:65], v[48:49] op_sel_hi:[1,0]
	v_pk_mul_f32 v[52:53], v[66:67], v[48:49] op_sel_hi:[1,0]
	v_cvt_pk_bf16_f32 v50, v50, v51
	v_cvt_pk_bf16_f32 v51, v52, v53
	v_pk_mul_f32 v[52:53], v[68:69], v[48:49] op_sel_hi:[1,0]
	v_pk_mul_f32 v[54:55], v[70:71], v[48:49] op_sel_hi:[1,0]
	v_add_u32_e32 v49, 0xa000, v49
	v_pk_mul_f32 v[32:33], v[32:33], v[48:49] op_sel_hi:[1,0]
	v_pk_mul_f32 v[34:35], v[34:35], v[48:49] op_sel_hi:[1,0]
	v_pk_mul_f32 v[16:17], v[16:17], v[48:49] op_sel_hi:[1,0]
	v_pk_mul_f32 v[18:19], v[18:19], v[48:49] op_sel_hi:[1,0]
	v_pk_mul_f32 v[0:1], v[0:1], v[48:49] op_sel_hi:[1,0]
	v_pk_mul_f32 v[2:3], v[2:3], v[48:49] op_sel_hi:[1,0]
	v_cvt_pk_bf16_f32 v32, v32, v33
	v_cvt_pk_bf16_f32 v33, v34, v35
	v_pk_mul_f32 v[34:35], v[36:37], v[48:49] op_sel_hi:[1,0]
	v_pk_mul_f32 v[36:37], v[38:39], v[48:49] op_sel_hi:[1,0]
	v_cvt_pk_bf16_f32 v16, v16, v17
	v_cvt_pk_bf16_f32 v17, v18, v19
	v_pk_mul_f32 v[18:19], v[20:21], v[48:49] op_sel_hi:[1,0]
	v_pk_mul_f32 v[20:21], v[22:23], v[48:49] op_sel_hi:[1,0]
	v_cvt_pk_bf16_f32 v0, v0, v1
	v_cvt_pk_bf16_f32 v1, v2, v3
	v_pk_mul_f32 v[2:3], v[4:5], v[48:49] op_sel_hi:[1,0]
	v_pk_mul_f32 v[4:5], v[6:7], v[48:49] op_sel_hi:[1,0]
	v_cvt_pk_bf16_f32 v52, v52, v53
	v_cvt_pk_bf16_f32 v53, v54, v55
	v_cvt_pk_bf16_f32 v34, v34, v35
	v_cvt_pk_bf16_f32 v35, v36, v37
	v_cvt_pk_bf16_f32 v18, v18, v19
	v_cvt_pk_bf16_f32 v19, v20, v21
	v_cvt_pk_bf16_f32 v2, v2, v3
	v_cvt_pk_bf16_f32 v3, v4, v5
	ds_write2_b64 v49, v[50:51], v[52:53] offset1:2
	v_pk_mul_f32 v[50:51], v[72:73], v[48:49] op_sel_hi:[1,0]
	v_pk_mul_f32 v[52:53], v[74:75], v[48:49] op_sel_hi:[1,0]
	ds_write2_b64 v49, v[32:33], v[34:35] offset0:8 offset1:10
	v_pk_mul_f32 v[32:33], v[40:41], v[48:49] op_sel_hi:[1,0]
	v_pk_mul_f32 v[34:35], v[42:43], v[48:49] op_sel_hi:[1,0]
	ds_write2_b64 v49, v[16:17], v[18:19] offset0:16 offset1:18
	v_pk_mul_f32 v[16:17], v[24:25], v[48:49] op_sel_hi:[1,0]
	v_pk_mul_f32 v[18:19], v[26:27], v[48:49] op_sel_hi:[1,0]
	ds_write2_b64 v49, v[0:1], v[2:3] offset0:24 offset1:26
	v_pk_mul_f32 v[0:1], v[8:9], v[48:49] op_sel_hi:[1,0]
	v_pk_mul_f32 v[2:3], v[10:11], v[48:49] op_sel_hi:[1,0]
	v_cvt_pk_bf16_f32 v50, v50, v51
	v_cvt_pk_bf16_f32 v51, v52, v53
	v_pk_mul_f32 v[52:53], v[76:77], v[48:49] op_sel_hi:[1,0]
	v_pk_mul_f32 v[54:55], v[78:79], v[48:49] op_sel_hi:[1,0]
	v_cvt_pk_bf16_f32 v32, v32, v33
	v_cvt_pk_bf16_f32 v33, v34, v35
	v_pk_mul_f32 v[34:35], v[44:45], v[48:49] op_sel_hi:[1,0]
	v_pk_mul_f32 v[36:37], v[46:47], v[48:49] op_sel_hi:[1,0]
	v_cvt_pk_bf16_f32 v16, v16, v17
	v_cvt_pk_bf16_f32 v17, v18, v19
	v_pk_mul_f32 v[18:19], v[28:29], v[48:49] op_sel_hi:[1,0]
	v_pk_mul_f32 v[20:21], v[30:31], v[48:49] op_sel_hi:[1,0]
	v_cvt_pk_bf16_f32 v0, v0, v1
	v_cvt_pk_bf16_f32 v1, v2, v3
	v_pk_mul_f32 v[2:3], v[12:13], v[48:49] op_sel_hi:[1,0]
	v_pk_mul_f32 v[4:5], v[14:15], v[48:49] op_sel_hi:[1,0]
	v_cvt_pk_bf16_f32 v52, v52, v53
	v_cvt_pk_bf16_f32 v53, v54, v55
	v_cvt_pk_bf16_f32 v34, v34, v35
	v_cvt_pk_bf16_f32 v35, v36, v37
	v_cvt_pk_bf16_f32 v18, v18, v19
	v_cvt_pk_bf16_f32 v19, v20, v21
	v_cvt_pk_bf16_f32 v2, v2, v3
	v_cvt_pk_bf16_f32 v3, v4, v5
	s_mulk_i32 s20, 0x1800
	s_mul_hi_u32 s2, s19, 0x1800
	ds_write2_b64 v49, v[50:51], v[52:53] offset0:4 offset1:6
	ds_write2_b64 v49, v[32:33], v[34:35] offset0:12 offset1:14
	ds_write2_b64 v49, v[16:17], v[18:19] offset0:20 offset1:22
	ds_write2_b64 v49, v[0:1], v[2:3] offset0:28 offset1:30
	s_add_i32 s2, s2, s20
	s_mulk_i32 s19, 0x1800
	s_waitcnt lgkmcnt(0)
	s_add_u32 s3, s4, s19
	v_add3_u32 v14, s7, v144, v196
	s_addc_u32 s10, s5, s2
	ds_read_b128 v[0:3], v14 offset:40960
	s_add_u32 s2, s3, s6
	s_addc_u32 s3, s10, 0
	v_mov_b32_e32 v159, 0
	ds_read_b128 v[4:7], v14 offset:42048
	v_lshl_add_u64 v[8:9], s[2:3], 0, v[158:159]
	v_mov_b32_e32 v147, v159
	v_lshl_add_u64 v[10:11], v[8:9], 0, v[146:147]
	s_movk_i32 s2, 0x6000
	s_waitcnt lgkmcnt(0)
	global_store_dwordx4 v[10:11], v[0:3], off
	v_mov_b32_e32 v149, v159
	v_mov_b32_e32 v153, v159
	v_add_co_u32_e32 v0, vcc, s2, v10
	s_mov_b32 s2, 0xc000
	s_nop 0
	v_addc_co_u32_e32 v1, vcc, 0, v11, vcc
	global_store_dwordx4 v[0:1], v[4:7], off
	ds_read_b128 v[0:3], v14 offset:43136
	ds_read_b128 v[4:7], v14 offset:44224
	v_add_co_u32_e32 v12, vcc, s2, v10
	s_mov_b32 s2, 0x12000
	s_nop 0
	v_addc_co_u32_e32 v13, vcc, 0, v11, vcc
	v_add_co_u32_e32 v10, vcc, s2, v10
	s_waitcnt lgkmcnt(0)
	global_store_dwordx4 v[12:13], v[0:3], off
	v_addc_co_u32_e32 v11, vcc, 0, v11, vcc
	ds_read_b128 v[0:3], v14 offset:45312
	global_store_dwordx4 v[10:11], v[4:7], off
	ds_read_b128 v[4:7], v14 offset:46400
	v_lshl_add_u64 v[10:11], v[8:9], 0, v[148:149]
	v_mov_b32_e32 v151, v159
	s_waitcnt lgkmcnt(0)
	global_store_dwordx4 v[10:11], v[0:3], off
	v_lshl_add_u64 v[10:11], v[8:9], 0, v[152:153]
	ds_read_b128 v[0:3], v14 offset:47488
	global_store_dwordx4 v[10:11], v[4:7], off
	ds_read_b128 v[4:7], v14 offset:48576
	v_lshl_add_u64 v[10:11], v[8:9], 0, v[150:151]
	v_mov_b32_e32 v155, v159
	v_readfirstlane_b32 s12, v222
	s_waitcnt lgkmcnt(0)
	global_store_dwordx4 v[10:11], v[0:3], off
	s_and_b32 s2, s12, 0xffffffc0
	s_nop 0
	v_lshl_add_u64 v[0:1], v[8:9], 0, v[154:155]
	global_store_dwordx4 v[0:1], v[4:7], off
	v_or_b32_e32 v0, s2, v197
	s_mov_b32 s2, 0x2aaaaaab
	v_mul_hi_i32 v1, v0, s2
	v_lshrrev_b32_e32 v2, 31, v1
	v_ashrrev_i32_e32 v1, 2, v1
	v_add_u32_e32 v2, v1, v2
	s_movk_i32 s2, 0xffe8
	v_lshrrev_b32_e32 v159, 1, v2
	v_mad_u64_u32 v[160:161], s[2:3], v2, s2, v[0:1]
	v_xor_b32_e32 v1, v159, v222
	v_bfi_b32 v1, -8, v160, v1
	v_cmp_lt_i32_e32 vcc, 15, v1
	v_add_u32_e32 v2, s8, v2
	s_and_saveexec_b64 s[2:3], vcc
	s_xor_b64 s[2:3], exec, s[2:3]
	v_mov_b32_e32 v3, 0xbfff80
	v_lshl_add_u32 v153, v2, 6, v3
	s_or_saveexec_b64 s[2:3], s[2:3]
	v_mov_b32_e32 v145, 0x1000
	s_xor_b64 exec, exec, s[2:3]
	v_lshl_or_b32 v2, v2, 11, s17
	v_add_u32_e32 v153, 0x8000000, v2
	v_mov_b32_e32 v145, 0x20000
	s_or_b64 exec, exec, s[2:3]
	v_add_u32_e32 v2, 0x200, v0
	s_mov_b32 s2, 0x2aaaaaab
	v_mul_hi_i32 v3, v2, s2
	v_lshrrev_b32_e32 v4, 31, v3
	v_ashrrev_i32_e32 v3, 2, v3
	v_add_u32_e32 v4, v3, v4
	s_movk_i32 s2, 0xffe8
	v_mad_u64_u32 v[162:163], s[2:3], v4, s2, v[2:3]
	v_lshrrev_b32_e32 v163, 1, v4
	v_xor_b32_e32 v3, v163, v222
	v_bfi_b32 v3, -8, v162, v3
	v_cmp_lt_i32_e32 vcc, 15, v3
	v_add_u32_e32 v4, s8, v4
	s_and_saveexec_b64 s[2:3], vcc
	s_xor_b64 s[2:3], exec, s[2:3]
	v_mov_b32_e32 v5, 0xbfff80
	v_lshl_add_u32 v155, v4, 6, v5
	s_or_saveexec_b64 s[2:3], s[2:3]
	v_mov_b32_e32 v147, 0x1000
	s_xor_b64 exec, exec, s[2:3]
	v_lshl_or_b32 v4, v4, 11, s17
	v_add_u32_e32 v155, 0x8000000, v4
	v_mov_b32_e32 v147, 0x20000
	s_or_b64 exec, exec, s[2:3]
	v_add_u32_e32 v4, 0x400, v0
	s_mov_b32 s2, 0x2aaaaaab
	v_mul_hi_i32 v5, v4, s2
	v_lshrrev_b32_e32 v6, 31, v5
	v_ashrrev_i32_e32 v5, 2, v5
	v_add_u32_e32 v5, v5, v6
	s_movk_i32 s2, 0xffe8
	v_mad_u64_u32 v[164:165], s[2:3], v5, s2, v[4:5]
	v_lshrrev_b32_e32 v165, 1, v5
	v_xor_b32_e32 v4, v165, v222
	v_bfi_b32 v4, -8, v164, v4
	v_cmp_lt_i32_e32 vcc, 15, v4
	v_add_u32_e32 v5, s8, v5
	s_and_saveexec_b64 s[2:3], vcc
	s_xor_b64 s[2:3], exec, s[2:3]
	v_mov_b32_e32 v6, 0xbfff80
	v_lshl_add_u32 v161, v5, 6, v6
	s_or_saveexec_b64 s[2:3], s[2:3]
	v_mov_b32_e32 v149, 0x1000
	s_xor_b64 exec, exec, s[2:3]
	v_lshl_or_b32 v5, v5, 11, s17
	v_add_u32_e32 v161, 0x8000000, v5
	v_mov_b32_e32 v149, 0x20000
	s_or_b64 exec, exec, s[2:3]
	s_lshr_b32 s21, s12, 6
	s_xor_b32 s22, s16, 0x700
	s_lshl_b32 s23, s21, 5
	s_or_b32 s2, s8, s22
	s_add_u32 s19, s2, s23
	v_or_b32_e32 v5, s19, v194
	s_movk_i32 s2, 0x1800
	v_mov_b64_e32 v[6:7], s[4:5]
	s_addc_u32 s20, s9, 0
	v_mad_u64_u32 v[6:7], s[2:3], v5, s2, v[6:7]
	v_mov_b32_e32 v5, 0x1800
	s_mov_b32 s7, 0
	v_mad_i32_i24 v7, s20, v5, v7
	v_lshl_add_u32 v8, v1, 3, v153
	v_ashrrev_i32_e32 v1, 31, v0
	v_lshl_add_u64 v[6:7], v[6:7], 0, s[6:7]
	v_mov_b32_e32 v157, 0
	v_lshrrev_b32_e32 v10, 28, v1
	v_lshl_add_u64 v[6:7], v[6:7], 0, v[156:157]
	v_lshl_add_u32 v4, v4, 3, v161
	v_mov_b32_e32 v5, v157
	v_add_u32_e32 v16, v0, v10
	global_load_dwordx4 v[96:99], v[6:7], off
	global_load_dwordx4 v[100:103], v[6:7], off offset:32
	global_load_dwordx4 v[104:107], v[6:7], off offset:64
	global_load_dwordx4 v[108:111], v[6:7], off offset:96
	global_load_dwordx4 v[112:115], v[6:7], off offset:128
	global_load_dwordx4 v[116:119], v[6:7], off offset:160
	global_load_dwordx4 v[120:123], v[6:7], off offset:192
	global_load_dwordx4 v[124:127], v[6:7], off offset:224
	global_load_dwordx4 v[128:131], v[6:7], off offset:256
	global_load_dwordx4 v[132:135], v[6:7], off offset:288
	global_load_dwordx4 v[136:139], v[6:7], off offset:320
	global_load_dwordx4 v[140:143], v[6:7], off offset:352
	v_lshl_add_u32 v6, v3, 3, v155
	v_ashrrev_i32_e32 v3, 31, v2
	v_lshl_add_u64 v[14:15], v[4:5], 1, s[84:85]
	v_ashrrev_i32_e32 v167, 4, v16
	v_and_b32_e32 v5, 0x1ffffff0, v16
	v_lshrrev_b32_e32 v11, 28, v3
	v_mov_b32_e32 v9, v157
	s_lshl_b32 s2, s21, 10
	v_sub_u32_e32 v0, v0, v5
	v_lshlrev_b32_e32 v5, 2, v167
	v_mov_b32_e32 v7, v157
	v_add_u32_e32 v17, v2, v11
	v_lshl_add_u64 v[10:11], v[8:9], 1, s[84:85]
	v_bfe_u32 v9, v167, 2, 2
	s_add_i32 s7, s2, 0
	v_and_b32_e32 v5, 12, v5
	v_lshl_add_u64 v[12:13], v[6:7], 1, s[84:85]
	v_ashrrev_i32_e32 v166, 4, v17
	v_and_b32_e32 v7, 0x1ffffff0, v17
	v_bitop3_b32 v0, v5, v0, v9 bitop3:0x36
	s_mov_b32 m0, s7
	v_add_lshl_u32 v16, v167, s8, 11
	v_sub_u32_e32 v2, v2, v7
	v_lshlrev_b32_e32 v7, 2, v166
	global_load_lds_dwordx4 v[10:11], off
	s_add_i32 m0, s7, 0x2000
	v_lshlrev_b32_e32 v168, 3, v0
	v_mov_b32_e32 v1, v157
	v_bfe_u32 v17, v166, 2, 2
	v_and_b32_e32 v7, 12, v7
	global_load_lds_dwordx4 v[12:13], off
	s_add_i32 m0, s7, 0x4000
	v_add3_u32 v0, s18, v16, v168
	v_bitop3_b32 v2, v7, v2, v17 bitop3:0x36
	global_load_lds_dwordx4 v[14:15], off
	s_add_i32 m0, s7, 0x6000
	v_lshl_add_u64 v[10:11], v[0:1], 1, s[84:85]
	v_add_lshl_u32 v18, v166, s8, 11
	v_lshlrev_b32_e32 v169, 3, v2
	global_load_lds_dwordx4 v[10:11], off
	s_add_i32 m0, s7, 0x8000
	v_mov_b32_e32 v3, v157
	v_add3_u32 v2, s18, v18, v169
	s_cmpk_gt_u32 s12, 0xff
	v_lshl_add_u64 v[12:13], v[2:3], 1, s[84:85]
	s_cselect_b64 s[10:11], -1, 0
	s_cmpk_lt_u32 s12, 0x100
	v_add_u32_e32 v8, v8, v145
	v_mov_b32_e32 v9, v157
	global_load_lds_dwordx4 v[12:13], off
	s_cselect_b64 s[12:13], -1, 0
	s_add_i32 m0, s7, 0xa000
	v_lshl_add_u64 v[8:9], v[8:9], 1, s[84:85]
	v_add_u32_e32 v6, v6, v147
	v_mov_b32_e32 v7, v157
	s_waitcnt vmcnt(0) lgkmcnt(0)
	s_barrier
	s_waitcnt vmcnt(0)
	global_load_lds_dwordx4 v[8:9], off
	v_lshl_add_u64 v[6:7], v[6:7], 1, s[84:85]
	s_add_i32 m0, s7, 0xc000
	v_add_u32_e32 v4, v4, v149
	v_mov_b32_e32 v5, v157
	global_load_lds_dwordx4 v[6:7], off
	v_lshl_add_u64 v[4:5], v[4:5], 1, s[84:85]
	s_add_i32 m0, s7, 0xe000
	v_add_u32_e32 v0, 0x20000, v0
	v_mov_b32_e32 v1, v157
	global_load_lds_dwordx4 v[4:5], off
	s_add_i32 m0, s7, 0x10000
	v_lshl_add_u64 v[0:1], v[0:1], 1, s[84:85]
	global_load_lds_dwordx4 v[0:1], off
	v_add_u32_e32 v0, 0x20000, v2
	v_mov_b32_e32 v1, v157
	v_lshl_add_u64 v[0:1], v[0:1], 1, s[84:85]
	s_add_i32 m0, s7, 0x12000
	s_and_b64 vcc, exec, s[12:13]
	global_load_lds_dwordx4 v[0:1], off
	ds_read_b128 v[0:3], v190
	ds_read_b128 v[4:7], v191
	ds_read_b128 v[8:11], v192
	ds_read_b128 v[12:15], v193
	s_waitcnt lgkmcnt(0)
	v_mfma_f32_32x32x16_bf16 v[48:63], v[0:3], v[96:99], 0
	ds_read_b128 v[0:3], v190 offset:128
	v_mfma_f32_32x32x16_bf16 v[48:63], v[4:7], v[100:103], v[48:63]
	ds_read_b128 v[4:7], v191 offset:128
	v_mfma_f32_32x32x16_bf16 v[48:63], v[8:11], v[104:107], v[48:63]
	ds_read_b128 v[8:11], v192 offset:128
	v_mfma_f32_32x32x16_bf16 v[48:63], v[12:15], v[108:111], v[48:63]
	ds_read_b128 v[12:15], v193 offset:128
	s_waitcnt lgkmcnt(0)
	v_mfma_f32_32x32x16_bf16 v[48:63], v[0:3], v[112:115], v[48:63]
	ds_read_b128 v[0:3], v190 offset:256
	v_mfma_f32_32x32x16_bf16 v[48:63], v[4:7], v[116:119], v[48:63]
	ds_read_b128 v[4:7], v191 offset:256
	v_mfma_f32_32x32x16_bf16 v[48:63], v[8:11], v[120:123], v[48:63]
	ds_read_b128 v[8:11], v192 offset:256
	v_mfma_f32_32x32x16_bf16 v[48:63], v[12:15], v[124:127], v[48:63]
	ds_read_b128 v[12:15], v193 offset:256
	s_waitcnt lgkmcnt(0)
	v_mfma_f32_32x32x16_bf16 v[48:63], v[0:3], v[128:131], v[48:63]
	ds_read_b128 v[0:3], v190 offset:12288
	v_mfma_f32_32x32x16_bf16 v[48:63], v[4:7], v[132:135], v[48:63]
	ds_read_b128 v[4:7], v191 offset:12288
	v_mfma_f32_32x32x16_bf16 v[48:63], v[8:11], v[136:139], v[48:63]
	ds_read_b128 v[8:11], v192 offset:12288
	s_waitcnt lgkmcnt(0)
	v_mfma_f32_32x32x16_bf16 v[80:95], v[0:3], v[96:99], 0
	ds_read_b128 v[16:19], v193 offset:12288
	v_mfma_f32_32x32x16_bf16 v[80:95], v[4:7], v[100:103], v[80:95]
	ds_read_b128 v[20:23], v190 offset:12416
	v_mfma_f32_32x32x16_bf16 v[80:95], v[8:11], v[104:107], v[80:95]
	ds_read_b128 v[24:27], v191 offset:12416
	s_waitcnt lgkmcnt(0)
	v_mfma_f32_32x32x16_bf16 v[80:95], v[16:19], v[108:111], v[80:95]
	ds_read_b128 v[28:31], v192 offset:12416
	v_mfma_f32_32x32x16_bf16 v[80:95], v[20:23], v[112:115], v[80:95]
	ds_read_b128 v[32:35], v193 offset:12416
	v_mfma_f32_32x32x16_bf16 v[80:95], v[24:27], v[116:119], v[80:95]
	ds_read_b128 v[36:39], v190 offset:12544
	s_waitcnt lgkmcnt(0)
	v_mfma_f32_32x32x16_bf16 v[80:95], v[28:31], v[120:123], v[80:95]
	ds_read_b128 v[40:43], v191 offset:12544
	v_mfma_f32_32x32x16_bf16 v[80:95], v[32:35], v[124:127], v[80:95]
	ds_read_b128 v[44:47], v192 offset:12544
	v_mfma_f32_32x32x16_bf16 v[80:95], v[36:39], v[128:131], v[80:95]
	ds_read_b128 v[64:67], v193 offset:12544
	s_waitcnt lgkmcnt(0)
	v_mfma_f32_32x32x16_bf16 v[80:95], v[40:43], v[132:135], v[80:95]
	v_mfma_f32_32x32x16_bf16 v[80:95], v[44:47], v[136:139], v[80:95]
	v_mfma_f32_32x32x16_bf16 v[80:95], v[64:67], v[140:143], v[80:95]
	v_mfma_f32_32x32x16_bf16 v[48:63], v[12:15], v[140:143], v[48:63]
	s_cbranch_vccnz .LBB0_2013
	s_waitcnt vmcnt(0) lgkmcnt(0)
	s_barrier

.LBB0_2033:
	s_setprio 0
	v_mov_b32_e32 v48, v157
	s_nop 1
	v_permlane32_swap_b32_e32 v157, v48
	v_add_f32_e32 v48, v157, v48
	v_div_scale_f32 v49, s[2:3], v48, v48, 1.0
	v_rcp_f32_e32 v50, v49
	s_mulk_i32 s21, 0x2200
	s_add_i32 s7, s21, 0
	s_waitcnt vmcnt(0) lgkmcnt(0)
	s_barrier
	v_fma_f32 v51, -v49, v50, 1.0
	v_fmac_f32_e32 v50, v51, v50
	v_div_scale_f32 v51, vcc, 1.0, v48, 1.0
	v_mul_f32_e32 v52, v51, v50
	v_fma_f32 v53, -v49, v52, v51
	v_fmac_f32_e32 v52, v53, v50
	v_fma_f32 v49, -v49, v52, v51
	v_div_fmas_f32 v49, v49, v50, v52
	v_div_fixup_f32 v48, v49, v48, 1.0
	v_add3_u32 v49, s7, v195, v181
	v_pk_mul_f32 v[50:51], v[64:65], v[48:49] op_sel_hi:[1,0]
	v_pk_mul_f32 v[52:53], v[66:67], v[48:49] op_sel_hi:[1,0]
	v_cvt_pk_bf16_f32 v50, v50, v51
	v_cvt_pk_bf16_f32 v51, v52, v53
	v_pk_mul_f32 v[52:53], v[68:69], v[48:49] op_sel_hi:[1,0]
	v_pk_mul_f32 v[54:55], v[70:71], v[48:49] op_sel_hi:[1,0]
	v_add_u32_e32 v49, 0xa000, v49
	v_pk_mul_f32 v[32:33], v[32:33], v[48:49] op_sel_hi:[1,0]
	v_pk_mul_f32 v[34:35], v[34:35], v[48:49] op_sel_hi:[1,0]
	v_pk_mul_f32 v[16:17], v[16:17], v[48:49] op_sel_hi:[1,0]
	v_pk_mul_f32 v[18:19], v[18:19], v[48:49] op_sel_hi:[1,0]
	v_pk_mul_f32 v[0:1], v[0:1], v[48:49] op_sel_hi:[1,0]
	v_pk_mul_f32 v[2:3], v[2:3], v[48:49] op_sel_hi:[1,0]
	v_cvt_pk_bf16_f32 v32, v32, v33
	v_cvt_pk_bf16_f32 v33, v34, v35
	v_pk_mul_f32 v[34:35], v[36:37], v[48:49] op_sel_hi:[1,0]
	v_pk_mul_f32 v[36:37], v[38:39], v[48:49] op_sel_hi:[1,0]
	v_cvt_pk_bf16_f32 v16, v16, v17
	v_cvt_pk_bf16_f32 v17, v18, v19
	v_pk_mul_f32 v[18:19], v[20:21], v[48:49] op_sel_hi:[1,0]
	v_pk_mul_f32 v[20:21], v[22:23], v[48:49] op_sel_hi:[1,0]
	v_cvt_pk_bf16_f32 v0, v0, v1
	v_cvt_pk_bf16_f32 v1, v2, v3
	v_pk_mul_f32 v[2:3], v[4:5], v[48:49] op_sel_hi:[1,0]
	v_pk_mul_f32 v[4:5], v[6:7], v[48:49] op_sel_hi:[1,0]
	v_cvt_pk_bf16_f32 v52, v52, v53
	v_cvt_pk_bf16_f32 v53, v54, v55
	v_cvt_pk_bf16_f32 v34, v34, v35
	v_cvt_pk_bf16_f32 v35, v36, v37
	v_cvt_pk_bf16_f32 v18, v18, v19
	v_cvt_pk_bf16_f32 v19, v20, v21
	v_cvt_pk_bf16_f32 v2, v2, v3
	v_cvt_pk_bf16_f32 v3, v4, v5
	ds_write2_b64 v49, v[50:51], v[52:53] offset1:2
	v_pk_mul_f32 v[50:51], v[72:73], v[48:49] op_sel_hi:[1,0]
	v_pk_mul_f32 v[52:53], v[74:75], v[48:49] op_sel_hi:[1,0]
	ds_write2_b64 v49, v[32:33], v[34:35] offset0:8 offset1:10
	v_pk_mul_f32 v[32:33], v[40:41], v[48:49] op_sel_hi:[1,0]
	v_pk_mul_f32 v[34:35], v[42:43], v[48:49] op_sel_hi:[1,0]
	ds_write2_b64 v49, v[16:17], v[18:19] offset0:16 offset1:18
	v_pk_mul_f32 v[16:17], v[24:25], v[48:49] op_sel_hi:[1,0]
	v_pk_mul_f32 v[18:19], v[26:27], v[48:49] op_sel_hi:[1,0]
	ds_write2_b64 v49, v[0:1], v[2:3] offset0:24 offset1:26
	v_pk_mul_f32 v[0:1], v[8:9], v[48:49] op_sel_hi:[1,0]
	v_pk_mul_f32 v[2:3], v[10:11], v[48:49] op_sel_hi:[1,0]
	v_cvt_pk_bf16_f32 v50, v50, v51
	v_cvt_pk_bf16_f32 v51, v52, v53
	v_pk_mul_f32 v[52:53], v[76:77], v[48:49] op_sel_hi:[1,0]
	v_pk_mul_f32 v[54:55], v[78:79], v[48:49] op_sel_hi:[1,0]
	v_cvt_pk_bf16_f32 v32, v32, v33
	v_cvt_pk_bf16_f32 v33, v34, v35
	v_pk_mul_f32 v[34:35], v[44:45], v[48:49] op_sel_hi:[1,0]
	v_pk_mul_f32 v[36:37], v[46:47], v[48:49] op_sel_hi:[1,0]
	v_cvt_pk_bf16_f32 v16, v16, v17
	v_cvt_pk_bf16_f32 v17, v18, v19
	v_pk_mul_f32 v[18:19], v[28:29], v[48:49] op_sel_hi:[1,0]
	v_pk_mul_f32 v[20:21], v[30:31], v[48:49] op_sel_hi:[1,0]
	v_cvt_pk_bf16_f32 v0, v0, v1
	v_cvt_pk_bf16_f32 v1, v2, v3
	v_pk_mul_f32 v[2:3], v[12:13], v[48:49] op_sel_hi:[1,0]
	v_pk_mul_f32 v[4:5], v[14:15], v[48:49] op_sel_hi:[1,0]
	v_cvt_pk_bf16_f32 v52, v52, v53
	v_cvt_pk_bf16_f32 v53, v54, v55
	v_cvt_pk_bf16_f32 v34, v34, v35
	v_cvt_pk_bf16_f32 v35, v36, v37
	v_cvt_pk_bf16_f32 v18, v18, v19
	v_cvt_pk_bf16_f32 v19, v20, v21
	v_cvt_pk_bf16_f32 v2, v2, v3
	v_cvt_pk_bf16_f32 v3, v4, v5
	s_mulk_i32 s20, 0x1800
	s_mul_hi_u32 s2, s19, 0x1800
	ds_write2_b64 v49, v[50:51], v[52:53] offset0:4 offset1:6
	ds_write2_b64 v49, v[32:33], v[34:35] offset0:12 offset1:14
	ds_write2_b64 v49, v[16:17], v[18:19] offset0:20 offset1:22
	ds_write2_b64 v49, v[0:1], v[2:3] offset0:28 offset1:30
	s_add_i32 s2, s2, s20
	s_mulk_i32 s19, 0x1800
	s_waitcnt lgkmcnt(0)
	s_add_u32 s3, s4, s19
	v_add3_u32 v14, s7, v144, v196
	s_addc_u32 s10, s5, s2
	ds_read_b128 v[0:3], v14 offset:40960
	s_add_u32 s2, s3, s6
	s_addc_u32 s3, s10, 0
	v_mov_b32_e32 v159, 0
	ds_read_b128 v[4:7], v14 offset:42048
	v_lshl_add_u64 v[8:9], s[2:3], 0, v[158:159]
	v_mov_b32_e32 v147, v159
	v_lshl_add_u64 v[10:11], v[8:9], 0, v[146:147]
	s_movk_i32 s2, 0x6000
	s_waitcnt lgkmcnt(0)
	global_store_dwordx4 v[10:11], v[0:3], off
	v_mov_b32_e32 v149, v159
	v_mov_b32_e32 v153, v159
	v_add_co_u32_e32 v0, vcc, s2, v10
	s_mov_b32 s2, 0xc000
	s_nop 0
	v_addc_co_u32_e32 v1, vcc, 0, v11, vcc
	global_store_dwordx4 v[0:1], v[4:7], off
	ds_read_b128 v[0:3], v14 offset:43136
	ds_read_b128 v[4:7], v14 offset:44224
	v_add_co_u32_e32 v12, vcc, s2, v10
	s_mov_b32 s2, 0x12000
	s_nop 0
	v_addc_co_u32_e32 v13, vcc, 0, v11, vcc
	v_add_co_u32_e32 v10, vcc, s2, v10
	s_waitcnt lgkmcnt(0)
	global_store_dwordx4 v[12:13], v[0:3], off
	v_addc_co_u32_e32 v11, vcc, 0, v11, vcc
	ds_read_b128 v[0:3], v14 offset:45312
	global_store_dwordx4 v[10:11], v[4:7], off
	ds_read_b128 v[4:7], v14 offset:46400
	v_lshl_add_u64 v[10:11], v[8:9], 0, v[148:149]
	v_mov_b32_e32 v151, v159
	s_waitcnt lgkmcnt(0)
	global_store_dwordx4 v[10:11], v[0:3], off
	v_lshl_add_u64 v[10:11], v[8:9], 0, v[152:153]
	ds_read_b128 v[0:3], v14 offset:47488
	global_store_dwordx4 v[10:11], v[4:7], off
	ds_read_b128 v[4:7], v14 offset:48576
	v_lshl_add_u64 v[10:11], v[8:9], 0, v[150:151]
	v_mov_b32_e32 v155, v159
	v_readfirstlane_b32 s10, v222
	s_waitcnt lgkmcnt(0)
	global_store_dwordx4 v[10:11], v[0:3], off
	s_and_b32 s2, s10, 0xffffffc0
	s_nop 0
	v_lshl_add_u64 v[0:1], v[8:9], 0, v[154:155]
	global_store_dwordx4 v[0:1], v[4:7], off
	v_or_b32_e32 v0, s2, v197
	s_mov_b32 s2, 0x2aaaaaab
	v_mul_hi_i32 v1, v0, s2
	v_lshrrev_b32_e32 v2, 31, v1
	v_ashrrev_i32_e32 v1, 2, v1
	v_add_u32_e32 v2, v1, v2
	s_movk_i32 s2, 0xffe8
	v_lshrrev_b32_e32 v159, 1, v2
	v_mad_u64_u32 v[160:161], s[2:3], v2, s2, v[0:1]
	v_xor_b32_e32 v1, v159, v222
	v_bfi_b32 v1, -8, v160, v1
	v_cmp_lt_i32_e32 vcc, 15, v1
	v_add_u32_e32 v2, s8, v2
	s_and_saveexec_b64 s[2:3], vcc
	s_xor_b64 s[2:3], exec, s[2:3]
	v_mov_b32_e32 v3, 0xbfff80
	v_lshl_add_u32 v153, v2, 6, v3
	s_or_saveexec_b64 s[2:3], s[2:3]
	v_mov_b32_e32 v145, 0x1000
	s_xor_b64 exec, exec, s[2:3]
	v_lshl_or_b32 v2, v2, 11, s17
	v_add_u32_e32 v153, 0x8000000, v2
	v_mov_b32_e32 v145, 0x20000
	s_or_b64 exec, exec, s[2:3]
	v_add_u32_e32 v2, 0x200, v0
	s_mov_b32 s2, 0x2aaaaaab
	v_mul_hi_i32 v3, v2, s2
	v_lshrrev_b32_e32 v4, 31, v3
	v_ashrrev_i32_e32 v3, 2, v3
	v_add_u32_e32 v4, v3, v4
	s_movk_i32 s2, 0xffe8
	v_mad_u64_u32 v[162:163], s[2:3], v4, s2, v[2:3]
	v_lshrrev_b32_e32 v163, 1, v4
	v_xor_b32_e32 v3, v163, v222
	v_bfi_b32 v3, -8, v162, v3
	v_cmp_lt_i32_e32 vcc, 15, v3
	v_add_u32_e32 v4, s8, v4
	s_and_saveexec_b64 s[2:3], vcc
	s_xor_b64 s[2:3], exec, s[2:3]
	v_mov_b32_e32 v5, 0xbfff80
	v_lshl_add_u32 v155, v4, 6, v5
	s_or_saveexec_b64 s[2:3], s[2:3]
	v_mov_b32_e32 v147, 0x1000
	s_xor_b64 exec, exec, s[2:3]
	v_lshl_or_b32 v4, v4, 11, s17
	v_add_u32_e32 v155, 0x8000000, v4
	v_mov_b32_e32 v147, 0x20000
	s_or_b64 exec, exec, s[2:3]
	v_add_u32_e32 v4, 0x400, v0
	s_mov_b32 s2, 0x2aaaaaab
	v_mul_hi_i32 v5, v4, s2
	v_lshrrev_b32_e32 v6, 31, v5
	v_ashrrev_i32_e32 v5, 2, v5
	v_add_u32_e32 v5, v5, v6
	s_movk_i32 s2, 0xffe8
	v_mad_u64_u32 v[164:165], s[2:3], v5, s2, v[4:5]
	v_lshrrev_b32_e32 v165, 1, v5
	v_xor_b32_e32 v4, v165, v222
	v_bfi_b32 v4, -8, v164, v4
	v_cmp_lt_i32_e32 vcc, 15, v4
	v_add_u32_e32 v5, s8, v5
	s_and_saveexec_b64 s[2:3], vcc
	s_xor_b64 s[2:3], exec, s[2:3]
	v_mov_b32_e32 v6, 0xbfff80
	v_lshl_add_u32 v161, v5, 6, v6
	s_or_saveexec_b64 s[2:3], s[2:3]
	v_mov_b32_e32 v149, 0x1000
	s_xor_b64 exec, exec, s[2:3]
	v_lshl_or_b32 v5, v5, 11, s17
	v_add_u32_e32 v161, 0x8000000, v5
	v_mov_b32_e32 v149, 0x20000
	s_or_b64 exec, exec, s[2:3]
	s_lshr_b32 s17, s10, 6
	s_lshl_b32 s19, s17, 5
	s_or_b32 s2, s8, s16
	s_add_u32 s12, s2, s19
	v_or_b32_e32 v5, s12, v194
	s_movk_i32 s2, 0x1800
	v_mov_b64_e32 v[6:7], s[4:5]
	s_addc_u32 s13, s9, 0
	v_mad_u64_u32 v[6:7], s[2:3], v5, s2, v[6:7]
	v_mov_b32_e32 v5, 0x1800
	s_mov_b32 s7, 0
	v_mad_i32_i24 v7, s13, v5, v7
	v_lshl_add_u32 v8, v1, 3, v153
	v_ashrrev_i32_e32 v1, 31, v0
	v_lshl_add_u64 v[6:7], v[6:7], 0, s[6:7]
	v_mov_b32_e32 v157, 0
	v_lshrrev_b32_e32 v10, 28, v1
	v_lshl_add_u64 v[6:7], v[6:7], 0, v[156:157]
	v_lshl_add_u32 v4, v4, 3, v161
	v_mov_b32_e32 v5, v157
	v_add_u32_e32 v16, v0, v10
	global_load_dwordx4 v[96:99], v[6:7], off
	global_load_dwordx4 v[100:103], v[6:7], off offset:32
	global_load_dwordx4 v[104:107], v[6:7], off offset:64
	global_load_dwordx4 v[108:111], v[6:7], off offset:96
	global_load_dwordx4 v[112:115], v[6:7], off offset:128
	global_load_dwordx4 v[116:119], v[6:7], off offset:160
	global_load_dwordx4 v[120:123], v[6:7], off offset:192
	global_load_dwordx4 v[124:127], v[6:7], off offset:224
	global_load_dwordx4 v[128:131], v[6:7], off offset:256
	global_load_dwordx4 v[132:135], v[6:7], off offset:288
	global_load_dwordx4 v[136:139], v[6:7], off offset:320
	global_load_dwordx4 v[140:143], v[6:7], off offset:352
	v_lshl_add_u32 v6, v3, 3, v155
	v_ashrrev_i32_e32 v3, 31, v2
	v_lshl_add_u64 v[14:15], v[4:5], 1, s[84:85]
	v_ashrrev_i32_e32 v166, 4, v16
	v_and_b32_e32 v5, 0x1ffffff0, v16
	v_lshrrev_b32_e32 v11, 28, v3
	v_mov_b32_e32 v9, v157
	s_lshl_b32 s2, s17, 10
	v_sub_u32_e32 v0, v0, v5
	v_lshlrev_b32_e32 v5, 2, v166
	v_mov_b32_e32 v7, v157
	v_add_u32_e32 v17, v2, v11
	v_lshl_add_u64 v[10:11], v[8:9], 1, s[84:85]
	v_bfe_u32 v9, v166, 2, 2
	s_add_i32 s7, s2, 0
	v_and_b32_e32 v5, 12, v5
	v_lshl_add_u64 v[12:13], v[6:7], 1, s[84:85]
	v_ashrrev_i32_e32 v167, 4, v17
	v_and_b32_e32 v7, 0x1ffffff0, v17
	v_bitop3_b32 v0, v5, v0, v9 bitop3:0x36
	s_mov_b32 m0, s7
	v_add_lshl_u32 v16, v166, s8, 11
	v_sub_u32_e32 v2, v2, v7
	v_lshlrev_b32_e32 v7, 2, v167
	global_load_lds_dwordx4 v[10:11], off
	s_add_i32 m0, s7, 0x2000
	v_lshlrev_b32_e32 v168, 3, v0
	v_mov_b32_e32 v1, v157
	v_bfe_u32 v17, v167, 2, 2
	v_and_b32_e32 v7, 12, v7
	global_load_lds_dwordx4 v[12:13], off
	s_add_i32 m0, s7, 0x4000
	v_add3_u32 v0, s18, v16, v168
	v_bitop3_b32 v2, v7, v2, v17 bitop3:0x36
	global_load_lds_dwordx4 v[14:15], off
	s_add_i32 m0, s7, 0x6000
	v_lshl_add_u64 v[10:11], v[0:1], 1, s[84:85]
	v_add_lshl_u32 v18, v167, s8, 11
	v_lshlrev_b32_e32 v169, 3, v2
	global_load_lds_dwordx4 v[10:11], off
	s_add_i32 m0, s7, 0x8000
	v_mov_b32_e32 v3, v157
	v_add3_u32 v2, s18, v18, v169
	s_cmpk_gt_u32 s10, 0xff
	v_lshl_add_u64 v[12:13], v[2:3], 1, s[84:85]
	s_cselect_b64 s[8:9], -1, 0
	s_cmpk_lt_u32 s10, 0x100
	v_add_u32_e32 v156, v8, v145
	global_load_lds_dwordx4 v[12:13], off
	s_cselect_b64 s[10:11], -1, 0
	s_add_i32 m0, s7, 0xa000
	v_lshl_add_u64 v[8:9], v[156:157], 1, s[84:85]
	v_add_u32_e32 v156, v6, v147
	s_waitcnt vmcnt(0) lgkmcnt(0)
	s_barrier
	s_waitcnt vmcnt(0)
	global_load_lds_dwordx4 v[8:9], off
	v_lshl_add_u64 v[6:7], v[156:157], 1, s[84:85]
	s_add_i32 m0, s7, 0xc000
	v_add_u32_e32 v156, v4, v149
	global_load_lds_dwordx4 v[6:7], off
	v_lshl_add_u64 v[4:5], v[156:157], 1, s[84:85]
	s_add_i32 m0, s7, 0xe000
	v_add_u32_e32 v156, 0x20000, v0
	global_load_lds_dwordx4 v[4:5], off
	s_add_i32 m0, s7, 0x10000
	v_lshl_add_u64 v[0:1], v[156:157], 1, s[84:85]
	v_add_u32_e32 v156, 0x20000, v2
	global_load_lds_dwordx4 v[0:1], off
	v_lshl_add_u64 v[0:1], v[156:157], 1, s[84:85]
	s_add_i32 m0, s7, 0x12000
	s_and_b64 vcc, exec, s[10:11]
	global_load_lds_dwordx4 v[0:1], off
	ds_read_b128 v[0:3], v190
	ds_read_b128 v[4:7], v191
	ds_read_b128 v[8:11], v192
	ds_read_b128 v[12:15], v193
	s_waitcnt lgkmcnt(0)
	v_mfma_f32_32x32x16_bf16 v[48:63], v[0:3], v[96:99], 0
	ds_read_b128 v[0:3], v190 offset:128
	v_mfma_f32_32x32x16_bf16 v[48:63], v[4:7], v[100:103], v[48:63]
	ds_read_b128 v[4:7], v191 offset:128
	v_mfma_f32_32x32x16_bf16 v[48:63], v[8:11], v[104:107], v[48:63]
	ds_read_b128 v[8:11], v192 offset:128
	v_mfma_f32_32x32x16_bf16 v[48:63], v[12:15], v[108:111], v[48:63]
	ds_read_b128 v[12:15], v193 offset:128
	s_waitcnt lgkmcnt(0)
	v_mfma_f32_32x32x16_bf16 v[48:63], v[0:3], v[112:115], v[48:63]
	ds_read_b128 v[0:3], v190 offset:256
	v_mfma_f32_32x32x16_bf16 v[48:63], v[4:7], v[116:119], v[48:63]
	ds_read_b128 v[4:7], v191 offset:256
	v_mfma_f32_32x32x16_bf16 v[48:63], v[8:11], v[120:123], v[48:63]
	ds_read_b128 v[8:11], v192 offset:256
	v_mfma_f32_32x32x16_bf16 v[48:63], v[12:15], v[124:127], v[48:63]
	ds_read_b128 v[12:15], v193 offset:256
	s_waitcnt lgkmcnt(0)
	v_mfma_f32_32x32x16_bf16 v[48:63], v[0:3], v[128:131], v[48:63]
	ds_read_b128 v[0:3], v190 offset:12288
	v_mfma_f32_32x32x16_bf16 v[48:63], v[4:7], v[132:135], v[48:63]
	ds_read_b128 v[4:7], v191 offset:12288
	v_mfma_f32_32x32x16_bf16 v[48:63], v[8:11], v[136:139], v[48:63]
	ds_read_b128 v[8:11], v192 offset:12288
	s_waitcnt lgkmcnt(0)
	v_mfma_f32_32x32x16_bf16 v[80:95], v[0:3], v[96:99], 0
	ds_read_b128 v[16:19], v193 offset:12288
	v_mfma_f32_32x32x16_bf16 v[80:95], v[4:7], v[100:103], v[80:95]
	ds_read_b128 v[20:23], v190 offset:12416
	v_mfma_f32_32x32x16_bf16 v[80:95], v[8:11], v[104:107], v[80:95]
	ds_read_b128 v[24:27], v191 offset:12416
	s_waitcnt lgkmcnt(0)
	v_mfma_f32_32x32x16_bf16 v[80:95], v[16:19], v[108:111], v[80:95]
	ds_read_b128 v[28:31], v192 offset:12416
	v_mfma_f32_32x32x16_bf16 v[80:95], v[20:23], v[112:115], v[80:95]
	ds_read_b128 v[32:35], v193 offset:12416
	v_mfma_f32_32x32x16_bf16 v[80:95], v[24:27], v[116:119], v[80:95]
	ds_read_b128 v[36:39], v190 offset:12544
	s_waitcnt lgkmcnt(0)
	v_mfma_f32_32x32x16_bf16 v[80:95], v[28:31], v[120:123], v[80:95]
	ds_read_b128 v[40:43], v191 offset:12544
	v_mfma_f32_32x32x16_bf16 v[80:95], v[32:35], v[124:127], v[80:95]
	ds_read_b128 v[44:47], v192 offset:12544
	v_mfma_f32_32x32x16_bf16 v[80:95], v[36:39], v[128:131], v[80:95]
	ds_read_b128 v[64:67], v193 offset:12544
	s_waitcnt lgkmcnt(0)
	v_mfma_f32_32x32x16_bf16 v[80:95], v[40:43], v[132:135], v[80:95]
	v_mfma_f32_32x32x16_bf16 v[80:95], v[44:47], v[136:139], v[80:95]
	v_mfma_f32_32x32x16_bf16 v[80:95], v[64:67], v[140:143], v[80:95]
	v_mfma_f32_32x32x16_bf16 v[48:63], v[12:15], v[140:143], v[48:63]
	s_cbranch_vccnz .LBB0_2047
	s_waitcnt vmcnt(0) lgkmcnt(0)
	s_barrier
.LBB0_2047:
	s_nop 10
	v_max_f32_e32 v0, v49, v49
	v_max_f32_e32 v1, v48, v48
	v_max_f32_e32 v0, v1, v0
	v_max3_f32 v0, v0, v50, v51
	v_max3_f32 v0, v0, v52, v53
	v_max3_f32 v0, v0, v54, v55
	v_max3_f32 v0, v0, v56, v57
	v_max3_f32 v0, v0, v58, v59
	v_max3_f32 v0, v0, v60, v61
	v_max3_f32 v0, v0, v62, v63
	v_mov_b32_e32 v1, v0
	s_nop 1
	v_permlane32_swap_b32_e32 v0, v1
	v_max_f32_e32 v1, v1, v1
	v_max_f32_e32 v0, v0, v0
	v_max_f32_e32 v0, v0, v1
	s_cmp_lg_u64 exec, 0
	v_add_f32_e32 v0, 0, v0
	s_cselect_b64 vcc, -1, 0
	v_cndmask_b32_e32 v151, 0, v0, vcc
	v_sub_f32_e32 v0, v48, v151
	v_exp_f32_e32 v48, v0
	v_sub_f32_e32 v0, v49, v151
	v_exp_f32_e32 v49, v0
	v_sub_f32_e32 v0, v50, v151
	v_exp_f32_e32 v50, v0
	v_sub_f32_e32 v0, v51, v151
	v_exp_f32_e32 v51, v0
	v_sub_f32_e32 v0, v52, v151
	v_exp_f32_e32 v52, v0
	v_sub_f32_e32 v0, v53, v151
	v_exp_f32_e32 v53, v0
	v_sub_f32_e32 v0, v54, v151
	v_exp_f32_e32 v54, v0
	v_sub_f32_e32 v0, v55, v151
	v_exp_f32_e32 v55, v0
	v_sub_f32_e32 v0, v56, v151
	v_exp_f32_e32 v56, v0
	ds_read_b64_tr_b16 v[0:1], v183 offset:24576
	ds_read_b64_tr_b16 v[2:3], v185 offset:26624
	v_cvt_pk_bf16_f32 v4, v48, v49
	v_cvt_pk_bf16_f32 v5, v50, v51
	v_cvt_pk_bf16_f32 v6, v52, v53
	v_cvt_pk_bf16_f32 v7, v54, v55
	ds_read_b64_tr_b16 v[8:9], v182 offset:24576
	ds_read_b64_tr_b16 v[10:11], v184 offset:26624
	ds_read_b64_tr_b16 v[192:193], v185 offset:30720
	ds_read_b64_tr_b16 v[190:191], v183 offset:28672
	s_waitcnt lgkmcnt(0)
	v_mfma_f32_32x32x16_bf16 v[64:79], v[0:3], v[4:7], 0
	v_sub_f32_e32 v0, v57, v151
	v_exp_f32_e32 v57, v0
	ds_read_b64_tr_b16 v[0:1], v186 offset:24576
	ds_read_b64_tr_b16 v[2:3], v188 offset:26624
	ds_read_b64_tr_b16 v[200:201], v184 offset:30720
	ds_read_b64_tr_b16 v[198:199], v182 offset:28672
	v_sub_f32_e32 v12, v58, v151
	v_sub_f32_e32 v62, v62, v151
	v_sub_f32_e32 v63, v63, v151
	v_exp_f32_e32 v58, v12
	s_waitcnt lgkmcnt(0)
	v_mfma_f32_32x32x16_bf16 v[16:31], v[0:3], v[4:7], 0
	v_sub_f32_e32 v0, v60, v151
	v_exp_f32_e32 v60, v0
	v_sub_f32_e32 v0, v61, v151
	v_exp_f32_e32 v61, v0
	v_exp_f32_e32 v62, v62
	v_exp_f32_e32 v63, v63
	v_add_f32_e32 v156, 0, v48
	v_mfma_f32_32x32x16_bf16 v[32:47], v[8:11], v[4:7], 0
	v_sub_f32_e32 v8, v59, v151
	v_exp_f32_e32 v59, v8
	ds_read_b64_tr_b16 v[8:9], v187 offset:24576
	ds_read_b64_tr_b16 v[10:11], v189 offset:26624
	ds_read_b64_tr_b16 v[204:205], v188 offset:30720
	ds_read_b64_tr_b16 v[202:203], v186 offset:28672
	v_cvt_pk_bf16_f32 v210, v56, v57
	v_cvt_pk_bf16_f32 v212, v60, v61
	v_cvt_pk_bf16_f32 v211, v58, v59
	v_cvt_pk_bf16_f32 v213, v62, v63
	s_waitcnt lgkmcnt(0)
	v_mfma_f32_32x32x16_bf16 v[0:15], v[8:11], v[4:7], 0
	v_add_f32_e32 v156, v49, v156
	v_add_f32_e32 v156, v50, v156
	v_max_f32_e32 v157, v81, v81
	v_add_f32_e32 v156, v51, v156
	ds_read_b64_tr_b16 v[208:209], v189 offset:30720
	ds_read_b64_tr_b16 v[206:207], v187 offset:28672
	v_add_f32_e32 v156, v52, v156
	v_add_f32_e32 v156, v53, v156
	v_mfma_f32_32x32x16_bf16 v[64:79], v[190:193], v[210:213], v[64:79]
	v_max_f32_e32 v190, v80, v80
	v_max_f32_e32 v157, v190, v157
	v_max3_f32 v157, v157, v82, v83
	v_max3_f32 v157, v157, v84, v85
	v_add_f32_e32 v156, v54, v156
	v_max3_f32 v157, v157, v86, v87
	v_add_f32_e32 v156, v55, v156
	v_max3_f32 v157, v157, v88, v89
	v_add_f32_e32 v156, v56, v156
	v_max3_f32 v157, v157, v90, v91
	v_mfma_f32_32x32x16_bf16 v[32:47], v[198:201], v[210:213], v[32:47]
	v_add_f32_e32 v156, v57, v156
	v_max3_f32 v157, v157, v92, v93
	v_add_f32_e32 v156, v58, v156
	v_max3_f32 v157, v157, v94, v95
	v_add_f32_e32 v156, v59, v156
	v_mov_b32_e32 v190, v157
	v_add_f32_e32 v156, v60, v156
	v_mfma_f32_32x32x16_bf16 v[16:31], v[202:205], v[210:213], v[16:31]
	v_permlane32_swap_b32_e32 v157, v190
	v_add_f32_e32 v156, v61, v156
	v_max_f32_e32 v190, v190, v190
	v_max_f32_e32 v157, v157, v157
	v_add_f32_e32 v156, v62, v156
	v_max_f32_e32 v157, v157, v190
	s_waitcnt lgkmcnt(0)
	v_mfma_f32_32x32x16_bf16 v[0:15], v[206:209], v[210:213], v[0:15]
	v_add_f32_e32 v156, v63, v156
	v_sub_f32_e32 v157, v157, v151
	s_mov_b32 s2, 0x41000000
	v_add_f32_e32 v156, 0, v156
	v_cmp_lt_f32_e32 vcc, s2, v157
	s_cbranch_vccz .LBB0_2049
	v_max_f32_e32 v157, v157, v157
	v_max_f32_e32 v157, 0, v157
	v_exp_f32_e64 v190, -v157
	v_add_f32_e32 v151, v151, v157
	v_pk_mul_f32 v[78:79], v[78:79], v[190:191] op_sel_hi:[1,0]
	v_pk_mul_f32 v[76:77], v[76:77], v[190:191] op_sel_hi:[1,0]
	v_pk_mul_f32 v[74:75], v[74:75], v[190:191] op_sel_hi:[1,0]
	v_pk_mul_f32 v[72:73], v[72:73], v[190:191] op_sel_hi:[1,0]
	v_pk_mul_f32 v[70:71], v[70:71], v[190:191] op_sel_hi:[1,0]
	v_pk_mul_f32 v[68:69], v[68:69], v[190:191] op_sel_hi:[1,0]
	v_pk_mul_f32 v[66:67], v[66:67], v[190:191] op_sel_hi:[1,0]
	v_pk_mul_f32 v[64:65], v[64:65], v[190:191] op_sel_hi:[1,0]
	v_pk_mul_f32 v[46:47], v[46:47], v[190:191] op_sel_hi:[1,0]
	v_pk_mul_f32 v[44:45], v[44:45], v[190:191] op_sel_hi:[1,0]
	v_pk_mul_f32 v[42:43], v[42:43], v[190:191] op_sel_hi:[1,0]
	v_pk_mul_f32 v[40:41], v[40:41], v[190:191] op_sel_hi:[1,0]
	v_pk_mul_f32 v[38:39], v[38:39], v[190:191] op_sel_hi:[1,0]
	v_pk_mul_f32 v[36:37], v[36:37], v[190:191] op_sel_hi:[1,0]
	v_pk_mul_f32 v[34:35], v[34:35], v[190:191] op_sel_hi:[1,0]
	v_pk_mul_f32 v[32:33], v[32:33], v[190:191] op_sel_hi:[1,0]
	v_pk_mul_f32 v[30:31], v[30:31], v[190:191] op_sel_hi:[1,0]
	v_pk_mul_f32 v[28:29], v[28:29], v[190:191] op_sel_hi:[1,0]
	v_pk_mul_f32 v[26:27], v[26:27], v[190:191] op_sel_hi:[1,0]
	v_pk_mul_f32 v[24:25], v[24:25], v[190:191] op_sel_hi:[1,0]
	v_pk_mul_f32 v[22:23], v[22:23], v[190:191] op_sel_hi:[1,0]
	v_pk_mul_f32 v[20:21], v[20:21], v[190:191] op_sel_hi:[1,0]
	v_pk_mul_f32 v[18:19], v[18:19], v[190:191] op_sel_hi:[1,0]
	v_pk_mul_f32 v[16:17], v[16:17], v[190:191] op_sel_hi:[1,0]
	v_pk_mul_f32 v[14:15], v[14:15], v[190:191] op_sel_hi:[1,0]
	v_pk_mul_f32 v[12:13], v[12:13], v[190:191] op_sel_hi:[1,0]
	v_pk_mul_f32 v[10:11], v[10:11], v[190:191] op_sel_hi:[1,0]
	v_pk_mul_f32 v[8:9], v[8:9], v[190:191] op_sel_hi:[1,0]
	v_pk_mul_f32 v[6:7], v[6:7], v[190:191] op_sel_hi:[1,0]
	v_pk_mul_f32 v[4:5], v[4:5], v[190:191] op_sel_hi:[1,0]
	v_pk_mul_f32 v[2:3], v[2:3], v[190:191] op_sel_hi:[1,0]
	v_pk_mul_f32 v[0:1], v[0:1], v[190:191] op_sel_hi:[1,0]
	v_mul_f32_e32 v156, v156, v190
.LBB0_2049:
	v_sub_f32_e32 v80, v80, v151
	v_sub_f32_e32 v81, v81, v151
	v_sub_f32_e32 v82, v82, v151
	v_sub_f32_e32 v83, v83, v151
	v_sub_f32_e32 v84, v84, v151
	v_sub_f32_e32 v85, v85, v151
	v_sub_f32_e32 v86, v86, v151
	v_sub_f32_e32 v87, v87, v151
	v_exp_f32_e32 v80, v80
	v_exp_f32_e32 v81, v81
	v_exp_f32_e32 v82, v82
	v_exp_f32_e32 v83, v83
	v_exp_f32_e32 v84, v84
	v_exp_f32_e32 v85, v85
	v_exp_f32_e32 v86, v86
	v_exp_f32_e32 v87, v87
	ds_read_b64_tr_b16 v[190:191], v183 offset:32768
	ds_read_b64_tr_b16 v[192:193], v185 offset:34816
	ds_read_b64_tr_b16 v[202:203], v182 offset:32768
	ds_read_b64_tr_b16 v[204:205], v184 offset:34816
	ds_read_b64_tr_b16 v[208:209], v185 offset:38912
	ds_read_b64_tr_b16 v[206:207], v183 offset:36864
	v_cvt_pk_bf16_f32 v198, v80, v81
	v_cvt_pk_bf16_f32 v199, v82, v83
	v_cvt_pk_bf16_f32 v200, v84, v85
	v_cvt_pk_bf16_f32 v201, v86, v87
	v_sub_f32_e32 v88, v88, v151
	v_sub_f32_e32 v89, v89, v151
	s_waitcnt lgkmcnt(0)
	v_mfma_f32_32x32x16_bf16 v[64:79], v[190:193], v[198:201], v[64:79]
	ds_read_b64_tr_b16 v[190:191], v186 offset:32768
	ds_read_b64_tr_b16 v[192:193], v188 offset:34816
	ds_read_b64_tr_b16 v[184:185], v184 offset:38912
	ds_read_b64_tr_b16 v[182:183], v182 offset:36864
	v_sub_f32_e32 v90, v90, v151
	v_sub_f32_e32 v91, v91, v151
	v_sub_f32_e32 v92, v92, v151
	v_sub_f32_e32 v93, v93, v151
	v_sub_f32_e32 v94, v94, v151
	v_sub_f32_e32 v95, v95, v151
	v_mfma_f32_32x32x16_bf16 v[32:47], v[202:205], v[198:201], v[32:47]
	ds_read_b64_tr_b16 v[202:203], v187 offset:32768
	ds_read_b64_tr_b16 v[204:205], v189 offset:34816
	ds_read_b64_tr_b16 v[212:213], v188 offset:38912
	ds_read_b64_tr_b16 v[210:211], v186 offset:36864
	v_exp_f32_e32 v88, v88
	v_exp_f32_e32 v89, v89
	v_exp_f32_e32 v90, v90
	v_exp_f32_e32 v91, v91
	v_exp_f32_e32 v92, v92
	v_exp_f32_e32 v93, v93
	s_waitcnt lgkmcnt(0)
	v_mfma_f32_32x32x16_bf16 v[16:31], v[190:193], v[198:201], v[16:31]
	ds_read_b64_tr_b16 v[188:189], v189 offset:38912
	ds_read_b64_tr_b16 v[186:187], v187 offset:36864
	v_exp_f32_e32 v94, v94
	v_exp_f32_e32 v95, v95
	v_cvt_pk_bf16_f32 v190, v88, v89
	v_cvt_pk_bf16_f32 v191, v90, v91
	v_cvt_pk_bf16_f32 v192, v92, v93
	v_cvt_pk_bf16_f32 v193, v94, v95
	v_mfma_f32_32x32x16_bf16 v[0:15], v[202:205], v[198:201], v[0:15]
	v_bitop3_b32 v163, v163, 7, v222 bitop3:0x48
	v_bitop3_b32 v157, v165, 7, v222 bitop3:0x48
	s_andn2_b64 vcc, exec, s[10:11]
	v_mfma_f32_32x32x16_bf16 v[64:79], v[206:209], v[190:193], v[64:79]
	v_mfma_f32_32x32x16_bf16 v[32:47], v[182:185], v[190:193], v[32:47]
	v_bitop3_b32 v182, v159, 7, v222 bitop3:0x48
	v_cndmask_b32_e64 v159, 0, 1, s[10:11]
	v_cmp_ne_u32_e64 s[2:3], 1, v159
	v_mfma_f32_32x32x16_bf16 v[16:31], v[210:213], v[190:193], v[16:31]
	s_waitcnt lgkmcnt(0)
	v_mfma_f32_32x32x16_bf16 v[0:15], v[186:189], v[190:193], v[0:15]
	s_cbranch_vccnz .LBB0_2051
	s_waitcnt vmcnt(0) lgkmcnt(0)
	s_barrier

.LBB0_2060:
	s_setprio 0
	v_add_u32_e32 v153, s21, v170
	ds_read_b128 v[48:51], v153
	v_add_u32_e32 v155, s21, v171
	v_add_u32_e32 v161, s21, v172
	v_add_u32_e32 v163, s21, v173
	ds_read_b128 v[80:83], v155
	ds_read_b128 v[84:87], v161
	ds_read_b128 v[88:91], v163
	s_waitcnt lgkmcnt(0)
	v_mfma_f32_32x32x16_bf16 v[48:63], v[48:51], v[96:99], 0
	ds_read_b128 v[92:95], v153 offset:128
	v_mfma_f32_32x32x16_bf16 v[48:63], v[80:83], v[100:103], v[48:63]
	ds_read_b128 v[80:83], v155 offset:128
	v_mfma_f32_32x32x16_bf16 v[48:63], v[84:87], v[104:107], v[48:63]
	ds_read_b128 v[84:87], v161 offset:128
	v_mfma_f32_32x32x16_bf16 v[48:63], v[88:91], v[108:111], v[48:63]
	ds_read_b128 v[88:91], v163 offset:128
	s_waitcnt lgkmcnt(0)
	v_mfma_f32_32x32x16_bf16 v[48:63], v[92:95], v[112:115], v[48:63]
	ds_read_b128 v[92:95], v153 offset:256
	v_mfma_f32_32x32x16_bf16 v[48:63], v[80:83], v[116:119], v[48:63]
	ds_read_b128 v[80:83], v155 offset:256
	v_mfma_f32_32x32x16_bf16 v[48:63], v[84:87], v[120:123], v[48:63]
	ds_read_b128 v[84:87], v161 offset:256
	v_mfma_f32_32x32x16_bf16 v[48:63], v[88:91], v[124:127], v[48:63]
	ds_read_b128 v[182:185], v163 offset:256
	s_waitcnt lgkmcnt(0)
	v_mfma_f32_32x32x16_bf16 v[48:63], v[92:95], v[128:131], v[48:63]
	ds_read_b128 v[88:91], v153 offset:12288
	v_mfma_f32_32x32x16_bf16 v[48:63], v[80:83], v[132:135], v[48:63]
	ds_read_b128 v[186:189], v155 offset:12288
	v_mfma_f32_32x32x16_bf16 v[48:63], v[84:87], v[136:139], v[48:63]
	ds_read_b128 v[190:193], v161 offset:12288
	s_waitcnt lgkmcnt(0)
	v_mfma_f32_32x32x16_bf16 v[80:95], v[88:91], v[96:99], 0
	ds_read_b128 v[198:201], v163 offset:12288
	v_mfma_f32_32x32x16_bf16 v[80:95], v[186:189], v[100:103], v[80:95]
	ds_read_b128 v[202:205], v153 offset:12416
	v_mfma_f32_32x32x16_bf16 v[80:95], v[190:193], v[104:107], v[80:95]
	ds_read_b128 v[206:209], v155 offset:12416
	s_waitcnt lgkmcnt(0)
	v_mfma_f32_32x32x16_bf16 v[80:95], v[198:201], v[108:111], v[80:95]
	ds_read_b128 v[210:213], v161 offset:12416
	v_mfma_f32_32x32x16_bf16 v[80:95], v[202:205], v[112:115], v[80:95]
	ds_read_b128 v[214:217], v163 offset:12416
	v_mfma_f32_32x32x16_bf16 v[80:95], v[206:209], v[116:119], v[80:95]
	ds_read_b128 v[218:221], v153 offset:12544
	s_waitcnt lgkmcnt(0)
	v_mfma_f32_32x32x16_bf16 v[80:95], v[210:213], v[120:123], v[80:95]
	ds_read_b128 v[224:227], v155 offset:12544
	v_mfma_f32_32x32x16_bf16 v[80:95], v[214:217], v[124:127], v[80:95]
	ds_read_b128 v[228:231], v161 offset:12544
	v_mfma_f32_32x32x16_bf16 v[80:95], v[218:221], v[128:131], v[80:95]
	ds_read_b128 v[232:235], v163 offset:12544
	s_waitcnt lgkmcnt(0)
	v_mfma_f32_32x32x16_bf16 v[80:95], v[224:227], v[132:135], v[80:95]
	v_mfma_f32_32x32x16_bf16 v[80:95], v[228:231], v[136:139], v[80:95]
	v_mfma_f32_32x32x16_bf16 v[80:95], v[232:235], v[140:143], v[80:95]
	v_mfma_f32_32x32x16_bf16 v[48:63], v[182:185], v[140:143], v[48:63]
	s_andn2_b64 vcc, exec, s[8:9]
	s_cbranch_vccnz .LBB0_2055

.LBB0_2062:
	s_setprio 1
	s_nop 7
	v_max_f32_e32 v153, v49, v49
	v_max_f32_e32 v155, v48, v48
	v_max_f32_e32 v153, v155, v153
	v_max3_f32 v153, v153, v50, v51
	v_max3_f32 v153, v153, v52, v53
	v_max3_f32 v153, v153, v54, v55
	v_max3_f32 v153, v153, v56, v57
	v_max3_f32 v153, v153, v58, v59
	v_max3_f32 v153, v153, v60, v61
	v_max3_f32 v153, v153, v62, v63
	v_mov_b32_e32 v155, v153
	s_nop 1
	v_permlane32_swap_b32_e32 v153, v155
	v_max_f32_e32 v155, v155, v155
	v_max_f32_e32 v153, v153, v153
	v_max_f32_e32 v153, v153, v155
	v_sub_f32_e32 v153, v153, v151
	v_cmp_lt_f32_e32 vcc, s20, v153
	s_cbranch_vccz .LBB0_2064
	v_max_f32_e32 v153, v153, v153
	v_max_f32_e32 v153, 0, v153
	v_exp_f32_e64 v168, -v153
	v_add_f32_e32 v151, v151, v153
	v_pk_mul_f32 v[78:79], v[78:79], v[168:169] op_sel_hi:[1,0]
	v_pk_mul_f32 v[76:77], v[76:77], v[168:169] op_sel_hi:[1,0]
	v_pk_mul_f32 v[74:75], v[74:75], v[168:169] op_sel_hi:[1,0]
	v_pk_mul_f32 v[72:73], v[72:73], v[168:169] op_sel_hi:[1,0]
	v_pk_mul_f32 v[70:71], v[70:71], v[168:169] op_sel_hi:[1,0]
	v_pk_mul_f32 v[68:69], v[68:69], v[168:169] op_sel_hi:[1,0]
	v_pk_mul_f32 v[66:67], v[66:67], v[168:169] op_sel_hi:[1,0]
	v_pk_mul_f32 v[64:65], v[64:65], v[168:169] op_sel_hi:[1,0]
	v_pk_mul_f32 v[46:47], v[46:47], v[168:169] op_sel_hi:[1,0]
	v_pk_mul_f32 v[44:45], v[44:45], v[168:169] op_sel_hi:[1,0]
	v_pk_mul_f32 v[42:43], v[42:43], v[168:169] op_sel_hi:[1,0]
	v_pk_mul_f32 v[40:41], v[40:41], v[168:169] op_sel_hi:[1,0]
	v_pk_mul_f32 v[38:39], v[38:39], v[168:169] op_sel_hi:[1,0]
	v_pk_mul_f32 v[36:37], v[36:37], v[168:169] op_sel_hi:[1,0]
	v_pk_mul_f32 v[34:35], v[34:35], v[168:169] op_sel_hi:[1,0]
	v_pk_mul_f32 v[32:33], v[32:33], v[168:169] op_sel_hi:[1,0]
	v_pk_mul_f32 v[30:31], v[30:31], v[168:169] op_sel_hi:[1,0]
	v_pk_mul_f32 v[28:29], v[28:29], v[168:169] op_sel_hi:[1,0]
	v_pk_mul_f32 v[26:27], v[26:27], v[168:169] op_sel_hi:[1,0]
	v_pk_mul_f32 v[24:25], v[24:25], v[168:169] op_sel_hi:[1,0]
	v_pk_mul_f32 v[22:23], v[22:23], v[168:169] op_sel_hi:[1,0]
	v_pk_mul_f32 v[20:21], v[20:21], v[168:169] op_sel_hi:[1,0]
	v_pk_mul_f32 v[18:19], v[18:19], v[168:169] op_sel_hi:[1,0]
	v_pk_mul_f32 v[16:17], v[16:17], v[168:169] op_sel_hi:[1,0]
	v_pk_mul_f32 v[14:15], v[14:15], v[168:169] op_sel_hi:[1,0]
	v_pk_mul_f32 v[12:13], v[12:13], v[168:169] op_sel_hi:[1,0]
	v_pk_mul_f32 v[10:11], v[10:11], v[168:169] op_sel_hi:[1,0]
	v_pk_mul_f32 v[8:9], v[8:9], v[168:169] op_sel_hi:[1,0]
	v_pk_mul_f32 v[6:7], v[6:7], v[168:169] op_sel_hi:[1,0]
	v_pk_mul_f32 v[4:5], v[4:5], v[168:169] op_sel_hi:[1,0]
	v_pk_mul_f32 v[2:3], v[2:3], v[168:169] op_sel_hi:[1,0]
	v_pk_mul_f32 v[0:1], v[0:1], v[168:169] op_sel_hi:[1,0]
	v_mul_f32_e32 v159, v159, v168
.LBB0_2064:
	v_add_u32_e32 v167, s21, v174
	v_add_u32_e32 v169, s21, v175
	v_sub_f32_e32 v48, v48, v151
	v_sub_f32_e32 v49, v49, v151
	v_sub_f32_e32 v50, v50, v151
	v_sub_f32_e32 v51, v51, v151
	v_sub_f32_e32 v52, v52, v151
	v_sub_f32_e32 v53, v53, v151
	v_sub_f32_e32 v54, v54, v151
	v_sub_f32_e32 v55, v55, v151
	v_add_u32_e32 v155, v167, v177
	v_exp_f32_e32 v48, v48
	v_exp_f32_e32 v49, v49
	v_exp_f32_e32 v50, v50
	v_exp_f32_e32 v51, v51
	v_exp_f32_e32 v52, v52
	v_exp_f32_e32 v53, v53
	v_exp_f32_e32 v54, v54
	v_exp_f32_e32 v55, v55
	v_add_u32_e32 v163, v169, v177
	ds_read_b64_tr_b16 v[186:187], v155 offset:24576
	ds_read_b64_tr_b16 v[188:189], v163 offset:26624
	v_add_u32_e32 v153, v167, v178
	v_add_u32_e32 v161, v169, v178
	ds_read_b64_tr_b16 v[190:191], v153 offset:24576
	ds_read_b64_tr_b16 v[192:193], v161 offset:26624
	ds_read_b64_tr_b16 v[200:201], v163 offset:30720
	ds_read_b64_tr_b16 v[198:199], v155 offset:28672
	v_cvt_pk_bf16_f32 v182, v48, v49
	v_cvt_pk_bf16_f32 v183, v50, v51
	v_cvt_pk_bf16_f32 v184, v52, v53
	v_cvt_pk_bf16_f32 v185, v54, v55
	v_add_u32_e32 v165, v167, v179
	v_add_u32_e32 v167, v167, v180
	s_waitcnt lgkmcnt(0)
	v_mfma_f32_32x32x16_bf16 v[64:79], v[186:189], v[182:185], v[64:79]
	v_add_u32_e32 v168, v169, v179
	ds_read_b64_tr_b16 v[186:187], v165 offset:24576
	ds_read_b64_tr_b16 v[188:189], v168 offset:26624
	ds_read_b64_tr_b16 v[204:205], v161 offset:30720
	ds_read_b64_tr_b16 v[202:203], v153 offset:28672
	v_add_u32_e32 v169, v169, v180
	v_sub_f32_e32 v56, v56, v151
	v_sub_f32_e32 v57, v57, v151
	v_sub_f32_e32 v58, v58, v151
	v_sub_f32_e32 v59, v59, v151
	v_mfma_f32_32x32x16_bf16 v[32:47], v[190:193], v[182:185], v[32:47]
	ds_read_b64_tr_b16 v[190:191], v167 offset:24576
	ds_read_b64_tr_b16 v[192:193], v169 offset:26624
	ds_read_b64_tr_b16 v[208:209], v168 offset:30720
	ds_read_b64_tr_b16 v[206:207], v165 offset:28672
	v_sub_f32_e32 v60, v60, v151
	v_sub_f32_e32 v61, v61, v151
	v_sub_f32_e32 v62, v62, v151
	v_sub_f32_e32 v63, v63, v151
	v_exp_f32_e32 v56, v56
	v_exp_f32_e32 v57, v57
	s_waitcnt lgkmcnt(0)
	v_mfma_f32_32x32x16_bf16 v[16:31], v[186:189], v[182:185], v[16:31]
	v_exp_f32_e32 v58, v58
	v_exp_f32_e32 v59, v59
	v_exp_f32_e32 v60, v60
	v_exp_f32_e32 v61, v61
	ds_read_b64_tr_b16 v[188:189], v169 offset:30720
	ds_read_b64_tr_b16 v[186:187], v167 offset:28672
	v_exp_f32_e32 v62, v62
	v_exp_f32_e32 v63, v63
	v_mfma_f32_32x32x16_bf16 v[0:15], v[190:193], v[182:185], v[0:15]
	v_add_f32_e32 v190, 0, v48
	v_cvt_pk_bf16_f32 v182, v56, v57
	v_cvt_pk_bf16_f32 v183, v58, v59
	v_cvt_pk_bf16_f32 v184, v60, v61
	v_cvt_pk_bf16_f32 v185, v62, v63
	v_add_f32_e32 v190, v49, v190
	v_add_f32_e32 v190, v50, v190
	v_mfma_f32_32x32x16_bf16 v[64:79], v[198:201], v[182:185], v[64:79]
	v_add_f32_e32 v190, v51, v190
	v_add_f32_e32 v190, v52, v190
	v_add_f32_e32 v190, v53, v190
	v_add_f32_e32 v190, v54, v190
	v_add_f32_e32 v190, v55, v190
	v_add_f32_e32 v190, v56, v190
	v_add_f32_e32 v190, v57, v190
	v_mfma_f32_32x32x16_bf16 v[32:47], v[202:205], v[182:185], v[32:47]
	v_add_f32_e32 v190, v58, v190
	v_add_f32_e32 v190, v59, v190
	v_add_f32_e32 v190, v60, v190
	v_add_f32_e32 v190, v61, v190
	v_add_f32_e32 v190, v62, v190
	v_add_f32_e32 v190, v63, v190
	v_add_f32_e32 v159, v159, v190
	v_mfma_f32_32x32x16_bf16 v[16:31], v[206:209], v[182:185], v[16:31]
	s_waitcnt lgkmcnt(0)
	v_mfma_f32_32x32x16_bf16 v[0:15], v[186:189], v[182:185], v[0:15]
	v_max_f32_e32 v182, v81, v81
	v_max_f32_e32 v183, v80, v80
	v_max_f32_e32 v182, v183, v182
	v_max3_f32 v182, v182, v82, v83
	v_max3_f32 v182, v182, v84, v85
	v_max3_f32 v182, v182, v86, v87
	v_max3_f32 v182, v182, v88, v89
	v_max3_f32 v182, v182, v90, v91
	v_max3_f32 v182, v182, v92, v93
	v_max3_f32 v182, v182, v94, v95
	v_mov_b32_e32 v183, v182
	s_nop 1
	v_permlane32_swap_b32_e32 v182, v183
	v_max_f32_e32 v183, v183, v183
	v_max_f32_e32 v182, v182, v182
	v_max_f32_e32 v182, v182, v183
	v_sub_f32_e32 v182, v182, v151
	v_cmp_lt_f32_e32 vcc, s20, v182
	s_cbranch_vccz .LBB0_2066
	v_max_f32_e32 v182, v182, v182
	v_max_f32_e32 v183, 0, v182
	v_exp_f32_e64 v182, -v183
	v_add_f32_e32 v151, v151, v183
	v_pk_mul_f32 v[78:79], v[78:79], v[182:183] op_sel_hi:[1,0]
	v_pk_mul_f32 v[76:77], v[76:77], v[182:183] op_sel_hi:[1,0]
	v_pk_mul_f32 v[74:75], v[74:75], v[182:183] op_sel_hi:[1,0]
	v_pk_mul_f32 v[72:73], v[72:73], v[182:183] op_sel_hi:[1,0]
	v_pk_mul_f32 v[70:71], v[70:71], v[182:183] op_sel_hi:[1,0]
	v_pk_mul_f32 v[68:69], v[68:69], v[182:183] op_sel_hi:[1,0]
	v_pk_mul_f32 v[66:67], v[66:67], v[182:183] op_sel_hi:[1,0]
	v_pk_mul_f32 v[64:65], v[64:65], v[182:183] op_sel_hi:[1,0]
	v_pk_mul_f32 v[46:47], v[46:47], v[182:183] op_sel_hi:[1,0]
	v_pk_mul_f32 v[44:45], v[44:45], v[182:183] op_sel_hi:[1,0]
	v_pk_mul_f32 v[42:43], v[42:43], v[182:183] op_sel_hi:[1,0]
	v_pk_mul_f32 v[40:41], v[40:41], v[182:183] op_sel_hi:[1,0]
	v_pk_mul_f32 v[38:39], v[38:39], v[182:183] op_sel_hi:[1,0]
	v_pk_mul_f32 v[36:37], v[36:37], v[182:183] op_sel_hi:[1,0]
	v_pk_mul_f32 v[34:35], v[34:35], v[182:183] op_sel_hi:[1,0]
	v_pk_mul_f32 v[32:33], v[32:33], v[182:183] op_sel_hi:[1,0]
	v_pk_mul_f32 v[30:31], v[30:31], v[182:183] op_sel_hi:[1,0]
	v_pk_mul_f32 v[28:29], v[28:29], v[182:183] op_sel_hi:[1,0]
	v_pk_mul_f32 v[26:27], v[26:27], v[182:183] op_sel_hi:[1,0]
	v_pk_mul_f32 v[24:25], v[24:25], v[182:183] op_sel_hi:[1,0]
	v_pk_mul_f32 v[22:23], v[22:23], v[182:183] op_sel_hi:[1,0]
	v_pk_mul_f32 v[20:21], v[20:21], v[182:183] op_sel_hi:[1,0]
	v_pk_mul_f32 v[18:19], v[18:19], v[182:183] op_sel_hi:[1,0]
	v_pk_mul_f32 v[16:17], v[16:17], v[182:183] op_sel_hi:[1,0]
	v_pk_mul_f32 v[14:15], v[14:15], v[182:183] op_sel_hi:[1,0]
	v_pk_mul_f32 v[12:13], v[12:13], v[182:183] op_sel_hi:[1,0]
	v_pk_mul_f32 v[10:11], v[10:11], v[182:183] op_sel_hi:[1,0]
	v_pk_mul_f32 v[8:9], v[8:9], v[182:183] op_sel_hi:[1,0]
	v_pk_mul_f32 v[6:7], v[6:7], v[182:183] op_sel_hi:[1,0]
	v_pk_mul_f32 v[4:5], v[4:5], v[182:183] op_sel_hi:[1,0]
	v_pk_mul_f32 v[2:3], v[2:3], v[182:183] op_sel_hi:[1,0]
	v_pk_mul_f32 v[0:1], v[0:1], v[182:183] op_sel_hi:[1,0]
	v_mul_f32_e32 v159, v159, v182
.LBB0_2066:
	v_sub_f32_e32 v80, v80, v151
	v_sub_f32_e32 v81, v81, v151
	v_sub_f32_e32 v82, v82, v151
	v_sub_f32_e32 v83, v83, v151
	v_sub_f32_e32 v84, v84, v151
	v_sub_f32_e32 v85, v85, v151
	v_sub_f32_e32 v86, v86, v151
	v_sub_f32_e32 v87, v87, v151
	v_exp_f32_e32 v80, v80
	v_exp_f32_e32 v81, v81
	v_exp_f32_e32 v82, v82
	v_exp_f32_e32 v83, v83
	v_exp_f32_e32 v84, v84
	v_exp_f32_e32 v85, v85
	v_exp_f32_e32 v86, v86
	v_exp_f32_e32 v87, v87
	ds_read_b64_tr_b16 v[182:183], v155 offset:32768
	ds_read_b64_tr_b16 v[184:185], v163 offset:34816
	ds_read_b64_tr_b16 v[190:191], v153 offset:32768
	ds_read_b64_tr_b16 v[192:193], v161 offset:34816
	ds_read_b64_tr_b16 v[200:201], v163 offset:38912
	ds_read_b64_tr_b16 v[198:199], v155 offset:36864
	v_cvt_pk_bf16_f32 v186, v80, v81
	v_cvt_pk_bf16_f32 v187, v82, v83
	v_cvt_pk_bf16_f32 v188, v84, v85
	v_cvt_pk_bf16_f32 v189, v86, v87
	v_sub_f32_e32 v88, v88, v151
	v_sub_f32_e32 v89, v89, v151
	s_waitcnt lgkmcnt(0)
	v_mfma_f32_32x32x16_bf16 v[64:79], v[182:185], v[186:189], v[64:79]
	ds_read_b64_tr_b16 v[182:183], v165 offset:32768
	ds_read_b64_tr_b16 v[184:185], v168 offset:34816
	ds_read_b64_tr_b16 v[204:205], v161 offset:38912
	ds_read_b64_tr_b16 v[202:203], v153 offset:36864
	v_add_f32_e32 v153, 0, v80
	v_add_f32_e32 v153, v81, v153
	v_add_f32_e32 v153, v82, v153
	v_sub_f32_e32 v90, v90, v151
	v_sub_f32_e32 v91, v91, v151
	v_sub_f32_e32 v92, v92, v151
	v_mfma_f32_32x32x16_bf16 v[32:47], v[190:193], v[186:189], v[32:47]
	ds_read_b64_tr_b16 v[190:191], v167 offset:32768
	ds_read_b64_tr_b16 v[192:193], v169 offset:34816
	ds_read_b64_tr_b16 v[208:209], v168 offset:38912
	ds_read_b64_tr_b16 v[206:207], v165 offset:36864
	v_sub_f32_e32 v93, v93, v151
	v_sub_f32_e32 v94, v94, v151
	v_sub_f32_e32 v95, v95, v151
	v_add_f32_e32 v153, v83, v153
	v_exp_f32_e32 v88, v88
	v_exp_f32_e32 v89, v89
	s_waitcnt lgkmcnt(0)
	v_mfma_f32_32x32x16_bf16 v[16:31], v[182:185], v[186:189], v[16:31]
	v_exp_f32_e32 v90, v90
	v_exp_f32_e32 v91, v91
	v_exp_f32_e32 v92, v92
	v_exp_f32_e32 v93, v93
	ds_read_b64_tr_b16 v[184:185], v169 offset:38912
	ds_read_b64_tr_b16 v[182:183], v167 offset:36864
	v_exp_f32_e32 v94, v94
	v_exp_f32_e32 v95, v95
	v_mfma_f32_32x32x16_bf16 v[0:15], v[190:193], v[186:189], v[0:15]
	v_add_f32_e32 v153, v84, v153
	v_add_f32_e32 v153, v85, v153
	v_add_f32_e32 v153, v86, v153
	v_add_f32_e32 v153, v87, v153
	v_cvt_pk_bf16_f32 v186, v88, v89
	v_cvt_pk_bf16_f32 v187, v90, v91
	v_cvt_pk_bf16_f32 v188, v92, v93
	v_cvt_pk_bf16_f32 v189, v94, v95
	v_add_f32_e32 v153, v88, v153
	v_add_f32_e32 v153, v89, v153
	v_mfma_f32_32x32x16_bf16 v[64:79], v[198:201], v[186:189], v[64:79]
	v_add_f32_e32 v153, v90, v153
	v_add_f32_e32 v153, v91, v153
	v_add_f32_e32 v153, v92, v153
	v_add_f32_e32 v153, v93, v153
	v_add_f32_e32 v153, v94, v153
	v_add_f32_e32 v153, v95, v153
	v_add_f32_e32 v159, v159, v153
	v_mfma_f32_32x32x16_bf16 v[32:47], v[202:205], v[186:189], v[32:47]
	v_mfma_f32_32x32x16_bf16 v[16:31], v[206:209], v[186:189], v[16:31]
	s_waitcnt lgkmcnt(0)
	v_mfma_f32_32x32x16_bf16 v[0:15], v[182:185], v[186:189], v[0:15]
	s_and_b64 vcc, exec, s[2:3]
	s_cbranch_vccz .LBB0_2057
	s_branch .LBB0_2058
.LBB0_2067:
	v_mov_b32_e32 v48, v159
	s_nop 1
	v_permlane32_swap_b32_e32 v159, v48
	v_add_f32_e32 v48, v159, v48
	v_div_scale_f32 v49, s[2:3], v48, v48, 1.0
	v_rcp_f32_e32 v50, v49
	s_mulk_i32 s17, 0x2200
	s_add_i32 s7, s17, 0
	s_waitcnt vmcnt(0) lgkmcnt(0)
	s_barrier
	v_fma_f32 v51, -v49, v50, 1.0
	v_fmac_f32_e32 v50, v51, v50
	v_div_scale_f32 v51, vcc, 1.0, v48, 1.0
	v_mul_f32_e32 v52, v51, v50
	v_fma_f32 v53, -v49, v52, v51
	v_fmac_f32_e32 v52, v53, v50
	v_fma_f32 v49, -v49, v52, v51
	v_div_fmas_f32 v49, v49, v50, v52
	v_div_fixup_f32 v48, v49, v48, 1.0
	v_add3_u32 v49, s7, v195, v181
	v_pk_mul_f32 v[50:51], v[64:65], v[48:49] op_sel_hi:[1,0]
	v_pk_mul_f32 v[52:53], v[66:67], v[48:49] op_sel_hi:[1,0]
	v_cvt_pk_bf16_f32 v50, v50, v51
	v_cvt_pk_bf16_f32 v51, v52, v53
	v_pk_mul_f32 v[52:53], v[68:69], v[48:49] op_sel_hi:[1,0]
	v_pk_mul_f32 v[54:55], v[70:71], v[48:49] op_sel_hi:[1,0]
	v_add_u32_e32 v49, 0xa000, v49
	v_pk_mul_f32 v[32:33], v[32:33], v[48:49] op_sel_hi:[1,0]
	v_pk_mul_f32 v[34:35], v[34:35], v[48:49] op_sel_hi:[1,0]
	v_pk_mul_f32 v[16:17], v[16:17], v[48:49] op_sel_hi:[1,0]
	v_pk_mul_f32 v[18:19], v[18:19], v[48:49] op_sel_hi:[1,0]
	v_pk_mul_f32 v[0:1], v[0:1], v[48:49] op_sel_hi:[1,0]
	v_pk_mul_f32 v[2:3], v[2:3], v[48:49] op_sel_hi:[1,0]
	v_cvt_pk_bf16_f32 v32, v32, v33
	v_cvt_pk_bf16_f32 v33, v34, v35
	v_pk_mul_f32 v[34:35], v[36:37], v[48:49] op_sel_hi:[1,0]
	v_pk_mul_f32 v[36:37], v[38:39], v[48:49] op_sel_hi:[1,0]
	v_cvt_pk_bf16_f32 v16, v16, v17
	v_cvt_pk_bf16_f32 v17, v18, v19
	v_pk_mul_f32 v[18:19], v[20:21], v[48:49] op_sel_hi:[1,0]
	v_pk_mul_f32 v[20:21], v[22:23], v[48:49] op_sel_hi:[1,0]
	v_cvt_pk_bf16_f32 v0, v0, v1
	v_cvt_pk_bf16_f32 v1, v2, v3
	v_pk_mul_f32 v[2:3], v[4:5], v[48:49] op_sel_hi:[1,0]
	v_pk_mul_f32 v[4:5], v[6:7], v[48:49] op_sel_hi:[1,0]
	v_cvt_pk_bf16_f32 v52, v52, v53
	v_cvt_pk_bf16_f32 v53, v54, v55
	v_cvt_pk_bf16_f32 v34, v34, v35
	v_cvt_pk_bf16_f32 v35, v36, v37
	v_cvt_pk_bf16_f32 v18, v18, v19
	v_cvt_pk_bf16_f32 v19, v20, v21
	v_cvt_pk_bf16_f32 v2, v2, v3
	v_cvt_pk_bf16_f32 v3, v4, v5
	ds_write2_b64 v49, v[50:51], v[52:53] offset1:2
	v_pk_mul_f32 v[50:51], v[72:73], v[48:49] op_sel_hi:[1,0]
	v_pk_mul_f32 v[52:53], v[74:75], v[48:49] op_sel_hi:[1,0]
	ds_write2_b64 v49, v[32:33], v[34:35] offset0:8 offset1:10
	v_pk_mul_f32 v[32:33], v[40:41], v[48:49] op_sel_hi:[1,0]
	v_pk_mul_f32 v[34:35], v[42:43], v[48:49] op_sel_hi:[1,0]
	ds_write2_b64 v49, v[16:17], v[18:19] offset0:16 offset1:18
	v_pk_mul_f32 v[16:17], v[24:25], v[48:49] op_sel_hi:[1,0]
	v_pk_mul_f32 v[18:19], v[26:27], v[48:49] op_sel_hi:[1,0]
	ds_write2_b64 v49, v[0:1], v[2:3] offset0:24 offset1:26
	v_pk_mul_f32 v[0:1], v[8:9], v[48:49] op_sel_hi:[1,0]
	v_pk_mul_f32 v[2:3], v[10:11], v[48:49] op_sel_hi:[1,0]
	v_cvt_pk_bf16_f32 v50, v50, v51
	v_cvt_pk_bf16_f32 v51, v52, v53
	v_pk_mul_f32 v[52:53], v[76:77], v[48:49] op_sel_hi:[1,0]
	v_pk_mul_f32 v[54:55], v[78:79], v[48:49] op_sel_hi:[1,0]
	v_cvt_pk_bf16_f32 v32, v32, v33
	v_cvt_pk_bf16_f32 v33, v34, v35
	v_pk_mul_f32 v[34:35], v[44:45], v[48:49] op_sel_hi:[1,0]
	v_pk_mul_f32 v[36:37], v[46:47], v[48:49] op_sel_hi:[1,0]
	v_cvt_pk_bf16_f32 v16, v16, v17
	v_cvt_pk_bf16_f32 v17, v18, v19
	v_pk_mul_f32 v[18:19], v[28:29], v[48:49] op_sel_hi:[1,0]
	v_pk_mul_f32 v[20:21], v[30:31], v[48:49] op_sel_hi:[1,0]
	v_cvt_pk_bf16_f32 v0, v0, v1
	v_cvt_pk_bf16_f32 v1, v2, v3
	v_pk_mul_f32 v[2:3], v[12:13], v[48:49] op_sel_hi:[1,0]
	v_pk_mul_f32 v[4:5], v[14:15], v[48:49] op_sel_hi:[1,0]
	v_cvt_pk_bf16_f32 v52, v52, v53
	v_cvt_pk_bf16_f32 v53, v54, v55
	v_cvt_pk_bf16_f32 v34, v34, v35
	v_cvt_pk_bf16_f32 v35, v36, v37
	v_cvt_pk_bf16_f32 v18, v18, v19
	v_cvt_pk_bf16_f32 v19, v20, v21
	v_cvt_pk_bf16_f32 v2, v2, v3
	v_cvt_pk_bf16_f32 v3, v4, v5
	s_mulk_i32 s13, 0x1800
	s_mul_hi_u32 s2, s12, 0x1800
	ds_write2_b64 v49, v[50:51], v[52:53] offset0:4 offset1:6
	ds_write2_b64 v49, v[32:33], v[34:35] offset0:12 offset1:14
	ds_write2_b64 v49, v[16:17], v[18:19] offset0:20 offset1:22
	ds_write2_b64 v49, v[0:1], v[2:3] offset0:28 offset1:30
	s_add_i32 s2, s2, s13
	s_mulk_i32 s12, 0x1800
	s_waitcnt lgkmcnt(0)
	s_add_u32 s3, s4, s12
	v_add3_u32 v14, s7, v144, v196
	s_addc_u32 s4, s5, s2
	ds_read_b128 v[0:3], v14 offset:40960
	s_add_u32 s2, s3, s6
	s_addc_u32 s3, s4, 0
	v_mov_b32_e32 v159, 0
	ds_read_b128 v[4:7], v14 offset:42048
	v_lshl_add_u64 v[8:9], s[2:3], 0, v[158:159]
	v_mov_b32_e32 v147, v159
	v_lshl_add_u64 v[10:11], v[8:9], 0, v[146:147]
	s_movk_i32 s2, 0x6000
	s_waitcnt lgkmcnt(0)
	global_store_dwordx4 v[10:11], v[0:3], off
	v_mov_b32_e32 v149, v159
	v_mov_b32_e32 v153, v159
	v_add_co_u32_e32 v0, vcc, s2, v10
	s_mov_b32 s2, 0xc000
	s_nop 0
	v_addc_co_u32_e32 v1, vcc, 0, v11, vcc
	global_store_dwordx4 v[0:1], v[4:7], off
	ds_read_b128 v[0:3], v14 offset:43136
	ds_read_b128 v[4:7], v14 offset:44224
	v_add_co_u32_e32 v12, vcc, s2, v10
	s_mov_b32 s2, 0x12000
	s_nop 0
	v_addc_co_u32_e32 v13, vcc, 0, v11, vcc
	v_add_co_u32_e32 v10, vcc, s2, v10
	s_waitcnt lgkmcnt(0)
	global_store_dwordx4 v[12:13], v[0:3], off
	v_addc_co_u32_e32 v11, vcc, 0, v11, vcc
	ds_read_b128 v[0:3], v14 offset:45312
	global_store_dwordx4 v[10:11], v[4:7], off
	ds_read_b128 v[4:7], v14 offset:46400
	v_lshl_add_u64 v[10:11], v[8:9], 0, v[148:149]
	v_mov_b32_e32 v151, v159
	s_waitcnt lgkmcnt(0)
	global_store_dwordx4 v[10:11], v[0:3], off
	v_lshl_add_u64 v[10:11], v[8:9], 0, v[152:153]
	ds_read_b128 v[0:3], v14 offset:47488
	global_store_dwordx4 v[10:11], v[4:7], off
	ds_read_b128 v[4:7], v14 offset:48576
	v_lshl_add_u64 v[10:11], v[8:9], 0, v[150:151]
	v_mov_b32_e32 v155, v159
	s_waitcnt lgkmcnt(0)
	global_store_dwordx4 v[10:11], v[0:3], off
	s_nop 1
	v_lshl_add_u64 v[0:1], v[8:9], 0, v[154:155]
	global_store_dwordx4 v[0:1], v[4:7], off
